# GEMM k-loops: one counted vmcnt wait per two staging segments (vmcnt(7) every other segment instead of vmcnt(8) every segment)
# speedup vs baseline: 1.0136x; 1.0010x over previous
; template <int MODE>
; __device__ __forceinline__ void gemm_tile(const Params& P, int tm, int tn, unsigned char* smem) {
;     ...
;     const int tid = opaque_tid(), lane = tid & 63, wave = tid >> 6, wr = wave >> 1, wc = wave & 1, g = lane >> 4, lr = lane & 15;
;     const int m0 = tm * 128, n0 = tn * 128;
;     const int srow = tid >> 3, sc = tid & 7;
;     constexpr unsigned LDA = (MODE == 2 ? NZ : 1024) * 2u;
;     unsigned aoff, boff; int soff0;
;     {
;         int ar = m0 + srow;
;         if (MODE == 2) { const int b = ar >> 11, t = ar & 2047; ar = b * L + NMETA + t; }
;         aoff = (unsigned)ar * LDA + (unsigned)sc * 16u;
;         boff = (unsigned)(n0 + srow) * 2048u + (unsigned)sc * 16u;
;         soff0 = srow * 128 + ((sc ^ (srow & 7)) << 4);
;     }
;     const unsigned char* Ab = (const unsigned char*)A; const unsigned char* Bb = (const unsigned char*)Bt;
;     float4 ssp0, ssp1, ssp2, ssp3;
;     if (MODE == 3) {
;         const float* ssq = (const float*)(P.ws + WS_SSQ) + (size_t)(m0 + wr * 64 + lr) * 16 + 4 * g;
;         ssp0 = *(const float4*)(ssq); ssp1 = *(const float4*)(ssq + 16 * 16); ssp2 = *(const float4*)(ssq + 32 * 16); ssp3 = *(const float4*)(ssq + 48 * 16);
;     }
;     f32x4 acc[4][4];
; #pragma unroll
;     for (int i = 0; i < 4; ++i)
; #pragma unroll
;         for (int j = 0; j < 4; ++j) acc[i][j] = (f32x4){0.f, 0.f, 0.f, 0.f};
;     uint4 ra0, ra1, ra2, ra3, rb0, rb1, rb2, rb3;
;     ...
;     unsigned char* sA0 = smem; unsigned char* sB0 = smem + 16384; unsigned char* sA1 = smem + 32768; unsigned char* sB1 = smem + 49152;
;     G_LOAD(0)
;     G_WRITE(sA0, sB0)
;     __syncthreads();
;     const int arow_off = (wr * 64 + lr) * 128, brow_off = (wc * 64 + lr) * 128, sw = lr & 7;
;     G_LOAD(1)
;     for (int kt = 0; kt < 16; ++kt) {
;         unsigned char* sA = (kt & 1) ? sA1 : sA0; unsigned char* sB = (kt & 1) ? sB1 : sB0;
;         unsigned char* nA = (kt & 1) ? sA0 : sA1; unsigned char* nB = (kt & 1) ? sB0 : sB1;
;         bf16x8 fa[4], fb[4], ga[4], gb[4];
;         const int ch0 = ((g ^ sw) << 4), ch1 = (((4 + g) ^ sw) << 4);
;         const unsigned ko = (unsigned)(kt + 2) * 128u;
;         const unsigned koa = ko + ((MODE == 2 && kt + 2 >= 8) ? (unsigned)(ZC_FQ - 512) * 2u : 0u);
;         const bool wr_ok = kt < 15, ld_ok = kt < 14;
; #pragma unroll
.LBB0_182:
	s_mul_hi_i32 s0, s35, 0x92492493
	s_add_i32 s0, s0, s35
	s_lshr_b32 s1, s0, 31
	s_ashr_i32 s0, s0, 7
	s_add_i32 s1, s0, s1
	s_mul_i32 s0, s1, 0xffffff20
	s_lshl_b32 s10, s1, 3
	s_add_i32 s0, s35, s0
	s_sub_i32 s10, 0x81, s10
	s_cmpk_gt_i32 s35, 0xdff
	s_cselect_b32 s10, s10, 8
	s_abs_i32 s11, s10
	v_cvt_f32_u32_e32 v2, s11
	s_ashr_i32 s0, s0, 31
	s_mul_i32 s13, s1, 0xe0
	s_sub_i32 s13, s0, s13
	v_rcp_iflag_f32_e32 v2, v2
	s_ashr_i32 s12, s10, 31
	s_add_i32 s13, s35, s13
	s_xor_b32 s12, s0, s12
	v_mul_f32_e32 v2, 0x4f7ffffe, v2
	v_cvt_u32_f32_e32 v2, v2
	s_xor_b32 s0, s13, s0
	s_sub_i32 s13, 0, s11
	s_mulk_i32 s1, 0xd8
	v_readfirstlane_b32 s42, v2
	s_mul_i32 s13, s13, s42
	s_mul_hi_u32 s13, s42, s13
	s_add_i32 s42, s42, s13
	s_mul_hi_u32 s13, s0, s42
	s_mul_i32 s42, s13, s11
	s_sub_i32 s0, s0, s42
	s_add_i32 s42, s13, 1
	s_sub_i32 s43, s0, s11
	s_cmp_ge_u32 s0, s11
	s_cselect_b32 s13, s42, s13
	s_cselect_b32 s0, s43, s0
	s_add_i32 s42, s13, 1
	s_cmp_ge_u32 s0, s11
	s_cselect_b32 s0, s42, s13
	s_xor_b32 s0, s0, s12
	s_sub_i32 s0, s0, s12
	s_mul_i32 s10, s10, s0
	s_add_i32 s10, s10, s1
	s_sub_i32 s1, s35, s10
	v_mov_b32_e32 v79, v0
	s_lshl_b32 s42, s1, 7
	v_ashrrev_i32_e32 v2, 3, v79
	v_lshlrev_b32_e32 v4, 4, v79
	s_lshl_b32 s10, s0, 7
	v_add_u32_e32 v3, s42, v2
	v_and_b32_e32 v4, 0x70, v4
	v_add_u32_e32 v5, s10, v2
	v_lshl_or_b32 v8, v3, 11, v4
	v_lshl_or_b32 v5, v5, 11, v4
	v_add_u32_e32 v3, 0x10000, v8
	v_add_u32_e32 v4, 0x20000, v8
	global_load_dwordx4 v[10:13], v3, s[36:37]
	global_load_dwordx4 v[14:17], v4, s[36:37]
	v_add_u32_e32 v3, 0x20000, v5
	v_add_u32_e32 v4, 0x30000, v5
	global_load_dwordx4 v[18:21], v3, s[4:5]
	global_load_dwordx4 v[22:25], v4, s[4:5]
	global_load_dwordx4 v[26:29], v8, s[36:37]
	global_load_dwordx4 v[30:33], v5, s[4:5]
	v_add_u32_e32 v3, 0x30000, v8
	v_add_u32_e32 v4, 0x10000, v5
	global_load_dwordx4 v[34:37], v3, s[36:37]
	global_load_dwordx4 v[38:41], v4, s[4:5]
	v_xor_b32_e32 v3, v2, v79
	v_lshlrev_b32_e32 v2, 7, v2
	v_lshlrev_b32_e32 v3, 4, v3
	v_and_or_b32 v2, v3, s20, v2
	v_add_u32_e32 v2, 0, v2
	v_or_b32_e32 v9, 0x80, v8
	v_or_b32_e32 v3, 0x80, v5
	v_add_u32_e32 v4, 0x10080, v5
	v_add_u32_e32 v6, 0x20080, v5
	v_add_u32_e32 v7, 0x30080, v5
	v_add_u32_e32 v42, 0x10080, v8
	v_add_u32_e32 v43, 0x20080, v8
	v_add_u32_e32 v44, 0x30080, v8
	v_and_b32_e32 v80, 15, v79
	v_ashrrev_i32_e32 v81, 7, v79
	v_bfe_u32 v82, v79, 6, 1
	v_bfe_u32 v83, v79, 4, 2
	s_waitcnt vmcnt(5)
	ds_write_b128 v2, v[18:21] offset:24576
	s_waitcnt vmcnt(4)
	ds_write_b128 v2, v[22:25] offset:28672
	s_waitcnt vmcnt(3)
	ds_write_b128 v2, v[26:29]
	s_waitcnt vmcnt(2)
	ds_write_b128 v2, v[30:33] offset:16384
	ds_write_b128 v2, v[10:13] offset:4096
	ds_write_b128 v2, v[14:17] offset:8192
	s_waitcnt vmcnt(1)
	ds_write_b128 v2, v[34:37] offset:12288
	s_waitcnt vmcnt(0)
	ds_write_b128 v2, v[38:41] offset:20480
	s_waitcnt lgkmcnt(0)
	s_barrier
	global_load_dwordx4 v[10:13], v9, s[36:37]
	global_load_dwordx4 v[14:17], v42, s[36:37]
	global_load_dwordx4 v[18:21], v43, s[36:37]
	global_load_dwordx4 v[22:25], v44, s[36:37]
	global_load_dwordx4 v[26:29], v3, s[4:5]
	global_load_dwordx4 v[30:33], v4, s[4:5]
	global_load_dwordx4 v[34:37], v6, s[4:5]
	global_load_dwordx4 v[38:41], v7, s[4:5]
	v_lshrrev_b32_e32 v3, 4, v79
	v_lshlrev_b32_e32 v4, 7, v80
	v_and_b32_e32 v9, 7, v79
	v_lshl_or_b32 v6, v81, 13, v4
	v_bitop3_b32 v3, v3, v9, 3 bitop3:0x6c
	v_lshl_or_b32 v4, v82, 13, v4
	v_lshlrev_b32_e32 v3, 4, v3
	v_add_u32_e32 v66, 0, v6
	v_add_u32_e32 v6, v66, v3
	v_add_u32_e32 v4, 0, v4
	v_add_u32_e32 v7, v4, v3
	ds_read_b128 v[42:45], v6
	ds_read_b128 v[46:49], v6 offset:2048
	ds_read_b128 v[50:53], v7 offset:16384
	ds_read_b128 v[54:57], v7 offset:18432
	ds_read_b128 v[58:61], v6 offset:4096
	ds_read_b128 v[62:65], v6 offset:6144
	ds_read_b128 v[84:87], v7 offset:20480
	ds_read_b128 v[88:91], v7 offset:22528
	v_bitop3_b32 v3, v83, v9, 4 bitop3:0x36
	v_lshlrev_b32_e32 v9, 4, v3
	s_setprio 2
	global_load_dwordx4 v[92:95], v8, s[36:37] offset:256
	s_waitcnt vmcnt(7)
	ds_write_b128 v2, v[10:13] offset:32768
	v_add_u32_e32 v3, v66, v9
	v_add_u32_e32 v4, v4, v9
	ds_read_b128 v[10:13], v3
	ds_read_b128 v[96:99], v4 offset:16384
	s_waitcnt lgkmcnt(8)
	v_mfma_f32_16x16x32_bf16 v[100:103], v[50:53], v[42:45], 0
	s_waitcnt lgkmcnt(7)
	v_mfma_f32_16x16x32_bf16 v[104:107], v[54:57], v[42:45], 0
	s_waitcnt lgkmcnt(4)
	v_mfma_f32_16x16x32_bf16 v[108:111], v[84:87], v[42:45], 0
	s_waitcnt lgkmcnt(3)
	v_mfma_f32_16x16x32_bf16 v[42:45], v[88:91], v[42:45], 0
	v_add_u32_e32 v216, 0x10000, v8
	global_load_dwordx4 v[112:115], v216, s[36:37] offset:256
	ds_write_b128 v2, v[14:17] offset:36864
	ds_read_b128 v[14:17], v3 offset:2048
	ds_read_b128 v[116:119], v4 offset:18432
	v_mfma_f32_16x16x32_bf16 v[120:123], v[50:53], v[46:49], 0
	v_mfma_f32_16x16x32_bf16 v[124:127], v[54:57], v[46:49], 0
	v_mfma_f32_16x16x32_bf16 v[132:135], v[84:87], v[46:49], 0
	v_mfma_f32_16x16x32_bf16 v[46:49], v[88:91], v[46:49], 0
	v_add_u32_e32 v217, 0x20000, v8
	global_load_dwordx4 v[146:149], v217, s[36:37] offset:256
	s_waitcnt vmcnt(7)
	ds_write_b128 v2, v[18:21] offset:40960
	ds_read_b128 v[18:21], v3 offset:4096
	ds_read_b128 v[150:153], v4 offset:20480
	v_mfma_f32_16x16x32_bf16 v[154:157], v[50:53], v[58:61], 0
	v_mfma_f32_16x16x32_bf16 v[158:161], v[54:57], v[58:61], 0
	v_mfma_f32_16x16x32_bf16 v[162:165], v[84:87], v[58:61], 0
	v_mfma_f32_16x16x32_bf16 v[58:61], v[88:91], v[58:61], 0
	v_add_u32_e32 v218, 0x30000, v8
	global_load_dwordx4 v[166:169], v218, s[36:37] offset:256
	ds_write_b128 v2, v[22:25] offset:45056
	ds_read_b128 v[22:25], v3 offset:6144
	ds_read_b128 v[170:173], v4 offset:22528
	v_mfma_f32_16x16x32_bf16 v[50:53], v[50:53], v[62:65], 0
	v_mfma_f32_16x16x32_bf16 v[54:57], v[54:57], v[62:65], 0
	v_mfma_f32_16x16x32_bf16 v[84:87], v[84:87], v[62:65], 0
	v_mfma_f32_16x16x32_bf16 v[62:65], v[88:91], v[62:65], 0
	global_load_dwordx4 v[88:91], v5, s[4:5] offset:256
	s_waitcnt vmcnt(7)
; template <int MODE>
; __device__ __forceinline__ void gemm_tile(const Params& P, int tm, int tn, unsigned char* smem) {
;     ...
;     for (int kt = 0; kt < 16; ++kt) {
;         unsigned char* sA = (kt & 1) ? sA1 : sA0; unsigned char* sB = (kt & 1) ? sB1 : sB0;
;         unsigned char* nA = (kt & 1) ? sA0 : sA1; unsigned char* nB = (kt & 1) ? sB0 : sB1;
;         bf16x8 fa[4], fb[4], ga[4], gb[4];
;         const int ch0 = ((g ^ sw) << 4), ch1 = (((4 + g) ^ sw) << 4);
;         const unsigned ko = (unsigned)(kt + 2) * 128u;
;         const unsigned koa = ko + ((MODE == 2 && kt + 2 >= 8) ? (unsigned)(ZC_FQ - 512) * 2u : 0u);
;         const bool wr_ok = kt < 15, ld_ok = kt < 14;
; #pragma unroll
;         for (int i = 0; i < 4; ++i) { fa[i] = *(const bf16x8*)(sA + arow_off + i * 2048 + ch0); fb[i] = *(const bf16x8*)(sB + brow_off + i * 2048 + ch0); }
;         __builtin_amdgcn_sched_barrier(0);
;         __builtin_amdgcn_s_setprio(2);
;         if (wr_ok) *(uint4*)(nA + soff0) = ra0;
;         if (ld_ok) ra0 = *(const uint4*)(Ab + (aoff + 0u * LDA + koa));
;         ga[0] = *(const bf16x8*)(sA + arow_off + 0 * 2048 + ch1); gb[0] = *(const bf16x8*)(sB + brow_off + 0 * 2048 + ch1);
;         __builtin_amdgcn_sched_barrier(0);
; #pragma unroll
;         for (int j = 0; j < 4; ++j) acc[0][j] = __builtin_amdgcn_mfma_f32_16x16x32_bf16(fb[j], fa[0], acc[0][j], 0, 0, 0);
;         __builtin_amdgcn_sched_barrier(0);
;         if (wr_ok) *(uint4*)(nA + soff0 + 4096) = ra1;
;         if (ld_ok) ra1 = *(const uint4*)(Ab + (aoff + 32u * LDA + koa));
;         ga[1] = *(const bf16x8*)(sA + arow_off + 1 * 2048 + ch1); gb[1] = *(const bf16x8*)(sB + brow_off + 1 * 2048 + ch1);
;         __builtin_amdgcn_sched_barrier(0);
; #pragma unroll
;         for (int j = 0; j < 4; ++j) acc[1][j] = __builtin_amdgcn_mfma_f32_16x16x32_bf16(fb[j], fa[1], acc[1][j], 0, 0, 0);
;         __builtin_amdgcn_sched_barrier(0);
;         if (wr_ok) *(uint4*)(nA + soff0 + 8192) = ra2;
;         if (ld_ok) ra2 = *(const uint4*)(Ab + (aoff + 64u * LDA + koa));
;         ga[2] = *(const bf16x8*)(sA + arow_off + 2 * 2048 + ch1); gb[2] = *(const bf16x8*)(sB + brow_off + 2 * 2048 + ch1);
;         __builtin_amdgcn_sched_barrier(0);
; #pragma unroll
;         for (int j = 0; j < 4; ++j) acc[2][j] = __builtin_amdgcn_mfma_f32_16x16x32_bf16(fb[j], fa[2], acc[2][j], 0, 0, 0);
	ds_write_b128 v2, v[26:29] offset:49152
	s_waitcnt lgkmcnt(10)
	v_mfma_f32_16x16x32_bf16 v[26:29], v[96:99], v[10:13], v[100:103]
	s_waitcnt lgkmcnt(7)
	v_mfma_f32_16x16x32_bf16 v[100:103], v[116:119], v[10:13], v[104:107]
	s_waitcnt lgkmcnt(4)
	v_mfma_f32_16x16x32_bf16 v[104:107], v[150:153], v[10:13], v[108:111]
	s_waitcnt lgkmcnt(1)
	v_mfma_f32_16x16x32_bf16 v[10:13], v[170:173], v[10:13], v[42:45]
	v_add_u32_e32 v219, 0x10000, v5
	global_load_dwordx4 v[42:45], v219, s[4:5] offset:256
	ds_write_b128 v2, v[30:33] offset:53248
	v_mfma_f32_16x16x32_bf16 v[30:33], v[96:99], v[14:17], v[120:123]
	v_mfma_f32_16x16x32_bf16 v[108:111], v[116:119], v[14:17], v[124:127]
	v_mfma_f32_16x16x32_bf16 v[120:123], v[150:153], v[14:17], v[132:135]
	v_mfma_f32_16x16x32_bf16 v[14:17], v[170:173], v[14:17], v[46:49]
	v_add_u32_e32 v220, 0x20000, v5
	global_load_dwordx4 v[46:49], v220, s[4:5] offset:256
	s_waitcnt vmcnt(7)
	ds_write_b128 v2, v[34:37] offset:57344
	v_mfma_f32_16x16x32_bf16 v[34:37], v[96:99], v[18:21], v[154:157]
	v_mfma_f32_16x16x32_bf16 v[124:127], v[116:119], v[18:21], v[158:161]
	v_mfma_f32_16x16x32_bf16 v[132:135], v[150:153], v[18:21], v[162:165]
	v_mfma_f32_16x16x32_bf16 v[18:21], v[170:173], v[18:21], v[58:61]
	v_add_u32_e32 v221, 0x30000, v5
	global_load_dwordx4 v[58:61], v221, s[4:5] offset:256
	ds_write_b128 v2, v[38:41] offset:61440
	v_mfma_f32_16x16x32_bf16 v[38:41], v[96:99], v[22:25], v[50:53]
	v_mfma_f32_16x16x32_bf16 v[50:53], v[116:119], v[22:25], v[54:57]
	v_mfma_f32_16x16x32_bf16 v[54:57], v[150:153], v[22:25], v[84:87]
	v_mfma_f32_16x16x32_bf16 v[22:25], v[170:173], v[22:25], v[62:65]
	s_setprio 0
	s_waitcnt lgkmcnt(0)
	s_barrier
	ds_read_b128 v[62:65], v6 offset:32768
	ds_read_b128 v[84:87], v6 offset:34816
	ds_read_b128 v[96:99], v7 offset:49152
	ds_read_b128 v[116:119], v7 offset:51200
	ds_read_b128 v[150:153], v6 offset:36864
	ds_read_b128 v[154:157], v6 offset:38912
	ds_read_b128 v[158:161], v7 offset:53248
	ds_read_b128 v[162:165], v7 offset:55296
	s_setprio 2
	global_load_dwordx4 v[170:173], v8, s[36:37] offset:384
	s_waitcnt vmcnt(7)
	ds_write_b128 v2, v[92:95]
	ds_read_b128 v[92:95], v3 offset:32768
	ds_read_b128 v[174:177], v4 offset:49152
	s_waitcnt lgkmcnt(8)
	v_mfma_f32_16x16x32_bf16 v[26:29], v[96:99], v[62:65], v[26:29]
	s_waitcnt lgkmcnt(3)
	v_mfma_f32_16x16x32_bf16 v[10:13], v[162:165], v[62:65], v[10:13]
	v_mfma_f32_16x16x32_bf16 v[100:103], v[116:119], v[62:65], v[100:103]
	v_mfma_f32_16x16x32_bf16 v[104:107], v[158:161], v[62:65], v[104:107]
	global_load_dwordx4 v[62:65], v216, s[36:37] offset:384
	ds_write_b128 v2, v[112:115] offset:4096
	ds_read_b128 v[112:115], v3 offset:34816
	ds_read_b128 v[178:181], v4 offset:51200
	v_mfma_f32_16x16x32_bf16 v[30:33], v[96:99], v[84:87], v[30:33]
	v_mfma_f32_16x16x32_bf16 v[14:17], v[162:165], v[84:87], v[14:17]
	v_mfma_f32_16x16x32_bf16 v[108:111], v[116:119], v[84:87], v[108:111]
	v_mfma_f32_16x16x32_bf16 v[120:123], v[158:161], v[84:87], v[120:123]
	global_load_dwordx4 v[84:87], v217, s[36:37] offset:384
	s_waitcnt vmcnt(7)
	ds_write_b128 v2, v[146:149] offset:8192
	ds_read_b128 v[146:149], v3 offset:36864
	ds_read_b128 v[182:185], v4 offset:53248
	v_mfma_f32_16x16x32_bf16 v[34:37], v[96:99], v[150:153], v[34:37]
	v_mfma_f32_16x16x32_bf16 v[18:21], v[162:165], v[150:153], v[18:21]
	v_mfma_f32_16x16x32_bf16 v[124:127], v[116:119], v[150:153], v[124:127]
	v_mfma_f32_16x16x32_bf16 v[132:135], v[158:161], v[150:153], v[132:135]
	global_load_dwordx4 v[150:153], v218, s[36:37] offset:384
	ds_write_b128 v2, v[166:169] offset:12288
	ds_read_b128 v[166:169], v3 offset:38912
	ds_read_b128 v[186:189], v4 offset:55296
	v_mfma_f32_16x16x32_bf16 v[38:41], v[96:99], v[154:157], v[38:41]
	v_mfma_f32_16x16x32_bf16 v[50:53], v[116:119], v[154:157], v[50:53]
	v_mfma_f32_16x16x32_bf16 v[54:57], v[158:161], v[154:157], v[54:57]
	v_mfma_f32_16x16x32_bf16 v[22:25], v[162:165], v[154:157], v[22:25]
	global_load_dwordx4 v[96:99], v5, s[4:5] offset:384
	s_waitcnt vmcnt(7)
	ds_write_b128 v2, v[88:91] offset:16384
	s_waitcnt lgkmcnt(10)
	v_mfma_f32_16x16x32_bf16 v[26:29], v[174:177], v[92:95], v[26:29]
	s_waitcnt lgkmcnt(1)
	v_mfma_f32_16x16x32_bf16 v[10:13], v[186:189], v[92:95], v[10:13]
	v_mfma_f32_16x16x32_bf16 v[88:91], v[178:181], v[92:95], v[100:103]
	v_mfma_f32_16x16x32_bf16 v[100:103], v[182:185], v[92:95], v[104:107]
	global_load_dwordx4 v[92:95], v219, s[4:5] offset:384
	ds_write_b128 v2, v[42:45] offset:20480
	v_mfma_f32_16x16x32_bf16 v[30:33], v[174:177], v[112:115], v[30:33]
	v_mfma_f32_16x16x32_bf16 v[42:45], v[178:181], v[112:115], v[108:111]
	v_mfma_f32_16x16x32_bf16 v[14:17], v[186:189], v[112:115], v[14:17]
	v_mfma_f32_16x16x32_bf16 v[104:107], v[182:185], v[112:115], v[120:123]
	global_load_dwordx4 v[108:111], v220, s[4:5] offset:384
	s_waitcnt vmcnt(7)
	ds_write_b128 v2, v[46:49] offset:24576
	v_mfma_f32_16x16x32_bf16 v[34:37], v[174:177], v[146:149], v[34:37]
	v_mfma_f32_16x16x32_bf16 v[46:49], v[178:181], v[146:149], v[124:127]
	v_mfma_f32_16x16x32_bf16 v[18:21], v[186:189], v[146:149], v[18:21]
	v_mfma_f32_16x16x32_bf16 v[112:115], v[182:185], v[146:149], v[132:135]
	global_load_dwordx4 v[116:119], v221, s[4:5] offset:384
	ds_write_b128 v2, v[58:61] offset:28672
	v_mfma_f32_16x16x32_bf16 v[38:41], v[174:177], v[166:169], v[38:41]
	v_mfma_f32_16x16x32_bf16 v[50:53], v[178:181], v[166:169], v[50:53]
	v_mfma_f32_16x16x32_bf16 v[54:57], v[182:185], v[166:169], v[54:57]
	v_mfma_f32_16x16x32_bf16 v[22:25], v[186:189], v[166:169], v[22:25]
	s_setprio 0
	s_waitcnt lgkmcnt(0)
	s_barrier
; template <int MODE>
; __device__ __forceinline__ void gemm_tile(const Params& P, int tm, int tn, unsigned char* smem) {
;     ...
;     for (int kt = 0; kt < 16; ++kt) {
;         unsigned char* sA = (kt & 1) ? sA1 : sA0; unsigned char* sB = (kt & 1) ? sB1 : sB0;
;         unsigned char* nA = (kt & 1) ? sA0 : sA1; unsigned char* nB = (kt & 1) ? sB0 : sB1;
;         bf16x8 fa[4], fb[4], ga[4], gb[4];
;         const int ch0 = ((g ^ sw) << 4), ch1 = (((4 + g) ^ sw) << 4);
;         const unsigned ko = (unsigned)(kt + 2) * 128u;
;         const unsigned koa = ko + ((MODE == 2 && kt + 2 >= 8) ? (unsigned)(ZC_FQ - 512) * 2u : 0u);
;         const bool wr_ok = kt < 15, ld_ok = kt < 14;
; #pragma unroll
;         for (int i = 0; i < 4; ++i) { fa[i] = *(const bf16x8*)(sA + arow_off + i * 2048 + ch0); fb[i] = *(const bf16x8*)(sB + brow_off + i * 2048 + ch0); }
;         __builtin_amdgcn_sched_barrier(0);
;         __builtin_amdgcn_s_setprio(2);
;         if (wr_ok) *(uint4*)(nA + soff0) = ra0;
;         if (ld_ok) ra0 = *(const uint4*)(Ab + (aoff + 0u * LDA + koa));
;         ga[0] = *(const bf16x8*)(sA + arow_off + 0 * 2048 + ch1); gb[0] = *(const bf16x8*)(sB + brow_off + 0 * 2048 + ch1);
;         __builtin_amdgcn_sched_barrier(0);
; #pragma unroll
;         for (int j = 0; j < 4; ++j) acc[0][j] = __builtin_amdgcn_mfma_f32_16x16x32_bf16(fb[j], fa[0], acc[0][j], 0, 0, 0);
;         __builtin_amdgcn_sched_barrier(0);
;         if (wr_ok) *(uint4*)(nA + soff0 + 4096) = ra1;
;         if (ld_ok) ra1 = *(const uint4*)(Ab + (aoff + 32u * LDA + koa));
;         ga[1] = *(const bf16x8*)(sA + arow_off + 1 * 2048 + ch1); gb[1] = *(const bf16x8*)(sB + brow_off + 1 * 2048 + ch1);
;         __builtin_amdgcn_sched_barrier(0);
; #pragma unroll
;         for (int j = 0; j < 4; ++j) acc[1][j] = __builtin_amdgcn_mfma_f32_16x16x32_bf16(fb[j], fa[1], acc[1][j], 0, 0, 0);
;         __builtin_amdgcn_sched_barrier(0);
;         if (wr_ok) *(uint4*)(nA + soff0 + 8192) = ra2;
;         if (ld_ok) ra2 = *(const uint4*)(Ab + (aoff + 64u * LDA + koa));
;         ga[2] = *(const bf16x8*)(sA + arow_off + 2 * 2048 + ch1); gb[2] = *(const bf16x8*)(sB + brow_off + 2 * 2048 + ch1);
;         __builtin_amdgcn_sched_barrier(0);
; #pragma unroll
;         for (int j = 0; j < 4; ++j) acc[2][j] = __builtin_amdgcn_mfma_f32_16x16x32_bf16(fb[j], fa[2], acc[2][j], 0, 0, 0);
	ds_read_b128 v[58:61], v6
	ds_read_b128 v[120:123], v6 offset:2048
	ds_read_b128 v[124:127], v7 offset:16384
	ds_read_b128 v[132:135], v7 offset:18432
	ds_read_b128 v[146:149], v6 offset:4096
	ds_read_b128 v[154:157], v6 offset:6144
	ds_read_b128 v[158:161], v7 offset:20480
	ds_read_b128 v[162:165], v7 offset:22528
	s_setprio 2
	global_load_dwordx4 v[166:169], v8, s[36:37] offset:512
	s_waitcnt vmcnt(7)
	ds_write_b128 v2, v[170:173] offset:32768
	ds_read_b128 v[170:173], v3
	ds_read_b128 v[174:177], v4 offset:16384
	s_waitcnt lgkmcnt(8)
	v_mfma_f32_16x16x32_bf16 v[26:29], v[124:127], v[58:61], v[26:29]
	s_waitcnt lgkmcnt(3)
	v_mfma_f32_16x16x32_bf16 v[10:13], v[162:165], v[58:61], v[10:13]
	v_mfma_f32_16x16x32_bf16 v[88:91], v[132:135], v[58:61], v[88:91]
	v_mfma_f32_16x16x32_bf16 v[100:103], v[158:161], v[58:61], v[100:103]
	global_load_dwordx4 v[58:61], v216, s[36:37] offset:512
	ds_write_b128 v2, v[62:65] offset:36864
	ds_read_b128 v[62:65], v3 offset:2048
	ds_read_b128 v[178:181], v4 offset:18432
	v_mfma_f32_16x16x32_bf16 v[30:33], v[124:127], v[120:123], v[30:33]
	v_mfma_f32_16x16x32_bf16 v[42:45], v[132:135], v[120:123], v[42:45]
	v_mfma_f32_16x16x32_bf16 v[14:17], v[162:165], v[120:123], v[14:17]
	v_mfma_f32_16x16x32_bf16 v[104:107], v[158:161], v[120:123], v[104:107]
	global_load_dwordx4 v[120:123], v217, s[36:37] offset:512
	s_waitcnt vmcnt(7)
	ds_write_b128 v2, v[84:87] offset:40960
	ds_read_b128 v[84:87], v3 offset:4096
	ds_read_b128 v[182:185], v4 offset:20480
	v_mfma_f32_16x16x32_bf16 v[34:37], v[124:127], v[146:149], v[34:37]
	v_mfma_f32_16x16x32_bf16 v[46:49], v[132:135], v[146:149], v[46:49]
	v_mfma_f32_16x16x32_bf16 v[18:21], v[162:165], v[146:149], v[18:21]
	v_mfma_f32_16x16x32_bf16 v[112:115], v[158:161], v[146:149], v[112:115]
	global_load_dwordx4 v[146:149], v218, s[36:37] offset:512
	ds_write_b128 v2, v[150:153] offset:45056
	ds_read_b128 v[150:153], v3 offset:6144
	ds_read_b128 v[186:189], v4 offset:22528
	v_mfma_f32_16x16x32_bf16 v[38:41], v[124:127], v[154:157], v[38:41]
	v_mfma_f32_16x16x32_bf16 v[50:53], v[132:135], v[154:157], v[50:53]
	v_mfma_f32_16x16x32_bf16 v[54:57], v[158:161], v[154:157], v[54:57]
	v_mfma_f32_16x16x32_bf16 v[22:25], v[162:165], v[154:157], v[22:25]
	global_load_dwordx4 v[124:127], v5, s[4:5] offset:512
	s_waitcnt vmcnt(7)
	ds_write_b128 v2, v[96:99] offset:49152
	s_waitcnt lgkmcnt(10)
	v_mfma_f32_16x16x32_bf16 v[26:29], v[174:177], v[170:173], v[26:29]
	s_waitcnt lgkmcnt(1)
	v_mfma_f32_16x16x32_bf16 v[10:13], v[186:189], v[170:173], v[10:13]
	v_mfma_f32_16x16x32_bf16 v[88:91], v[178:181], v[170:173], v[88:91]
	v_mfma_f32_16x16x32_bf16 v[96:99], v[182:185], v[170:173], v[100:103]
	global_load_dwordx4 v[100:103], v219, s[4:5] offset:512
	ds_write_b128 v2, v[92:95] offset:53248
	v_mfma_f32_16x16x32_bf16 v[30:33], v[174:177], v[62:65], v[30:33]
	v_mfma_f32_16x16x32_bf16 v[42:45], v[178:181], v[62:65], v[42:45]
	v_mfma_f32_16x16x32_bf16 v[14:17], v[186:189], v[62:65], v[14:17]
	v_mfma_f32_16x16x32_bf16 v[92:95], v[182:185], v[62:65], v[104:107]
	global_load_dwordx4 v[62:65], v220, s[4:5] offset:512
	s_waitcnt vmcnt(7)
	ds_write_b128 v2, v[108:111] offset:57344
	v_mfma_f32_16x16x32_bf16 v[34:37], v[174:177], v[84:87], v[34:37]
	v_mfma_f32_16x16x32_bf16 v[46:49], v[178:181], v[84:87], v[46:49]
	v_mfma_f32_16x16x32_bf16 v[18:21], v[186:189], v[84:87], v[18:21]
	v_mfma_f32_16x16x32_bf16 v[104:107], v[182:185], v[84:87], v[112:115]
	global_load_dwordx4 v[84:87], v221, s[4:5] offset:512
	ds_write_b128 v2, v[116:119] offset:61440
	v_mfma_f32_16x16x32_bf16 v[38:41], v[174:177], v[150:153], v[38:41]
	v_mfma_f32_16x16x32_bf16 v[50:53], v[178:181], v[150:153], v[50:53]
	v_mfma_f32_16x16x32_bf16 v[54:57], v[182:185], v[150:153], v[54:57]
	v_mfma_f32_16x16x32_bf16 v[22:25], v[186:189], v[150:153], v[22:25]
	s_setprio 0
	s_waitcnt lgkmcnt(0)
	s_barrier
	ds_read_b128 v[108:111], v6 offset:32768
	ds_read_b128 v[112:115], v6 offset:34816
	ds_read_b128 v[116:119], v7 offset:49152
	ds_read_b128 v[132:135], v7 offset:51200
	ds_read_b128 v[150:153], v6 offset:36864
	ds_read_b128 v[154:157], v6 offset:38912
	ds_read_b128 v[158:161], v7 offset:53248
	ds_read_b128 v[162:165], v7 offset:55296
	s_setprio 2
	global_load_dwordx4 v[170:173], v8, s[36:37] offset:640
	s_waitcnt vmcnt(7)
	ds_write_b128 v2, v[166:169]
	ds_read_b128 v[166:169], v3 offset:32768
	ds_read_b128 v[174:177], v4 offset:49152
	s_waitcnt lgkmcnt(8)
	v_mfma_f32_16x16x32_bf16 v[26:29], v[116:119], v[108:111], v[26:29]
	s_waitcnt lgkmcnt(3)
	v_mfma_f32_16x16x32_bf16 v[10:13], v[162:165], v[108:111], v[10:13]
	v_mfma_f32_16x16x32_bf16 v[88:91], v[132:135], v[108:111], v[88:91]
	v_mfma_f32_16x16x32_bf16 v[96:99], v[158:161], v[108:111], v[96:99]
	global_load_dwordx4 v[108:111], v216, s[36:37] offset:640
	ds_write_b128 v2, v[58:61] offset:4096
	ds_read_b128 v[58:61], v3 offset:34816
	ds_read_b128 v[178:181], v4 offset:51200
	v_mfma_f32_16x16x32_bf16 v[30:33], v[116:119], v[112:115], v[30:33]
	v_mfma_f32_16x16x32_bf16 v[42:45], v[132:135], v[112:115], v[42:45]
	v_mfma_f32_16x16x32_bf16 v[14:17], v[162:165], v[112:115], v[14:17]
	v_mfma_f32_16x16x32_bf16 v[92:95], v[158:161], v[112:115], v[92:95]
	global_load_dwordx4 v[112:115], v217, s[36:37] offset:640
	s_waitcnt vmcnt(7)
; template <int MODE>
; __device__ __forceinline__ void gemm_tile(const Params& P, int tm, int tn, unsigned char* smem) {
;     ...
; #pragma unroll
;         for (int i = 0; i < 4; ++i) { fa[i] = *(const bf16x8*)(sA + arow_off + i * 2048 + ch0); fb[i] = *(const bf16x8*)(sB + brow_off + i * 2048 + ch0); }
;         __builtin_amdgcn_sched_barrier(0);
;         __builtin_amdgcn_s_setprio(2);
;         if (wr_ok) *(uint4*)(nA + soff0) = ra0;
;         if (ld_ok) ra0 = *(const uint4*)(Ab + (aoff + 0u * LDA + koa));
;         ga[0] = *(const bf16x8*)(sA + arow_off + 0 * 2048 + ch1); gb[0] = *(const bf16x8*)(sB + brow_off + 0 * 2048 + ch1);
;         __builtin_amdgcn_sched_barrier(0);
; #pragma unroll
;         for (int j = 0; j < 4; ++j) acc[0][j] = __builtin_amdgcn_mfma_f32_16x16x32_bf16(fb[j], fa[0], acc[0][j], 0, 0, 0);
;         __builtin_amdgcn_sched_barrier(0);
;         if (wr_ok) *(uint4*)(nA + soff0 + 4096) = ra1;
;         if (ld_ok) ra1 = *(const uint4*)(Ab + (aoff + 32u * LDA + koa));
;         ga[1] = *(const bf16x8*)(sA + arow_off + 1 * 2048 + ch1); gb[1] = *(const bf16x8*)(sB + brow_off + 1 * 2048 + ch1);
;         __builtin_amdgcn_sched_barrier(0);
; #pragma unroll
;         for (int j = 0; j < 4; ++j) acc[1][j] = __builtin_amdgcn_mfma_f32_16x16x32_bf16(fb[j], fa[1], acc[1][j], 0, 0, 0);
;         __builtin_amdgcn_sched_barrier(0);
;         if (wr_ok) *(uint4*)(nA + soff0 + 8192) = ra2;
;         if (ld_ok) ra2 = *(const uint4*)(Ab + (aoff + 64u * LDA + koa));
;         ga[2] = *(const bf16x8*)(sA + arow_off + 2 * 2048 + ch1); gb[2] = *(const bf16x8*)(sB + brow_off + 2 * 2048 + ch1);
;         __builtin_amdgcn_sched_barrier(0);
; #pragma unroll
;         for (int j = 0; j < 4; ++j) acc[2][j] = __builtin_amdgcn_mfma_f32_16x16x32_bf16(fb[j], fa[2], acc[2][j], 0, 0, 0);
;         __builtin_amdgcn_sched_barrier(0);
;         if (wr_ok) *(uint4*)(nA + soff0 + 12288) = ra3;
;         if (ld_ok) ra3 = *(const uint4*)(Ab + (aoff + 96u * LDA + koa));
;         ga[3] = *(const bf16x8*)(sA + arow_off + 3 * 2048 + ch1); gb[3] = *(const bf16x8*)(sB + brow_off + 3 * 2048 + ch1);
;         __builtin_amdgcn_sched_barrier(0);
; #pragma unroll
;         for (int j = 0; j < 4; ++j) acc[3][j] = __builtin_amdgcn_mfma_f32_16x16x32_bf16(fb[j], fa[3], acc[3][j], 0, 0, 0);
;         __builtin_amdgcn_sched_barrier(0);
;         if (wr_ok) *(uint4*)(nB + soff0) = rb0;
	ds_write_b128 v2, v[120:123] offset:8192
	ds_read_b128 v[120:123], v3 offset:36864
	ds_read_b128 v[182:185], v4 offset:53248
	v_mfma_f32_16x16x32_bf16 v[34:37], v[116:119], v[150:153], v[34:37]
	v_mfma_f32_16x16x32_bf16 v[46:49], v[132:135], v[150:153], v[46:49]
	v_mfma_f32_16x16x32_bf16 v[18:21], v[162:165], v[150:153], v[18:21]
	v_mfma_f32_16x16x32_bf16 v[104:107], v[158:161], v[150:153], v[104:107]
	global_load_dwordx4 v[150:153], v218, s[36:37] offset:640
	ds_write_b128 v2, v[146:149] offset:12288
	ds_read_b128 v[146:149], v3 offset:38912
	ds_read_b128 v[186:189], v4 offset:55296
	v_mfma_f32_16x16x32_bf16 v[38:41], v[116:119], v[154:157], v[38:41]
	v_mfma_f32_16x16x32_bf16 v[50:53], v[132:135], v[154:157], v[50:53]
	v_mfma_f32_16x16x32_bf16 v[54:57], v[158:161], v[154:157], v[54:57]
	v_mfma_f32_16x16x32_bf16 v[22:25], v[162:165], v[154:157], v[22:25]
	global_load_dwordx4 v[116:119], v5, s[4:5] offset:640
	s_waitcnt vmcnt(7)
	ds_write_b128 v2, v[124:127] offset:16384
	s_waitcnt lgkmcnt(10)
	v_mfma_f32_16x16x32_bf16 v[26:29], v[174:177], v[166:169], v[26:29]
	s_waitcnt lgkmcnt(1)
	v_mfma_f32_16x16x32_bf16 v[10:13], v[186:189], v[166:169], v[10:13]
	v_mfma_f32_16x16x32_bf16 v[88:91], v[178:181], v[166:169], v[88:91]
	v_mfma_f32_16x16x32_bf16 v[96:99], v[182:185], v[166:169], v[96:99]
	global_load_dwordx4 v[124:127], v219, s[4:5] offset:640
	ds_write_b128 v2, v[100:103] offset:20480
	v_mfma_f32_16x16x32_bf16 v[30:33], v[174:177], v[58:61], v[30:33]
	v_mfma_f32_16x16x32_bf16 v[42:45], v[178:181], v[58:61], v[42:45]
	v_mfma_f32_16x16x32_bf16 v[14:17], v[186:189], v[58:61], v[14:17]
	v_mfma_f32_16x16x32_bf16 v[92:95], v[182:185], v[58:61], v[92:95]
	global_load_dwordx4 v[58:61], v220, s[4:5] offset:640
	s_waitcnt vmcnt(7)
	ds_write_b128 v2, v[62:65] offset:24576
	v_mfma_f32_16x16x32_bf16 v[34:37], v[174:177], v[120:123], v[34:37]
	v_mfma_f32_16x16x32_bf16 v[46:49], v[178:181], v[120:123], v[46:49]
	v_mfma_f32_16x16x32_bf16 v[62:65], v[182:185], v[120:123], v[104:107]
	v_mfma_f32_16x16x32_bf16 v[18:21], v[186:189], v[120:123], v[18:21]
	global_load_dwordx4 v[100:103], v221, s[4:5] offset:640
	ds_write_b128 v2, v[84:87] offset:28672
	v_mfma_f32_16x16x32_bf16 v[38:41], v[174:177], v[146:149], v[38:41]
	v_mfma_f32_16x16x32_bf16 v[50:53], v[178:181], v[146:149], v[50:53]
	v_mfma_f32_16x16x32_bf16 v[54:57], v[182:185], v[146:149], v[54:57]
	v_mfma_f32_16x16x32_bf16 v[22:25], v[186:189], v[146:149], v[22:25]
	s_setprio 0
	s_waitcnt lgkmcnt(0)
	s_barrier
	ds_read_b128 v[84:87], v6
	ds_read_b128 v[104:107], v6 offset:2048
	ds_read_b128 v[120:123], v7 offset:16384
	ds_read_b128 v[132:135], v7 offset:18432
	ds_read_b128 v[146:149], v6 offset:4096
	ds_read_b128 v[154:157], v6 offset:6144
	ds_read_b128 v[158:161], v7 offset:20480
	ds_read_b128 v[162:165], v7 offset:22528
	s_setprio 2
	global_load_dwordx4 v[166:169], v8, s[36:37] offset:768
	s_waitcnt vmcnt(7)
	ds_write_b128 v2, v[170:173] offset:32768
	ds_read_b128 v[170:173], v3
	ds_read_b128 v[174:177], v4 offset:16384
	s_waitcnt lgkmcnt(8)
	v_mfma_f32_16x16x32_bf16 v[26:29], v[120:123], v[84:87], v[26:29]
	s_waitcnt lgkmcnt(3)
	v_mfma_f32_16x16x32_bf16 v[10:13], v[162:165], v[84:87], v[10:13]
	v_mfma_f32_16x16x32_bf16 v[88:91], v[132:135], v[84:87], v[88:91]
	v_mfma_f32_16x16x32_bf16 v[96:99], v[158:161], v[84:87], v[96:99]
	global_load_dwordx4 v[84:87], v216, s[36:37] offset:768
	ds_write_b128 v2, v[108:111] offset:36864
	ds_read_b128 v[108:111], v3 offset:2048
	ds_read_b128 v[178:181], v4 offset:18432
	v_mfma_f32_16x16x32_bf16 v[30:33], v[120:123], v[104:107], v[30:33]
	v_mfma_f32_16x16x32_bf16 v[42:45], v[132:135], v[104:107], v[42:45]
	v_mfma_f32_16x16x32_bf16 v[14:17], v[162:165], v[104:107], v[14:17]
	v_mfma_f32_16x16x32_bf16 v[92:95], v[158:161], v[104:107], v[92:95]
	global_load_dwordx4 v[104:107], v217, s[36:37] offset:768
	s_waitcnt vmcnt(7)
	ds_write_b128 v2, v[112:115] offset:40960
	ds_read_b128 v[112:115], v3 offset:4096
	ds_read_b128 v[182:185], v4 offset:20480
	v_mfma_f32_16x16x32_bf16 v[34:37], v[120:123], v[146:149], v[34:37]
	v_mfma_f32_16x16x32_bf16 v[46:49], v[132:135], v[146:149], v[46:49]
	v_mfma_f32_16x16x32_bf16 v[62:65], v[158:161], v[146:149], v[62:65]
	v_mfma_f32_16x16x32_bf16 v[18:21], v[162:165], v[146:149], v[18:21]
	global_load_dwordx4 v[146:149], v218, s[36:37] offset:768
	ds_write_b128 v2, v[150:153] offset:45056
	ds_read_b128 v[150:153], v3 offset:6144
	ds_read_b128 v[186:189], v4 offset:22528
	v_mfma_f32_16x16x32_bf16 v[38:41], v[120:123], v[154:157], v[38:41]
	v_mfma_f32_16x16x32_bf16 v[50:53], v[132:135], v[154:157], v[50:53]
	v_mfma_f32_16x16x32_bf16 v[54:57], v[158:161], v[154:157], v[54:57]
	v_mfma_f32_16x16x32_bf16 v[22:25], v[162:165], v[154:157], v[22:25]
	global_load_dwordx4 v[120:123], v5, s[4:5] offset:768
	s_waitcnt vmcnt(7)
	ds_write_b128 v2, v[116:119] offset:49152
	s_waitcnt lgkmcnt(10)
	v_mfma_f32_16x16x32_bf16 v[26:29], v[174:177], v[170:173], v[26:29]
	s_waitcnt lgkmcnt(1)
	v_mfma_f32_16x16x32_bf16 v[10:13], v[186:189], v[170:173], v[10:13]
	v_mfma_f32_16x16x32_bf16 v[88:91], v[178:181], v[170:173], v[88:91]
	v_mfma_f32_16x16x32_bf16 v[96:99], v[182:185], v[170:173], v[96:99]
	global_load_dwordx4 v[116:119], v219, s[4:5] offset:768
	ds_write_b128 v2, v[124:127] offset:53248
	v_mfma_f32_16x16x32_bf16 v[30:33], v[174:177], v[108:111], v[30:33]
	v_mfma_f32_16x16x32_bf16 v[42:45], v[178:181], v[108:111], v[42:45]
	v_mfma_f32_16x16x32_bf16 v[14:17], v[186:189], v[108:111], v[14:17]
	v_mfma_f32_16x16x32_bf16 v[92:95], v[182:185], v[108:111], v[92:95]
	global_load_dwordx4 v[108:111], v220, s[4:5] offset:768
	s_waitcnt vmcnt(7)
	ds_write_b128 v2, v[58:61] offset:57344
	v_mfma_f32_16x16x32_bf16 v[34:37], v[174:177], v[112:115], v[34:37]
	v_mfma_f32_16x16x32_bf16 v[46:49], v[178:181], v[112:115], v[46:49]
	v_mfma_f32_16x16x32_bf16 v[58:61], v[182:185], v[112:115], v[62:65]
	v_mfma_f32_16x16x32_bf16 v[18:21], v[186:189], v[112:115], v[18:21]
	global_load_dwordx4 v[62:65], v221, s[4:5] offset:768
	ds_write_b128 v2, v[100:103] offset:61440
	v_mfma_f32_16x16x32_bf16 v[38:41], v[174:177], v[150:153], v[38:41]
	v_mfma_f32_16x16x32_bf16 v[50:53], v[178:181], v[150:153], v[50:53]
	v_mfma_f32_16x16x32_bf16 v[54:57], v[182:185], v[150:153], v[54:57]
	v_mfma_f32_16x16x32_bf16 v[22:25], v[186:189], v[150:153], v[22:25]
	s_setprio 0
	s_waitcnt lgkmcnt(0)
	s_barrier
; template <int MODE>
; __device__ __forceinline__ void gemm_tile(const Params& P, int tm, int tn, unsigned char* smem) {
;     ...
; #pragma unroll
;         for (int i = 0; i < 4; ++i) { fa[i] = *(const bf16x8*)(sA + arow_off + i * 2048 + ch0); fb[i] = *(const bf16x8*)(sB + brow_off + i * 2048 + ch0); }
;         __builtin_amdgcn_sched_barrier(0);
;         __builtin_amdgcn_s_setprio(2);
;         if (wr_ok) *(uint4*)(nA + soff0) = ra0;
;         if (ld_ok) ra0 = *(const uint4*)(Ab + (aoff + 0u * LDA + koa));
;         ga[0] = *(const bf16x8*)(sA + arow_off + 0 * 2048 + ch1); gb[0] = *(const bf16x8*)(sB + brow_off + 0 * 2048 + ch1);
;         __builtin_amdgcn_sched_barrier(0);
; #pragma unroll
;         for (int j = 0; j < 4; ++j) acc[0][j] = __builtin_amdgcn_mfma_f32_16x16x32_bf16(fb[j], fa[0], acc[0][j], 0, 0, 0);
;         __builtin_amdgcn_sched_barrier(0);
;         if (wr_ok) *(uint4*)(nA + soff0 + 4096) = ra1;
;         if (ld_ok) ra1 = *(const uint4*)(Ab + (aoff + 32u * LDA + koa));
;         ga[1] = *(const bf16x8*)(sA + arow_off + 1 * 2048 + ch1); gb[1] = *(const bf16x8*)(sB + brow_off + 1 * 2048 + ch1);
;         __builtin_amdgcn_sched_barrier(0);
; #pragma unroll
;         for (int j = 0; j < 4; ++j) acc[1][j] = __builtin_amdgcn_mfma_f32_16x16x32_bf16(fb[j], fa[1], acc[1][j], 0, 0, 0);
;         __builtin_amdgcn_sched_barrier(0);
;         if (wr_ok) *(uint4*)(nA + soff0 + 8192) = ra2;
;         if (ld_ok) ra2 = *(const uint4*)(Ab + (aoff + 64u * LDA + koa));
;         ga[2] = *(const bf16x8*)(sA + arow_off + 2 * 2048 + ch1); gb[2] = *(const bf16x8*)(sB + brow_off + 2 * 2048 + ch1);
;         __builtin_amdgcn_sched_barrier(0);
; #pragma unroll
;         for (int j = 0; j < 4; ++j) acc[2][j] = __builtin_amdgcn_mfma_f32_16x16x32_bf16(fb[j], fa[2], acc[2][j], 0, 0, 0);
;         __builtin_amdgcn_sched_barrier(0);
;         if (wr_ok) *(uint4*)(nA + soff0 + 12288) = ra3;
;         if (ld_ok) ra3 = *(const uint4*)(Ab + (aoff + 96u * LDA + koa));
;         ga[3] = *(const bf16x8*)(sA + arow_off + 3 * 2048 + ch1); gb[3] = *(const bf16x8*)(sB + brow_off + 3 * 2048 + ch1);
;         __builtin_amdgcn_sched_barrier(0);
; #pragma unroll
;         for (int j = 0; j < 4; ++j) acc[3][j] = __builtin_amdgcn_mfma_f32_16x16x32_bf16(fb[j], fa[3], acc[3][j], 0, 0, 0);
;         __builtin_amdgcn_sched_barrier(0);
;         if (wr_ok) *(uint4*)(nB + soff0) = rb0;
	ds_read_b128 v[100:103], v6 offset:32768
	ds_read_b128 v[112:115], v6 offset:34816
	ds_read_b128 v[124:127], v7 offset:49152
	ds_read_b128 v[132:135], v7 offset:51200
	ds_read_b128 v[150:153], v6 offset:36864
	ds_read_b128 v[154:157], v6 offset:38912
	ds_read_b128 v[158:161], v7 offset:53248
	ds_read_b128 v[162:165], v7 offset:55296
	s_setprio 2
	global_load_dwordx4 v[170:173], v8, s[36:37] offset:896
	s_waitcnt vmcnt(7)
	ds_write_b128 v2, v[166:169]
	ds_read_b128 v[166:169], v3 offset:32768
	ds_read_b128 v[174:177], v4 offset:49152
	s_waitcnt lgkmcnt(8)
	v_mfma_f32_16x16x32_bf16 v[26:29], v[124:127], v[100:103], v[26:29]
	s_waitcnt lgkmcnt(3)
	v_mfma_f32_16x16x32_bf16 v[10:13], v[162:165], v[100:103], v[10:13]
	v_mfma_f32_16x16x32_bf16 v[88:91], v[132:135], v[100:103], v[88:91]
	v_mfma_f32_16x16x32_bf16 v[96:99], v[158:161], v[100:103], v[96:99]
	global_load_dwordx4 v[100:103], v216, s[36:37] offset:896
	ds_write_b128 v2, v[84:87] offset:4096
	ds_read_b128 v[84:87], v3 offset:34816
	ds_read_b128 v[178:181], v4 offset:51200
	v_mfma_f32_16x16x32_bf16 v[30:33], v[124:127], v[112:115], v[30:33]
	v_mfma_f32_16x16x32_bf16 v[42:45], v[132:135], v[112:115], v[42:45]
	v_mfma_f32_16x16x32_bf16 v[14:17], v[162:165], v[112:115], v[14:17]
	v_mfma_f32_16x16x32_bf16 v[92:95], v[158:161], v[112:115], v[92:95]
	global_load_dwordx4 v[112:115], v217, s[36:37] offset:896
	s_waitcnt vmcnt(7)
	ds_write_b128 v2, v[104:107] offset:8192
	ds_read_b128 v[104:107], v3 offset:36864
	ds_read_b128 v[182:185], v4 offset:53248
	v_mfma_f32_16x16x32_bf16 v[34:37], v[124:127], v[150:153], v[34:37]
	v_mfma_f32_16x16x32_bf16 v[46:49], v[132:135], v[150:153], v[46:49]
	v_mfma_f32_16x16x32_bf16 v[58:61], v[158:161], v[150:153], v[58:61]
	v_mfma_f32_16x16x32_bf16 v[18:21], v[162:165], v[150:153], v[18:21]
	global_load_dwordx4 v[150:153], v218, s[36:37] offset:896
	ds_write_b128 v2, v[146:149] offset:12288
	ds_read_b128 v[146:149], v3 offset:38912
	ds_read_b128 v[186:189], v4 offset:55296
	v_mfma_f32_16x16x32_bf16 v[38:41], v[124:127], v[154:157], v[38:41]
	v_mfma_f32_16x16x32_bf16 v[50:53], v[132:135], v[154:157], v[50:53]
	v_mfma_f32_16x16x32_bf16 v[54:57], v[158:161], v[154:157], v[54:57]
	v_mfma_f32_16x16x32_bf16 v[22:25], v[162:165], v[154:157], v[22:25]
	global_load_dwordx4 v[124:127], v5, s[4:5] offset:896
	s_waitcnt vmcnt(7)
	ds_write_b128 v2, v[120:123] offset:16384
	s_waitcnt lgkmcnt(10)
	v_mfma_f32_16x16x32_bf16 v[26:29], v[174:177], v[166:169], v[26:29]
	s_waitcnt lgkmcnt(1)
	v_mfma_f32_16x16x32_bf16 v[10:13], v[186:189], v[166:169], v[10:13]
	v_mfma_f32_16x16x32_bf16 v[88:91], v[178:181], v[166:169], v[88:91]
	v_mfma_f32_16x16x32_bf16 v[96:99], v[182:185], v[166:169], v[96:99]
	global_load_dwordx4 v[120:123], v219, s[4:5] offset:896
	ds_write_b128 v2, v[116:119] offset:20480
	v_mfma_f32_16x16x32_bf16 v[30:33], v[174:177], v[84:87], v[30:33]
	v_mfma_f32_16x16x32_bf16 v[42:45], v[178:181], v[84:87], v[42:45]
	v_mfma_f32_16x16x32_bf16 v[14:17], v[186:189], v[84:87], v[14:17]
	v_mfma_f32_16x16x32_bf16 v[92:95], v[182:185], v[84:87], v[92:95]
	global_load_dwordx4 v[84:87], v220, s[4:5] offset:896
	s_waitcnt vmcnt(7)
	ds_write_b128 v2, v[108:111] offset:24576
	v_mfma_f32_16x16x32_bf16 v[34:37], v[174:177], v[104:107], v[34:37]
	v_mfma_f32_16x16x32_bf16 v[46:49], v[178:181], v[104:107], v[46:49]
	v_mfma_f32_16x16x32_bf16 v[58:61], v[182:185], v[104:107], v[58:61]
	v_mfma_f32_16x16x32_bf16 v[18:21], v[186:189], v[104:107], v[18:21]
	global_load_dwordx4 v[104:107], v221, s[4:5] offset:896
	ds_write_b128 v2, v[62:65] offset:28672
	v_mfma_f32_16x16x32_bf16 v[38:41], v[174:177], v[146:149], v[38:41]
	v_mfma_f32_16x16x32_bf16 v[50:53], v[178:181], v[146:149], v[50:53]
	v_mfma_f32_16x16x32_bf16 v[54:57], v[182:185], v[146:149], v[54:57]
	v_mfma_f32_16x16x32_bf16 v[22:25], v[186:189], v[146:149], v[22:25]
	s_setprio 0
	s_waitcnt lgkmcnt(0)
	s_barrier
	ds_read_b128 v[62:65], v6
	ds_read_b128 v[108:111], v6 offset:2048
	ds_read_b128 v[116:119], v7 offset:16384
	ds_read_b128 v[132:135], v7 offset:18432
	ds_read_b128 v[146:149], v6 offset:4096
	ds_read_b128 v[154:157], v6 offset:6144
	ds_read_b128 v[158:161], v7 offset:20480
	ds_read_b128 v[162:165], v7 offset:22528
	s_setprio 2
	global_load_dwordx4 v[166:169], v8, s[36:37] offset:1024
	s_waitcnt vmcnt(7)
	ds_write_b128 v2, v[170:173] offset:32768
	ds_read_b128 v[170:173], v3
	ds_read_b128 v[174:177], v4 offset:16384
	s_waitcnt lgkmcnt(8)
	v_mfma_f32_16x16x32_bf16 v[26:29], v[116:119], v[62:65], v[26:29]
	s_waitcnt lgkmcnt(3)
	v_mfma_f32_16x16x32_bf16 v[10:13], v[162:165], v[62:65], v[10:13]
	v_mfma_f32_16x16x32_bf16 v[88:91], v[132:135], v[62:65], v[88:91]
	v_mfma_f32_16x16x32_bf16 v[96:99], v[158:161], v[62:65], v[96:99]
	global_load_dwordx4 v[62:65], v216, s[36:37] offset:1024
	ds_write_b128 v2, v[100:103] offset:36864
	ds_read_b128 v[100:103], v3 offset:2048
	ds_read_b128 v[178:181], v4 offset:18432
	v_mfma_f32_16x16x32_bf16 v[30:33], v[116:119], v[108:111], v[30:33]
	v_mfma_f32_16x16x32_bf16 v[42:45], v[132:135], v[108:111], v[42:45]
	v_mfma_f32_16x16x32_bf16 v[14:17], v[162:165], v[108:111], v[14:17]
	v_mfma_f32_16x16x32_bf16 v[92:95], v[158:161], v[108:111], v[92:95]
	global_load_dwordx4 v[108:111], v217, s[36:37] offset:1024
	s_waitcnt vmcnt(7)
; template <int MODE>
; __device__ __forceinline__ void gemm_tile(const Params& P, int tm, int tn, unsigned char* smem) {
;     ...
; #pragma unroll
;         for (int i = 0; i < 4; ++i) { fa[i] = *(const bf16x8*)(sA + arow_off + i * 2048 + ch0); fb[i] = *(const bf16x8*)(sB + brow_off + i * 2048 + ch0); }
;         __builtin_amdgcn_sched_barrier(0);
;         __builtin_amdgcn_s_setprio(2);
;         if (wr_ok) *(uint4*)(nA + soff0) = ra0;
;         if (ld_ok) ra0 = *(const uint4*)(Ab + (aoff + 0u * LDA + koa));
;         ga[0] = *(const bf16x8*)(sA + arow_off + 0 * 2048 + ch1); gb[0] = *(const bf16x8*)(sB + brow_off + 0 * 2048 + ch1);
;         __builtin_amdgcn_sched_barrier(0);
; #pragma unroll
;         for (int j = 0; j < 4; ++j) acc[0][j] = __builtin_amdgcn_mfma_f32_16x16x32_bf16(fb[j], fa[0], acc[0][j], 0, 0, 0);
;         __builtin_amdgcn_sched_barrier(0);
;         if (wr_ok) *(uint4*)(nA + soff0 + 4096) = ra1;
;         if (ld_ok) ra1 = *(const uint4*)(Ab + (aoff + 32u * LDA + koa));
;         ga[1] = *(const bf16x8*)(sA + arow_off + 1 * 2048 + ch1); gb[1] = *(const bf16x8*)(sB + brow_off + 1 * 2048 + ch1);
;         __builtin_amdgcn_sched_barrier(0);
; #pragma unroll
;         for (int j = 0; j < 4; ++j) acc[1][j] = __builtin_amdgcn_mfma_f32_16x16x32_bf16(fb[j], fa[1], acc[1][j], 0, 0, 0);
;         __builtin_amdgcn_sched_barrier(0);
;         if (wr_ok) *(uint4*)(nA + soff0 + 8192) = ra2;
;         if (ld_ok) ra2 = *(const uint4*)(Ab + (aoff + 64u * LDA + koa));
;         ga[2] = *(const bf16x8*)(sA + arow_off + 2 * 2048 + ch1); gb[2] = *(const bf16x8*)(sB + brow_off + 2 * 2048 + ch1);
;         __builtin_amdgcn_sched_barrier(0);
; #pragma unroll
;         for (int j = 0; j < 4; ++j) acc[2][j] = __builtin_amdgcn_mfma_f32_16x16x32_bf16(fb[j], fa[2], acc[2][j], 0, 0, 0);
;         __builtin_amdgcn_sched_barrier(0);
;         if (wr_ok) *(uint4*)(nA + soff0 + 12288) = ra3;
;         if (ld_ok) ra3 = *(const uint4*)(Ab + (aoff + 96u * LDA + koa));
;         ga[3] = *(const bf16x8*)(sA + arow_off + 3 * 2048 + ch1); gb[3] = *(const bf16x8*)(sB + brow_off + 3 * 2048 + ch1);
;         __builtin_amdgcn_sched_barrier(0);
; #pragma unroll
;         for (int j = 0; j < 4; ++j) acc[3][j] = __builtin_amdgcn_mfma_f32_16x16x32_bf16(fb[j], fa[3], acc[3][j], 0, 0, 0);
;         __builtin_amdgcn_sched_barrier(0);
;         if (wr_ok) *(uint4*)(nB + soff0) = rb0;
	ds_write_b128 v2, v[112:115] offset:40960
	ds_read_b128 v[112:115], v3 offset:4096
	ds_read_b128 v[182:185], v4 offset:20480
	v_mfma_f32_16x16x32_bf16 v[34:37], v[116:119], v[146:149], v[34:37]
	v_mfma_f32_16x16x32_bf16 v[46:49], v[132:135], v[146:149], v[46:49]
	v_mfma_f32_16x16x32_bf16 v[58:61], v[158:161], v[146:149], v[58:61]
	v_mfma_f32_16x16x32_bf16 v[18:21], v[162:165], v[146:149], v[18:21]
	global_load_dwordx4 v[146:149], v218, s[36:37] offset:1024
	ds_write_b128 v2, v[150:153] offset:45056
	ds_read_b128 v[150:153], v3 offset:6144
	ds_read_b128 v[186:189], v4 offset:22528
	v_mfma_f32_16x16x32_bf16 v[38:41], v[116:119], v[154:157], v[38:41]
	v_mfma_f32_16x16x32_bf16 v[50:53], v[132:135], v[154:157], v[50:53]
	v_mfma_f32_16x16x32_bf16 v[54:57], v[158:161], v[154:157], v[54:57]
	v_mfma_f32_16x16x32_bf16 v[22:25], v[162:165], v[154:157], v[22:25]
	global_load_dwordx4 v[116:119], v5, s[4:5] offset:1024
	s_waitcnt vmcnt(7)
	ds_write_b128 v2, v[124:127] offset:49152
	s_waitcnt lgkmcnt(10)
	v_mfma_f32_16x16x32_bf16 v[26:29], v[174:177], v[170:173], v[26:29]
	s_waitcnt lgkmcnt(1)
	v_mfma_f32_16x16x32_bf16 v[10:13], v[186:189], v[170:173], v[10:13]
	v_mfma_f32_16x16x32_bf16 v[88:91], v[178:181], v[170:173], v[88:91]
	v_mfma_f32_16x16x32_bf16 v[96:99], v[182:185], v[170:173], v[96:99]
	global_load_dwordx4 v[124:127], v219, s[4:5] offset:1024
	ds_write_b128 v2, v[120:123] offset:53248
	v_mfma_f32_16x16x32_bf16 v[30:33], v[174:177], v[100:103], v[30:33]
	v_mfma_f32_16x16x32_bf16 v[42:45], v[178:181], v[100:103], v[42:45]
	v_mfma_f32_16x16x32_bf16 v[14:17], v[186:189], v[100:103], v[14:17]
	v_mfma_f32_16x16x32_bf16 v[92:95], v[182:185], v[100:103], v[92:95]
	global_load_dwordx4 v[100:103], v220, s[4:5] offset:1024
	s_waitcnt vmcnt(7)
	ds_write_b128 v2, v[84:87] offset:57344
	v_mfma_f32_16x16x32_bf16 v[34:37], v[174:177], v[112:115], v[34:37]
	v_mfma_f32_16x16x32_bf16 v[46:49], v[178:181], v[112:115], v[46:49]
	v_mfma_f32_16x16x32_bf16 v[58:61], v[182:185], v[112:115], v[58:61]
	v_mfma_f32_16x16x32_bf16 v[18:21], v[186:189], v[112:115], v[18:21]
	global_load_dwordx4 v[84:87], v221, s[4:5] offset:1024
	ds_write_b128 v2, v[104:107] offset:61440
	v_mfma_f32_16x16x32_bf16 v[38:41], v[174:177], v[150:153], v[38:41]
	v_mfma_f32_16x16x32_bf16 v[50:53], v[178:181], v[150:153], v[50:53]
	v_mfma_f32_16x16x32_bf16 v[54:57], v[182:185], v[150:153], v[54:57]
	v_mfma_f32_16x16x32_bf16 v[22:25], v[186:189], v[150:153], v[22:25]
	s_setprio 0
	s_waitcnt lgkmcnt(0)
	s_barrier
	ds_read_b128 v[104:107], v6 offset:32768
	ds_read_b128 v[112:115], v6 offset:34816
	ds_read_b128 v[120:123], v7 offset:49152
	ds_read_b128 v[132:135], v7 offset:51200
	ds_read_b128 v[150:153], v6 offset:36864
	ds_read_b128 v[154:157], v6 offset:38912
	ds_read_b128 v[158:161], v7 offset:53248
	ds_read_b128 v[162:165], v7 offset:55296
	s_setprio 2
	global_load_dwordx4 v[170:173], v8, s[36:37] offset:1152
	s_waitcnt vmcnt(7)
	ds_write_b128 v2, v[166:169]
	ds_read_b128 v[166:169], v3 offset:32768
	ds_read_b128 v[174:177], v4 offset:49152
	s_waitcnt lgkmcnt(8)
	v_mfma_f32_16x16x32_bf16 v[26:29], v[120:123], v[104:107], v[26:29]
	s_waitcnt lgkmcnt(3)
	v_mfma_f32_16x16x32_bf16 v[10:13], v[162:165], v[104:107], v[10:13]
	v_mfma_f32_16x16x32_bf16 v[88:91], v[132:135], v[104:107], v[88:91]
	v_mfma_f32_16x16x32_bf16 v[96:99], v[158:161], v[104:107], v[96:99]
	global_load_dwordx4 v[104:107], v216, s[36:37] offset:1152
	ds_write_b128 v2, v[62:65] offset:4096
	ds_read_b128 v[62:65], v3 offset:34816
	ds_read_b128 v[178:181], v4 offset:51200
	v_mfma_f32_16x16x32_bf16 v[30:33], v[120:123], v[112:115], v[30:33]
	v_mfma_f32_16x16x32_bf16 v[42:45], v[132:135], v[112:115], v[42:45]
	v_mfma_f32_16x16x32_bf16 v[14:17], v[162:165], v[112:115], v[14:17]
	v_mfma_f32_16x16x32_bf16 v[92:95], v[158:161], v[112:115], v[92:95]
	global_load_dwordx4 v[112:115], v217, s[36:37] offset:1152
	s_waitcnt vmcnt(7)
	ds_write_b128 v2, v[108:111] offset:8192
	ds_read_b128 v[108:111], v3 offset:36864
	ds_read_b128 v[182:185], v4 offset:53248
	v_mfma_f32_16x16x32_bf16 v[34:37], v[120:123], v[150:153], v[34:37]
	v_mfma_f32_16x16x32_bf16 v[46:49], v[132:135], v[150:153], v[46:49]
	v_mfma_f32_16x16x32_bf16 v[58:61], v[158:161], v[150:153], v[58:61]
	v_mfma_f32_16x16x32_bf16 v[18:21], v[162:165], v[150:153], v[18:21]
	global_load_dwordx4 v[150:153], v218, s[36:37] offset:1152
	ds_write_b128 v2, v[146:149] offset:12288
	ds_read_b128 v[146:149], v3 offset:38912
	ds_read_b128 v[186:189], v4 offset:55296
	v_mfma_f32_16x16x32_bf16 v[38:41], v[120:123], v[154:157], v[38:41]
	v_mfma_f32_16x16x32_bf16 v[50:53], v[132:135], v[154:157], v[50:53]
	v_mfma_f32_16x16x32_bf16 v[54:57], v[158:161], v[154:157], v[54:57]
	v_mfma_f32_16x16x32_bf16 v[22:25], v[162:165], v[154:157], v[22:25]
	global_load_dwordx4 v[120:123], v5, s[4:5] offset:1152
	s_waitcnt vmcnt(7)
	ds_write_b128 v2, v[116:119] offset:16384
	s_waitcnt lgkmcnt(10)
	v_mfma_f32_16x16x32_bf16 v[26:29], v[174:177], v[166:169], v[26:29]
	s_waitcnt lgkmcnt(1)
	v_mfma_f32_16x16x32_bf16 v[10:13], v[186:189], v[166:169], v[10:13]
	v_mfma_f32_16x16x32_bf16 v[88:91], v[178:181], v[166:169], v[88:91]
	v_mfma_f32_16x16x32_bf16 v[96:99], v[182:185], v[166:169], v[96:99]
	global_load_dwordx4 v[116:119], v219, s[4:5] offset:1152
	ds_write_b128 v2, v[124:127] offset:20480
	v_mfma_f32_16x16x32_bf16 v[30:33], v[174:177], v[62:65], v[30:33]
	v_mfma_f32_16x16x32_bf16 v[42:45], v[178:181], v[62:65], v[42:45]
	v_mfma_f32_16x16x32_bf16 v[14:17], v[186:189], v[62:65], v[14:17]
	v_mfma_f32_16x16x32_bf16 v[92:95], v[182:185], v[62:65], v[92:95]
	global_load_dwordx4 v[62:65], v220, s[4:5] offset:1152
	s_waitcnt vmcnt(7)
	ds_write_b128 v2, v[100:103] offset:24576
	v_mfma_f32_16x16x32_bf16 v[34:37], v[174:177], v[108:111], v[34:37]
	v_mfma_f32_16x16x32_bf16 v[46:49], v[178:181], v[108:111], v[46:49]
	v_mfma_f32_16x16x32_bf16 v[58:61], v[182:185], v[108:111], v[58:61]
	v_mfma_f32_16x16x32_bf16 v[18:21], v[186:189], v[108:111], v[18:21]
	global_load_dwordx4 v[100:103], v221, s[4:5] offset:1152
	ds_write_b128 v2, v[84:87] offset:28672
	v_mfma_f32_16x16x32_bf16 v[38:41], v[174:177], v[146:149], v[38:41]
	v_mfma_f32_16x16x32_bf16 v[50:53], v[178:181], v[146:149], v[50:53]
	v_mfma_f32_16x16x32_bf16 v[54:57], v[182:185], v[146:149], v[54:57]
	v_mfma_f32_16x16x32_bf16 v[22:25], v[186:189], v[146:149], v[22:25]
	s_setprio 0
	s_waitcnt lgkmcnt(0)
	s_barrier
; template <int MODE>
; __device__ __forceinline__ void gemm_tile(const Params& P, int tm, int tn, unsigned char* smem) {
;     ...
; #pragma unroll
;         for (int i = 0; i < 4; ++i) { fa[i] = *(const bf16x8*)(sA + arow_off + i * 2048 + ch0); fb[i] = *(const bf16x8*)(sB + brow_off + i * 2048 + ch0); }
;         __builtin_amdgcn_sched_barrier(0);
;         __builtin_amdgcn_s_setprio(2);
;         if (wr_ok) *(uint4*)(nA + soff0) = ra0;
;         if (ld_ok) ra0 = *(const uint4*)(Ab + (aoff + 0u * LDA + koa));
;         ga[0] = *(const bf16x8*)(sA + arow_off + 0 * 2048 + ch1); gb[0] = *(const bf16x8*)(sB + brow_off + 0 * 2048 + ch1);
;         __builtin_amdgcn_sched_barrier(0);
; #pragma unroll
;         for (int j = 0; j < 4; ++j) acc[0][j] = __builtin_amdgcn_mfma_f32_16x16x32_bf16(fb[j], fa[0], acc[0][j], 0, 0, 0);
;         __builtin_amdgcn_sched_barrier(0);
;         if (wr_ok) *(uint4*)(nA + soff0 + 4096) = ra1;
;         if (ld_ok) ra1 = *(const uint4*)(Ab + (aoff + 32u * LDA + koa));
;         ga[1] = *(const bf16x8*)(sA + arow_off + 1 * 2048 + ch1); gb[1] = *(const bf16x8*)(sB + brow_off + 1 * 2048 + ch1);
;         __builtin_amdgcn_sched_barrier(0);
; #pragma unroll
;         for (int j = 0; j < 4; ++j) acc[1][j] = __builtin_amdgcn_mfma_f32_16x16x32_bf16(fb[j], fa[1], acc[1][j], 0, 0, 0);
;         __builtin_amdgcn_sched_barrier(0);
;         if (wr_ok) *(uint4*)(nA + soff0 + 8192) = ra2;
;         if (ld_ok) ra2 = *(const uint4*)(Ab + (aoff + 64u * LDA + koa));
;         ga[2] = *(const bf16x8*)(sA + arow_off + 2 * 2048 + ch1); gb[2] = *(const bf16x8*)(sB + brow_off + 2 * 2048 + ch1);
;         __builtin_amdgcn_sched_barrier(0);
; #pragma unroll
;         for (int j = 0; j < 4; ++j) acc[2][j] = __builtin_amdgcn_mfma_f32_16x16x32_bf16(fb[j], fa[2], acc[2][j], 0, 0, 0);
;         __builtin_amdgcn_sched_barrier(0);
;         if (wr_ok) *(uint4*)(nA + soff0 + 12288) = ra3;
;         if (ld_ok) ra3 = *(const uint4*)(Ab + (aoff + 96u * LDA + koa));
;         ga[3] = *(const bf16x8*)(sA + arow_off + 3 * 2048 + ch1); gb[3] = *(const bf16x8*)(sB + brow_off + 3 * 2048 + ch1);
;         __builtin_amdgcn_sched_barrier(0);
; #pragma unroll
;         for (int j = 0; j < 4; ++j) acc[3][j] = __builtin_amdgcn_mfma_f32_16x16x32_bf16(fb[j], fa[3], acc[3][j], 0, 0, 0);
;         __builtin_amdgcn_sched_barrier(0);
;         if (wr_ok) *(uint4*)(nB + soff0) = rb0;
	ds_read_b128 v[84:87], v6
	ds_read_b128 v[108:111], v6 offset:2048
	ds_read_b128 v[124:127], v7 offset:16384
	ds_read_b128 v[132:135], v7 offset:18432
	ds_read_b128 v[146:149], v6 offset:4096
	ds_read_b128 v[154:157], v6 offset:6144
	ds_read_b128 v[158:161], v7 offset:20480
	ds_read_b128 v[162:165], v7 offset:22528
	s_setprio 2
	global_load_dwordx4 v[166:169], v8, s[36:37] offset:1280
	s_waitcnt vmcnt(7)
	ds_write_b128 v2, v[170:173] offset:32768
	ds_read_b128 v[170:173], v3
	ds_read_b128 v[174:177], v4 offset:16384
	s_waitcnt lgkmcnt(8)
	v_mfma_f32_16x16x32_bf16 v[26:29], v[124:127], v[84:87], v[26:29]
	s_waitcnt lgkmcnt(3)
	v_mfma_f32_16x16x32_bf16 v[10:13], v[162:165], v[84:87], v[10:13]
	v_mfma_f32_16x16x32_bf16 v[88:91], v[132:135], v[84:87], v[88:91]
	v_mfma_f32_16x16x32_bf16 v[96:99], v[158:161], v[84:87], v[96:99]
	global_load_dwordx4 v[84:87], v216, s[36:37] offset:1280
	ds_write_b128 v2, v[104:107] offset:36864
	ds_read_b128 v[104:107], v3 offset:2048
	ds_read_b128 v[178:181], v4 offset:18432
	v_mfma_f32_16x16x32_bf16 v[30:33], v[124:127], v[108:111], v[30:33]
	v_mfma_f32_16x16x32_bf16 v[42:45], v[132:135], v[108:111], v[42:45]
	v_mfma_f32_16x16x32_bf16 v[14:17], v[162:165], v[108:111], v[14:17]
	v_mfma_f32_16x16x32_bf16 v[92:95], v[158:161], v[108:111], v[92:95]
	global_load_dwordx4 v[108:111], v217, s[36:37] offset:1280
	s_waitcnt vmcnt(7)
	ds_write_b128 v2, v[112:115] offset:40960
	ds_read_b128 v[112:115], v3 offset:4096
	ds_read_b128 v[182:185], v4 offset:20480
	v_mfma_f32_16x16x32_bf16 v[34:37], v[124:127], v[146:149], v[34:37]
	v_mfma_f32_16x16x32_bf16 v[46:49], v[132:135], v[146:149], v[46:49]
	v_mfma_f32_16x16x32_bf16 v[58:61], v[158:161], v[146:149], v[58:61]
	v_mfma_f32_16x16x32_bf16 v[18:21], v[162:165], v[146:149], v[18:21]
	global_load_dwordx4 v[146:149], v218, s[36:37] offset:1280
	ds_write_b128 v2, v[150:153] offset:45056
	ds_read_b128 v[150:153], v3 offset:6144
	ds_read_b128 v[186:189], v4 offset:22528
	v_mfma_f32_16x16x32_bf16 v[38:41], v[124:127], v[154:157], v[38:41]
	v_mfma_f32_16x16x32_bf16 v[50:53], v[132:135], v[154:157], v[50:53]
	v_mfma_f32_16x16x32_bf16 v[54:57], v[158:161], v[154:157], v[54:57]
	v_mfma_f32_16x16x32_bf16 v[22:25], v[162:165], v[154:157], v[22:25]
	global_load_dwordx4 v[124:127], v5, s[4:5] offset:1280
	s_waitcnt vmcnt(7)
	ds_write_b128 v2, v[120:123] offset:49152
	s_waitcnt lgkmcnt(10)
	v_mfma_f32_16x16x32_bf16 v[26:29], v[174:177], v[170:173], v[26:29]
	s_waitcnt lgkmcnt(1)
	v_mfma_f32_16x16x32_bf16 v[10:13], v[186:189], v[170:173], v[10:13]
	v_mfma_f32_16x16x32_bf16 v[88:91], v[178:181], v[170:173], v[88:91]
	v_mfma_f32_16x16x32_bf16 v[96:99], v[182:185], v[170:173], v[96:99]
	global_load_dwordx4 v[120:123], v219, s[4:5] offset:1280
	ds_write_b128 v2, v[116:119] offset:53248
	v_mfma_f32_16x16x32_bf16 v[30:33], v[174:177], v[104:107], v[30:33]
	v_mfma_f32_16x16x32_bf16 v[42:45], v[178:181], v[104:107], v[42:45]
	v_mfma_f32_16x16x32_bf16 v[14:17], v[186:189], v[104:107], v[14:17]
	v_mfma_f32_16x16x32_bf16 v[92:95], v[182:185], v[104:107], v[92:95]
	global_load_dwordx4 v[104:107], v220, s[4:5] offset:1280
	s_waitcnt vmcnt(7)
	ds_write_b128 v2, v[62:65] offset:57344
	v_mfma_f32_16x16x32_bf16 v[34:37], v[174:177], v[112:115], v[34:37]
	v_mfma_f32_16x16x32_bf16 v[46:49], v[178:181], v[112:115], v[46:49]
	v_mfma_f32_16x16x32_bf16 v[58:61], v[182:185], v[112:115], v[58:61]
	v_mfma_f32_16x16x32_bf16 v[18:21], v[186:189], v[112:115], v[18:21]
	global_load_dwordx4 v[62:65], v221, s[4:5] offset:1280
	ds_write_b128 v2, v[100:103] offset:61440
	v_mfma_f32_16x16x32_bf16 v[38:41], v[174:177], v[150:153], v[38:41]
	v_mfma_f32_16x16x32_bf16 v[50:53], v[178:181], v[150:153], v[50:53]
	v_mfma_f32_16x16x32_bf16 v[54:57], v[182:185], v[150:153], v[54:57]
	v_mfma_f32_16x16x32_bf16 v[22:25], v[186:189], v[150:153], v[22:25]
	s_setprio 0
	s_waitcnt lgkmcnt(0)
	s_barrier
	ds_read_b128 v[100:103], v6 offset:32768
	ds_read_b128 v[112:115], v6 offset:34816
	ds_read_b128 v[116:119], v7 offset:49152
	ds_read_b128 v[132:135], v7 offset:51200
	ds_read_b128 v[150:153], v6 offset:36864
	ds_read_b128 v[154:157], v6 offset:38912
	ds_read_b128 v[158:161], v7 offset:53248
	ds_read_b128 v[162:165], v7 offset:55296
	s_setprio 2
	global_load_dwordx4 v[170:173], v8, s[36:37] offset:1408
	s_waitcnt vmcnt(7)
	ds_write_b128 v2, v[166:169]
	ds_read_b128 v[166:169], v3 offset:32768
	ds_read_b128 v[174:177], v4 offset:49152
	s_waitcnt lgkmcnt(8)
	v_mfma_f32_16x16x32_bf16 v[26:29], v[116:119], v[100:103], v[26:29]
	s_waitcnt lgkmcnt(3)
	v_mfma_f32_16x16x32_bf16 v[10:13], v[162:165], v[100:103], v[10:13]
	v_mfma_f32_16x16x32_bf16 v[88:91], v[132:135], v[100:103], v[88:91]
	v_mfma_f32_16x16x32_bf16 v[96:99], v[158:161], v[100:103], v[96:99]
	global_load_dwordx4 v[100:103], v216, s[36:37] offset:1408
	ds_write_b128 v2, v[84:87] offset:4096
	ds_read_b128 v[84:87], v3 offset:34816
	ds_read_b128 v[178:181], v4 offset:51200
	v_mfma_f32_16x16x32_bf16 v[30:33], v[116:119], v[112:115], v[30:33]
	v_mfma_f32_16x16x32_bf16 v[42:45], v[132:135], v[112:115], v[42:45]
	v_mfma_f32_16x16x32_bf16 v[14:17], v[162:165], v[112:115], v[14:17]
	v_mfma_f32_16x16x32_bf16 v[92:95], v[158:161], v[112:115], v[92:95]
	global_load_dwordx4 v[112:115], v217, s[36:37] offset:1408
	s_waitcnt vmcnt(7)
; template <int MODE>
; __device__ __forceinline__ void gemm_tile(const Params& P, int tm, int tn, unsigned char* smem) {
;     ...
; #pragma unroll
;         for (int i = 0; i < 4; ++i) { fa[i] = *(const bf16x8*)(sA + arow_off + i * 2048 + ch0); fb[i] = *(const bf16x8*)(sB + brow_off + i * 2048 + ch0); }
;         __builtin_amdgcn_sched_barrier(0);
;         __builtin_amdgcn_s_setprio(2);
;         if (wr_ok) *(uint4*)(nA + soff0) = ra0;
;         if (ld_ok) ra0 = *(const uint4*)(Ab + (aoff + 0u * LDA + koa));
;         ga[0] = *(const bf16x8*)(sA + arow_off + 0 * 2048 + ch1); gb[0] = *(const bf16x8*)(sB + brow_off + 0 * 2048 + ch1);
;         __builtin_amdgcn_sched_barrier(0);
; #pragma unroll
;         for (int j = 0; j < 4; ++j) acc[0][j] = __builtin_amdgcn_mfma_f32_16x16x32_bf16(fb[j], fa[0], acc[0][j], 0, 0, 0);
;         __builtin_amdgcn_sched_barrier(0);
;         if (wr_ok) *(uint4*)(nA + soff0 + 4096) = ra1;
;         if (ld_ok) ra1 = *(const uint4*)(Ab + (aoff + 32u * LDA + koa));
;         ga[1] = *(const bf16x8*)(sA + arow_off + 1 * 2048 + ch1); gb[1] = *(const bf16x8*)(sB + brow_off + 1 * 2048 + ch1);
;         __builtin_amdgcn_sched_barrier(0);
; #pragma unroll
;         for (int j = 0; j < 4; ++j) acc[1][j] = __builtin_amdgcn_mfma_f32_16x16x32_bf16(fb[j], fa[1], acc[1][j], 0, 0, 0);
;         __builtin_amdgcn_sched_barrier(0);
;         if (wr_ok) *(uint4*)(nA + soff0 + 8192) = ra2;
;         if (ld_ok) ra2 = *(const uint4*)(Ab + (aoff + 64u * LDA + koa));
;         ga[2] = *(const bf16x8*)(sA + arow_off + 2 * 2048 + ch1); gb[2] = *(const bf16x8*)(sB + brow_off + 2 * 2048 + ch1);
;         __builtin_amdgcn_sched_barrier(0);
; #pragma unroll
;         for (int j = 0; j < 4; ++j) acc[2][j] = __builtin_amdgcn_mfma_f32_16x16x32_bf16(fb[j], fa[2], acc[2][j], 0, 0, 0);
;         __builtin_amdgcn_sched_barrier(0);
;         if (wr_ok) *(uint4*)(nA + soff0 + 12288) = ra3;
;         if (ld_ok) ra3 = *(const uint4*)(Ab + (aoff + 96u * LDA + koa));
;         ga[3] = *(const bf16x8*)(sA + arow_off + 3 * 2048 + ch1); gb[3] = *(const bf16x8*)(sB + brow_off + 3 * 2048 + ch1);
;         __builtin_amdgcn_sched_barrier(0);
; #pragma unroll
;         for (int j = 0; j < 4; ++j) acc[3][j] = __builtin_amdgcn_mfma_f32_16x16x32_bf16(fb[j], fa[3], acc[3][j], 0, 0, 0);
;         __builtin_amdgcn_sched_barrier(0);
;         if (wr_ok) *(uint4*)(nB + soff0) = rb0;
	ds_write_b128 v2, v[108:111] offset:8192
	ds_read_b128 v[108:111], v3 offset:36864
	ds_read_b128 v[182:185], v4 offset:53248
	v_mfma_f32_16x16x32_bf16 v[34:37], v[116:119], v[150:153], v[34:37]
	v_mfma_f32_16x16x32_bf16 v[46:49], v[132:135], v[150:153], v[46:49]
	v_mfma_f32_16x16x32_bf16 v[58:61], v[158:161], v[150:153], v[58:61]
	v_mfma_f32_16x16x32_bf16 v[18:21], v[162:165], v[150:153], v[18:21]
	global_load_dwordx4 v[150:153], v218, s[36:37] offset:1408
	ds_write_b128 v2, v[146:149] offset:12288
	ds_read_b128 v[146:149], v3 offset:38912
	ds_read_b128 v[186:189], v4 offset:55296
	v_mfma_f32_16x16x32_bf16 v[38:41], v[116:119], v[154:157], v[38:41]
	v_mfma_f32_16x16x32_bf16 v[50:53], v[132:135], v[154:157], v[50:53]
	v_mfma_f32_16x16x32_bf16 v[54:57], v[158:161], v[154:157], v[54:57]
	v_mfma_f32_16x16x32_bf16 v[22:25], v[162:165], v[154:157], v[22:25]
	global_load_dwordx4 v[116:119], v5, s[4:5] offset:1408
	s_waitcnt vmcnt(7)
	ds_write_b128 v2, v[124:127] offset:16384
	s_waitcnt lgkmcnt(10)
	v_mfma_f32_16x16x32_bf16 v[26:29], v[174:177], v[166:169], v[26:29]
	s_waitcnt lgkmcnt(1)
	v_mfma_f32_16x16x32_bf16 v[10:13], v[186:189], v[166:169], v[10:13]
	v_mfma_f32_16x16x32_bf16 v[88:91], v[178:181], v[166:169], v[88:91]
	v_mfma_f32_16x16x32_bf16 v[96:99], v[182:185], v[166:169], v[96:99]
	global_load_dwordx4 v[124:127], v219, s[4:5] offset:1408
	ds_write_b128 v2, v[120:123] offset:20480
	v_mfma_f32_16x16x32_bf16 v[30:33], v[174:177], v[84:87], v[30:33]
	v_mfma_f32_16x16x32_bf16 v[42:45], v[178:181], v[84:87], v[42:45]
	v_mfma_f32_16x16x32_bf16 v[14:17], v[186:189], v[84:87], v[14:17]
	v_mfma_f32_16x16x32_bf16 v[92:95], v[182:185], v[84:87], v[92:95]
	global_load_dwordx4 v[84:87], v220, s[4:5] offset:1408
	s_waitcnt vmcnt(7)
	ds_write_b128 v2, v[104:107] offset:24576
	v_mfma_f32_16x16x32_bf16 v[34:37], v[174:177], v[108:111], v[34:37]
	v_mfma_f32_16x16x32_bf16 v[46:49], v[178:181], v[108:111], v[46:49]
	v_mfma_f32_16x16x32_bf16 v[58:61], v[182:185], v[108:111], v[58:61]
	v_mfma_f32_16x16x32_bf16 v[18:21], v[186:189], v[108:111], v[18:21]
	global_load_dwordx4 v[104:107], v221, s[4:5] offset:1408
	ds_write_b128 v2, v[62:65] offset:28672
	v_mfma_f32_16x16x32_bf16 v[38:41], v[174:177], v[146:149], v[38:41]
	v_mfma_f32_16x16x32_bf16 v[50:53], v[178:181], v[146:149], v[50:53]
	v_mfma_f32_16x16x32_bf16 v[54:57], v[182:185], v[146:149], v[54:57]
	v_mfma_f32_16x16x32_bf16 v[22:25], v[186:189], v[146:149], v[22:25]
	s_setprio 0
	s_waitcnt lgkmcnt(0)
	s_barrier
	ds_read_b128 v[62:65], v6
	ds_read_b128 v[108:111], v6 offset:2048
	ds_read_b128 v[120:123], v7 offset:16384
	ds_read_b128 v[132:135], v7 offset:18432
	ds_read_b128 v[146:149], v6 offset:4096
	ds_read_b128 v[154:157], v6 offset:6144
	ds_read_b128 v[158:161], v7 offset:20480
	ds_read_b128 v[162:165], v7 offset:22528
	s_setprio 2
	global_load_dwordx4 v[166:169], v8, s[36:37] offset:1536
	s_waitcnt vmcnt(7)
	ds_write_b128 v2, v[170:173] offset:32768
	ds_read_b128 v[170:173], v3
	ds_read_b128 v[174:177], v4 offset:16384
	s_waitcnt lgkmcnt(8)
	v_mfma_f32_16x16x32_bf16 v[26:29], v[120:123], v[62:65], v[26:29]
	s_waitcnt lgkmcnt(3)
	v_mfma_f32_16x16x32_bf16 v[10:13], v[162:165], v[62:65], v[10:13]
	v_mfma_f32_16x16x32_bf16 v[88:91], v[132:135], v[62:65], v[88:91]
	v_mfma_f32_16x16x32_bf16 v[96:99], v[158:161], v[62:65], v[96:99]
	global_load_dwordx4 v[62:65], v216, s[36:37] offset:1536
	ds_write_b128 v2, v[100:103] offset:36864
	ds_read_b128 v[100:103], v3 offset:2048
	ds_read_b128 v[178:181], v4 offset:18432
	v_mfma_f32_16x16x32_bf16 v[30:33], v[120:123], v[108:111], v[30:33]
	v_mfma_f32_16x16x32_bf16 v[42:45], v[132:135], v[108:111], v[42:45]
	v_mfma_f32_16x16x32_bf16 v[14:17], v[162:165], v[108:111], v[14:17]
	v_mfma_f32_16x16x32_bf16 v[92:95], v[158:161], v[108:111], v[92:95]
	global_load_dwordx4 v[108:111], v217, s[36:37] offset:1536
	s_waitcnt vmcnt(7)
	ds_write_b128 v2, v[112:115] offset:40960
	ds_read_b128 v[112:115], v3 offset:4096
	ds_read_b128 v[182:185], v4 offset:20480
	v_mfma_f32_16x16x32_bf16 v[34:37], v[120:123], v[146:149], v[34:37]
	v_mfma_f32_16x16x32_bf16 v[46:49], v[132:135], v[146:149], v[46:49]
	v_mfma_f32_16x16x32_bf16 v[58:61], v[158:161], v[146:149], v[58:61]
	v_mfma_f32_16x16x32_bf16 v[18:21], v[162:165], v[146:149], v[18:21]
	global_load_dwordx4 v[146:149], v218, s[36:37] offset:1536
	ds_write_b128 v2, v[150:153] offset:45056
	ds_read_b128 v[150:153], v3 offset:6144
	ds_read_b128 v[186:189], v4 offset:22528
	v_mfma_f32_16x16x32_bf16 v[38:41], v[120:123], v[154:157], v[38:41]
	v_mfma_f32_16x16x32_bf16 v[50:53], v[132:135], v[154:157], v[50:53]
	v_mfma_f32_16x16x32_bf16 v[54:57], v[158:161], v[154:157], v[54:57]
	v_mfma_f32_16x16x32_bf16 v[22:25], v[162:165], v[154:157], v[22:25]
	global_load_dwordx4 v[120:123], v5, s[4:5] offset:1536
	s_waitcnt vmcnt(7)
	ds_write_b128 v2, v[116:119] offset:49152
	s_waitcnt lgkmcnt(10)
	v_mfma_f32_16x16x32_bf16 v[26:29], v[174:177], v[170:173], v[26:29]
	s_waitcnt lgkmcnt(1)
	v_mfma_f32_16x16x32_bf16 v[10:13], v[186:189], v[170:173], v[10:13]
	v_mfma_f32_16x16x32_bf16 v[88:91], v[178:181], v[170:173], v[88:91]
	v_mfma_f32_16x16x32_bf16 v[96:99], v[182:185], v[170:173], v[96:99]
	global_load_dwordx4 v[116:119], v219, s[4:5] offset:1536
	ds_write_b128 v2, v[124:127] offset:53248
	v_mfma_f32_16x16x32_bf16 v[30:33], v[174:177], v[100:103], v[30:33]
	v_mfma_f32_16x16x32_bf16 v[42:45], v[178:181], v[100:103], v[42:45]
	v_mfma_f32_16x16x32_bf16 v[14:17], v[186:189], v[100:103], v[14:17]
	v_mfma_f32_16x16x32_bf16 v[92:95], v[182:185], v[100:103], v[92:95]
	global_load_dwordx4 v[100:103], v220, s[4:5] offset:1536
	s_waitcnt vmcnt(7)
	ds_write_b128 v2, v[84:87] offset:57344
	v_mfma_f32_16x16x32_bf16 v[34:37], v[174:177], v[112:115], v[34:37]
	v_mfma_f32_16x16x32_bf16 v[46:49], v[178:181], v[112:115], v[46:49]
	v_mfma_f32_16x16x32_bf16 v[58:61], v[182:185], v[112:115], v[58:61]
	v_mfma_f32_16x16x32_bf16 v[18:21], v[186:189], v[112:115], v[18:21]
	global_load_dwordx4 v[84:87], v221, s[4:5] offset:1536
	ds_write_b128 v2, v[104:107] offset:61440
	v_mfma_f32_16x16x32_bf16 v[38:41], v[174:177], v[150:153], v[38:41]
	v_mfma_f32_16x16x32_bf16 v[50:53], v[178:181], v[150:153], v[50:53]
	v_mfma_f32_16x16x32_bf16 v[54:57], v[182:185], v[150:153], v[54:57]
	v_mfma_f32_16x16x32_bf16 v[22:25], v[186:189], v[150:153], v[22:25]
	s_setprio 0
	s_waitcnt lgkmcnt(0)
	s_barrier
; template <int MODE>
; __device__ __forceinline__ void gemm_tile(const Params& P, int tm, int tn, unsigned char* smem) {
;     ...
; #pragma unroll
;         for (int i = 0; i < 4; ++i) { fa[i] = *(const bf16x8*)(sA + arow_off + i * 2048 + ch0); fb[i] = *(const bf16x8*)(sB + brow_off + i * 2048 + ch0); }
;         __builtin_amdgcn_sched_barrier(0);
;         __builtin_amdgcn_s_setprio(2);
;         if (wr_ok) *(uint4*)(nA + soff0) = ra0;
;         if (ld_ok) ra0 = *(const uint4*)(Ab + (aoff + 0u * LDA + koa));
;         ga[0] = *(const bf16x8*)(sA + arow_off + 0 * 2048 + ch1); gb[0] = *(const bf16x8*)(sB + brow_off + 0 * 2048 + ch1);
;         __builtin_amdgcn_sched_barrier(0);
; #pragma unroll
;         for (int j = 0; j < 4; ++j) acc[0][j] = __builtin_amdgcn_mfma_f32_16x16x32_bf16(fb[j], fa[0], acc[0][j], 0, 0, 0);
;         __builtin_amdgcn_sched_barrier(0);
;         if (wr_ok) *(uint4*)(nA + soff0 + 4096) = ra1;
;         if (ld_ok) ra1 = *(const uint4*)(Ab + (aoff + 32u * LDA + koa));
;         ga[1] = *(const bf16x8*)(sA + arow_off + 1 * 2048 + ch1); gb[1] = *(const bf16x8*)(sB + brow_off + 1 * 2048 + ch1);
;         __builtin_amdgcn_sched_barrier(0);
; #pragma unroll
;         for (int j = 0; j < 4; ++j) acc[1][j] = __builtin_amdgcn_mfma_f32_16x16x32_bf16(fb[j], fa[1], acc[1][j], 0, 0, 0);
;         __builtin_amdgcn_sched_barrier(0);
;         if (wr_ok) *(uint4*)(nA + soff0 + 8192) = ra2;
;         if (ld_ok) ra2 = *(const uint4*)(Ab + (aoff + 64u * LDA + koa));
;         ga[2] = *(const bf16x8*)(sA + arow_off + 2 * 2048 + ch1); gb[2] = *(const bf16x8*)(sB + brow_off + 2 * 2048 + ch1);
;         __builtin_amdgcn_sched_barrier(0);
; #pragma unroll
;         for (int j = 0; j < 4; ++j) acc[2][j] = __builtin_amdgcn_mfma_f32_16x16x32_bf16(fb[j], fa[2], acc[2][j], 0, 0, 0);
;         __builtin_amdgcn_sched_barrier(0);
;         if (wr_ok) *(uint4*)(nA + soff0 + 12288) = ra3;
;         if (ld_ok) ra3 = *(const uint4*)(Ab + (aoff + 96u * LDA + koa));
;         ga[3] = *(const bf16x8*)(sA + arow_off + 3 * 2048 + ch1); gb[3] = *(const bf16x8*)(sB + brow_off + 3 * 2048 + ch1);
;         __builtin_amdgcn_sched_barrier(0);
; #pragma unroll
;         for (int j = 0; j < 4; ++j) acc[3][j] = __builtin_amdgcn_mfma_f32_16x16x32_bf16(fb[j], fa[3], acc[3][j], 0, 0, 0);
;         __builtin_amdgcn_sched_barrier(0);
;         if (wr_ok) *(uint4*)(nB + soff0) = rb0;
	ds_read_b128 v[104:107], v6 offset:32768
	ds_read_b128 v[112:115], v6 offset:34816
	ds_read_b128 v[124:127], v7 offset:49152
	ds_read_b128 v[132:135], v7 offset:51200
	ds_read_b128 v[150:153], v6 offset:36864
	ds_read_b128 v[154:157], v6 offset:38912
	ds_read_b128 v[158:161], v7 offset:53248
	ds_read_b128 v[162:165], v7 offset:55296
	s_setprio 2
	global_load_dwordx4 v[170:173], v8, s[36:37] offset:1664
	s_waitcnt vmcnt(7)
	ds_write_b128 v2, v[166:169]
	ds_read_b128 v[166:169], v3 offset:32768
	ds_read_b128 v[174:177], v4 offset:49152
	s_waitcnt lgkmcnt(8)
	v_mfma_f32_16x16x32_bf16 v[26:29], v[124:127], v[104:107], v[26:29]
	s_waitcnt lgkmcnt(3)
	v_mfma_f32_16x16x32_bf16 v[10:13], v[162:165], v[104:107], v[10:13]
	v_mfma_f32_16x16x32_bf16 v[88:91], v[132:135], v[104:107], v[88:91]
	v_mfma_f32_16x16x32_bf16 v[96:99], v[158:161], v[104:107], v[96:99]
	global_load_dwordx4 v[104:107], v216, s[36:37] offset:1664
	ds_write_b128 v2, v[62:65] offset:4096
	ds_read_b128 v[62:65], v3 offset:34816
	ds_read_b128 v[178:181], v4 offset:51200
	v_mfma_f32_16x16x32_bf16 v[30:33], v[124:127], v[112:115], v[30:33]
	v_mfma_f32_16x16x32_bf16 v[42:45], v[132:135], v[112:115], v[42:45]
	v_mfma_f32_16x16x32_bf16 v[14:17], v[162:165], v[112:115], v[14:17]
	v_mfma_f32_16x16x32_bf16 v[92:95], v[158:161], v[112:115], v[92:95]
	global_load_dwordx4 v[112:115], v217, s[36:37] offset:1664
	s_waitcnt vmcnt(7)
	ds_write_b128 v2, v[108:111] offset:8192
	ds_read_b128 v[108:111], v3 offset:36864
	ds_read_b128 v[182:185], v4 offset:53248
	v_mfma_f32_16x16x32_bf16 v[34:37], v[124:127], v[150:153], v[34:37]
	v_mfma_f32_16x16x32_bf16 v[46:49], v[132:135], v[150:153], v[46:49]
	v_mfma_f32_16x16x32_bf16 v[58:61], v[158:161], v[150:153], v[58:61]
	v_mfma_f32_16x16x32_bf16 v[18:21], v[162:165], v[150:153], v[18:21]
	global_load_dwordx4 v[150:153], v218, s[36:37] offset:1664
	ds_write_b128 v2, v[146:149] offset:12288
	ds_read_b128 v[146:149], v3 offset:38912
	ds_read_b128 v[186:189], v4 offset:55296
	v_mfma_f32_16x16x32_bf16 v[38:41], v[124:127], v[154:157], v[38:41]
	v_mfma_f32_16x16x32_bf16 v[50:53], v[132:135], v[154:157], v[50:53]
	v_mfma_f32_16x16x32_bf16 v[54:57], v[158:161], v[154:157], v[54:57]
	v_mfma_f32_16x16x32_bf16 v[22:25], v[162:165], v[154:157], v[22:25]
	global_load_dwordx4 v[124:127], v5, s[4:5] offset:1664
	s_waitcnt vmcnt(7)
	ds_write_b128 v2, v[120:123] offset:16384
	s_waitcnt lgkmcnt(10)
	v_mfma_f32_16x16x32_bf16 v[26:29], v[174:177], v[166:169], v[26:29]
	s_waitcnt lgkmcnt(1)
	v_mfma_f32_16x16x32_bf16 v[10:13], v[186:189], v[166:169], v[10:13]
	v_mfma_f32_16x16x32_bf16 v[88:91], v[178:181], v[166:169], v[88:91]
	v_mfma_f32_16x16x32_bf16 v[96:99], v[182:185], v[166:169], v[96:99]
	global_load_dwordx4 v[120:123], v219, s[4:5] offset:1664
	ds_write_b128 v2, v[116:119] offset:20480
	v_mfma_f32_16x16x32_bf16 v[30:33], v[174:177], v[62:65], v[30:33]
	v_mfma_f32_16x16x32_bf16 v[42:45], v[178:181], v[62:65], v[42:45]
	v_mfma_f32_16x16x32_bf16 v[14:17], v[186:189], v[62:65], v[14:17]
	v_mfma_f32_16x16x32_bf16 v[92:95], v[182:185], v[62:65], v[92:95]
	global_load_dwordx4 v[62:65], v220, s[4:5] offset:1664
	s_waitcnt vmcnt(7)
	ds_write_b128 v2, v[100:103] offset:24576
	v_mfma_f32_16x16x32_bf16 v[34:37], v[174:177], v[108:111], v[34:37]
	v_mfma_f32_16x16x32_bf16 v[46:49], v[178:181], v[108:111], v[46:49]
	v_mfma_f32_16x16x32_bf16 v[58:61], v[182:185], v[108:111], v[58:61]
	v_mfma_f32_16x16x32_bf16 v[18:21], v[186:189], v[108:111], v[18:21]
	global_load_dwordx4 v[100:103], v221, s[4:5] offset:1664
	ds_write_b128 v2, v[84:87] offset:28672
	v_mfma_f32_16x16x32_bf16 v[38:41], v[174:177], v[146:149], v[38:41]
	v_mfma_f32_16x16x32_bf16 v[50:53], v[178:181], v[146:149], v[50:53]
	v_mfma_f32_16x16x32_bf16 v[54:57], v[182:185], v[146:149], v[54:57]
	v_mfma_f32_16x16x32_bf16 v[22:25], v[186:189], v[146:149], v[22:25]
	s_setprio 0
	s_waitcnt lgkmcnt(0)
	s_barrier
	ds_read_b128 v[84:87], v6
	ds_read_b128 v[108:111], v6 offset:2048
	ds_read_b128 v[116:119], v7 offset:16384
	ds_read_b128 v[132:135], v7 offset:18432
	ds_read_b128 v[146:149], v6 offset:4096
	ds_read_b128 v[154:157], v6 offset:6144
	ds_read_b128 v[158:161], v7 offset:20480
	ds_read_b128 v[162:165], v7 offset:22528
	s_setprio 2
	global_load_dwordx4 v[166:169], v8, s[36:37] offset:1792
	s_waitcnt vmcnt(7)
	ds_write_b128 v2, v[170:173] offset:32768
	ds_read_b128 v[170:173], v3
	ds_read_b128 v[174:177], v4 offset:16384
	s_waitcnt lgkmcnt(8)
	v_mfma_f32_16x16x32_bf16 v[26:29], v[116:119], v[84:87], v[26:29]
	s_waitcnt lgkmcnt(3)
	v_mfma_f32_16x16x32_bf16 v[10:13], v[162:165], v[84:87], v[10:13]
	v_mfma_f32_16x16x32_bf16 v[88:91], v[132:135], v[84:87], v[88:91]
	v_mfma_f32_16x16x32_bf16 v[96:99], v[158:161], v[84:87], v[96:99]
	global_load_dwordx4 v[84:87], v216, s[36:37] offset:1792
	ds_write_b128 v2, v[104:107] offset:36864
	ds_read_b128 v[104:107], v3 offset:2048
	ds_read_b128 v[178:181], v4 offset:18432
	v_mfma_f32_16x16x32_bf16 v[30:33], v[116:119], v[108:111], v[30:33]
	v_mfma_f32_16x16x32_bf16 v[42:45], v[132:135], v[108:111], v[42:45]
	v_mfma_f32_16x16x32_bf16 v[14:17], v[162:165], v[108:111], v[14:17]
	v_mfma_f32_16x16x32_bf16 v[92:95], v[158:161], v[108:111], v[92:95]
	global_load_dwordx4 v[108:111], v217, s[36:37] offset:1792
	s_waitcnt vmcnt(7)
; template <int MODE>
; __device__ __forceinline__ void gemm_tile(const Params& P, int tm, int tn, unsigned char* smem) {
;     ...
; #pragma unroll
;         for (int i = 0; i < 4; ++i) { fa[i] = *(const bf16x8*)(sA + arow_off + i * 2048 + ch0); fb[i] = *(const bf16x8*)(sB + brow_off + i * 2048 + ch0); }
;         __builtin_amdgcn_sched_barrier(0);
;         __builtin_amdgcn_s_setprio(2);
;         if (wr_ok) *(uint4*)(nA + soff0) = ra0;
;         if (ld_ok) ra0 = *(const uint4*)(Ab + (aoff + 0u * LDA + koa));
;         ga[0] = *(const bf16x8*)(sA + arow_off + 0 * 2048 + ch1); gb[0] = *(const bf16x8*)(sB + brow_off + 0 * 2048 + ch1);
;         __builtin_amdgcn_sched_barrier(0);
; #pragma unroll
;         for (int j = 0; j < 4; ++j) acc[0][j] = __builtin_amdgcn_mfma_f32_16x16x32_bf16(fb[j], fa[0], acc[0][j], 0, 0, 0);
;         __builtin_amdgcn_sched_barrier(0);
;         if (wr_ok) *(uint4*)(nA + soff0 + 4096) = ra1;
;         if (ld_ok) ra1 = *(const uint4*)(Ab + (aoff + 32u * LDA + koa));
;         ga[1] = *(const bf16x8*)(sA + arow_off + 1 * 2048 + ch1); gb[1] = *(const bf16x8*)(sB + brow_off + 1 * 2048 + ch1);
;         __builtin_amdgcn_sched_barrier(0);
; #pragma unroll
;         for (int j = 0; j < 4; ++j) acc[1][j] = __builtin_amdgcn_mfma_f32_16x16x32_bf16(fb[j], fa[1], acc[1][j], 0, 0, 0);
;         __builtin_amdgcn_sched_barrier(0);
;         if (wr_ok) *(uint4*)(nA + soff0 + 8192) = ra2;
;         if (ld_ok) ra2 = *(const uint4*)(Ab + (aoff + 64u * LDA + koa));
;         ga[2] = *(const bf16x8*)(sA + arow_off + 2 * 2048 + ch1); gb[2] = *(const bf16x8*)(sB + brow_off + 2 * 2048 + ch1);
;         __builtin_amdgcn_sched_barrier(0);
; #pragma unroll
;         for (int j = 0; j < 4; ++j) acc[2][j] = __builtin_amdgcn_mfma_f32_16x16x32_bf16(fb[j], fa[2], acc[2][j], 0, 0, 0);
;         __builtin_amdgcn_sched_barrier(0);
;         if (wr_ok) *(uint4*)(nA + soff0 + 12288) = ra3;
;         if (ld_ok) ra3 = *(const uint4*)(Ab + (aoff + 96u * LDA + koa));
;         ga[3] = *(const bf16x8*)(sA + arow_off + 3 * 2048 + ch1); gb[3] = *(const bf16x8*)(sB + brow_off + 3 * 2048 + ch1);
;         __builtin_amdgcn_sched_barrier(0);
; #pragma unroll
;         for (int j = 0; j < 4; ++j) acc[3][j] = __builtin_amdgcn_mfma_f32_16x16x32_bf16(fb[j], fa[3], acc[3][j], 0, 0, 0);
;         __builtin_amdgcn_sched_barrier(0);
;         if (wr_ok) *(uint4*)(nB + soff0) = rb0;
	ds_write_b128 v2, v[112:115] offset:40960
	ds_read_b128 v[112:115], v3 offset:4096
	ds_read_b128 v[182:185], v4 offset:20480
	v_mfma_f32_16x16x32_bf16 v[34:37], v[116:119], v[146:149], v[34:37]
	v_mfma_f32_16x16x32_bf16 v[46:49], v[132:135], v[146:149], v[46:49]
	v_mfma_f32_16x16x32_bf16 v[58:61], v[158:161], v[146:149], v[58:61]
	v_mfma_f32_16x16x32_bf16 v[18:21], v[162:165], v[146:149], v[18:21]
	global_load_dwordx4 v[146:149], v218, s[36:37] offset:1792
	ds_write_b128 v2, v[150:153] offset:45056
	ds_read_b128 v[150:153], v3 offset:6144
	ds_read_b128 v[186:189], v4 offset:22528
	v_mfma_f32_16x16x32_bf16 v[38:41], v[116:119], v[154:157], v[38:41]
	v_mfma_f32_16x16x32_bf16 v[50:53], v[132:135], v[154:157], v[50:53]
	v_mfma_f32_16x16x32_bf16 v[54:57], v[158:161], v[154:157], v[54:57]
	v_mfma_f32_16x16x32_bf16 v[22:25], v[162:165], v[154:157], v[22:25]
	global_load_dwordx4 v[116:119], v5, s[4:5] offset:1792
	s_waitcnt vmcnt(7)
	ds_write_b128 v2, v[124:127] offset:49152
	s_waitcnt lgkmcnt(10)
	v_mfma_f32_16x16x32_bf16 v[26:29], v[174:177], v[170:173], v[26:29]
	s_waitcnt lgkmcnt(1)
	v_mfma_f32_16x16x32_bf16 v[10:13], v[186:189], v[170:173], v[10:13]
	v_mfma_f32_16x16x32_bf16 v[88:91], v[178:181], v[170:173], v[88:91]
	v_mfma_f32_16x16x32_bf16 v[96:99], v[182:185], v[170:173], v[96:99]
	global_load_dwordx4 v[124:127], v219, s[4:5] offset:1792
	ds_write_b128 v2, v[120:123] offset:53248
	v_mfma_f32_16x16x32_bf16 v[30:33], v[174:177], v[104:107], v[30:33]
	v_mfma_f32_16x16x32_bf16 v[42:45], v[178:181], v[104:107], v[42:45]
	v_mfma_f32_16x16x32_bf16 v[14:17], v[186:189], v[104:107], v[14:17]
	v_mfma_f32_16x16x32_bf16 v[92:95], v[182:185], v[104:107], v[92:95]
	global_load_dwordx4 v[104:107], v220, s[4:5] offset:1792
	s_waitcnt vmcnt(7)
	ds_write_b128 v2, v[62:65] offset:57344
	v_mfma_f32_16x16x32_bf16 v[34:37], v[174:177], v[112:115], v[34:37]
	v_mfma_f32_16x16x32_bf16 v[46:49], v[178:181], v[112:115], v[46:49]
	v_mfma_f32_16x16x32_bf16 v[58:61], v[182:185], v[112:115], v[58:61]
	v_mfma_f32_16x16x32_bf16 v[18:21], v[186:189], v[112:115], v[18:21]
	global_load_dwordx4 v[62:65], v221, s[4:5] offset:1792
	ds_write_b128 v2, v[100:103] offset:61440
	v_mfma_f32_16x16x32_bf16 v[38:41], v[174:177], v[150:153], v[38:41]
	v_mfma_f32_16x16x32_bf16 v[50:53], v[178:181], v[150:153], v[50:53]
	v_mfma_f32_16x16x32_bf16 v[54:57], v[182:185], v[150:153], v[54:57]
	v_mfma_f32_16x16x32_bf16 v[22:25], v[186:189], v[150:153], v[22:25]
	s_setprio 0
	s_waitcnt lgkmcnt(0)
	s_barrier
	ds_read_b128 v[100:103], v6 offset:32768
	ds_read_b128 v[112:115], v6 offset:34816
	ds_read_b128 v[120:123], v7 offset:49152
	ds_read_b128 v[132:135], v7 offset:51200
	ds_read_b128 v[150:153], v6 offset:36864
	ds_read_b128 v[154:157], v6 offset:38912
	ds_read_b128 v[158:161], v7 offset:53248
	ds_read_b128 v[162:165], v7 offset:55296
	s_setprio 2
	global_load_dwordx4 v[170:173], v8, s[36:37] offset:1920
	s_waitcnt vmcnt(7)
	ds_write_b128 v2, v[166:169]
	ds_read_b128 v[166:169], v3 offset:32768
	ds_read_b128 v[174:177], v4 offset:49152
	s_waitcnt lgkmcnt(8)
	v_mfma_f32_16x16x32_bf16 v[26:29], v[120:123], v[100:103], v[26:29]
	s_waitcnt lgkmcnt(3)
	v_mfma_f32_16x16x32_bf16 v[10:13], v[162:165], v[100:103], v[10:13]
	v_mfma_f32_16x16x32_bf16 v[88:91], v[132:135], v[100:103], v[88:91]
	v_mfma_f32_16x16x32_bf16 v[96:99], v[158:161], v[100:103], v[96:99]
	global_load_dwordx4 v[100:103], v216, s[36:37] offset:1920
	ds_write_b128 v2, v[84:87] offset:4096
	ds_read_b128 v[84:87], v3 offset:34816
	ds_read_b128 v[178:181], v4 offset:51200
	v_mfma_f32_16x16x32_bf16 v[30:33], v[120:123], v[112:115], v[30:33]
	v_mfma_f32_16x16x32_bf16 v[42:45], v[132:135], v[112:115], v[42:45]
	v_mfma_f32_16x16x32_bf16 v[14:17], v[162:165], v[112:115], v[14:17]
	v_mfma_f32_16x16x32_bf16 v[92:95], v[158:161], v[112:115], v[92:95]
	global_load_dwordx4 v[112:115], v217, s[36:37] offset:1920
	s_waitcnt vmcnt(7)
	ds_write_b128 v2, v[108:111] offset:8192
	ds_read_b128 v[108:111], v3 offset:36864
	ds_read_b128 v[182:185], v4 offset:53248
	v_mfma_f32_16x16x32_bf16 v[34:37], v[120:123], v[150:153], v[34:37]
	v_mfma_f32_16x16x32_bf16 v[46:49], v[132:135], v[150:153], v[46:49]
	v_mfma_f32_16x16x32_bf16 v[58:61], v[158:161], v[150:153], v[58:61]
	v_mfma_f32_16x16x32_bf16 v[18:21], v[162:165], v[150:153], v[18:21]
	v_add_u32_e32 v8, 0x30780, v8
	global_load_dwordx4 v[150:153], v8, s[36:37]
	ds_write_b128 v2, v[146:149] offset:12288
	ds_read_b128 v[146:149], v3 offset:38912
	ds_read_b128 v[186:189], v4 offset:55296
	v_mfma_f32_16x16x32_bf16 v[38:41], v[120:123], v[154:157], v[38:41]
	v_mfma_f32_16x16x32_bf16 v[50:53], v[132:135], v[154:157], v[50:53]
	v_mfma_f32_16x16x32_bf16 v[54:57], v[158:161], v[154:157], v[54:57]
	v_mfma_f32_16x16x32_bf16 v[22:25], v[162:165], v[154:157], v[22:25]
	global_load_dwordx4 v[120:123], v5, s[4:5] offset:1920
	s_waitcnt vmcnt(7)
	ds_write_b128 v2, v[116:119] offset:16384
	s_waitcnt lgkmcnt(10)
	v_mfma_f32_16x16x32_bf16 v[26:29], v[174:177], v[166:169], v[26:29]
	s_waitcnt lgkmcnt(1)
	v_mfma_f32_16x16x32_bf16 v[8:11], v[186:189], v[166:169], v[10:13]
	v_mfma_f32_16x16x32_bf16 v[88:91], v[178:181], v[166:169], v[88:91]
	v_mfma_f32_16x16x32_bf16 v[96:99], v[182:185], v[166:169], v[96:99]
	s_nop 0
	global_load_dwordx4 v[116:119], v219, s[4:5] offset:1920
	ds_write_b128 v2, v[124:127] offset:20480
	v_mfma_f32_16x16x32_bf16 v[30:33], v[174:177], v[84:87], v[30:33]
	v_mfma_f32_16x16x32_bf16 v[42:45], v[178:181], v[84:87], v[42:45]
	v_mfma_f32_16x16x32_bf16 v[12:15], v[186:189], v[84:87], v[14:17]
	v_mfma_f32_16x16x32_bf16 v[92:95], v[182:185], v[84:87], v[92:95]
	s_nop 1
	global_load_dwordx4 v[84:87], v220, s[4:5] offset:1920
	s_waitcnt vmcnt(7)
	ds_write_b128 v2, v[104:107] offset:24576
	v_mfma_f32_16x16x32_bf16 v[34:37], v[174:177], v[108:111], v[34:37]
	v_mfma_f32_16x16x32_bf16 v[46:49], v[178:181], v[108:111], v[46:49]
	v_mfma_f32_16x16x32_bf16 v[58:61], v[182:185], v[108:111], v[58:61]
	v_mfma_f32_16x16x32_bf16 v[16:19], v[186:189], v[108:111], v[18:21]
	v_add_u32_e32 v5, 0x30780, v5
	global_load_dwordx4 v[104:107], v5, s[4:5]
	ds_write_b128 v2, v[62:65] offset:28672
	v_mfma_f32_16x16x32_bf16 v[38:41], v[174:177], v[146:149], v[38:41]
	v_mfma_f32_16x16x32_bf16 v[50:53], v[178:181], v[146:149], v[50:53]
	v_mfma_f32_16x16x32_bf16 v[54:57], v[182:185], v[146:149], v[54:57]
	v_mfma_f32_16x16x32_bf16 v[20:23], v[186:189], v[146:149], v[22:25]
	s_setprio 0
	s_waitcnt lgkmcnt(0)
	s_barrier
; template <int MODE>
; __device__ __forceinline__ void gemm_tile(const Params& P, int tm, int tn, unsigned char* smem) {
;     ...
; #pragma unroll
;         for (int i = 0; i < 4; ++i) { fa[i] = *(const bf16x8*)(sA + arow_off + i * 2048 + ch0); fb[i] = *(const bf16x8*)(sB + brow_off + i * 2048 + ch0); }
;         __builtin_amdgcn_sched_barrier(0);
;         __builtin_amdgcn_s_setprio(2);
;         if (wr_ok) *(uint4*)(nA + soff0) = ra0;
;         if (ld_ok) ra0 = *(const uint4*)(Ab + (aoff + 0u * LDA + koa));
;         ga[0] = *(const bf16x8*)(sA + arow_off + 0 * 2048 + ch1); gb[0] = *(const bf16x8*)(sB + brow_off + 0 * 2048 + ch1);
;         __builtin_amdgcn_sched_barrier(0);
; #pragma unroll
;         for (int j = 0; j < 4; ++j) acc[0][j] = __builtin_amdgcn_mfma_f32_16x16x32_bf16(fb[j], fa[0], acc[0][j], 0, 0, 0);
;         __builtin_amdgcn_sched_barrier(0);
;         if (wr_ok) *(uint4*)(nA + soff0 + 4096) = ra1;
;         if (ld_ok) ra1 = *(const uint4*)(Ab + (aoff + 32u * LDA + koa));
;         ga[1] = *(const bf16x8*)(sA + arow_off + 1 * 2048 + ch1); gb[1] = *(const bf16x8*)(sB + brow_off + 1 * 2048 + ch1);
;         __builtin_amdgcn_sched_barrier(0);
; #pragma unroll
;         for (int j = 0; j < 4; ++j) acc[1][j] = __builtin_amdgcn_mfma_f32_16x16x32_bf16(fb[j], fa[1], acc[1][j], 0, 0, 0);
;         __builtin_amdgcn_sched_barrier(0);
;         if (wr_ok) *(uint4*)(nA + soff0 + 8192) = ra2;
;         if (ld_ok) ra2 = *(const uint4*)(Ab + (aoff + 64u * LDA + koa));
;         ga[2] = *(const bf16x8*)(sA + arow_off + 2 * 2048 + ch1); gb[2] = *(const bf16x8*)(sB + brow_off + 2 * 2048 + ch1);
;         __builtin_amdgcn_sched_barrier(0);
; #pragma unroll
;         for (int j = 0; j < 4; ++j) acc[2][j] = __builtin_amdgcn_mfma_f32_16x16x32_bf16(fb[j], fa[2], acc[2][j], 0, 0, 0);
;         __builtin_amdgcn_sched_barrier(0);
;         if (wr_ok) *(uint4*)(nA + soff0 + 12288) = ra3;
;         if (ld_ok) ra3 = *(const uint4*)(Ab + (aoff + 96u * LDA + koa));
;         ga[3] = *(const bf16x8*)(sA + arow_off + 3 * 2048 + ch1); gb[3] = *(const bf16x8*)(sB + brow_off + 3 * 2048 + ch1);
;         __builtin_amdgcn_sched_barrier(0);
; #pragma unroll
;         for (int j = 0; j < 4; ++j) acc[3][j] = __builtin_amdgcn_mfma_f32_16x16x32_bf16(fb[j], fa[3], acc[3][j], 0, 0, 0);
;         __builtin_amdgcn_sched_barrier(0);
;         if (wr_ok) *(uint4*)(nB + soff0) = rb0;
	ds_read_b128 v[62:65], v6
	ds_read_b128 v[108:111], v6 offset:2048
	ds_read_b128 v[124:127], v7 offset:16384
	ds_read_b128 v[132:135], v7 offset:18432
	ds_read_b128 v[146:149], v6 offset:4096
	ds_read_b128 v[154:157], v6 offset:6144
	ds_read_b128 v[158:161], v7 offset:20480
	ds_read_b128 v[162:165], v7 offset:22528
	s_setprio 2
	s_waitcnt vmcnt(7)
	ds_write_b128 v2, v[170:173] offset:32768
	ds_read_b128 v[166:169], v3
	ds_read_b128 v[170:173], v4 offset:16384
	s_waitcnt lgkmcnt(8)
	v_mfma_f32_16x16x32_bf16 v[24:27], v[124:127], v[62:65], v[26:29]
	s_waitcnt lgkmcnt(3)
	v_mfma_f32_16x16x32_bf16 v[8:11], v[162:165], v[62:65], v[8:11]
	v_mfma_f32_16x16x32_bf16 v[88:91], v[132:135], v[62:65], v[88:91]
	v_mfma_f32_16x16x32_bf16 v[96:99], v[158:161], v[62:65], v[96:99]
	s_waitcnt vmcnt(6)
	ds_write_b128 v2, v[100:103] offset:36864
	ds_read_b128 v[62:65], v3 offset:2048
	ds_read_b128 v[100:103], v4 offset:18432
	v_mfma_f32_16x16x32_bf16 v[28:31], v[124:127], v[108:111], v[30:33]
	v_mfma_f32_16x16x32_bf16 v[42:45], v[132:135], v[108:111], v[42:45]
	v_mfma_f32_16x16x32_bf16 v[12:15], v[162:165], v[108:111], v[12:15]
	v_mfma_f32_16x16x32_bf16 v[92:95], v[158:161], v[108:111], v[92:95]
	s_waitcnt vmcnt(5)
	ds_write_b128 v2, v[112:115] offset:40960
	ds_read_b128 v[108:111], v3 offset:4096
	ds_read_b128 v[112:115], v4 offset:20480
	v_mfma_f32_16x16x32_bf16 v[32:35], v[124:127], v[146:149], v[34:37]
	v_mfma_f32_16x16x32_bf16 v[46:49], v[132:135], v[146:149], v[46:49]
	v_mfma_f32_16x16x32_bf16 v[58:61], v[158:161], v[146:149], v[58:61]
	v_mfma_f32_16x16x32_bf16 v[16:19], v[162:165], v[146:149], v[16:19]
	s_waitcnt vmcnt(4)
	ds_write_b128 v2, v[150:153] offset:45056
	ds_read_b128 v[146:149], v3 offset:6144
	ds_read_b128 v[150:153], v4 offset:22528
	v_mfma_f32_16x16x32_bf16 v[36:39], v[124:127], v[154:157], v[38:41]
	v_mfma_f32_16x16x32_bf16 v[50:53], v[132:135], v[154:157], v[50:53]
	v_mfma_f32_16x16x32_bf16 v[54:57], v[158:161], v[154:157], v[54:57]
	v_mfma_f32_16x16x32_bf16 v[20:23], v[162:165], v[154:157], v[20:23]
	s_waitcnt vmcnt(3)
	ds_write_b128 v2, v[120:123] offset:49152
	s_waitcnt lgkmcnt(10)
	v_mfma_f32_16x16x32_bf16 v[24:27], v[170:173], v[166:169], v[24:27]
	s_waitcnt lgkmcnt(1)
	v_mfma_f32_16x16x32_bf16 v[8:11], v[150:153], v[166:169], v[8:11]
	v_mfma_f32_16x16x32_bf16 v[88:91], v[100:103], v[166:169], v[88:91]
	v_mfma_f32_16x16x32_bf16 v[96:99], v[112:115], v[166:169], v[96:99]
	s_waitcnt vmcnt(2)
	ds_write_b128 v2, v[116:119] offset:53248
	v_mfma_f32_16x16x32_bf16 v[28:31], v[170:173], v[62:65], v[28:31]
	v_mfma_f32_16x16x32_bf16 v[40:43], v[100:103], v[62:65], v[42:45]
	v_mfma_f32_16x16x32_bf16 v[12:15], v[150:153], v[62:65], v[12:15]
	v_mfma_f32_16x16x32_bf16 v[92:95], v[112:115], v[62:65], v[92:95]
	s_waitcnt vmcnt(1)
	ds_write_b128 v2, v[84:87] offset:57344
	v_mfma_f32_16x16x32_bf16 v[32:35], v[170:173], v[108:111], v[32:35]
	v_mfma_f32_16x16x32_bf16 v[44:47], v[100:103], v[108:111], v[46:49]
	v_mfma_f32_16x16x32_bf16 v[58:61], v[112:115], v[108:111], v[58:61]
	v_mfma_f32_16x16x32_bf16 v[16:19], v[150:153], v[108:111], v[16:19]
	s_waitcnt vmcnt(0)
	ds_write_b128 v2, v[104:107] offset:61440
	v_mfma_f32_16x16x32_bf16 v[36:39], v[170:173], v[146:149], v[36:39]
	v_mfma_f32_16x16x32_bf16 v[48:51], v[100:103], v[146:149], v[50:53]
	v_mfma_f32_16x16x32_bf16 v[52:55], v[112:115], v[146:149], v[54:57]
	v_mfma_f32_16x16x32_bf16 v[20:23], v[150:153], v[146:149], v[20:23]
	s_setprio 0
	s_waitcnt lgkmcnt(0)
	s_barrier
	ds_read_b128 v[62:65], v6 offset:32768
	ds_read_b128 v[84:87], v6 offset:34816
	ds_read_b128 v[100:103], v7 offset:49152
	ds_read_b128 v[104:107], v7 offset:51200
	ds_read_b128 v[108:111], v6 offset:36864
	ds_read_b128 v[112:115], v6 offset:38912
	ds_read_b128 v[116:119], v7 offset:53248
	ds_read_b128 v[120:123], v7 offset:55296
	s_setprio 2
	ds_read_b128 v[124:127], v3 offset:32768
	ds_read_b128 v[132:135], v4 offset:49152
	s_waitcnt lgkmcnt(7)
	v_mfma_f32_16x16x32_bf16 v[24:27], v[100:103], v[62:65], v[24:27]
	s_waitcnt lgkmcnt(2)
	v_mfma_f32_16x16x32_bf16 v[6:9], v[120:123], v[62:65], v[8:11]
	v_mfma_f32_16x16x32_bf16 v[88:91], v[104:107], v[62:65], v[88:91]
	v_mfma_f32_16x16x32_bf16 v[96:99], v[116:119], v[62:65], v[96:99]
	ds_read_b128 v[146:149], v3 offset:34816
	ds_read_b128 v[150:153], v4 offset:51200
	v_mfma_f32_16x16x32_bf16 v[28:31], v[100:103], v[84:87], v[28:31]
	v_mfma_f32_16x16x32_bf16 v[40:43], v[104:107], v[84:87], v[40:43]
	v_mfma_f32_16x16x32_bf16 v[10:13], v[120:123], v[84:87], v[12:15]
	v_mfma_f32_16x16x32_bf16 v[92:95], v[116:119], v[84:87], v[92:95]
	ds_read_b128 v[84:87], v3 offset:36864
	ds_read_b128 v[154:157], v4 offset:53248
	v_mfma_f32_16x16x32_bf16 v[14:17], v[120:123], v[108:111], v[16:19]
	v_mfma_f32_16x16x32_bf16 v[158:161], v[100:103], v[108:111], v[32:35]
	v_mfma_f32_16x16x32_bf16 v[162:165], v[104:107], v[108:111], v[44:47]
	v_mfma_f32_16x16x32_bf16 v[166:169], v[116:119], v[108:111], v[58:61]
	ds_read_b128 v[108:111], v3 offset:38912
	ds_read_b128 v[2:5], v4 offset:55296
	v_mfma_f32_16x16x32_bf16 v[100:103], v[100:103], v[112:115], v[36:39]
	v_mfma_f32_16x16x32_bf16 v[104:107], v[104:107], v[112:115], v[48:51]
	v_mfma_f32_16x16x32_bf16 v[116:119], v[116:119], v[112:115], v[52:55]
	v_mfma_f32_16x16x32_bf16 v[112:115], v[120:123], v[112:115], v[20:23]
	s_waitcnt lgkmcnt(6)
	v_mfma_f32_16x16x32_bf16 v[62:65], v[132:135], v[124:127], v[24:27]
	s_waitcnt lgkmcnt(4)
	v_mfma_f32_16x16x32_bf16 v[58:61], v[150:153], v[124:127], v[88:91]
	s_waitcnt lgkmcnt(2)
	v_mfma_f32_16x16x32_bf16 v[54:57], v[154:157], v[124:127], v[96:99]
	s_waitcnt lgkmcnt(0)
	v_mfma_f32_16x16x32_bf16 v[50:53], v[2:5], v[124:127], v[6:9]
	v_mfma_f32_16x16x32_bf16 v[46:49], v[132:135], v[146:149], v[28:31]
	v_mfma_f32_16x16x32_bf16 v[42:45], v[150:153], v[146:149], v[40:43]
	v_mfma_f32_16x16x32_bf16 v[38:41], v[154:157], v[146:149], v[92:95]
	v_mfma_f32_16x16x32_bf16 v[34:37], v[2:5], v[146:149], v[10:13]
	v_mfma_f32_16x16x32_bf16 v[30:33], v[132:135], v[84:87], v[158:161]
	v_mfma_f32_16x16x32_bf16 v[26:29], v[150:153], v[84:87], v[162:165]
	v_mfma_f32_16x16x32_bf16 v[22:25], v[154:157], v[84:87], v[166:169]
	v_mfma_f32_16x16x32_bf16 v[18:21], v[2:5], v[84:87], v[14:17]
	v_mfma_f32_16x16x32_bf16 v[14:17], v[132:135], v[108:111], v[100:103]
	v_mfma_f32_16x16x32_bf16 v[10:13], v[150:153], v[108:111], v[104:107]
	v_mfma_f32_16x16x32_bf16 v[6:9], v[154:157], v[108:111], v[116:119]
	v_mfma_f32_16x16x32_bf16 v[2:5], v[2:5], v[108:111], v[112:115]
	s_setprio 0
	s_and_b32 s1, s0, -8
	s_cmp_lg_u32 s1, 16
	s_barrier
; template <int MODE>
; __device__ __forceinline__ void gemm_tile(const Params& P, int tm, int tn, unsigned char* smem) {
;     ...
;         if (n0 >= ZC_FQ && n0 < ZC_FV) {
;             const bool isk = n0 >= ZC_FK;
;             const float* gain = isk ? P.f_k_norm : P.f_q_norm;
;             const float scl = isk ? 1.0f : 0.125f * LOG2E;
;             float gn[4][4];
; #pragma unroll
;             for (int j = 0; j < 4; ++j)
; #pragma unroll
;                 for (int r = 0; r < 4; ++r) gn[j][r] = gain[16 * j + 4 * g + r];
; #pragma unroll
;             for (int i = 0; i < 4; ++i) {
;                 float ss = 0.f;
; #pragma unroll
;                 for (int j = 0; j < 4; ++j)
; #pragma unroll
;                     for (int r = 0; r < 4; ++r) ss += acc[i][j][r] * acc[i][j][r];
;                 ss = x4_sum(ss);
;                 const float rstd = rsqrtf(ss * (1.0f / 64.0f) + EPS) * scl;
	s_cbranch_scc1 .LBB0_181
	v_mul_f32_e32 v66, v63, v63
	v_fmac_f32_e32 v66, v62, v62
	v_fmac_f32_e32 v66, v64, v64
	v_fmac_f32_e32 v66, v65, v65
	v_fmac_f32_e32 v66, v58, v58
	v_fmac_f32_e32 v66, v59, v59
	v_fmac_f32_e32 v66, v60, v60
	v_fmac_f32_e32 v66, v61, v61
	v_fmac_f32_e32 v66, v54, v54
	v_fmac_f32_e32 v66, v55, v55
	v_fmac_f32_e32 v66, v56, v56
	v_fmac_f32_e32 v66, v57, v57
	v_pk_mul_f32 v[84:85], v[50:51], v[50:51]
	v_pk_mul_f32 v[68:69], v[52:53], v[52:53]
	v_add_f32_e32 v66, v84, v66
	v_add_f32_e32 v66, v85, v66
	v_add_f32_e32 v66, v68, v66
	v_add_f32_e32 v66, v69, v66
	v_mov_b32_e32 v68, v66
	s_nop 1
	v_permlane32_swap_b32_e32 v66, v68
	v_add_f32_e32 v69, v66, v68
	v_mul_f32_e32 v66, v47, v47
	v_fmac_f32_e32 v66, v46, v46
	v_fmac_f32_e32 v66, v48, v48
	v_fmac_f32_e32 v66, v49, v49
	v_fmac_f32_e32 v66, v42, v42
	v_fmac_f32_e32 v66, v43, v43
	v_fmac_f32_e32 v66, v44, v44
	v_fmac_f32_e32 v66, v45, v45
	v_fmac_f32_e32 v66, v38, v38
	v_fmac_f32_e32 v66, v39, v39
	v_fmac_f32_e32 v66, v40, v40
	v_fmac_f32_e32 v66, v41, v41
	v_pk_mul_f32 v[88:89], v[34:35], v[34:35]
	v_pk_mul_f32 v[86:87], v[36:37], v[36:37]
	v_add_f32_e32 v66, v88, v66
	v_add_f32_e32 v66, v89, v66
	v_add_f32_e32 v66, v86, v66
	v_add_f32_e32 v66, v87, v66
	v_mov_b32_e32 v68, v66
	s_nop 1
	v_permlane32_swap_b32_e32 v66, v68
	v_add_f32_e32 v68, v66, v68
	v_mov_b32_e32 v85, v69
	v_mov_b32_e32 v84, v68
	s_nop 0
	v_permlane16_swap_b32_e32 v69, v85
	v_permlane16_swap_b32_e32 v68, v84
	v_pk_add_f32 v[84:85], v[68:69], v[84:85]
	v_mov_b64_e32 v[68:69], s[8:9]
	v_mul_f32_e32 v97, v31, v31
	s_cmp_gt_u32 s0, 19
	v_pk_fma_f32 v[88:89], v[84:85], s[6:7], v[68:69] op_sel_hi:[1,0,0]
	v_fmac_f32_e32 v97, v30, v30
	s_cselect_b64 s[0:1], -1, 0
	v_mul_f32_e32 v66, 0x4b800000, v89
	v_cmp_gt_f32_e32 vcc, s21, v89
	v_fmac_f32_e32 v97, v32, v32
	v_cndmask_b32_e64 v108, v78, 1.0, s[0:1]
	s_and_b64 s[0:1], s[0:1], exec
	v_cndmask_b32_e32 v66, v89, v66, vcc
	v_fmac_f32_e32 v97, v33, v33
	v_rsq_f32_e32 v66, v66
	v_mul_f32_e32 v70, 0x4b800000, v88
	v_cmp_gt_f32_e64 s[0:1], s21, v88
	v_fmac_f32_e32 v97, v26, v26
	v_fmac_f32_e32 v97, v27, v27
	v_cndmask_b32_e64 v70, v88, v70, s[0:1]
	v_rsq_f32_e32 v88, v70
	v_fmac_f32_e32 v97, v28, v28
	s_cselect_b32 s13, s41, s39
	s_cselect_b32 s12, s40, s38
	v_lshlrev_b32_e32 v96, 4, v83
	v_fmac_f32_e32 v97, v29, v29
	global_load_dwordx4 v[84:87], v96, s[12:13]
	v_mul_f32_e32 v70, 0x45800000, v66
	v_fmac_f32_e32 v97, v22, v22
	v_cndmask_b32_e32 v66, v66, v70, vcc
	v_fmac_f32_e32 v97, v23, v23
	v_mul_f32_e32 v70, v108, v66
	v_mul_f32_e32 v66, 0x45800000, v88
	v_fmac_f32_e32 v97, v24, v24
	v_cndmask_b32_e64 v66, v88, v66, s[0:1]
	global_load_dwordx4 v[88:91], v96, s[12:13] offset:64
	v_fmac_f32_e32 v97, v25, v25
	v_pk_mul_f32 v[94:95], v[18:19], v[18:19]
	v_pk_mul_f32 v[92:93], v[20:21], v[20:21]
	v_add_f32_e32 v94, v94, v97
	v_add_f32_e32 v94, v95, v94
	v_add_f32_e32 v92, v92, v94
	v_add_f32_e32 v97, v93, v92
	global_load_dwordx4 v[92:95], v96, s[12:13] offset:128
	v_mov_b32_e32 v98, v97
	s_nop 1
	v_permlane32_swap_b32_e32 v97, v98
	v_add_f32_e32 v101, v97, v98
	global_load_dwordx4 v[96:99], v96, s[12:13] offset:192
	v_mul_f32_e32 v100, v15, v15
	v_fmac_f32_e32 v100, v14, v14
	v_fmac_f32_e32 v100, v16, v16
	v_fmac_f32_e32 v100, v17, v17
	v_fmac_f32_e32 v100, v10, v10
	v_fmac_f32_e32 v100, v11, v11
	v_fmac_f32_e32 v100, v12, v12
	v_fmac_f32_e32 v100, v13, v13
	v_fmac_f32_e32 v100, v6, v6
	v_fmac_f32_e32 v100, v7, v7
	v_fmac_f32_e32 v100, v8, v8
	v_fmac_f32_e32 v100, v9, v9
	v_pk_mul_f32 v[106:107], v[2:3], v[2:3]
	v_pk_mul_f32 v[104:105], v[4:5], v[4:5]
	v_add_f32_e32 v100, v106, v100
	v_add_f32_e32 v100, v107, v100
	v_add_f32_e32 v100, v104, v100
	v_add_f32_e32 v100, v105, v100
	v_mov_b32_e32 v102, v100
	s_nop 1
	v_permlane32_swap_b32_e32 v100, v102
	v_add_f32_e32 v100, v100, v102
	v_mov_b32_e32 v103, v101
	v_mov_b32_e32 v102, v100
	s_nop 0
	v_permlane16_swap_b32_e32 v101, v103
	v_permlane16_swap_b32_e32 v100, v102
	v_pk_add_f32 v[100:101], v[100:101], v[102:103]
	v_mul_f32_e32 v66, v108, v66
	v_pk_fma_f32 v[68:69], v[100:101], s[6:7], v[68:69] op_sel_hi:[1,0,0]
	s_waitcnt vmcnt(3)
; template <int MODE>
; __device__ __forceinline__ void gemm_tile(const Params& P, int tm, int tn, unsigned char* smem) {
;     ...
; #pragma unroll
;                 for (int j = 0; j < 4; ++j)
; #pragma unroll
;                     for (int r = 0; r < 4; ++r) acc[i][j][r] *= rstd * gn[j][r];
;             }
	v_pk_mul_f32 v[102:103], v[84:85], v[70:71] op_sel_hi:[1,0]
	v_mul_f32_e32 v100, 0x4b800000, v69
	v_cmp_gt_f32_e32 vcc, s21, v69
	v_cmp_gt_f32_e64 s[0:1], s21, v68
	v_pk_mul_f32 v[62:63], v[62:63], v[102:103]
	v_cndmask_b32_e32 v69, v69, v100, vcc
	v_mul_f32_e32 v100, 0x4b800000, v68
	v_rsq_f32_e32 v69, v69
	v_cndmask_b32_e64 v68, v68, v100, s[0:1]
	v_rsq_f32_e32 v100, v68
	v_pk_mul_f32 v[102:103], v[84:85], v[66:67] op_sel_hi:[1,0]
	v_mul_f32_e32 v68, 0x45800000, v69
	v_cndmask_b32_e32 v68, v69, v68, vcc
	v_mul_f32_e32 v69, 0x45800000, v100
	v_cndmask_b32_e64 v69, v100, v69, s[0:1]
	v_mul_f32_e32 v68, v108, v68
	v_mul_f32_e32 v100, v108, v69
	v_pk_mul_f32 v[104:105], v[86:87], v[70:71] op_sel_hi:[1,0]
	v_pk_mul_f32 v[46:47], v[46:47], v[102:103]
	v_pk_mul_f32 v[102:103], v[84:85], v[68:69] op_sel_hi:[1,0]
	v_pk_mul_f32 v[84:85], v[84:85], v[100:101] op_sel_hi:[1,0]
	v_pk_mul_f32 v[64:65], v[64:65], v[104:105]
	v_pk_mul_f32 v[104:105], v[86:87], v[66:67] op_sel_hi:[1,0]
	v_pk_mul_f32 v[14:15], v[14:15], v[84:85]
	s_waitcnt vmcnt(2)
	v_pk_mul_f32 v[84:85], v[88:89], v[70:71] op_sel_hi:[1,0]
	v_pk_mul_f32 v[48:49], v[48:49], v[104:105]
	v_pk_mul_f32 v[104:105], v[86:87], v[68:69] op_sel_hi:[1,0]
	v_pk_mul_f32 v[86:87], v[86:87], v[100:101] op_sel_hi:[1,0]
	v_pk_mul_f32 v[58:59], v[58:59], v[84:85]
	v_pk_mul_f32 v[84:85], v[88:89], v[66:67] op_sel_hi:[1,0]
	v_pk_mul_f32 v[16:17], v[16:17], v[86:87]
	v_pk_mul_f32 v[86:87], v[90:91], v[70:71] op_sel_hi:[1,0]
	v_pk_mul_f32 v[42:43], v[42:43], v[84:85]
	v_pk_mul_f32 v[84:85], v[88:89], v[68:69] op_sel_hi:[1,0]
	v_pk_mul_f32 v[60:61], v[60:61], v[86:87]
	v_pk_mul_f32 v[86:87], v[90:91], v[66:67] op_sel_hi:[1,0]
	v_pk_mul_f32 v[26:27], v[26:27], v[84:85]
	v_pk_mul_f32 v[84:85], v[88:89], v[100:101] op_sel_hi:[1,0]
	v_pk_mul_f32 v[44:45], v[44:45], v[86:87]
	v_pk_mul_f32 v[86:87], v[90:91], v[68:69] op_sel_hi:[1,0]
	v_pk_mul_f32 v[10:11], v[10:11], v[84:85]
	s_waitcnt vmcnt(1)
	v_pk_mul_f32 v[84:85], v[92:93], v[70:71] op_sel_hi:[1,0]
	v_pk_mul_f32 v[28:29], v[28:29], v[86:87]
	v_pk_mul_f32 v[86:87], v[90:91], v[100:101] op_sel_hi:[1,0]
	v_pk_mul_f32 v[54:55], v[54:55], v[84:85]
	v_pk_mul_f32 v[84:85], v[92:93], v[66:67] op_sel_hi:[1,0]
	v_pk_mul_f32 v[12:13], v[12:13], v[86:87]
	v_pk_mul_f32 v[86:87], v[94:95], v[70:71] op_sel_hi:[1,0]
	v_pk_mul_f32 v[38:39], v[38:39], v[84:85]
	v_pk_mul_f32 v[84:85], v[92:93], v[68:69] op_sel_hi:[1,0]
	v_pk_mul_f32 v[56:57], v[56:57], v[86:87]
	v_pk_mul_f32 v[86:87], v[94:95], v[66:67] op_sel_hi:[1,0]
	v_pk_mul_f32 v[22:23], v[22:23], v[84:85]
	v_pk_mul_f32 v[84:85], v[92:93], v[100:101] op_sel_hi:[1,0]
	v_pk_mul_f32 v[40:41], v[40:41], v[86:87]
	v_pk_mul_f32 v[86:87], v[94:95], v[68:69] op_sel_hi:[1,0]
	v_pk_mul_f32 v[6:7], v[6:7], v[84:85]
	s_waitcnt vmcnt(0)
	v_pk_mul_f32 v[84:85], v[96:97], v[70:71] op_sel_hi:[1,0]
	v_pk_mul_f32 v[24:25], v[24:25], v[86:87]
	v_pk_mul_f32 v[86:87], v[94:95], v[100:101] op_sel_hi:[1,0]
	v_pk_mul_f32 v[50:51], v[50:51], v[84:85]
	v_pk_mul_f32 v[84:85], v[96:97], v[66:67] op_sel_hi:[1,0]
	v_pk_mul_f32 v[8:9], v[8:9], v[86:87]
	v_pk_mul_f32 v[86:87], v[98:99], v[70:71] op_sel_hi:[1,0]
	v_pk_mul_f32 v[34:35], v[34:35], v[84:85]
	v_pk_mul_f32 v[84:85], v[96:97], v[68:69] op_sel_hi:[1,0]
	v_pk_mul_f32 v[68:69], v[98:99], v[68:69] op_sel_hi:[1,0]
	v_pk_mul_f32 v[52:53], v[52:53], v[86:87]
	v_pk_mul_f32 v[86:87], v[98:99], v[66:67] op_sel_hi:[1,0]
	v_pk_mul_f32 v[20:21], v[20:21], v[68:69]
	v_pk_mul_f32 v[18:19], v[18:19], v[84:85]
	v_pk_mul_f32 v[68:69], v[96:97], v[100:101] op_sel_hi:[1,0]
	v_pk_mul_f32 v[84:85], v[98:99], v[100:101] op_sel_hi:[1,0]
	v_pk_mul_f32 v[32:33], v[32:33], v[104:105]
	v_pk_mul_f32 v[30:31], v[30:31], v[102:103]
	v_pk_mul_f32 v[36:37], v[36:37], v[86:87]
	v_pk_mul_f32 v[4:5], v[4:5], v[84:85]
	v_pk_mul_f32 v[2:3], v[2:3], v[68:69]
	s_branch .LBB0_181

; template <int MODE>
; __device__ __forceinline__ void gemm_tile(const Params& P, int tm, int tn, unsigned char* smem) {
;     ...
;     unsigned char* sA0 = smem; unsigned char* sB0 = smem + 16384; unsigned char* sA1 = smem + 32768; unsigned char* sB1 = smem + 49152;
;     G_LOAD(0)
;     G_WRITE(sA0, sB0)
;     __syncthreads();
;     const int arow_off = (wr * 64 + lr) * 128, brow_off = (wc * 64 + lr) * 128, sw = lr & 7;
;     G_LOAD(1)
;     for (int kt = 0; kt < 16; ++kt) {
;         unsigned char* sA = (kt & 1) ? sA1 : sA0; unsigned char* sB = (kt & 1) ? sB1 : sB0;
;         unsigned char* nA = (kt & 1) ? sA0 : sA1; unsigned char* nB = (kt & 1) ? sB0 : sB1;
;         bf16x8 fa[4], fb[4], ga[4], gb[4];
;         const int ch0 = ((g ^ sw) << 4), ch1 = (((4 + g) ^ sw) << 4);
;         const unsigned ko = (unsigned)(kt + 2) * 128u;
;         const unsigned koa = ko + ((MODE == 2 && kt + 2 >= 8) ? (unsigned)(ZC_FQ - 512) * 2u : 0u);
;         const bool wr_ok = kt < 15, ld_ok = kt < 14;
; #pragma unroll
;         for (int i = 0; i < 4; ++i) { fa[i] = *(const bf16x8*)(sA + arow_off + i * 2048 + ch0); fb[i] = *(const bf16x8*)(sB + brow_off + i * 2048 + ch0); }
;         __builtin_amdgcn_sched_barrier(0);
;         __builtin_amdgcn_s_setprio(2);
;         if (wr_ok) *(uint4*)(nA + soff0) = ra0;
;         if (ld_ok) ra0 = *(const uint4*)(Ab + (aoff + 0u * LDA + koa));
;         ga[0] = *(const bf16x8*)(sA + arow_off + 0 * 2048 + ch1); gb[0] = *(const bf16x8*)(sB + brow_off + 0 * 2048 + ch1);
;         __builtin_amdgcn_sched_barrier(0);
; #pragma unroll
;         for (int j = 0; j < 4; ++j) acc[0][j] = __builtin_amdgcn_mfma_f32_16x16x32_bf16(fb[j], fa[0], acc[0][j], 0, 0, 0);
;         __builtin_amdgcn_sched_barrier(0);
;         if (wr_ok) *(uint4*)(nA + soff0 + 4096) = ra1;
;         if (ld_ok) ra1 = *(const uint4*)(Ab + (aoff + 32u * LDA + koa));
;         ga[1] = *(const bf16x8*)(sA + arow_off + 1 * 2048 + ch1); gb[1] = *(const bf16x8*)(sB + brow_off + 1 * 2048 + ch1);
;         __builtin_amdgcn_sched_barrier(0);
; #pragma unroll
;         for (int j = 0; j < 4; ++j) acc[1][j] = __builtin_amdgcn_mfma_f32_16x16x32_bf16(fb[j], fa[1], acc[1][j], 0, 0, 0);
;         __builtin_amdgcn_sched_barrier(0);
;         if (wr_ok) *(uint4*)(nA + soff0 + 8192) = ra2;
;         if (ld_ok) ra2 = *(const uint4*)(Ab + (aoff + 64u * LDA + koa));
.LBB0_221:
	s_add_i32 s0, s14, s3
	s_mul_hi_i32 s1, s0, 0x92492493
	s_add_i32 s1, s1, s0
	s_lshr_b32 s6, s1, 31
	s_ashr_i32 s1, s1, 7
	s_add_i32 s1, s1, s6
	s_mul_i32 s6, s1, 0xffffff20
	s_lshl_b32 s1, s1, 3
	s_add_i32 s6, s6, s0
	s_sub_i32 s7, 0x81, s1
	s_cmpk_gt_i32 s0, 0xdff
	s_cselect_b32 s0, s7, 8
	s_abs_i32 s7, s0
	v_cvt_f32_u32_e32 v2, s7
	s_sub_i32 s10, 0, s7
	s_abs_i32 s8, s6
	s_xor_b32 s9, s6, s0
	v_rcp_iflag_f32_e32 v2, v2
	s_ashr_i32 s9, s9, 31
	v_mov_b32_e32 v69, v0
	v_mul_f32_e32 v2, 0x4f7ffffe, v2
	v_cvt_u32_f32_e32 v2, v2
	v_lshlrev_b32_e32 v3, 4, v69
	v_and_b32_e32 v5, 0x70, v3
	v_and_b32_e32 v78, 15, v69
	v_readfirstlane_b32 s11, v2
	s_mul_i32 s10, s10, s11
	s_mul_hi_u32 s10, s11, s10
	s_add_i32 s11, s11, s10
	s_mul_hi_u32 s10, s8, s11
	s_mul_i32 s11, s10, s7
	s_sub_i32 s8, s8, s11
	s_add_i32 s12, s10, 1
	s_sub_i32 s11, s8, s7
	s_cmp_ge_u32 s8, s7
	s_cselect_b32 s10, s12, s10
	s_cselect_b32 s8, s11, s8
	s_add_i32 s11, s10, 1
	s_cmp_ge_u32 s8, s7
	s_cselect_b32 s7, s11, s10
	s_xor_b32 s7, s7, s9
	s_sub_i32 s7, s7, s9
	s_mul_i32 s0, s7, s0
	s_add_i32 s6, s6, s1
	s_sub_i32 s0, s6, s0
	s_lshl_b32 s11, s0, 7
	v_ashrrev_i32_e32 v2, 3, v69
	s_lshl_b32 s6, s7, 7
	v_add_u32_e32 v4, s11, v2
	v_add_u32_e32 v3, s6, v2
	v_lshl_or_b32 v8, v4, 11, v5
	v_lshl_or_b32 v3, v3, 11, v5
	s_add_u32 s0, s28, 0xc075800
	v_add_u32_e32 v9, 0x10000, v8
	s_addc_u32 s1, s29, 0
	v_add_u32_e32 v22, 0x20000, v8
	global_load_dwordx4 v[4:7], v9, s[36:37]
	global_load_dwordx4 v[10:13], v22, s[36:37]
	global_load_dwordx4 v[14:17], v8, s[36:37]
	global_load_dwordx4 v[18:21], v3, s[0:1]
	v_add_u32_e32 v9, 0x20000, v3
	v_add_u32_e32 v30, 0x30000, v3
	global_load_dwordx4 v[22:25], v9, s[0:1]
	global_load_dwordx4 v[26:29], v30, s[0:1]
	v_add_u32_e32 v9, 0x30000, v8
	v_add_u32_e32 v38, 0x10000, v3
	global_load_dwordx4 v[30:33], v9, s[36:37]
	global_load_dwordx4 v[34:37], v38, s[0:1]
	v_xor_b32_e32 v9, v2, v69
	s_movk_i32 s8, 0x70
	v_lshlrev_b32_e32 v2, 7, v2
	v_lshlrev_b32_e32 v9, 4, v9
	v_and_or_b32 v2, v9, s8, v2
	v_add_u32_e32 v2, 0, v2
	v_or_b32_e32 v45, 0x80, v8
	v_or_b32_e32 v9, 0x80, v3
	v_add_u32_e32 v42, 0x10080, v3
	v_add_u32_e32 v43, 0x20080, v3
	v_add_u32_e32 v44, 0x30080, v3
	v_add_u32_e32 v46, 0x10080, v8
	v_add_u32_e32 v47, 0x20080, v8
	v_add_u32_e32 v48, 0x30080, v8
	v_ashrrev_i32_e32 v79, 7, v69
	v_bfe_u32 v80, v69, 6, 1
	v_bfe_u32 v81, v69, 4, 2
	s_waitcnt vmcnt(5)
	ds_write_b128 v2, v[14:17]
	s_waitcnt vmcnt(4)
	ds_write_b128 v2, v[18:21] offset:16384
	s_waitcnt vmcnt(3)
	ds_write_b128 v2, v[22:25] offset:24576
	s_waitcnt vmcnt(2)
	ds_write_b128 v2, v[26:29] offset:28672
	ds_write_b128 v2, v[4:7] offset:4096
	ds_write_b128 v2, v[10:13] offset:8192
	s_waitcnt vmcnt(1)
	ds_write_b128 v2, v[30:33] offset:12288
	s_waitcnt vmcnt(0)
	ds_write_b128 v2, v[34:37] offset:20480
	s_waitcnt lgkmcnt(0)
	s_barrier
	global_load_dwordx4 v[10:13], v45, s[36:37]
	global_load_dwordx4 v[14:17], v46, s[36:37]
	global_load_dwordx4 v[18:21], v47, s[36:37]
	global_load_dwordx4 v[22:25], v48, s[36:37]
	global_load_dwordx4 v[26:29], v9, s[0:1]
	global_load_dwordx4 v[30:33], v42, s[0:1]
	global_load_dwordx4 v[34:37], v43, s[0:1]
	global_load_dwordx4 v[38:41], v44, s[0:1]
	v_lshrrev_b32_e32 v4, 4, v69
	v_lshlrev_b32_e32 v5, 7, v78
	v_and_b32_e32 v9, 7, v69
	v_lshl_or_b32 v6, v79, 13, v5
	v_bitop3_b32 v4, v4, v9, 3 bitop3:0x6c
	v_lshl_or_b32 v5, v80, 13, v5
	v_lshlrev_b32_e32 v4, 4, v4
	v_add_u32_e32 v66, 0, v6
	v_add_u32_e32 v6, v66, v4
	v_add_u32_e32 v5, 0, v5
	v_add_u32_e32 v7, v5, v4
	ds_read_b128 v[42:45], v6
	ds_read_b128 v[46:49], v6 offset:2048
	ds_read_b128 v[50:53], v7 offset:16384
	ds_read_b128 v[54:57], v7 offset:18432
	ds_read_b128 v[58:61], v6 offset:4096
	ds_read_b128 v[62:65], v6 offset:6144
	ds_read_b128 v[82:85], v7 offset:20480
	ds_read_b128 v[86:89], v7 offset:22528
	v_bitop3_b32 v4, v81, v9, 4 bitop3:0x36
	v_lshlrev_b32_e32 v9, 4, v4
	s_setprio 2
	global_load_dwordx4 v[90:93], v8, s[36:37] offset:256
	s_waitcnt vmcnt(7)
	ds_write_b128 v2, v[10:13] offset:32768
	v_add_u32_e32 v4, v66, v9
	v_add_u32_e32 v5, v5, v9
	ds_read_b128 v[10:13], v4
	ds_read_b128 v[94:97], v5 offset:16384
	s_waitcnt lgkmcnt(8)
	v_mfma_f32_16x16x32_bf16 v[98:101], v[50:53], v[42:45], 0
	s_waitcnt lgkmcnt(7)
	v_mfma_f32_16x16x32_bf16 v[102:105], v[54:57], v[42:45], 0
	s_waitcnt lgkmcnt(4)
	v_mfma_f32_16x16x32_bf16 v[106:109], v[82:85], v[42:45], 0
	s_waitcnt lgkmcnt(3)
	v_mfma_f32_16x16x32_bf16 v[42:45], v[86:89], v[42:45], 0
	v_add_u32_e32 v222, 0x10000, v8
	global_load_dwordx4 v[110:113], v222, s[36:37] offset:256
	ds_write_b128 v2, v[14:17] offset:36864
	ds_read_b128 v[14:17], v4 offset:2048
	ds_read_b128 v[114:117], v5 offset:18432
	v_mfma_f32_16x16x32_bf16 v[118:121], v[50:53], v[46:49], 0
	v_mfma_f32_16x16x32_bf16 v[122:125], v[54:57], v[46:49], 0
	v_mfma_f32_16x16x32_bf16 v[126:129], v[82:85], v[46:49], 0
	v_mfma_f32_16x16x32_bf16 v[46:49], v[86:89], v[46:49], 0
	v_add_u32_e32 v223, 0x20000, v8
	global_load_dwordx4 v[132:135], v223, s[36:37] offset:256
	s_waitcnt vmcnt(7)
	ds_write_b128 v2, v[18:21] offset:40960
	ds_read_b128 v[18:21], v4 offset:4096
	ds_read_b128 v[146:149], v5 offset:20480
	v_mfma_f32_16x16x32_bf16 v[150:153], v[50:53], v[58:61], 0
	v_mfma_f32_16x16x32_bf16 v[154:157], v[54:57], v[58:61], 0
	v_mfma_f32_16x16x32_bf16 v[158:161], v[82:85], v[58:61], 0
	v_mfma_f32_16x16x32_bf16 v[58:61], v[86:89], v[58:61], 0
	v_add_u32_e32 v224, 0x30000, v8
	global_load_dwordx4 v[162:165], v224, s[36:37] offset:256
	ds_write_b128 v2, v[22:25] offset:45056
	ds_read_b128 v[22:25], v4 offset:6144
	ds_read_b128 v[166:169], v5 offset:22528
	v_mfma_f32_16x16x32_bf16 v[50:53], v[50:53], v[62:65], 0
	v_mfma_f32_16x16x32_bf16 v[54:57], v[54:57], v[62:65], 0
	v_mfma_f32_16x16x32_bf16 v[82:85], v[82:85], v[62:65], 0
	v_mfma_f32_16x16x32_bf16 v[62:65], v[86:89], v[62:65], 0
	global_load_dwordx4 v[86:89], v3, s[0:1] offset:256
	s_waitcnt vmcnt(7)
; template <int MODE>
; __device__ __forceinline__ void gemm_tile(const Params& P, int tm, int tn, unsigned char* smem) {
;     ...
; #pragma unroll
;         for (int i = 0; i < 4; ++i) { fa[i] = *(const bf16x8*)(sA + arow_off + i * 2048 + ch0); fb[i] = *(const bf16x8*)(sB + brow_off + i * 2048 + ch0); }
;         __builtin_amdgcn_sched_barrier(0);
;         __builtin_amdgcn_s_setprio(2);
;         if (wr_ok) *(uint4*)(nA + soff0) = ra0;
;         if (ld_ok) ra0 = *(const uint4*)(Ab + (aoff + 0u * LDA + koa));
;         ga[0] = *(const bf16x8*)(sA + arow_off + 0 * 2048 + ch1); gb[0] = *(const bf16x8*)(sB + brow_off + 0 * 2048 + ch1);
;         __builtin_amdgcn_sched_barrier(0);
; #pragma unroll
;         for (int j = 0; j < 4; ++j) acc[0][j] = __builtin_amdgcn_mfma_f32_16x16x32_bf16(fb[j], fa[0], acc[0][j], 0, 0, 0);
;         __builtin_amdgcn_sched_barrier(0);
;         if (wr_ok) *(uint4*)(nA + soff0 + 4096) = ra1;
;         if (ld_ok) ra1 = *(const uint4*)(Ab + (aoff + 32u * LDA + koa));
;         ga[1] = *(const bf16x8*)(sA + arow_off + 1 * 2048 + ch1); gb[1] = *(const bf16x8*)(sB + brow_off + 1 * 2048 + ch1);
;         __builtin_amdgcn_sched_barrier(0);
; #pragma unroll
;         for (int j = 0; j < 4; ++j) acc[1][j] = __builtin_amdgcn_mfma_f32_16x16x32_bf16(fb[j], fa[1], acc[1][j], 0, 0, 0);
;         __builtin_amdgcn_sched_barrier(0);
;         if (wr_ok) *(uint4*)(nA + soff0 + 8192) = ra2;
;         if (ld_ok) ra2 = *(const uint4*)(Ab + (aoff + 64u * LDA + koa));
;         ga[2] = *(const bf16x8*)(sA + arow_off + 2 * 2048 + ch1); gb[2] = *(const bf16x8*)(sB + brow_off + 2 * 2048 + ch1);
;         __builtin_amdgcn_sched_barrier(0);
; #pragma unroll
;         for (int j = 0; j < 4; ++j) acc[2][j] = __builtin_amdgcn_mfma_f32_16x16x32_bf16(fb[j], fa[2], acc[2][j], 0, 0, 0);
;         __builtin_amdgcn_sched_barrier(0);
;         if (wr_ok) *(uint4*)(nA + soff0 + 12288) = ra3;
;         if (ld_ok) ra3 = *(const uint4*)(Ab + (aoff + 96u * LDA + koa));
;         ga[3] = *(const bf16x8*)(sA + arow_off + 3 * 2048 + ch1); gb[3] = *(const bf16x8*)(sB + brow_off + 3 * 2048 + ch1);
;         __builtin_amdgcn_sched_barrier(0);
; #pragma unroll
;         for (int j = 0; j < 4; ++j) acc[3][j] = __builtin_amdgcn_mfma_f32_16x16x32_bf16(fb[j], fa[3], acc[3][j], 0, 0, 0);
;         __builtin_amdgcn_sched_barrier(0);
;         if (wr_ok) *(uint4*)(nB + soff0) = rb0;
	ds_write_b128 v2, v[26:29] offset:49152
	s_waitcnt lgkmcnt(10)
	v_mfma_f32_16x16x32_bf16 v[26:29], v[94:97], v[10:13], v[98:101]
	s_waitcnt lgkmcnt(7)
	v_mfma_f32_16x16x32_bf16 v[98:101], v[114:117], v[10:13], v[102:105]
	s_waitcnt lgkmcnt(4)
	v_mfma_f32_16x16x32_bf16 v[102:105], v[146:149], v[10:13], v[106:109]
	s_waitcnt lgkmcnt(1)
	v_mfma_f32_16x16x32_bf16 v[10:13], v[166:169], v[10:13], v[42:45]
	v_add_u32_e32 v225, 0x10000, v3
	global_load_dwordx4 v[42:45], v225, s[0:1] offset:256
	ds_write_b128 v2, v[30:33] offset:53248
	v_mfma_f32_16x16x32_bf16 v[30:33], v[94:97], v[14:17], v[118:121]
	v_mfma_f32_16x16x32_bf16 v[106:109], v[114:117], v[14:17], v[122:125]
	v_mfma_f32_16x16x32_bf16 v[118:121], v[146:149], v[14:17], v[126:129]
	v_mfma_f32_16x16x32_bf16 v[14:17], v[166:169], v[14:17], v[46:49]
	v_add_u32_e32 v226, 0x20000, v3
	global_load_dwordx4 v[46:49], v226, s[0:1] offset:256
	s_waitcnt vmcnt(7)
	ds_write_b128 v2, v[34:37] offset:57344
	v_mfma_f32_16x16x32_bf16 v[34:37], v[94:97], v[18:21], v[150:153]
	v_mfma_f32_16x16x32_bf16 v[122:125], v[114:117], v[18:21], v[154:157]
	v_mfma_f32_16x16x32_bf16 v[126:129], v[146:149], v[18:21], v[158:161]
	v_mfma_f32_16x16x32_bf16 v[18:21], v[166:169], v[18:21], v[58:61]
	v_add_u32_e32 v227, 0x30000, v3
	global_load_dwordx4 v[58:61], v227, s[0:1] offset:256
	ds_write_b128 v2, v[38:41] offset:61440
	v_mfma_f32_16x16x32_bf16 v[38:41], v[94:97], v[22:25], v[50:53]
	v_mfma_f32_16x16x32_bf16 v[50:53], v[114:117], v[22:25], v[54:57]
	v_mfma_f32_16x16x32_bf16 v[54:57], v[146:149], v[22:25], v[82:85]
	v_mfma_f32_16x16x32_bf16 v[22:25], v[166:169], v[22:25], v[62:65]
	s_setprio 0
	s_waitcnt lgkmcnt(0)
	s_barrier
	ds_read_b128 v[62:65], v6 offset:32768
	ds_read_b128 v[82:85], v6 offset:34816
	ds_read_b128 v[94:97], v7 offset:49152
	ds_read_b128 v[114:117], v7 offset:51200
	ds_read_b128 v[146:149], v6 offset:36864
	ds_read_b128 v[150:153], v6 offset:38912
	ds_read_b128 v[154:157], v7 offset:53248
	ds_read_b128 v[158:161], v7 offset:55296
	s_setprio 2
	global_load_dwordx4 v[166:169], v8, s[36:37] offset:384
	s_waitcnt vmcnt(7)
	ds_write_b128 v2, v[90:93]
	ds_read_b128 v[90:93], v4 offset:32768
	ds_read_b128 v[170:173], v5 offset:49152
	s_waitcnt lgkmcnt(8)
	v_mfma_f32_16x16x32_bf16 v[26:29], v[94:97], v[62:65], v[26:29]
	s_waitcnt lgkmcnt(3)
	v_mfma_f32_16x16x32_bf16 v[10:13], v[158:161], v[62:65], v[10:13]
	v_mfma_f32_16x16x32_bf16 v[98:101], v[114:117], v[62:65], v[98:101]
	v_mfma_f32_16x16x32_bf16 v[102:105], v[154:157], v[62:65], v[102:105]
	global_load_dwordx4 v[62:65], v222, s[36:37] offset:384
	ds_write_b128 v2, v[110:113] offset:4096
	ds_read_b128 v[110:113], v4 offset:34816
	ds_read_b128 v[174:177], v5 offset:51200
	v_mfma_f32_16x16x32_bf16 v[30:33], v[94:97], v[82:85], v[30:33]
	v_mfma_f32_16x16x32_bf16 v[14:17], v[158:161], v[82:85], v[14:17]
	v_mfma_f32_16x16x32_bf16 v[106:109], v[114:117], v[82:85], v[106:109]
	v_mfma_f32_16x16x32_bf16 v[118:121], v[154:157], v[82:85], v[118:121]
	global_load_dwordx4 v[82:85], v223, s[36:37] offset:384
	s_waitcnt vmcnt(7)
	ds_write_b128 v2, v[132:135] offset:8192
	ds_read_b128 v[132:135], v4 offset:36864
	ds_read_b128 v[178:181], v5 offset:53248
	v_mfma_f32_16x16x32_bf16 v[34:37], v[94:97], v[146:149], v[34:37]
	v_mfma_f32_16x16x32_bf16 v[18:21], v[158:161], v[146:149], v[18:21]
	v_mfma_f32_16x16x32_bf16 v[122:125], v[114:117], v[146:149], v[122:125]
	v_mfma_f32_16x16x32_bf16 v[126:129], v[154:157], v[146:149], v[126:129]
	global_load_dwordx4 v[146:149], v224, s[36:37] offset:384
	ds_write_b128 v2, v[162:165] offset:12288
	ds_read_b128 v[162:165], v4 offset:38912
	ds_read_b128 v[182:185], v5 offset:55296
	v_mfma_f32_16x16x32_bf16 v[38:41], v[94:97], v[150:153], v[38:41]
	v_mfma_f32_16x16x32_bf16 v[50:53], v[114:117], v[150:153], v[50:53]
	v_mfma_f32_16x16x32_bf16 v[54:57], v[154:157], v[150:153], v[54:57]
	v_mfma_f32_16x16x32_bf16 v[22:25], v[158:161], v[150:153], v[22:25]
	global_load_dwordx4 v[94:97], v3, s[0:1] offset:384
	s_waitcnt vmcnt(7)
	ds_write_b128 v2, v[86:89] offset:16384
	s_waitcnt lgkmcnt(10)
	v_mfma_f32_16x16x32_bf16 v[26:29], v[170:173], v[90:93], v[26:29]
	s_waitcnt lgkmcnt(1)
	v_mfma_f32_16x16x32_bf16 v[10:13], v[182:185], v[90:93], v[10:13]
	v_mfma_f32_16x16x32_bf16 v[86:89], v[174:177], v[90:93], v[98:101]
	v_mfma_f32_16x16x32_bf16 v[98:101], v[178:181], v[90:93], v[102:105]
	global_load_dwordx4 v[90:93], v225, s[0:1] offset:384
	ds_write_b128 v2, v[42:45] offset:20480
	v_mfma_f32_16x16x32_bf16 v[30:33], v[170:173], v[110:113], v[30:33]
	v_mfma_f32_16x16x32_bf16 v[42:45], v[174:177], v[110:113], v[106:109]
	v_mfma_f32_16x16x32_bf16 v[14:17], v[182:185], v[110:113], v[14:17]
	v_mfma_f32_16x16x32_bf16 v[102:105], v[178:181], v[110:113], v[118:121]
	global_load_dwordx4 v[106:109], v226, s[0:1] offset:384
	s_waitcnt vmcnt(7)
	ds_write_b128 v2, v[46:49] offset:24576
	v_mfma_f32_16x16x32_bf16 v[34:37], v[170:173], v[132:135], v[34:37]
	v_mfma_f32_16x16x32_bf16 v[46:49], v[174:177], v[132:135], v[122:125]
	v_mfma_f32_16x16x32_bf16 v[18:21], v[182:185], v[132:135], v[18:21]
	v_mfma_f32_16x16x32_bf16 v[110:113], v[178:181], v[132:135], v[126:129]
	global_load_dwordx4 v[114:117], v227, s[0:1] offset:384
	ds_write_b128 v2, v[58:61] offset:28672
	v_mfma_f32_16x16x32_bf16 v[38:41], v[170:173], v[162:165], v[38:41]
	v_mfma_f32_16x16x32_bf16 v[50:53], v[174:177], v[162:165], v[50:53]
	v_mfma_f32_16x16x32_bf16 v[54:57], v[178:181], v[162:165], v[54:57]
	v_mfma_f32_16x16x32_bf16 v[22:25], v[182:185], v[162:165], v[22:25]
	s_setprio 0
	s_waitcnt lgkmcnt(0)
	s_barrier
; template <int MODE>
; __device__ __forceinline__ void gemm_tile(const Params& P, int tm, int tn, unsigned char* smem) {
;     ...
; #pragma unroll
;         for (int i = 0; i < 4; ++i) { fa[i] = *(const bf16x8*)(sA + arow_off + i * 2048 + ch0); fb[i] = *(const bf16x8*)(sB + brow_off + i * 2048 + ch0); }
;         __builtin_amdgcn_sched_barrier(0);
;         __builtin_amdgcn_s_setprio(2);
;         if (wr_ok) *(uint4*)(nA + soff0) = ra0;
;         if (ld_ok) ra0 = *(const uint4*)(Ab + (aoff + 0u * LDA + koa));
;         ga[0] = *(const bf16x8*)(sA + arow_off + 0 * 2048 + ch1); gb[0] = *(const bf16x8*)(sB + brow_off + 0 * 2048 + ch1);
;         __builtin_amdgcn_sched_barrier(0);
; #pragma unroll
;         for (int j = 0; j < 4; ++j) acc[0][j] = __builtin_amdgcn_mfma_f32_16x16x32_bf16(fb[j], fa[0], acc[0][j], 0, 0, 0);
;         __builtin_amdgcn_sched_barrier(0);
;         if (wr_ok) *(uint4*)(nA + soff0 + 4096) = ra1;
;         if (ld_ok) ra1 = *(const uint4*)(Ab + (aoff + 32u * LDA + koa));
;         ga[1] = *(const bf16x8*)(sA + arow_off + 1 * 2048 + ch1); gb[1] = *(const bf16x8*)(sB + brow_off + 1 * 2048 + ch1);
;         __builtin_amdgcn_sched_barrier(0);
; #pragma unroll
;         for (int j = 0; j < 4; ++j) acc[1][j] = __builtin_amdgcn_mfma_f32_16x16x32_bf16(fb[j], fa[1], acc[1][j], 0, 0, 0);
;         __builtin_amdgcn_sched_barrier(0);
;         if (wr_ok) *(uint4*)(nA + soff0 + 8192) = ra2;
;         if (ld_ok) ra2 = *(const uint4*)(Ab + (aoff + 64u * LDA + koa));
;         ga[2] = *(const bf16x8*)(sA + arow_off + 2 * 2048 + ch1); gb[2] = *(const bf16x8*)(sB + brow_off + 2 * 2048 + ch1);
;         __builtin_amdgcn_sched_barrier(0);
; #pragma unroll
;         for (int j = 0; j < 4; ++j) acc[2][j] = __builtin_amdgcn_mfma_f32_16x16x32_bf16(fb[j], fa[2], acc[2][j], 0, 0, 0);
;         __builtin_amdgcn_sched_barrier(0);
;         if (wr_ok) *(uint4*)(nA + soff0 + 12288) = ra3;
;         if (ld_ok) ra3 = *(const uint4*)(Ab + (aoff + 96u * LDA + koa));
;         ga[3] = *(const bf16x8*)(sA + arow_off + 3 * 2048 + ch1); gb[3] = *(const bf16x8*)(sB + brow_off + 3 * 2048 + ch1);
;         __builtin_amdgcn_sched_barrier(0);
; #pragma unroll
;         for (int j = 0; j < 4; ++j) acc[3][j] = __builtin_amdgcn_mfma_f32_16x16x32_bf16(fb[j], fa[3], acc[3][j], 0, 0, 0);
;         __builtin_amdgcn_sched_barrier(0);
;         if (wr_ok) *(uint4*)(nB + soff0) = rb0;
	ds_read_b128 v[58:61], v6
	ds_read_b128 v[118:121], v6 offset:2048
	ds_read_b128 v[122:125], v7 offset:16384
	ds_read_b128 v[126:129], v7 offset:18432
	ds_read_b128 v[132:135], v6 offset:4096
	ds_read_b128 v[150:153], v6 offset:6144
	ds_read_b128 v[154:157], v7 offset:20480
	ds_read_b128 v[158:161], v7 offset:22528
	s_setprio 2
	global_load_dwordx4 v[162:165], v8, s[36:37] offset:512
	s_waitcnt vmcnt(7)
	ds_write_b128 v2, v[166:169] offset:32768
	ds_read_b128 v[166:169], v4
	ds_read_b128 v[170:173], v5 offset:16384
	s_waitcnt lgkmcnt(8)
	v_mfma_f32_16x16x32_bf16 v[26:29], v[122:125], v[58:61], v[26:29]
	s_waitcnt lgkmcnt(3)
	v_mfma_f32_16x16x32_bf16 v[10:13], v[158:161], v[58:61], v[10:13]
	v_mfma_f32_16x16x32_bf16 v[86:89], v[126:129], v[58:61], v[86:89]
	v_mfma_f32_16x16x32_bf16 v[98:101], v[154:157], v[58:61], v[98:101]
	global_load_dwordx4 v[58:61], v222, s[36:37] offset:512
	ds_write_b128 v2, v[62:65] offset:36864
	ds_read_b128 v[62:65], v4 offset:2048
	ds_read_b128 v[174:177], v5 offset:18432
	v_mfma_f32_16x16x32_bf16 v[30:33], v[122:125], v[118:121], v[30:33]
	v_mfma_f32_16x16x32_bf16 v[42:45], v[126:129], v[118:121], v[42:45]
	v_mfma_f32_16x16x32_bf16 v[14:17], v[158:161], v[118:121], v[14:17]
	v_mfma_f32_16x16x32_bf16 v[102:105], v[154:157], v[118:121], v[102:105]
	global_load_dwordx4 v[118:121], v223, s[36:37] offset:512
	s_waitcnt vmcnt(7)
	ds_write_b128 v2, v[82:85] offset:40960
	ds_read_b128 v[82:85], v4 offset:4096
	ds_read_b128 v[178:181], v5 offset:20480
	v_mfma_f32_16x16x32_bf16 v[34:37], v[122:125], v[132:135], v[34:37]
	v_mfma_f32_16x16x32_bf16 v[46:49], v[126:129], v[132:135], v[46:49]
	v_mfma_f32_16x16x32_bf16 v[18:21], v[158:161], v[132:135], v[18:21]
	v_mfma_f32_16x16x32_bf16 v[110:113], v[154:157], v[132:135], v[110:113]
	global_load_dwordx4 v[132:135], v224, s[36:37] offset:512
	ds_write_b128 v2, v[146:149] offset:45056
	ds_read_b128 v[146:149], v4 offset:6144
	ds_read_b128 v[182:185], v5 offset:22528
	v_mfma_f32_16x16x32_bf16 v[38:41], v[122:125], v[150:153], v[38:41]
	v_mfma_f32_16x16x32_bf16 v[50:53], v[126:129], v[150:153], v[50:53]
	v_mfma_f32_16x16x32_bf16 v[54:57], v[154:157], v[150:153], v[54:57]
	v_mfma_f32_16x16x32_bf16 v[22:25], v[158:161], v[150:153], v[22:25]
	global_load_dwordx4 v[122:125], v3, s[0:1] offset:512
	s_waitcnt vmcnt(7)
	ds_write_b128 v2, v[94:97] offset:49152
	s_waitcnt lgkmcnt(10)
	v_mfma_f32_16x16x32_bf16 v[26:29], v[170:173], v[166:169], v[26:29]
	s_waitcnt lgkmcnt(1)
	v_mfma_f32_16x16x32_bf16 v[10:13], v[182:185], v[166:169], v[10:13]
	v_mfma_f32_16x16x32_bf16 v[86:89], v[174:177], v[166:169], v[86:89]
	v_mfma_f32_16x16x32_bf16 v[94:97], v[178:181], v[166:169], v[98:101]
	global_load_dwordx4 v[98:101], v225, s[0:1] offset:512
	ds_write_b128 v2, v[90:93] offset:53248
	v_mfma_f32_16x16x32_bf16 v[30:33], v[170:173], v[62:65], v[30:33]
	v_mfma_f32_16x16x32_bf16 v[42:45], v[174:177], v[62:65], v[42:45]
	v_mfma_f32_16x16x32_bf16 v[14:17], v[182:185], v[62:65], v[14:17]
	v_mfma_f32_16x16x32_bf16 v[90:93], v[178:181], v[62:65], v[102:105]
	global_load_dwordx4 v[62:65], v226, s[0:1] offset:512
	s_waitcnt vmcnt(7)
	ds_write_b128 v2, v[106:109] offset:57344
	v_mfma_f32_16x16x32_bf16 v[34:37], v[170:173], v[82:85], v[34:37]
	v_mfma_f32_16x16x32_bf16 v[46:49], v[174:177], v[82:85], v[46:49]
	v_mfma_f32_16x16x32_bf16 v[18:21], v[182:185], v[82:85], v[18:21]
	v_mfma_f32_16x16x32_bf16 v[102:105], v[178:181], v[82:85], v[110:113]
	global_load_dwordx4 v[82:85], v227, s[0:1] offset:512
	ds_write_b128 v2, v[114:117] offset:61440
	v_mfma_f32_16x16x32_bf16 v[38:41], v[170:173], v[146:149], v[38:41]
	v_mfma_f32_16x16x32_bf16 v[50:53], v[174:177], v[146:149], v[50:53]
	v_mfma_f32_16x16x32_bf16 v[54:57], v[178:181], v[146:149], v[54:57]
	v_mfma_f32_16x16x32_bf16 v[22:25], v[182:185], v[146:149], v[22:25]
	s_setprio 0
	s_waitcnt lgkmcnt(0)
	s_barrier
	ds_read_b128 v[106:109], v6 offset:32768
	ds_read_b128 v[110:113], v6 offset:34816
	ds_read_b128 v[114:117], v7 offset:49152
	ds_read_b128 v[126:129], v7 offset:51200
	ds_read_b128 v[146:149], v6 offset:36864
	ds_read_b128 v[150:153], v6 offset:38912
	ds_read_b128 v[154:157], v7 offset:53248
	ds_read_b128 v[158:161], v7 offset:55296
	s_setprio 2
	global_load_dwordx4 v[166:169], v8, s[36:37] offset:640
	s_waitcnt vmcnt(7)
	ds_write_b128 v2, v[162:165]
	ds_read_b128 v[162:165], v4 offset:32768
	ds_read_b128 v[170:173], v5 offset:49152
	s_waitcnt lgkmcnt(8)
	v_mfma_f32_16x16x32_bf16 v[26:29], v[114:117], v[106:109], v[26:29]
	s_waitcnt lgkmcnt(3)
	v_mfma_f32_16x16x32_bf16 v[10:13], v[158:161], v[106:109], v[10:13]
	v_mfma_f32_16x16x32_bf16 v[86:89], v[126:129], v[106:109], v[86:89]
	v_mfma_f32_16x16x32_bf16 v[94:97], v[154:157], v[106:109], v[94:97]
	global_load_dwordx4 v[106:109], v222, s[36:37] offset:640
	ds_write_b128 v2, v[58:61] offset:4096
	ds_read_b128 v[58:61], v4 offset:34816
	ds_read_b128 v[174:177], v5 offset:51200
	v_mfma_f32_16x16x32_bf16 v[30:33], v[114:117], v[110:113], v[30:33]
	v_mfma_f32_16x16x32_bf16 v[42:45], v[126:129], v[110:113], v[42:45]
	v_mfma_f32_16x16x32_bf16 v[14:17], v[158:161], v[110:113], v[14:17]
	v_mfma_f32_16x16x32_bf16 v[90:93], v[154:157], v[110:113], v[90:93]
	global_load_dwordx4 v[110:113], v223, s[36:37] offset:640
	s_waitcnt vmcnt(7)
; template <int MODE>
; __device__ __forceinline__ void gemm_tile(const Params& P, int tm, int tn, unsigned char* smem) {
;     ...
; #pragma unroll
;         for (int i = 0; i < 4; ++i) { fa[i] = *(const bf16x8*)(sA + arow_off + i * 2048 + ch0); fb[i] = *(const bf16x8*)(sB + brow_off + i * 2048 + ch0); }
;         __builtin_amdgcn_sched_barrier(0);
;         __builtin_amdgcn_s_setprio(2);
;         if (wr_ok) *(uint4*)(nA + soff0) = ra0;
;         if (ld_ok) ra0 = *(const uint4*)(Ab + (aoff + 0u * LDA + koa));
;         ga[0] = *(const bf16x8*)(sA + arow_off + 0 * 2048 + ch1); gb[0] = *(const bf16x8*)(sB + brow_off + 0 * 2048 + ch1);
;         __builtin_amdgcn_sched_barrier(0);
; #pragma unroll
;         for (int j = 0; j < 4; ++j) acc[0][j] = __builtin_amdgcn_mfma_f32_16x16x32_bf16(fb[j], fa[0], acc[0][j], 0, 0, 0);
;         __builtin_amdgcn_sched_barrier(0);
;         if (wr_ok) *(uint4*)(nA + soff0 + 4096) = ra1;
;         if (ld_ok) ra1 = *(const uint4*)(Ab + (aoff + 32u * LDA + koa));
;         ga[1] = *(const bf16x8*)(sA + arow_off + 1 * 2048 + ch1); gb[1] = *(const bf16x8*)(sB + brow_off + 1 * 2048 + ch1);
;         __builtin_amdgcn_sched_barrier(0);
; #pragma unroll
;         for (int j = 0; j < 4; ++j) acc[1][j] = __builtin_amdgcn_mfma_f32_16x16x32_bf16(fb[j], fa[1], acc[1][j], 0, 0, 0);
;         __builtin_amdgcn_sched_barrier(0);
;         if (wr_ok) *(uint4*)(nA + soff0 + 8192) = ra2;
;         if (ld_ok) ra2 = *(const uint4*)(Ab + (aoff + 64u * LDA + koa));
;         ga[2] = *(const bf16x8*)(sA + arow_off + 2 * 2048 + ch1); gb[2] = *(const bf16x8*)(sB + brow_off + 2 * 2048 + ch1);
;         __builtin_amdgcn_sched_barrier(0);
; #pragma unroll
;         for (int j = 0; j < 4; ++j) acc[2][j] = __builtin_amdgcn_mfma_f32_16x16x32_bf16(fb[j], fa[2], acc[2][j], 0, 0, 0);
;         __builtin_amdgcn_sched_barrier(0);
;         if (wr_ok) *(uint4*)(nA + soff0 + 12288) = ra3;
;         if (ld_ok) ra3 = *(const uint4*)(Ab + (aoff + 96u * LDA + koa));
;         ga[3] = *(const bf16x8*)(sA + arow_off + 3 * 2048 + ch1); gb[3] = *(const bf16x8*)(sB + brow_off + 3 * 2048 + ch1);
;         __builtin_amdgcn_sched_barrier(0);
; #pragma unroll
;         for (int j = 0; j < 4; ++j) acc[3][j] = __builtin_amdgcn_mfma_f32_16x16x32_bf16(fb[j], fa[3], acc[3][j], 0, 0, 0);
;         __builtin_amdgcn_sched_barrier(0);
;         if (wr_ok) *(uint4*)(nB + soff0) = rb0;
	ds_write_b128 v2, v[118:121] offset:8192
	ds_read_b128 v[118:121], v4 offset:36864
	ds_read_b128 v[178:181], v5 offset:53248
	v_mfma_f32_16x16x32_bf16 v[34:37], v[114:117], v[146:149], v[34:37]
	v_mfma_f32_16x16x32_bf16 v[46:49], v[126:129], v[146:149], v[46:49]
	v_mfma_f32_16x16x32_bf16 v[18:21], v[158:161], v[146:149], v[18:21]
	v_mfma_f32_16x16x32_bf16 v[102:105], v[154:157], v[146:149], v[102:105]
	global_load_dwordx4 v[146:149], v224, s[36:37] offset:640
	ds_write_b128 v2, v[132:135] offset:12288
	ds_read_b128 v[132:135], v4 offset:38912
	ds_read_b128 v[182:185], v5 offset:55296
	v_mfma_f32_16x16x32_bf16 v[38:41], v[114:117], v[150:153], v[38:41]
	v_mfma_f32_16x16x32_bf16 v[50:53], v[126:129], v[150:153], v[50:53]
	v_mfma_f32_16x16x32_bf16 v[54:57], v[154:157], v[150:153], v[54:57]
	v_mfma_f32_16x16x32_bf16 v[22:25], v[158:161], v[150:153], v[22:25]
	global_load_dwordx4 v[114:117], v3, s[0:1] offset:640
	s_waitcnt vmcnt(7)
	ds_write_b128 v2, v[122:125] offset:16384
	s_waitcnt lgkmcnt(10)
	v_mfma_f32_16x16x32_bf16 v[26:29], v[170:173], v[162:165], v[26:29]
	s_waitcnt lgkmcnt(1)
	v_mfma_f32_16x16x32_bf16 v[10:13], v[182:185], v[162:165], v[10:13]
	v_mfma_f32_16x16x32_bf16 v[86:89], v[174:177], v[162:165], v[86:89]
	v_mfma_f32_16x16x32_bf16 v[94:97], v[178:181], v[162:165], v[94:97]
	global_load_dwordx4 v[122:125], v225, s[0:1] offset:640
	ds_write_b128 v2, v[98:101] offset:20480
	v_mfma_f32_16x16x32_bf16 v[30:33], v[170:173], v[58:61], v[30:33]
	v_mfma_f32_16x16x32_bf16 v[42:45], v[174:177], v[58:61], v[42:45]
	v_mfma_f32_16x16x32_bf16 v[14:17], v[182:185], v[58:61], v[14:17]
	v_mfma_f32_16x16x32_bf16 v[90:93], v[178:181], v[58:61], v[90:93]
	global_load_dwordx4 v[58:61], v226, s[0:1] offset:640
	s_waitcnt vmcnt(7)
	ds_write_b128 v2, v[62:65] offset:24576
	v_mfma_f32_16x16x32_bf16 v[34:37], v[170:173], v[118:121], v[34:37]
	v_mfma_f32_16x16x32_bf16 v[46:49], v[174:177], v[118:121], v[46:49]
	v_mfma_f32_16x16x32_bf16 v[62:65], v[178:181], v[118:121], v[102:105]
	v_mfma_f32_16x16x32_bf16 v[18:21], v[182:185], v[118:121], v[18:21]
	global_load_dwordx4 v[98:101], v227, s[0:1] offset:640
	ds_write_b128 v2, v[82:85] offset:28672
	v_mfma_f32_16x16x32_bf16 v[38:41], v[170:173], v[132:135], v[38:41]
	v_mfma_f32_16x16x32_bf16 v[50:53], v[174:177], v[132:135], v[50:53]
	v_mfma_f32_16x16x32_bf16 v[54:57], v[178:181], v[132:135], v[54:57]
	v_mfma_f32_16x16x32_bf16 v[22:25], v[182:185], v[132:135], v[22:25]
	s_setprio 0
	s_waitcnt lgkmcnt(0)
	s_barrier
	ds_read_b128 v[82:85], v6
	ds_read_b128 v[102:105], v6 offset:2048
	ds_read_b128 v[118:121], v7 offset:16384
	ds_read_b128 v[126:129], v7 offset:18432
	ds_read_b128 v[132:135], v6 offset:4096
	ds_read_b128 v[150:153], v6 offset:6144
	ds_read_b128 v[154:157], v7 offset:20480
	ds_read_b128 v[158:161], v7 offset:22528
	s_setprio 2
	global_load_dwordx4 v[162:165], v8, s[36:37] offset:768
	s_waitcnt vmcnt(7)
	ds_write_b128 v2, v[166:169] offset:32768
	ds_read_b128 v[166:169], v4
	ds_read_b128 v[170:173], v5 offset:16384
	s_waitcnt lgkmcnt(8)
	v_mfma_f32_16x16x32_bf16 v[26:29], v[118:121], v[82:85], v[26:29]
	s_waitcnt lgkmcnt(3)
	v_mfma_f32_16x16x32_bf16 v[10:13], v[158:161], v[82:85], v[10:13]
	v_mfma_f32_16x16x32_bf16 v[86:89], v[126:129], v[82:85], v[86:89]
	v_mfma_f32_16x16x32_bf16 v[94:97], v[154:157], v[82:85], v[94:97]
	global_load_dwordx4 v[82:85], v222, s[36:37] offset:768
	ds_write_b128 v2, v[106:109] offset:36864
	ds_read_b128 v[106:109], v4 offset:2048
	ds_read_b128 v[174:177], v5 offset:18432
	v_mfma_f32_16x16x32_bf16 v[30:33], v[118:121], v[102:105], v[30:33]
	v_mfma_f32_16x16x32_bf16 v[42:45], v[126:129], v[102:105], v[42:45]
	v_mfma_f32_16x16x32_bf16 v[14:17], v[158:161], v[102:105], v[14:17]
	v_mfma_f32_16x16x32_bf16 v[90:93], v[154:157], v[102:105], v[90:93]
	global_load_dwordx4 v[102:105], v223, s[36:37] offset:768
	s_waitcnt vmcnt(7)
	ds_write_b128 v2, v[110:113] offset:40960
	ds_read_b128 v[110:113], v4 offset:4096
	ds_read_b128 v[178:181], v5 offset:20480
	v_mfma_f32_16x16x32_bf16 v[34:37], v[118:121], v[132:135], v[34:37]
	v_mfma_f32_16x16x32_bf16 v[46:49], v[126:129], v[132:135], v[46:49]
	v_mfma_f32_16x16x32_bf16 v[62:65], v[154:157], v[132:135], v[62:65]
	v_mfma_f32_16x16x32_bf16 v[18:21], v[158:161], v[132:135], v[18:21]
	global_load_dwordx4 v[132:135], v224, s[36:37] offset:768
	ds_write_b128 v2, v[146:149] offset:45056
	ds_read_b128 v[146:149], v4 offset:6144
	ds_read_b128 v[182:185], v5 offset:22528
	v_mfma_f32_16x16x32_bf16 v[38:41], v[118:121], v[150:153], v[38:41]
	v_mfma_f32_16x16x32_bf16 v[50:53], v[126:129], v[150:153], v[50:53]
	v_mfma_f32_16x16x32_bf16 v[54:57], v[154:157], v[150:153], v[54:57]
	v_mfma_f32_16x16x32_bf16 v[22:25], v[158:161], v[150:153], v[22:25]
	global_load_dwordx4 v[118:121], v3, s[0:1] offset:768
	s_waitcnt vmcnt(7)
	ds_write_b128 v2, v[114:117] offset:49152
	s_waitcnt lgkmcnt(10)
	v_mfma_f32_16x16x32_bf16 v[26:29], v[170:173], v[166:169], v[26:29]
	s_waitcnt lgkmcnt(1)
	v_mfma_f32_16x16x32_bf16 v[10:13], v[182:185], v[166:169], v[10:13]
	v_mfma_f32_16x16x32_bf16 v[86:89], v[174:177], v[166:169], v[86:89]
	v_mfma_f32_16x16x32_bf16 v[94:97], v[178:181], v[166:169], v[94:97]
	global_load_dwordx4 v[114:117], v225, s[0:1] offset:768
	ds_write_b128 v2, v[122:125] offset:53248
	v_mfma_f32_16x16x32_bf16 v[30:33], v[170:173], v[106:109], v[30:33]
	v_mfma_f32_16x16x32_bf16 v[42:45], v[174:177], v[106:109], v[42:45]
	v_mfma_f32_16x16x32_bf16 v[14:17], v[182:185], v[106:109], v[14:17]
	v_mfma_f32_16x16x32_bf16 v[90:93], v[178:181], v[106:109], v[90:93]
	global_load_dwordx4 v[106:109], v226, s[0:1] offset:768
	s_waitcnt vmcnt(7)
	ds_write_b128 v2, v[58:61] offset:57344
	v_mfma_f32_16x16x32_bf16 v[34:37], v[170:173], v[110:113], v[34:37]
	v_mfma_f32_16x16x32_bf16 v[46:49], v[174:177], v[110:113], v[46:49]
	v_mfma_f32_16x16x32_bf16 v[58:61], v[178:181], v[110:113], v[62:65]
	v_mfma_f32_16x16x32_bf16 v[18:21], v[182:185], v[110:113], v[18:21]
	global_load_dwordx4 v[62:65], v227, s[0:1] offset:768
	ds_write_b128 v2, v[98:101] offset:61440
	v_mfma_f32_16x16x32_bf16 v[38:41], v[170:173], v[146:149], v[38:41]
	v_mfma_f32_16x16x32_bf16 v[50:53], v[174:177], v[146:149], v[50:53]
	v_mfma_f32_16x16x32_bf16 v[54:57], v[178:181], v[146:149], v[54:57]
	v_mfma_f32_16x16x32_bf16 v[22:25], v[182:185], v[146:149], v[22:25]
	s_setprio 0
	s_waitcnt lgkmcnt(0)
	s_barrier
; template <int MODE>
; __device__ __forceinline__ void gemm_tile(const Params& P, int tm, int tn, unsigned char* smem) {
;     ...
; #pragma unroll
;         for (int i = 0; i < 4; ++i) { fa[i] = *(const bf16x8*)(sA + arow_off + i * 2048 + ch0); fb[i] = *(const bf16x8*)(sB + brow_off + i * 2048 + ch0); }
;         __builtin_amdgcn_sched_barrier(0);
;         __builtin_amdgcn_s_setprio(2);
;         if (wr_ok) *(uint4*)(nA + soff0) = ra0;
;         if (ld_ok) ra0 = *(const uint4*)(Ab + (aoff + 0u * LDA + koa));
;         ga[0] = *(const bf16x8*)(sA + arow_off + 0 * 2048 + ch1); gb[0] = *(const bf16x8*)(sB + brow_off + 0 * 2048 + ch1);
;         __builtin_amdgcn_sched_barrier(0);
; #pragma unroll
;         for (int j = 0; j < 4; ++j) acc[0][j] = __builtin_amdgcn_mfma_f32_16x16x32_bf16(fb[j], fa[0], acc[0][j], 0, 0, 0);
;         __builtin_amdgcn_sched_barrier(0);
;         if (wr_ok) *(uint4*)(nA + soff0 + 4096) = ra1;
;         if (ld_ok) ra1 = *(const uint4*)(Ab + (aoff + 32u * LDA + koa));
;         ga[1] = *(const bf16x8*)(sA + arow_off + 1 * 2048 + ch1); gb[1] = *(const bf16x8*)(sB + brow_off + 1 * 2048 + ch1);
;         __builtin_amdgcn_sched_barrier(0);
; #pragma unroll
;         for (int j = 0; j < 4; ++j) acc[1][j] = __builtin_amdgcn_mfma_f32_16x16x32_bf16(fb[j], fa[1], acc[1][j], 0, 0, 0);
;         __builtin_amdgcn_sched_barrier(0);
;         if (wr_ok) *(uint4*)(nA + soff0 + 8192) = ra2;
;         if (ld_ok) ra2 = *(const uint4*)(Ab + (aoff + 64u * LDA + koa));
;         ga[2] = *(const bf16x8*)(sA + arow_off + 2 * 2048 + ch1); gb[2] = *(const bf16x8*)(sB + brow_off + 2 * 2048 + ch1);
;         __builtin_amdgcn_sched_barrier(0);
; #pragma unroll
;         for (int j = 0; j < 4; ++j) acc[2][j] = __builtin_amdgcn_mfma_f32_16x16x32_bf16(fb[j], fa[2], acc[2][j], 0, 0, 0);
;         __builtin_amdgcn_sched_barrier(0);
;         if (wr_ok) *(uint4*)(nA + soff0 + 12288) = ra3;
;         if (ld_ok) ra3 = *(const uint4*)(Ab + (aoff + 96u * LDA + koa));
;         ga[3] = *(const bf16x8*)(sA + arow_off + 3 * 2048 + ch1); gb[3] = *(const bf16x8*)(sB + brow_off + 3 * 2048 + ch1);
;         __builtin_amdgcn_sched_barrier(0);
; #pragma unroll
;         for (int j = 0; j < 4; ++j) acc[3][j] = __builtin_amdgcn_mfma_f32_16x16x32_bf16(fb[j], fa[3], acc[3][j], 0, 0, 0);
;         __builtin_amdgcn_sched_barrier(0);
;         if (wr_ok) *(uint4*)(nB + soff0) = rb0;
	ds_read_b128 v[98:101], v6 offset:32768
	ds_read_b128 v[110:113], v6 offset:34816
	ds_read_b128 v[122:125], v7 offset:49152
	ds_read_b128 v[126:129], v7 offset:51200
	ds_read_b128 v[146:149], v6 offset:36864
	ds_read_b128 v[150:153], v6 offset:38912
	ds_read_b128 v[154:157], v7 offset:53248
	ds_read_b128 v[158:161], v7 offset:55296
	s_setprio 2
	global_load_dwordx4 v[166:169], v8, s[36:37] offset:896
	s_waitcnt vmcnt(7)
	ds_write_b128 v2, v[162:165]
	ds_read_b128 v[162:165], v4 offset:32768
	ds_read_b128 v[170:173], v5 offset:49152
	s_waitcnt lgkmcnt(8)
	v_mfma_f32_16x16x32_bf16 v[26:29], v[122:125], v[98:101], v[26:29]
	s_waitcnt lgkmcnt(3)
	v_mfma_f32_16x16x32_bf16 v[10:13], v[158:161], v[98:101], v[10:13]
	v_mfma_f32_16x16x32_bf16 v[86:89], v[126:129], v[98:101], v[86:89]
	v_mfma_f32_16x16x32_bf16 v[94:97], v[154:157], v[98:101], v[94:97]
	global_load_dwordx4 v[98:101], v222, s[36:37] offset:896
	ds_write_b128 v2, v[82:85] offset:4096
	ds_read_b128 v[82:85], v4 offset:34816
	ds_read_b128 v[174:177], v5 offset:51200
	v_mfma_f32_16x16x32_bf16 v[30:33], v[122:125], v[110:113], v[30:33]
	v_mfma_f32_16x16x32_bf16 v[42:45], v[126:129], v[110:113], v[42:45]
	v_mfma_f32_16x16x32_bf16 v[14:17], v[158:161], v[110:113], v[14:17]
	v_mfma_f32_16x16x32_bf16 v[90:93], v[154:157], v[110:113], v[90:93]
	global_load_dwordx4 v[110:113], v223, s[36:37] offset:896
	s_waitcnt vmcnt(7)
	ds_write_b128 v2, v[102:105] offset:8192
	ds_read_b128 v[102:105], v4 offset:36864
	ds_read_b128 v[178:181], v5 offset:53248
	v_mfma_f32_16x16x32_bf16 v[34:37], v[122:125], v[146:149], v[34:37]
	v_mfma_f32_16x16x32_bf16 v[46:49], v[126:129], v[146:149], v[46:49]
	v_mfma_f32_16x16x32_bf16 v[58:61], v[154:157], v[146:149], v[58:61]
	v_mfma_f32_16x16x32_bf16 v[18:21], v[158:161], v[146:149], v[18:21]
	global_load_dwordx4 v[146:149], v224, s[36:37] offset:896
	ds_write_b128 v2, v[132:135] offset:12288
	ds_read_b128 v[132:135], v4 offset:38912
	ds_read_b128 v[182:185], v5 offset:55296
	v_mfma_f32_16x16x32_bf16 v[38:41], v[122:125], v[150:153], v[38:41]
	v_mfma_f32_16x16x32_bf16 v[50:53], v[126:129], v[150:153], v[50:53]
	v_mfma_f32_16x16x32_bf16 v[54:57], v[154:157], v[150:153], v[54:57]
	v_mfma_f32_16x16x32_bf16 v[22:25], v[158:161], v[150:153], v[22:25]
	global_load_dwordx4 v[122:125], v3, s[0:1] offset:896
	s_waitcnt vmcnt(7)
	ds_write_b128 v2, v[118:121] offset:16384
	s_waitcnt lgkmcnt(10)
	v_mfma_f32_16x16x32_bf16 v[26:29], v[170:173], v[162:165], v[26:29]
	s_waitcnt lgkmcnt(1)
	v_mfma_f32_16x16x32_bf16 v[10:13], v[182:185], v[162:165], v[10:13]
	v_mfma_f32_16x16x32_bf16 v[86:89], v[174:177], v[162:165], v[86:89]
	v_mfma_f32_16x16x32_bf16 v[94:97], v[178:181], v[162:165], v[94:97]
	global_load_dwordx4 v[118:121], v225, s[0:1] offset:896
	ds_write_b128 v2, v[114:117] offset:20480
	v_mfma_f32_16x16x32_bf16 v[30:33], v[170:173], v[82:85], v[30:33]
	v_mfma_f32_16x16x32_bf16 v[42:45], v[174:177], v[82:85], v[42:45]
	v_mfma_f32_16x16x32_bf16 v[14:17], v[182:185], v[82:85], v[14:17]
	v_mfma_f32_16x16x32_bf16 v[90:93], v[178:181], v[82:85], v[90:93]
	global_load_dwordx4 v[82:85], v226, s[0:1] offset:896
	s_waitcnt vmcnt(7)
	ds_write_b128 v2, v[106:109] offset:24576
	v_mfma_f32_16x16x32_bf16 v[34:37], v[170:173], v[102:105], v[34:37]
	v_mfma_f32_16x16x32_bf16 v[46:49], v[174:177], v[102:105], v[46:49]
	v_mfma_f32_16x16x32_bf16 v[58:61], v[178:181], v[102:105], v[58:61]
	v_mfma_f32_16x16x32_bf16 v[18:21], v[182:185], v[102:105], v[18:21]
	global_load_dwordx4 v[102:105], v227, s[0:1] offset:896
	ds_write_b128 v2, v[62:65] offset:28672
	v_mfma_f32_16x16x32_bf16 v[38:41], v[170:173], v[132:135], v[38:41]
	v_mfma_f32_16x16x32_bf16 v[50:53], v[174:177], v[132:135], v[50:53]
	v_mfma_f32_16x16x32_bf16 v[54:57], v[178:181], v[132:135], v[54:57]
	v_mfma_f32_16x16x32_bf16 v[22:25], v[182:185], v[132:135], v[22:25]
	s_setprio 0
	s_waitcnt lgkmcnt(0)
	s_barrier
	ds_read_b128 v[62:65], v6
	ds_read_b128 v[106:109], v6 offset:2048
	ds_read_b128 v[114:117], v7 offset:16384
	ds_read_b128 v[126:129], v7 offset:18432
	ds_read_b128 v[132:135], v6 offset:4096
	ds_read_b128 v[150:153], v6 offset:6144
	ds_read_b128 v[154:157], v7 offset:20480
	ds_read_b128 v[158:161], v7 offset:22528
	s_setprio 2
	global_load_dwordx4 v[162:165], v8, s[36:37] offset:1024
	s_waitcnt vmcnt(7)
	ds_write_b128 v2, v[166:169] offset:32768
	ds_read_b128 v[166:169], v4
	ds_read_b128 v[170:173], v5 offset:16384
	s_waitcnt lgkmcnt(8)
	v_mfma_f32_16x16x32_bf16 v[26:29], v[114:117], v[62:65], v[26:29]
	s_waitcnt lgkmcnt(3)
	v_mfma_f32_16x16x32_bf16 v[10:13], v[158:161], v[62:65], v[10:13]
	v_mfma_f32_16x16x32_bf16 v[86:89], v[126:129], v[62:65], v[86:89]
	v_mfma_f32_16x16x32_bf16 v[94:97], v[154:157], v[62:65], v[94:97]
	global_load_dwordx4 v[62:65], v222, s[36:37] offset:1024
	ds_write_b128 v2, v[98:101] offset:36864
	ds_read_b128 v[98:101], v4 offset:2048
	ds_read_b128 v[174:177], v5 offset:18432
	v_mfma_f32_16x16x32_bf16 v[30:33], v[114:117], v[106:109], v[30:33]
	v_mfma_f32_16x16x32_bf16 v[42:45], v[126:129], v[106:109], v[42:45]
	v_mfma_f32_16x16x32_bf16 v[14:17], v[158:161], v[106:109], v[14:17]
	v_mfma_f32_16x16x32_bf16 v[90:93], v[154:157], v[106:109], v[90:93]
	global_load_dwordx4 v[106:109], v223, s[36:37] offset:1024
	s_waitcnt vmcnt(7)
; template <int MODE>
; __device__ __forceinline__ void gemm_tile(const Params& P, int tm, int tn, unsigned char* smem) {
;     ...
; #pragma unroll
;         for (int i = 0; i < 4; ++i) { fa[i] = *(const bf16x8*)(sA + arow_off + i * 2048 + ch0); fb[i] = *(const bf16x8*)(sB + brow_off + i * 2048 + ch0); }
;         __builtin_amdgcn_sched_barrier(0);
;         __builtin_amdgcn_s_setprio(2);
;         if (wr_ok) *(uint4*)(nA + soff0) = ra0;
;         if (ld_ok) ra0 = *(const uint4*)(Ab + (aoff + 0u * LDA + koa));
;         ga[0] = *(const bf16x8*)(sA + arow_off + 0 * 2048 + ch1); gb[0] = *(const bf16x8*)(sB + brow_off + 0 * 2048 + ch1);
;         __builtin_amdgcn_sched_barrier(0);
; #pragma unroll
;         for (int j = 0; j < 4; ++j) acc[0][j] = __builtin_amdgcn_mfma_f32_16x16x32_bf16(fb[j], fa[0], acc[0][j], 0, 0, 0);
;         __builtin_amdgcn_sched_barrier(0);
;         if (wr_ok) *(uint4*)(nA + soff0 + 4096) = ra1;
;         if (ld_ok) ra1 = *(const uint4*)(Ab + (aoff + 32u * LDA + koa));
;         ga[1] = *(const bf16x8*)(sA + arow_off + 1 * 2048 + ch1); gb[1] = *(const bf16x8*)(sB + brow_off + 1 * 2048 + ch1);
;         __builtin_amdgcn_sched_barrier(0);
; #pragma unroll
;         for (int j = 0; j < 4; ++j) acc[1][j] = __builtin_amdgcn_mfma_f32_16x16x32_bf16(fb[j], fa[1], acc[1][j], 0, 0, 0);
;         __builtin_amdgcn_sched_barrier(0);
;         if (wr_ok) *(uint4*)(nA + soff0 + 8192) = ra2;
;         if (ld_ok) ra2 = *(const uint4*)(Ab + (aoff + 64u * LDA + koa));
;         ga[2] = *(const bf16x8*)(sA + arow_off + 2 * 2048 + ch1); gb[2] = *(const bf16x8*)(sB + brow_off + 2 * 2048 + ch1);
;         __builtin_amdgcn_sched_barrier(0);
; #pragma unroll
;         for (int j = 0; j < 4; ++j) acc[2][j] = __builtin_amdgcn_mfma_f32_16x16x32_bf16(fb[j], fa[2], acc[2][j], 0, 0, 0);
;         __builtin_amdgcn_sched_barrier(0);
;         if (wr_ok) *(uint4*)(nA + soff0 + 12288) = ra3;
;         if (ld_ok) ra3 = *(const uint4*)(Ab + (aoff + 96u * LDA + koa));
;         ga[3] = *(const bf16x8*)(sA + arow_off + 3 * 2048 + ch1); gb[3] = *(const bf16x8*)(sB + brow_off + 3 * 2048 + ch1);
;         __builtin_amdgcn_sched_barrier(0);
; #pragma unroll
;         for (int j = 0; j < 4; ++j) acc[3][j] = __builtin_amdgcn_mfma_f32_16x16x32_bf16(fb[j], fa[3], acc[3][j], 0, 0, 0);
;         __builtin_amdgcn_sched_barrier(0);
;         if (wr_ok) *(uint4*)(nB + soff0) = rb0;
	ds_write_b128 v2, v[110:113] offset:40960
	ds_read_b128 v[110:113], v4 offset:4096
	ds_read_b128 v[178:181], v5 offset:20480
	v_mfma_f32_16x16x32_bf16 v[34:37], v[114:117], v[132:135], v[34:37]
	v_mfma_f32_16x16x32_bf16 v[46:49], v[126:129], v[132:135], v[46:49]
	v_mfma_f32_16x16x32_bf16 v[58:61], v[154:157], v[132:135], v[58:61]
	v_mfma_f32_16x16x32_bf16 v[18:21], v[158:161], v[132:135], v[18:21]
	global_load_dwordx4 v[132:135], v224, s[36:37] offset:1024
	ds_write_b128 v2, v[146:149] offset:45056
	ds_read_b128 v[146:149], v4 offset:6144
	ds_read_b128 v[182:185], v5 offset:22528
	v_mfma_f32_16x16x32_bf16 v[38:41], v[114:117], v[150:153], v[38:41]
	v_mfma_f32_16x16x32_bf16 v[50:53], v[126:129], v[150:153], v[50:53]
	v_mfma_f32_16x16x32_bf16 v[54:57], v[154:157], v[150:153], v[54:57]
	v_mfma_f32_16x16x32_bf16 v[22:25], v[158:161], v[150:153], v[22:25]
	global_load_dwordx4 v[114:117], v3, s[0:1] offset:1024
	s_waitcnt vmcnt(7)
	ds_write_b128 v2, v[122:125] offset:49152
	s_waitcnt lgkmcnt(10)
	v_mfma_f32_16x16x32_bf16 v[26:29], v[170:173], v[166:169], v[26:29]
	s_waitcnt lgkmcnt(1)
	v_mfma_f32_16x16x32_bf16 v[10:13], v[182:185], v[166:169], v[10:13]
	v_mfma_f32_16x16x32_bf16 v[86:89], v[174:177], v[166:169], v[86:89]
	v_mfma_f32_16x16x32_bf16 v[94:97], v[178:181], v[166:169], v[94:97]
	global_load_dwordx4 v[122:125], v225, s[0:1] offset:1024
	ds_write_b128 v2, v[118:121] offset:53248
	v_mfma_f32_16x16x32_bf16 v[30:33], v[170:173], v[98:101], v[30:33]
	v_mfma_f32_16x16x32_bf16 v[42:45], v[174:177], v[98:101], v[42:45]
	v_mfma_f32_16x16x32_bf16 v[14:17], v[182:185], v[98:101], v[14:17]
	v_mfma_f32_16x16x32_bf16 v[90:93], v[178:181], v[98:101], v[90:93]
	global_load_dwordx4 v[98:101], v226, s[0:1] offset:1024
	s_waitcnt vmcnt(7)
	ds_write_b128 v2, v[82:85] offset:57344
	v_mfma_f32_16x16x32_bf16 v[34:37], v[170:173], v[110:113], v[34:37]
	v_mfma_f32_16x16x32_bf16 v[46:49], v[174:177], v[110:113], v[46:49]
	v_mfma_f32_16x16x32_bf16 v[58:61], v[178:181], v[110:113], v[58:61]
	v_mfma_f32_16x16x32_bf16 v[18:21], v[182:185], v[110:113], v[18:21]
	global_load_dwordx4 v[82:85], v227, s[0:1] offset:1024
	ds_write_b128 v2, v[102:105] offset:61440
	v_mfma_f32_16x16x32_bf16 v[38:41], v[170:173], v[146:149], v[38:41]
	v_mfma_f32_16x16x32_bf16 v[50:53], v[174:177], v[146:149], v[50:53]
	v_mfma_f32_16x16x32_bf16 v[54:57], v[178:181], v[146:149], v[54:57]
	v_mfma_f32_16x16x32_bf16 v[22:25], v[182:185], v[146:149], v[22:25]
	s_setprio 0
	s_waitcnt lgkmcnt(0)
	s_barrier
	ds_read_b128 v[102:105], v6 offset:32768
	ds_read_b128 v[110:113], v6 offset:34816
	ds_read_b128 v[118:121], v7 offset:49152
	ds_read_b128 v[126:129], v7 offset:51200
	ds_read_b128 v[146:149], v6 offset:36864
	ds_read_b128 v[150:153], v6 offset:38912
	ds_read_b128 v[154:157], v7 offset:53248
	ds_read_b128 v[158:161], v7 offset:55296
	s_setprio 2
	global_load_dwordx4 v[166:169], v8, s[36:37] offset:1152
	s_waitcnt vmcnt(7)
	ds_write_b128 v2, v[162:165]
	ds_read_b128 v[162:165], v4 offset:32768
	ds_read_b128 v[170:173], v5 offset:49152
	s_waitcnt lgkmcnt(8)
	v_mfma_f32_16x16x32_bf16 v[26:29], v[118:121], v[102:105], v[26:29]
	s_waitcnt lgkmcnt(3)
	v_mfma_f32_16x16x32_bf16 v[10:13], v[158:161], v[102:105], v[10:13]
	v_mfma_f32_16x16x32_bf16 v[86:89], v[126:129], v[102:105], v[86:89]
	v_mfma_f32_16x16x32_bf16 v[94:97], v[154:157], v[102:105], v[94:97]
	global_load_dwordx4 v[102:105], v222, s[36:37] offset:1152
	ds_write_b128 v2, v[62:65] offset:4096
	ds_read_b128 v[62:65], v4 offset:34816
	ds_read_b128 v[174:177], v5 offset:51200
	v_mfma_f32_16x16x32_bf16 v[30:33], v[118:121], v[110:113], v[30:33]
	v_mfma_f32_16x16x32_bf16 v[42:45], v[126:129], v[110:113], v[42:45]
	v_mfma_f32_16x16x32_bf16 v[14:17], v[158:161], v[110:113], v[14:17]
	v_mfma_f32_16x16x32_bf16 v[90:93], v[154:157], v[110:113], v[90:93]
	global_load_dwordx4 v[110:113], v223, s[36:37] offset:1152
	s_waitcnt vmcnt(7)
	ds_write_b128 v2, v[106:109] offset:8192
	ds_read_b128 v[106:109], v4 offset:36864
	ds_read_b128 v[178:181], v5 offset:53248
	v_mfma_f32_16x16x32_bf16 v[34:37], v[118:121], v[146:149], v[34:37]
	v_mfma_f32_16x16x32_bf16 v[46:49], v[126:129], v[146:149], v[46:49]
	v_mfma_f32_16x16x32_bf16 v[58:61], v[154:157], v[146:149], v[58:61]
	v_mfma_f32_16x16x32_bf16 v[18:21], v[158:161], v[146:149], v[18:21]
	global_load_dwordx4 v[146:149], v224, s[36:37] offset:1152
	ds_write_b128 v2, v[132:135] offset:12288
	ds_read_b128 v[132:135], v4 offset:38912
	ds_read_b128 v[182:185], v5 offset:55296
	v_mfma_f32_16x16x32_bf16 v[38:41], v[118:121], v[150:153], v[38:41]
	v_mfma_f32_16x16x32_bf16 v[50:53], v[126:129], v[150:153], v[50:53]
	v_mfma_f32_16x16x32_bf16 v[54:57], v[154:157], v[150:153], v[54:57]
	v_mfma_f32_16x16x32_bf16 v[22:25], v[158:161], v[150:153], v[22:25]
	global_load_dwordx4 v[118:121], v3, s[0:1] offset:1152
	s_waitcnt vmcnt(7)
	ds_write_b128 v2, v[114:117] offset:16384
	s_waitcnt lgkmcnt(10)
	v_mfma_f32_16x16x32_bf16 v[26:29], v[170:173], v[162:165], v[26:29]
	s_waitcnt lgkmcnt(1)
	v_mfma_f32_16x16x32_bf16 v[10:13], v[182:185], v[162:165], v[10:13]
	v_mfma_f32_16x16x32_bf16 v[86:89], v[174:177], v[162:165], v[86:89]
	v_mfma_f32_16x16x32_bf16 v[94:97], v[178:181], v[162:165], v[94:97]
	global_load_dwordx4 v[114:117], v225, s[0:1] offset:1152
	ds_write_b128 v2, v[122:125] offset:20480
	v_mfma_f32_16x16x32_bf16 v[30:33], v[170:173], v[62:65], v[30:33]
	v_mfma_f32_16x16x32_bf16 v[42:45], v[174:177], v[62:65], v[42:45]
	v_mfma_f32_16x16x32_bf16 v[14:17], v[182:185], v[62:65], v[14:17]
	v_mfma_f32_16x16x32_bf16 v[90:93], v[178:181], v[62:65], v[90:93]
	global_load_dwordx4 v[62:65], v226, s[0:1] offset:1152
	s_waitcnt vmcnt(7)
	ds_write_b128 v2, v[98:101] offset:24576
	v_mfma_f32_16x16x32_bf16 v[34:37], v[170:173], v[106:109], v[34:37]
	v_mfma_f32_16x16x32_bf16 v[46:49], v[174:177], v[106:109], v[46:49]
	v_mfma_f32_16x16x32_bf16 v[58:61], v[178:181], v[106:109], v[58:61]
	v_mfma_f32_16x16x32_bf16 v[18:21], v[182:185], v[106:109], v[18:21]
	global_load_dwordx4 v[98:101], v227, s[0:1] offset:1152
	ds_write_b128 v2, v[82:85] offset:28672
	v_mfma_f32_16x16x32_bf16 v[38:41], v[170:173], v[132:135], v[38:41]
	v_mfma_f32_16x16x32_bf16 v[50:53], v[174:177], v[132:135], v[50:53]
	v_mfma_f32_16x16x32_bf16 v[54:57], v[178:181], v[132:135], v[54:57]
	v_mfma_f32_16x16x32_bf16 v[22:25], v[182:185], v[132:135], v[22:25]
	s_setprio 0
	s_waitcnt lgkmcnt(0)
	s_barrier
; template <int MODE>
; __device__ __forceinline__ void gemm_tile(const Params& P, int tm, int tn, unsigned char* smem) {
;     ...
; #pragma unroll
;         for (int i = 0; i < 4; ++i) { fa[i] = *(const bf16x8*)(sA + arow_off + i * 2048 + ch0); fb[i] = *(const bf16x8*)(sB + brow_off + i * 2048 + ch0); }
;         __builtin_amdgcn_sched_barrier(0);
;         __builtin_amdgcn_s_setprio(2);
;         if (wr_ok) *(uint4*)(nA + soff0) = ra0;
;         if (ld_ok) ra0 = *(const uint4*)(Ab + (aoff + 0u * LDA + koa));
;         ga[0] = *(const bf16x8*)(sA + arow_off + 0 * 2048 + ch1); gb[0] = *(const bf16x8*)(sB + brow_off + 0 * 2048 + ch1);
;         __builtin_amdgcn_sched_barrier(0);
; #pragma unroll
;         for (int j = 0; j < 4; ++j) acc[0][j] = __builtin_amdgcn_mfma_f32_16x16x32_bf16(fb[j], fa[0], acc[0][j], 0, 0, 0);
;         __builtin_amdgcn_sched_barrier(0);
;         if (wr_ok) *(uint4*)(nA + soff0 + 4096) = ra1;
;         if (ld_ok) ra1 = *(const uint4*)(Ab + (aoff + 32u * LDA + koa));
;         ga[1] = *(const bf16x8*)(sA + arow_off + 1 * 2048 + ch1); gb[1] = *(const bf16x8*)(sB + brow_off + 1 * 2048 + ch1);
;         __builtin_amdgcn_sched_barrier(0);
; #pragma unroll
;         for (int j = 0; j < 4; ++j) acc[1][j] = __builtin_amdgcn_mfma_f32_16x16x32_bf16(fb[j], fa[1], acc[1][j], 0, 0, 0);
;         __builtin_amdgcn_sched_barrier(0);
;         if (wr_ok) *(uint4*)(nA + soff0 + 8192) = ra2;
;         if (ld_ok) ra2 = *(const uint4*)(Ab + (aoff + 64u * LDA + koa));
;         ga[2] = *(const bf16x8*)(sA + arow_off + 2 * 2048 + ch1); gb[2] = *(const bf16x8*)(sB + brow_off + 2 * 2048 + ch1);
;         __builtin_amdgcn_sched_barrier(0);
; #pragma unroll
;         for (int j = 0; j < 4; ++j) acc[2][j] = __builtin_amdgcn_mfma_f32_16x16x32_bf16(fb[j], fa[2], acc[2][j], 0, 0, 0);
;         __builtin_amdgcn_sched_barrier(0);
;         if (wr_ok) *(uint4*)(nA + soff0 + 12288) = ra3;
;         if (ld_ok) ra3 = *(const uint4*)(Ab + (aoff + 96u * LDA + koa));
;         ga[3] = *(const bf16x8*)(sA + arow_off + 3 * 2048 + ch1); gb[3] = *(const bf16x8*)(sB + brow_off + 3 * 2048 + ch1);
;         __builtin_amdgcn_sched_barrier(0);
; #pragma unroll
;         for (int j = 0; j < 4; ++j) acc[3][j] = __builtin_amdgcn_mfma_f32_16x16x32_bf16(fb[j], fa[3], acc[3][j], 0, 0, 0);
;         __builtin_amdgcn_sched_barrier(0);
;         if (wr_ok) *(uint4*)(nB + soff0) = rb0;
	ds_read_b128 v[82:85], v6
	ds_read_b128 v[106:109], v6 offset:2048
	ds_read_b128 v[122:125], v7 offset:16384
	ds_read_b128 v[126:129], v7 offset:18432
	ds_read_b128 v[132:135], v6 offset:4096
	ds_read_b128 v[150:153], v6 offset:6144
	ds_read_b128 v[154:157], v7 offset:20480
	ds_read_b128 v[158:161], v7 offset:22528
	s_setprio 2
	global_load_dwordx4 v[162:165], v8, s[36:37] offset:1280
	s_waitcnt vmcnt(7)
	ds_write_b128 v2, v[166:169] offset:32768
	ds_read_b128 v[166:169], v4
	ds_read_b128 v[170:173], v5 offset:16384
	s_waitcnt lgkmcnt(8)
	v_mfma_f32_16x16x32_bf16 v[26:29], v[122:125], v[82:85], v[26:29]
	s_waitcnt lgkmcnt(3)
	v_mfma_f32_16x16x32_bf16 v[10:13], v[158:161], v[82:85], v[10:13]
	v_mfma_f32_16x16x32_bf16 v[86:89], v[126:129], v[82:85], v[86:89]
	v_mfma_f32_16x16x32_bf16 v[94:97], v[154:157], v[82:85], v[94:97]
	global_load_dwordx4 v[82:85], v222, s[36:37] offset:1280
	ds_write_b128 v2, v[102:105] offset:36864
	ds_read_b128 v[102:105], v4 offset:2048
	ds_read_b128 v[174:177], v5 offset:18432
	v_mfma_f32_16x16x32_bf16 v[30:33], v[122:125], v[106:109], v[30:33]
	v_mfma_f32_16x16x32_bf16 v[42:45], v[126:129], v[106:109], v[42:45]
	v_mfma_f32_16x16x32_bf16 v[14:17], v[158:161], v[106:109], v[14:17]
	v_mfma_f32_16x16x32_bf16 v[90:93], v[154:157], v[106:109], v[90:93]
	global_load_dwordx4 v[106:109], v223, s[36:37] offset:1280
	s_waitcnt vmcnt(7)
	ds_write_b128 v2, v[110:113] offset:40960
	ds_read_b128 v[110:113], v4 offset:4096
	ds_read_b128 v[178:181], v5 offset:20480
	v_mfma_f32_16x16x32_bf16 v[34:37], v[122:125], v[132:135], v[34:37]
	v_mfma_f32_16x16x32_bf16 v[46:49], v[126:129], v[132:135], v[46:49]
	v_mfma_f32_16x16x32_bf16 v[58:61], v[154:157], v[132:135], v[58:61]
	v_mfma_f32_16x16x32_bf16 v[18:21], v[158:161], v[132:135], v[18:21]
	global_load_dwordx4 v[132:135], v224, s[36:37] offset:1280
	ds_write_b128 v2, v[146:149] offset:45056
	ds_read_b128 v[146:149], v4 offset:6144
	ds_read_b128 v[182:185], v5 offset:22528
	v_mfma_f32_16x16x32_bf16 v[38:41], v[122:125], v[150:153], v[38:41]
	v_mfma_f32_16x16x32_bf16 v[50:53], v[126:129], v[150:153], v[50:53]
	v_mfma_f32_16x16x32_bf16 v[54:57], v[154:157], v[150:153], v[54:57]
	v_mfma_f32_16x16x32_bf16 v[22:25], v[158:161], v[150:153], v[22:25]
	global_load_dwordx4 v[122:125], v3, s[0:1] offset:1280
	s_waitcnt vmcnt(7)
	ds_write_b128 v2, v[118:121] offset:49152
	s_waitcnt lgkmcnt(10)
	v_mfma_f32_16x16x32_bf16 v[26:29], v[170:173], v[166:169], v[26:29]
	s_waitcnt lgkmcnt(1)
	v_mfma_f32_16x16x32_bf16 v[10:13], v[182:185], v[166:169], v[10:13]
	v_mfma_f32_16x16x32_bf16 v[86:89], v[174:177], v[166:169], v[86:89]
	v_mfma_f32_16x16x32_bf16 v[94:97], v[178:181], v[166:169], v[94:97]
	global_load_dwordx4 v[118:121], v225, s[0:1] offset:1280
	ds_write_b128 v2, v[114:117] offset:53248
	v_mfma_f32_16x16x32_bf16 v[30:33], v[170:173], v[102:105], v[30:33]
	v_mfma_f32_16x16x32_bf16 v[42:45], v[174:177], v[102:105], v[42:45]
	v_mfma_f32_16x16x32_bf16 v[14:17], v[182:185], v[102:105], v[14:17]
	v_mfma_f32_16x16x32_bf16 v[90:93], v[178:181], v[102:105], v[90:93]
	global_load_dwordx4 v[102:105], v226, s[0:1] offset:1280
	s_waitcnt vmcnt(7)
	ds_write_b128 v2, v[62:65] offset:57344
	v_mfma_f32_16x16x32_bf16 v[34:37], v[170:173], v[110:113], v[34:37]
	v_mfma_f32_16x16x32_bf16 v[46:49], v[174:177], v[110:113], v[46:49]
	v_mfma_f32_16x16x32_bf16 v[58:61], v[178:181], v[110:113], v[58:61]
	v_mfma_f32_16x16x32_bf16 v[18:21], v[182:185], v[110:113], v[18:21]
	global_load_dwordx4 v[62:65], v227, s[0:1] offset:1280
	ds_write_b128 v2, v[98:101] offset:61440
	v_mfma_f32_16x16x32_bf16 v[38:41], v[170:173], v[146:149], v[38:41]
	v_mfma_f32_16x16x32_bf16 v[50:53], v[174:177], v[146:149], v[50:53]
	v_mfma_f32_16x16x32_bf16 v[54:57], v[178:181], v[146:149], v[54:57]
	v_mfma_f32_16x16x32_bf16 v[22:25], v[182:185], v[146:149], v[22:25]
	s_setprio 0
	s_waitcnt lgkmcnt(0)
	s_barrier
	ds_read_b128 v[98:101], v6 offset:32768
	ds_read_b128 v[110:113], v6 offset:34816
	ds_read_b128 v[114:117], v7 offset:49152
	ds_read_b128 v[126:129], v7 offset:51200
	ds_read_b128 v[146:149], v6 offset:36864
	ds_read_b128 v[150:153], v6 offset:38912
	ds_read_b128 v[154:157], v7 offset:53248
	ds_read_b128 v[158:161], v7 offset:55296
	s_setprio 2
	global_load_dwordx4 v[166:169], v8, s[36:37] offset:1408
	s_waitcnt vmcnt(7)
	ds_write_b128 v2, v[162:165]
	ds_read_b128 v[162:165], v4 offset:32768
	ds_read_b128 v[170:173], v5 offset:49152
	s_waitcnt lgkmcnt(8)
	v_mfma_f32_16x16x32_bf16 v[26:29], v[114:117], v[98:101], v[26:29]
	s_waitcnt lgkmcnt(3)
	v_mfma_f32_16x16x32_bf16 v[10:13], v[158:161], v[98:101], v[10:13]
	v_mfma_f32_16x16x32_bf16 v[86:89], v[126:129], v[98:101], v[86:89]
	v_mfma_f32_16x16x32_bf16 v[94:97], v[154:157], v[98:101], v[94:97]
	global_load_dwordx4 v[98:101], v222, s[36:37] offset:1408
	ds_write_b128 v2, v[82:85] offset:4096
	ds_read_b128 v[82:85], v4 offset:34816
	ds_read_b128 v[174:177], v5 offset:51200
	v_mfma_f32_16x16x32_bf16 v[30:33], v[114:117], v[110:113], v[30:33]
	v_mfma_f32_16x16x32_bf16 v[42:45], v[126:129], v[110:113], v[42:45]
	v_mfma_f32_16x16x32_bf16 v[14:17], v[158:161], v[110:113], v[14:17]
	v_mfma_f32_16x16x32_bf16 v[90:93], v[154:157], v[110:113], v[90:93]
	global_load_dwordx4 v[110:113], v223, s[36:37] offset:1408
	s_waitcnt vmcnt(7)
; template <int MODE>
; __device__ __forceinline__ void gemm_tile(const Params& P, int tm, int tn, unsigned char* smem) {
;     ...
; #pragma unroll
;         for (int i = 0; i < 4; ++i) { fa[i] = *(const bf16x8*)(sA + arow_off + i * 2048 + ch0); fb[i] = *(const bf16x8*)(sB + brow_off + i * 2048 + ch0); }
;         __builtin_amdgcn_sched_barrier(0);
;         __builtin_amdgcn_s_setprio(2);
;         if (wr_ok) *(uint4*)(nA + soff0) = ra0;
;         if (ld_ok) ra0 = *(const uint4*)(Ab + (aoff + 0u * LDA + koa));
;         ga[0] = *(const bf16x8*)(sA + arow_off + 0 * 2048 + ch1); gb[0] = *(const bf16x8*)(sB + brow_off + 0 * 2048 + ch1);
;         __builtin_amdgcn_sched_barrier(0);
; #pragma unroll
;         for (int j = 0; j < 4; ++j) acc[0][j] = __builtin_amdgcn_mfma_f32_16x16x32_bf16(fb[j], fa[0], acc[0][j], 0, 0, 0);
;         __builtin_amdgcn_sched_barrier(0);
;         if (wr_ok) *(uint4*)(nA + soff0 + 4096) = ra1;
;         if (ld_ok) ra1 = *(const uint4*)(Ab + (aoff + 32u * LDA + koa));
;         ga[1] = *(const bf16x8*)(sA + arow_off + 1 * 2048 + ch1); gb[1] = *(const bf16x8*)(sB + brow_off + 1 * 2048 + ch1);
;         __builtin_amdgcn_sched_barrier(0);
; #pragma unroll
;         for (int j = 0; j < 4; ++j) acc[1][j] = __builtin_amdgcn_mfma_f32_16x16x32_bf16(fb[j], fa[1], acc[1][j], 0, 0, 0);
;         __builtin_amdgcn_sched_barrier(0);
;         if (wr_ok) *(uint4*)(nA + soff0 + 8192) = ra2;
;         if (ld_ok) ra2 = *(const uint4*)(Ab + (aoff + 64u * LDA + koa));
;         ga[2] = *(const bf16x8*)(sA + arow_off + 2 * 2048 + ch1); gb[2] = *(const bf16x8*)(sB + brow_off + 2 * 2048 + ch1);
;         __builtin_amdgcn_sched_barrier(0);
; #pragma unroll
;         for (int j = 0; j < 4; ++j) acc[2][j] = __builtin_amdgcn_mfma_f32_16x16x32_bf16(fb[j], fa[2], acc[2][j], 0, 0, 0);
;         __builtin_amdgcn_sched_barrier(0);
;         if (wr_ok) *(uint4*)(nA + soff0 + 12288) = ra3;
;         if (ld_ok) ra3 = *(const uint4*)(Ab + (aoff + 96u * LDA + koa));
;         ga[3] = *(const bf16x8*)(sA + arow_off + 3 * 2048 + ch1); gb[3] = *(const bf16x8*)(sB + brow_off + 3 * 2048 + ch1);
;         __builtin_amdgcn_sched_barrier(0);
; #pragma unroll
;         for (int j = 0; j < 4; ++j) acc[3][j] = __builtin_amdgcn_mfma_f32_16x16x32_bf16(fb[j], fa[3], acc[3][j], 0, 0, 0);
;         __builtin_amdgcn_sched_barrier(0);
;         if (wr_ok) *(uint4*)(nB + soff0) = rb0;
	ds_write_b128 v2, v[106:109] offset:8192
	ds_read_b128 v[106:109], v4 offset:36864
	ds_read_b128 v[178:181], v5 offset:53248
	v_mfma_f32_16x16x32_bf16 v[34:37], v[114:117], v[146:149], v[34:37]
	v_mfma_f32_16x16x32_bf16 v[46:49], v[126:129], v[146:149], v[46:49]
	v_mfma_f32_16x16x32_bf16 v[58:61], v[154:157], v[146:149], v[58:61]
	v_mfma_f32_16x16x32_bf16 v[18:21], v[158:161], v[146:149], v[18:21]
	global_load_dwordx4 v[146:149], v224, s[36:37] offset:1408
	ds_write_b128 v2, v[132:135] offset:12288
	ds_read_b128 v[132:135], v4 offset:38912
	ds_read_b128 v[182:185], v5 offset:55296
	v_mfma_f32_16x16x32_bf16 v[38:41], v[114:117], v[150:153], v[38:41]
	v_mfma_f32_16x16x32_bf16 v[50:53], v[126:129], v[150:153], v[50:53]
	v_mfma_f32_16x16x32_bf16 v[54:57], v[154:157], v[150:153], v[54:57]
	v_mfma_f32_16x16x32_bf16 v[22:25], v[158:161], v[150:153], v[22:25]
	global_load_dwordx4 v[114:117], v3, s[0:1] offset:1408
	s_waitcnt vmcnt(7)
	ds_write_b128 v2, v[122:125] offset:16384
	s_waitcnt lgkmcnt(10)
	v_mfma_f32_16x16x32_bf16 v[26:29], v[170:173], v[162:165], v[26:29]
	s_waitcnt lgkmcnt(1)
	v_mfma_f32_16x16x32_bf16 v[10:13], v[182:185], v[162:165], v[10:13]
	v_mfma_f32_16x16x32_bf16 v[86:89], v[174:177], v[162:165], v[86:89]
	v_mfma_f32_16x16x32_bf16 v[94:97], v[178:181], v[162:165], v[94:97]
	global_load_dwordx4 v[122:125], v225, s[0:1] offset:1408
	ds_write_b128 v2, v[118:121] offset:20480
	v_mfma_f32_16x16x32_bf16 v[30:33], v[170:173], v[82:85], v[30:33]
	v_mfma_f32_16x16x32_bf16 v[42:45], v[174:177], v[82:85], v[42:45]
	v_mfma_f32_16x16x32_bf16 v[14:17], v[182:185], v[82:85], v[14:17]
	v_mfma_f32_16x16x32_bf16 v[90:93], v[178:181], v[82:85], v[90:93]
	global_load_dwordx4 v[82:85], v226, s[0:1] offset:1408
	s_waitcnt vmcnt(7)
	ds_write_b128 v2, v[102:105] offset:24576
	v_mfma_f32_16x16x32_bf16 v[34:37], v[170:173], v[106:109], v[34:37]
	v_mfma_f32_16x16x32_bf16 v[46:49], v[174:177], v[106:109], v[46:49]
	v_mfma_f32_16x16x32_bf16 v[58:61], v[178:181], v[106:109], v[58:61]
	v_mfma_f32_16x16x32_bf16 v[18:21], v[182:185], v[106:109], v[18:21]
	global_load_dwordx4 v[102:105], v227, s[0:1] offset:1408
	ds_write_b128 v2, v[62:65] offset:28672
	v_mfma_f32_16x16x32_bf16 v[38:41], v[170:173], v[132:135], v[38:41]
	v_mfma_f32_16x16x32_bf16 v[50:53], v[174:177], v[132:135], v[50:53]
	v_mfma_f32_16x16x32_bf16 v[54:57], v[178:181], v[132:135], v[54:57]
	v_mfma_f32_16x16x32_bf16 v[22:25], v[182:185], v[132:135], v[22:25]
	s_setprio 0
	s_waitcnt lgkmcnt(0)
	s_barrier
	ds_read_b128 v[62:65], v6
	ds_read_b128 v[106:109], v6 offset:2048
	ds_read_b128 v[118:121], v7 offset:16384
	ds_read_b128 v[126:129], v7 offset:18432
	ds_read_b128 v[132:135], v6 offset:4096
	ds_read_b128 v[150:153], v6 offset:6144
	ds_read_b128 v[154:157], v7 offset:20480
	ds_read_b128 v[158:161], v7 offset:22528
	s_setprio 2
	global_load_dwordx4 v[162:165], v8, s[36:37] offset:1536
	s_waitcnt vmcnt(7)
	ds_write_b128 v2, v[166:169] offset:32768
	ds_read_b128 v[166:169], v4
	ds_read_b128 v[170:173], v5 offset:16384
	s_waitcnt lgkmcnt(8)
	v_mfma_f32_16x16x32_bf16 v[26:29], v[118:121], v[62:65], v[26:29]
	s_waitcnt lgkmcnt(3)
	v_mfma_f32_16x16x32_bf16 v[10:13], v[158:161], v[62:65], v[10:13]
	v_mfma_f32_16x16x32_bf16 v[86:89], v[126:129], v[62:65], v[86:89]
	v_mfma_f32_16x16x32_bf16 v[94:97], v[154:157], v[62:65], v[94:97]
	global_load_dwordx4 v[62:65], v222, s[36:37] offset:1536
	ds_write_b128 v2, v[98:101] offset:36864
	ds_read_b128 v[98:101], v4 offset:2048
	ds_read_b128 v[174:177], v5 offset:18432
	v_mfma_f32_16x16x32_bf16 v[30:33], v[118:121], v[106:109], v[30:33]
	v_mfma_f32_16x16x32_bf16 v[42:45], v[126:129], v[106:109], v[42:45]
	v_mfma_f32_16x16x32_bf16 v[14:17], v[158:161], v[106:109], v[14:17]
	v_mfma_f32_16x16x32_bf16 v[90:93], v[154:157], v[106:109], v[90:93]
	global_load_dwordx4 v[106:109], v223, s[36:37] offset:1536
	s_waitcnt vmcnt(7)
	ds_write_b128 v2, v[110:113] offset:40960
	ds_read_b128 v[110:113], v4 offset:4096
	ds_read_b128 v[178:181], v5 offset:20480
	v_mfma_f32_16x16x32_bf16 v[34:37], v[118:121], v[132:135], v[34:37]
	v_mfma_f32_16x16x32_bf16 v[46:49], v[126:129], v[132:135], v[46:49]
	v_mfma_f32_16x16x32_bf16 v[58:61], v[154:157], v[132:135], v[58:61]
	v_mfma_f32_16x16x32_bf16 v[18:21], v[158:161], v[132:135], v[18:21]
	global_load_dwordx4 v[132:135], v224, s[36:37] offset:1536
	ds_write_b128 v2, v[146:149] offset:45056
	ds_read_b128 v[146:149], v4 offset:6144
	ds_read_b128 v[182:185], v5 offset:22528
	v_mfma_f32_16x16x32_bf16 v[38:41], v[118:121], v[150:153], v[38:41]
	v_mfma_f32_16x16x32_bf16 v[50:53], v[126:129], v[150:153], v[50:53]
	v_mfma_f32_16x16x32_bf16 v[54:57], v[154:157], v[150:153], v[54:57]
	v_mfma_f32_16x16x32_bf16 v[22:25], v[158:161], v[150:153], v[22:25]
	global_load_dwordx4 v[118:121], v3, s[0:1] offset:1536
	s_waitcnt vmcnt(7)
	ds_write_b128 v2, v[114:117] offset:49152
	s_waitcnt lgkmcnt(10)
	v_mfma_f32_16x16x32_bf16 v[26:29], v[170:173], v[166:169], v[26:29]
	s_waitcnt lgkmcnt(1)
	v_mfma_f32_16x16x32_bf16 v[10:13], v[182:185], v[166:169], v[10:13]
	v_mfma_f32_16x16x32_bf16 v[86:89], v[174:177], v[166:169], v[86:89]
	v_mfma_f32_16x16x32_bf16 v[94:97], v[178:181], v[166:169], v[94:97]
	global_load_dwordx4 v[114:117], v225, s[0:1] offset:1536
	ds_write_b128 v2, v[122:125] offset:53248
	v_mfma_f32_16x16x32_bf16 v[30:33], v[170:173], v[98:101], v[30:33]
	v_mfma_f32_16x16x32_bf16 v[42:45], v[174:177], v[98:101], v[42:45]
	v_mfma_f32_16x16x32_bf16 v[14:17], v[182:185], v[98:101], v[14:17]
	v_mfma_f32_16x16x32_bf16 v[90:93], v[178:181], v[98:101], v[90:93]
	global_load_dwordx4 v[98:101], v226, s[0:1] offset:1536
	s_waitcnt vmcnt(7)
	ds_write_b128 v2, v[82:85] offset:57344
	v_mfma_f32_16x16x32_bf16 v[34:37], v[170:173], v[110:113], v[34:37]
	v_mfma_f32_16x16x32_bf16 v[46:49], v[174:177], v[110:113], v[46:49]
	v_mfma_f32_16x16x32_bf16 v[58:61], v[178:181], v[110:113], v[58:61]
	v_mfma_f32_16x16x32_bf16 v[18:21], v[182:185], v[110:113], v[18:21]
	global_load_dwordx4 v[82:85], v227, s[0:1] offset:1536
	ds_write_b128 v2, v[102:105] offset:61440
	v_mfma_f32_16x16x32_bf16 v[38:41], v[170:173], v[146:149], v[38:41]
	v_mfma_f32_16x16x32_bf16 v[50:53], v[174:177], v[146:149], v[50:53]
	v_mfma_f32_16x16x32_bf16 v[54:57], v[178:181], v[146:149], v[54:57]
	v_mfma_f32_16x16x32_bf16 v[22:25], v[182:185], v[146:149], v[22:25]
	s_setprio 0
	s_waitcnt lgkmcnt(0)
	s_barrier
; template <int MODE>
; __device__ __forceinline__ void gemm_tile(const Params& P, int tm, int tn, unsigned char* smem) {
;     ...
; #pragma unroll
;         for (int i = 0; i < 4; ++i) { fa[i] = *(const bf16x8*)(sA + arow_off + i * 2048 + ch0); fb[i] = *(const bf16x8*)(sB + brow_off + i * 2048 + ch0); }
;         __builtin_amdgcn_sched_barrier(0);
;         __builtin_amdgcn_s_setprio(2);
;         if (wr_ok) *(uint4*)(nA + soff0) = ra0;
;         if (ld_ok) ra0 = *(const uint4*)(Ab + (aoff + 0u * LDA + koa));
;         ga[0] = *(const bf16x8*)(sA + arow_off + 0 * 2048 + ch1); gb[0] = *(const bf16x8*)(sB + brow_off + 0 * 2048 + ch1);
;         __builtin_amdgcn_sched_barrier(0);
; #pragma unroll
;         for (int j = 0; j < 4; ++j) acc[0][j] = __builtin_amdgcn_mfma_f32_16x16x32_bf16(fb[j], fa[0], acc[0][j], 0, 0, 0);
;         __builtin_amdgcn_sched_barrier(0);
;         if (wr_ok) *(uint4*)(nA + soff0 + 4096) = ra1;
;         if (ld_ok) ra1 = *(const uint4*)(Ab + (aoff + 32u * LDA + koa));
;         ga[1] = *(const bf16x8*)(sA + arow_off + 1 * 2048 + ch1); gb[1] = *(const bf16x8*)(sB + brow_off + 1 * 2048 + ch1);
;         __builtin_amdgcn_sched_barrier(0);
; #pragma unroll
;         for (int j = 0; j < 4; ++j) acc[1][j] = __builtin_amdgcn_mfma_f32_16x16x32_bf16(fb[j], fa[1], acc[1][j], 0, 0, 0);
;         __builtin_amdgcn_sched_barrier(0);
;         if (wr_ok) *(uint4*)(nA + soff0 + 8192) = ra2;
;         if (ld_ok) ra2 = *(const uint4*)(Ab + (aoff + 64u * LDA + koa));
;         ga[2] = *(const bf16x8*)(sA + arow_off + 2 * 2048 + ch1); gb[2] = *(const bf16x8*)(sB + brow_off + 2 * 2048 + ch1);
;         __builtin_amdgcn_sched_barrier(0);
; #pragma unroll
;         for (int j = 0; j < 4; ++j) acc[2][j] = __builtin_amdgcn_mfma_f32_16x16x32_bf16(fb[j], fa[2], acc[2][j], 0, 0, 0);
;         __builtin_amdgcn_sched_barrier(0);
;         if (wr_ok) *(uint4*)(nA + soff0 + 12288) = ra3;
;         if (ld_ok) ra3 = *(const uint4*)(Ab + (aoff + 96u * LDA + koa));
;         ga[3] = *(const bf16x8*)(sA + arow_off + 3 * 2048 + ch1); gb[3] = *(const bf16x8*)(sB + brow_off + 3 * 2048 + ch1);
;         __builtin_amdgcn_sched_barrier(0);
; #pragma unroll
;         for (int j = 0; j < 4; ++j) acc[3][j] = __builtin_amdgcn_mfma_f32_16x16x32_bf16(fb[j], fa[3], acc[3][j], 0, 0, 0);
;         __builtin_amdgcn_sched_barrier(0);
;         if (wr_ok) *(uint4*)(nB + soff0) = rb0;
	ds_read_b128 v[102:105], v6 offset:32768
	ds_read_b128 v[110:113], v6 offset:34816
	ds_read_b128 v[122:125], v7 offset:49152
	ds_read_b128 v[126:129], v7 offset:51200
	ds_read_b128 v[146:149], v6 offset:36864
	ds_read_b128 v[150:153], v6 offset:38912
	ds_read_b128 v[154:157], v7 offset:53248
	ds_read_b128 v[158:161], v7 offset:55296
	s_setprio 2
	global_load_dwordx4 v[166:169], v8, s[36:37] offset:1664
	s_waitcnt vmcnt(7)
	ds_write_b128 v2, v[162:165]
	ds_read_b128 v[162:165], v4 offset:32768
	ds_read_b128 v[170:173], v5 offset:49152
	s_waitcnt lgkmcnt(8)
	v_mfma_f32_16x16x32_bf16 v[26:29], v[122:125], v[102:105], v[26:29]
	s_waitcnt lgkmcnt(3)
	v_mfma_f32_16x16x32_bf16 v[10:13], v[158:161], v[102:105], v[10:13]
	v_mfma_f32_16x16x32_bf16 v[86:89], v[126:129], v[102:105], v[86:89]
	v_mfma_f32_16x16x32_bf16 v[94:97], v[154:157], v[102:105], v[94:97]
	global_load_dwordx4 v[102:105], v222, s[36:37] offset:1664
	ds_write_b128 v2, v[62:65] offset:4096
	ds_read_b128 v[62:65], v4 offset:34816
	ds_read_b128 v[174:177], v5 offset:51200
	v_mfma_f32_16x16x32_bf16 v[30:33], v[122:125], v[110:113], v[30:33]
	v_mfma_f32_16x16x32_bf16 v[42:45], v[126:129], v[110:113], v[42:45]
	v_mfma_f32_16x16x32_bf16 v[14:17], v[158:161], v[110:113], v[14:17]
	v_mfma_f32_16x16x32_bf16 v[90:93], v[154:157], v[110:113], v[90:93]
	global_load_dwordx4 v[110:113], v223, s[36:37] offset:1664
	s_waitcnt vmcnt(7)
	ds_write_b128 v2, v[106:109] offset:8192
	ds_read_b128 v[106:109], v4 offset:36864
	ds_read_b128 v[178:181], v5 offset:53248
	v_mfma_f32_16x16x32_bf16 v[34:37], v[122:125], v[146:149], v[34:37]
	v_mfma_f32_16x16x32_bf16 v[46:49], v[126:129], v[146:149], v[46:49]
	v_mfma_f32_16x16x32_bf16 v[58:61], v[154:157], v[146:149], v[58:61]
	v_mfma_f32_16x16x32_bf16 v[18:21], v[158:161], v[146:149], v[18:21]
	global_load_dwordx4 v[146:149], v224, s[36:37] offset:1664
	ds_write_b128 v2, v[132:135] offset:12288
	ds_read_b128 v[132:135], v4 offset:38912
	ds_read_b128 v[182:185], v5 offset:55296
	v_mfma_f32_16x16x32_bf16 v[38:41], v[122:125], v[150:153], v[38:41]
	v_mfma_f32_16x16x32_bf16 v[50:53], v[126:129], v[150:153], v[50:53]
	v_mfma_f32_16x16x32_bf16 v[54:57], v[154:157], v[150:153], v[54:57]
	v_mfma_f32_16x16x32_bf16 v[22:25], v[158:161], v[150:153], v[22:25]
	global_load_dwordx4 v[122:125], v3, s[0:1] offset:1664
	s_waitcnt vmcnt(7)
	ds_write_b128 v2, v[118:121] offset:16384
	s_waitcnt lgkmcnt(10)
	v_mfma_f32_16x16x32_bf16 v[26:29], v[170:173], v[162:165], v[26:29]
	s_waitcnt lgkmcnt(1)
	v_mfma_f32_16x16x32_bf16 v[10:13], v[182:185], v[162:165], v[10:13]
	v_mfma_f32_16x16x32_bf16 v[86:89], v[174:177], v[162:165], v[86:89]
	v_mfma_f32_16x16x32_bf16 v[94:97], v[178:181], v[162:165], v[94:97]
	global_load_dwordx4 v[118:121], v225, s[0:1] offset:1664
	ds_write_b128 v2, v[114:117] offset:20480
	v_mfma_f32_16x16x32_bf16 v[30:33], v[170:173], v[62:65], v[30:33]
	v_mfma_f32_16x16x32_bf16 v[42:45], v[174:177], v[62:65], v[42:45]
	v_mfma_f32_16x16x32_bf16 v[14:17], v[182:185], v[62:65], v[14:17]
	v_mfma_f32_16x16x32_bf16 v[90:93], v[178:181], v[62:65], v[90:93]
	global_load_dwordx4 v[62:65], v226, s[0:1] offset:1664
	s_waitcnt vmcnt(7)
	ds_write_b128 v2, v[98:101] offset:24576
	v_mfma_f32_16x16x32_bf16 v[34:37], v[170:173], v[106:109], v[34:37]
	v_mfma_f32_16x16x32_bf16 v[46:49], v[174:177], v[106:109], v[46:49]
	v_mfma_f32_16x16x32_bf16 v[58:61], v[178:181], v[106:109], v[58:61]
	v_mfma_f32_16x16x32_bf16 v[18:21], v[182:185], v[106:109], v[18:21]
	global_load_dwordx4 v[98:101], v227, s[0:1] offset:1664
	ds_write_b128 v2, v[82:85] offset:28672
	v_mfma_f32_16x16x32_bf16 v[38:41], v[170:173], v[132:135], v[38:41]
	v_mfma_f32_16x16x32_bf16 v[50:53], v[174:177], v[132:135], v[50:53]
	v_mfma_f32_16x16x32_bf16 v[54:57], v[178:181], v[132:135], v[54:57]
	v_mfma_f32_16x16x32_bf16 v[22:25], v[182:185], v[132:135], v[22:25]
	s_setprio 0
	s_waitcnt lgkmcnt(0)
	s_barrier
	ds_read_b128 v[82:85], v6
	ds_read_b128 v[106:109], v6 offset:2048
	ds_read_b128 v[114:117], v7 offset:16384
	ds_read_b128 v[126:129], v7 offset:18432
	ds_read_b128 v[132:135], v6 offset:4096
	ds_read_b128 v[150:153], v6 offset:6144
	ds_read_b128 v[154:157], v7 offset:20480
	ds_read_b128 v[158:161], v7 offset:22528
	s_setprio 2
	global_load_dwordx4 v[162:165], v8, s[36:37] offset:1792
	s_waitcnt vmcnt(7)
	ds_write_b128 v2, v[166:169] offset:32768
	ds_read_b128 v[166:169], v4
	ds_read_b128 v[170:173], v5 offset:16384
	s_waitcnt lgkmcnt(8)
	v_mfma_f32_16x16x32_bf16 v[26:29], v[114:117], v[82:85], v[26:29]
	s_waitcnt lgkmcnt(3)
	v_mfma_f32_16x16x32_bf16 v[10:13], v[158:161], v[82:85], v[10:13]
	v_mfma_f32_16x16x32_bf16 v[86:89], v[126:129], v[82:85], v[86:89]
	v_mfma_f32_16x16x32_bf16 v[94:97], v[154:157], v[82:85], v[94:97]
	global_load_dwordx4 v[82:85], v222, s[36:37] offset:1792
	ds_write_b128 v2, v[102:105] offset:36864
	ds_read_b128 v[102:105], v4 offset:2048
	ds_read_b128 v[174:177], v5 offset:18432
	v_mfma_f32_16x16x32_bf16 v[30:33], v[114:117], v[106:109], v[30:33]
	v_mfma_f32_16x16x32_bf16 v[42:45], v[126:129], v[106:109], v[42:45]
	v_mfma_f32_16x16x32_bf16 v[14:17], v[158:161], v[106:109], v[14:17]
	v_mfma_f32_16x16x32_bf16 v[90:93], v[154:157], v[106:109], v[90:93]
	global_load_dwordx4 v[106:109], v223, s[36:37] offset:1792
	s_waitcnt vmcnt(7)
; template <int MODE>
; __device__ __forceinline__ void gemm_tile(const Params& P, int tm, int tn, unsigned char* smem) {
;     ...
; #pragma unroll
;         for (int i = 0; i < 4; ++i) { fa[i] = *(const bf16x8*)(sA + arow_off + i * 2048 + ch0); fb[i] = *(const bf16x8*)(sB + brow_off + i * 2048 + ch0); }
;         __builtin_amdgcn_sched_barrier(0);
;         __builtin_amdgcn_s_setprio(2);
;         if (wr_ok) *(uint4*)(nA + soff0) = ra0;
;         if (ld_ok) ra0 = *(const uint4*)(Ab + (aoff + 0u * LDA + koa));
;         ga[0] = *(const bf16x8*)(sA + arow_off + 0 * 2048 + ch1); gb[0] = *(const bf16x8*)(sB + brow_off + 0 * 2048 + ch1);
;         __builtin_amdgcn_sched_barrier(0);
; #pragma unroll
;         for (int j = 0; j < 4; ++j) acc[0][j] = __builtin_amdgcn_mfma_f32_16x16x32_bf16(fb[j], fa[0], acc[0][j], 0, 0, 0);
;         __builtin_amdgcn_sched_barrier(0);
;         if (wr_ok) *(uint4*)(nA + soff0 + 4096) = ra1;
;         if (ld_ok) ra1 = *(const uint4*)(Ab + (aoff + 32u * LDA + koa));
;         ga[1] = *(const bf16x8*)(sA + arow_off + 1 * 2048 + ch1); gb[1] = *(const bf16x8*)(sB + brow_off + 1 * 2048 + ch1);
;         __builtin_amdgcn_sched_barrier(0);
; #pragma unroll
;         for (int j = 0; j < 4; ++j) acc[1][j] = __builtin_amdgcn_mfma_f32_16x16x32_bf16(fb[j], fa[1], acc[1][j], 0, 0, 0);
;         __builtin_amdgcn_sched_barrier(0);
;         if (wr_ok) *(uint4*)(nA + soff0 + 8192) = ra2;
;         if (ld_ok) ra2 = *(const uint4*)(Ab + (aoff + 64u * LDA + koa));
;         ga[2] = *(const bf16x8*)(sA + arow_off + 2 * 2048 + ch1); gb[2] = *(const bf16x8*)(sB + brow_off + 2 * 2048 + ch1);
;         __builtin_amdgcn_sched_barrier(0);
; #pragma unroll
;         for (int j = 0; j < 4; ++j) acc[2][j] = __builtin_amdgcn_mfma_f32_16x16x32_bf16(fb[j], fa[2], acc[2][j], 0, 0, 0);
;         __builtin_amdgcn_sched_barrier(0);
;         if (wr_ok) *(uint4*)(nA + soff0 + 12288) = ra3;
;         if (ld_ok) ra3 = *(const uint4*)(Ab + (aoff + 96u * LDA + koa));
;         ga[3] = *(const bf16x8*)(sA + arow_off + 3 * 2048 + ch1); gb[3] = *(const bf16x8*)(sB + brow_off + 3 * 2048 + ch1);
;         __builtin_amdgcn_sched_barrier(0);
; #pragma unroll
;         for (int j = 0; j < 4; ++j) acc[3][j] = __builtin_amdgcn_mfma_f32_16x16x32_bf16(fb[j], fa[3], acc[3][j], 0, 0, 0);
;         __builtin_amdgcn_sched_barrier(0);
;         if (wr_ok) *(uint4*)(nB + soff0) = rb0;
	ds_write_b128 v2, v[110:113] offset:40960
	ds_read_b128 v[110:113], v4 offset:4096
	ds_read_b128 v[178:181], v5 offset:20480
	v_mfma_f32_16x16x32_bf16 v[34:37], v[114:117], v[132:135], v[34:37]
	v_mfma_f32_16x16x32_bf16 v[46:49], v[126:129], v[132:135], v[46:49]
	v_mfma_f32_16x16x32_bf16 v[58:61], v[154:157], v[132:135], v[58:61]
	v_mfma_f32_16x16x32_bf16 v[18:21], v[158:161], v[132:135], v[18:21]
	global_load_dwordx4 v[132:135], v224, s[36:37] offset:1792
	ds_write_b128 v2, v[146:149] offset:45056
	ds_read_b128 v[146:149], v4 offset:6144
	ds_read_b128 v[182:185], v5 offset:22528
	v_mfma_f32_16x16x32_bf16 v[38:41], v[114:117], v[150:153], v[38:41]
	v_mfma_f32_16x16x32_bf16 v[50:53], v[126:129], v[150:153], v[50:53]
	v_mfma_f32_16x16x32_bf16 v[54:57], v[154:157], v[150:153], v[54:57]
	v_mfma_f32_16x16x32_bf16 v[22:25], v[158:161], v[150:153], v[22:25]
	global_load_dwordx4 v[114:117], v3, s[0:1] offset:1792
	s_waitcnt vmcnt(7)
	ds_write_b128 v2, v[122:125] offset:49152
	s_waitcnt lgkmcnt(10)
	v_mfma_f32_16x16x32_bf16 v[26:29], v[170:173], v[166:169], v[26:29]
	s_waitcnt lgkmcnt(1)
	v_mfma_f32_16x16x32_bf16 v[10:13], v[182:185], v[166:169], v[10:13]
	v_mfma_f32_16x16x32_bf16 v[86:89], v[174:177], v[166:169], v[86:89]
	v_mfma_f32_16x16x32_bf16 v[94:97], v[178:181], v[166:169], v[94:97]
	global_load_dwordx4 v[122:125], v225, s[0:1] offset:1792
	ds_write_b128 v2, v[118:121] offset:53248
	v_mfma_f32_16x16x32_bf16 v[30:33], v[170:173], v[102:105], v[30:33]
	v_mfma_f32_16x16x32_bf16 v[42:45], v[174:177], v[102:105], v[42:45]
	v_mfma_f32_16x16x32_bf16 v[14:17], v[182:185], v[102:105], v[14:17]
	v_mfma_f32_16x16x32_bf16 v[90:93], v[178:181], v[102:105], v[90:93]
	global_load_dwordx4 v[102:105], v226, s[0:1] offset:1792
	s_waitcnt vmcnt(7)
	ds_write_b128 v2, v[62:65] offset:57344
	v_mfma_f32_16x16x32_bf16 v[34:37], v[170:173], v[110:113], v[34:37]
	v_mfma_f32_16x16x32_bf16 v[46:49], v[174:177], v[110:113], v[46:49]
	v_mfma_f32_16x16x32_bf16 v[58:61], v[178:181], v[110:113], v[58:61]
	v_mfma_f32_16x16x32_bf16 v[18:21], v[182:185], v[110:113], v[18:21]
	global_load_dwordx4 v[62:65], v227, s[0:1] offset:1792
	ds_write_b128 v2, v[98:101] offset:61440
	v_mfma_f32_16x16x32_bf16 v[38:41], v[170:173], v[146:149], v[38:41]
	v_mfma_f32_16x16x32_bf16 v[50:53], v[174:177], v[146:149], v[50:53]
	v_mfma_f32_16x16x32_bf16 v[54:57], v[178:181], v[146:149], v[54:57]
	v_mfma_f32_16x16x32_bf16 v[22:25], v[182:185], v[146:149], v[22:25]
	s_setprio 0
	s_waitcnt lgkmcnt(0)
	s_barrier
	ds_read_b128 v[98:101], v6 offset:32768
	ds_read_b128 v[110:113], v6 offset:34816
	ds_read_b128 v[118:121], v7 offset:49152
	ds_read_b128 v[126:129], v7 offset:51200
	ds_read_b128 v[146:149], v6 offset:36864
	ds_read_b128 v[150:153], v6 offset:38912
	ds_read_b128 v[154:157], v7 offset:53248
	ds_read_b128 v[158:161], v7 offset:55296
	s_setprio 2
	global_load_dwordx4 v[166:169], v8, s[36:37] offset:1920
	s_waitcnt vmcnt(7)
	ds_write_b128 v2, v[162:165]
	ds_read_b128 v[162:165], v4 offset:32768
	ds_read_b128 v[170:173], v5 offset:49152
	s_waitcnt lgkmcnt(8)
	v_mfma_f32_16x16x32_bf16 v[26:29], v[118:121], v[98:101], v[26:29]
	s_waitcnt lgkmcnt(3)
	v_mfma_f32_16x16x32_bf16 v[10:13], v[158:161], v[98:101], v[10:13]
	v_mfma_f32_16x16x32_bf16 v[86:89], v[126:129], v[98:101], v[86:89]
	v_mfma_f32_16x16x32_bf16 v[94:97], v[154:157], v[98:101], v[94:97]
	global_load_dwordx4 v[98:101], v222, s[36:37] offset:1920
	ds_write_b128 v2, v[82:85] offset:4096
	ds_read_b128 v[82:85], v4 offset:34816
	ds_read_b128 v[174:177], v5 offset:51200
	v_mfma_f32_16x16x32_bf16 v[30:33], v[118:121], v[110:113], v[30:33]
	v_mfma_f32_16x16x32_bf16 v[42:45], v[126:129], v[110:113], v[42:45]
	v_mfma_f32_16x16x32_bf16 v[14:17], v[158:161], v[110:113], v[14:17]
	v_mfma_f32_16x16x32_bf16 v[90:93], v[154:157], v[110:113], v[90:93]
	global_load_dwordx4 v[110:113], v223, s[36:37] offset:1920
	s_waitcnt vmcnt(7)
	ds_write_b128 v2, v[106:109] offset:8192
	ds_read_b128 v[106:109], v4 offset:36864
	ds_read_b128 v[178:181], v5 offset:53248
	v_mfma_f32_16x16x32_bf16 v[34:37], v[118:121], v[146:149], v[34:37]
	v_mfma_f32_16x16x32_bf16 v[46:49], v[126:129], v[146:149], v[46:49]
	v_mfma_f32_16x16x32_bf16 v[58:61], v[154:157], v[146:149], v[58:61]
	v_mfma_f32_16x16x32_bf16 v[18:21], v[158:161], v[146:149], v[18:21]
	v_add_u32_e32 v8, 0x30780, v8
	global_load_dwordx4 v[146:149], v8, s[36:37]
	ds_write_b128 v2, v[132:135] offset:12288
	ds_read_b128 v[132:135], v4 offset:38912
	ds_read_b128 v[182:185], v5 offset:55296
	v_mfma_f32_16x16x32_bf16 v[38:41], v[118:121], v[150:153], v[38:41]
	v_mfma_f32_16x16x32_bf16 v[50:53], v[126:129], v[150:153], v[50:53]
	v_mfma_f32_16x16x32_bf16 v[54:57], v[154:157], v[150:153], v[54:57]
	v_mfma_f32_16x16x32_bf16 v[22:25], v[158:161], v[150:153], v[22:25]
	global_load_dwordx4 v[118:121], v3, s[0:1] offset:1920
	s_waitcnt vmcnt(7)
	ds_write_b128 v2, v[114:117] offset:16384
	s_waitcnt lgkmcnt(10)
	v_mfma_f32_16x16x32_bf16 v[26:29], v[170:173], v[162:165], v[26:29]
	s_waitcnt lgkmcnt(1)
	v_mfma_f32_16x16x32_bf16 v[8:11], v[182:185], v[162:165], v[10:13]
	v_mfma_f32_16x16x32_bf16 v[86:89], v[174:177], v[162:165], v[86:89]
	v_mfma_f32_16x16x32_bf16 v[94:97], v[178:181], v[162:165], v[94:97]
	s_nop 0
	global_load_dwordx4 v[114:117], v225, s[0:1] offset:1920
	ds_write_b128 v2, v[122:125] offset:20480
	v_mfma_f32_16x16x32_bf16 v[30:33], v[170:173], v[82:85], v[30:33]
	v_mfma_f32_16x16x32_bf16 v[42:45], v[174:177], v[82:85], v[42:45]
	v_mfma_f32_16x16x32_bf16 v[12:15], v[182:185], v[82:85], v[14:17]
	v_mfma_f32_16x16x32_bf16 v[90:93], v[178:181], v[82:85], v[90:93]
	s_nop 1
	global_load_dwordx4 v[82:85], v226, s[0:1] offset:1920
	s_waitcnt vmcnt(7)
	ds_write_b128 v2, v[102:105] offset:24576
	v_mfma_f32_16x16x32_bf16 v[34:37], v[170:173], v[106:109], v[34:37]
	v_mfma_f32_16x16x32_bf16 v[46:49], v[174:177], v[106:109], v[46:49]
	v_mfma_f32_16x16x32_bf16 v[58:61], v[178:181], v[106:109], v[58:61]
	v_mfma_f32_16x16x32_bf16 v[16:19], v[182:185], v[106:109], v[18:21]
	v_add_u32_e32 v3, 0x30780, v3
	global_load_dwordx4 v[102:105], v3, s[0:1]
	ds_write_b128 v2, v[62:65] offset:28672
	v_mfma_f32_16x16x32_bf16 v[38:41], v[170:173], v[132:135], v[38:41]
	v_mfma_f32_16x16x32_bf16 v[50:53], v[174:177], v[132:135], v[50:53]
	v_mfma_f32_16x16x32_bf16 v[54:57], v[178:181], v[132:135], v[54:57]
	v_mfma_f32_16x16x32_bf16 v[20:23], v[182:185], v[132:135], v[22:25]
	s_setprio 0
	s_waitcnt lgkmcnt(0)
	s_barrier
; template <int MODE>
; __device__ __forceinline__ void gemm_tile(const Params& P, int tm, int tn, unsigned char* smem) {
;     ...
; #pragma unroll
;         for (int i = 0; i < 4; ++i) { fa[i] = *(const bf16x8*)(sA + arow_off + i * 2048 + ch0); fb[i] = *(const bf16x8*)(sB + brow_off + i * 2048 + ch0); }
;         __builtin_amdgcn_sched_barrier(0);
;         __builtin_amdgcn_s_setprio(2);
;         if (wr_ok) *(uint4*)(nA + soff0) = ra0;
;         if (ld_ok) ra0 = *(const uint4*)(Ab + (aoff + 0u * LDA + koa));
;         ga[0] = *(const bf16x8*)(sA + arow_off + 0 * 2048 + ch1); gb[0] = *(const bf16x8*)(sB + brow_off + 0 * 2048 + ch1);
;         __builtin_amdgcn_sched_barrier(0);
; #pragma unroll
;         for (int j = 0; j < 4; ++j) acc[0][j] = __builtin_amdgcn_mfma_f32_16x16x32_bf16(fb[j], fa[0], acc[0][j], 0, 0, 0);
;         __builtin_amdgcn_sched_barrier(0);
;         if (wr_ok) *(uint4*)(nA + soff0 + 4096) = ra1;
;         if (ld_ok) ra1 = *(const uint4*)(Ab + (aoff + 32u * LDA + koa));
;         ga[1] = *(const bf16x8*)(sA + arow_off + 1 * 2048 + ch1); gb[1] = *(const bf16x8*)(sB + brow_off + 1 * 2048 + ch1);
;         __builtin_amdgcn_sched_barrier(0);
; #pragma unroll
;         for (int j = 0; j < 4; ++j) acc[1][j] = __builtin_amdgcn_mfma_f32_16x16x32_bf16(fb[j], fa[1], acc[1][j], 0, 0, 0);
;         __builtin_amdgcn_sched_barrier(0);
;         if (wr_ok) *(uint4*)(nA + soff0 + 8192) = ra2;
;         if (ld_ok) ra2 = *(const uint4*)(Ab + (aoff + 64u * LDA + koa));
;         ga[2] = *(const bf16x8*)(sA + arow_off + 2 * 2048 + ch1); gb[2] = *(const bf16x8*)(sB + brow_off + 2 * 2048 + ch1);
;         __builtin_amdgcn_sched_barrier(0);
; #pragma unroll
;         for (int j = 0; j < 4; ++j) acc[2][j] = __builtin_amdgcn_mfma_f32_16x16x32_bf16(fb[j], fa[2], acc[2][j], 0, 0, 0);
;         __builtin_amdgcn_sched_barrier(0);
;         if (wr_ok) *(uint4*)(nA + soff0 + 12288) = ra3;
;         if (ld_ok) ra3 = *(const uint4*)(Ab + (aoff + 96u * LDA + koa));
;         ga[3] = *(const bf16x8*)(sA + arow_off + 3 * 2048 + ch1); gb[3] = *(const bf16x8*)(sB + brow_off + 3 * 2048 + ch1);
;         __builtin_amdgcn_sched_barrier(0);
; #pragma unroll
;         for (int j = 0; j < 4; ++j) acc[3][j] = __builtin_amdgcn_mfma_f32_16x16x32_bf16(fb[j], fa[3], acc[3][j], 0, 0, 0);
;         __builtin_amdgcn_sched_barrier(0);
;         if (wr_ok) *(uint4*)(nB + soff0) = rb0;
	ds_read_b128 v[62:65], v6
	ds_read_b128 v[106:109], v6 offset:2048
	ds_read_b128 v[122:125], v7 offset:16384
	ds_read_b128 v[126:129], v7 offset:18432
	ds_read_b128 v[132:135], v6 offset:4096
	ds_read_b128 v[150:153], v6 offset:6144
	ds_read_b128 v[154:157], v7 offset:20480
	ds_read_b128 v[158:161], v7 offset:22528
	s_setprio 2
	s_waitcnt vmcnt(7)
	ds_write_b128 v2, v[166:169] offset:32768
	ds_read_b128 v[162:165], v4
	ds_read_b128 v[166:169], v5 offset:16384
	s_waitcnt lgkmcnt(8)
	v_mfma_f32_16x16x32_bf16 v[24:27], v[122:125], v[62:65], v[26:29]
	s_waitcnt lgkmcnt(3)
	v_mfma_f32_16x16x32_bf16 v[8:11], v[158:161], v[62:65], v[8:11]
	v_mfma_f32_16x16x32_bf16 v[86:89], v[126:129], v[62:65], v[86:89]
	v_mfma_f32_16x16x32_bf16 v[94:97], v[154:157], v[62:65], v[94:97]
	s_waitcnt vmcnt(6)
	ds_write_b128 v2, v[98:101] offset:36864
	ds_read_b128 v[62:65], v4 offset:2048
	ds_read_b128 v[98:101], v5 offset:18432
	v_mfma_f32_16x16x32_bf16 v[28:31], v[122:125], v[106:109], v[30:33]
	v_mfma_f32_16x16x32_bf16 v[42:45], v[126:129], v[106:109], v[42:45]
	v_mfma_f32_16x16x32_bf16 v[12:15], v[158:161], v[106:109], v[12:15]
	v_mfma_f32_16x16x32_bf16 v[90:93], v[154:157], v[106:109], v[90:93]
	s_waitcnt vmcnt(5)
	ds_write_b128 v2, v[110:113] offset:40960
	ds_read_b128 v[106:109], v4 offset:4096
	ds_read_b128 v[110:113], v5 offset:20480
	v_mfma_f32_16x16x32_bf16 v[32:35], v[122:125], v[132:135], v[34:37]
	v_mfma_f32_16x16x32_bf16 v[46:49], v[126:129], v[132:135], v[46:49]
	v_mfma_f32_16x16x32_bf16 v[58:61], v[154:157], v[132:135], v[58:61]
	v_mfma_f32_16x16x32_bf16 v[16:19], v[158:161], v[132:135], v[16:19]
	s_waitcnt vmcnt(4)
	ds_write_b128 v2, v[146:149] offset:45056
	ds_read_b128 v[132:135], v4 offset:6144
	ds_read_b128 v[146:149], v5 offset:22528
	v_mfma_f32_16x16x32_bf16 v[36:39], v[122:125], v[150:153], v[38:41]
	v_mfma_f32_16x16x32_bf16 v[50:53], v[126:129], v[150:153], v[50:53]
	v_mfma_f32_16x16x32_bf16 v[54:57], v[154:157], v[150:153], v[54:57]
	v_mfma_f32_16x16x32_bf16 v[20:23], v[158:161], v[150:153], v[20:23]
	s_waitcnt vmcnt(3)
	ds_write_b128 v2, v[118:121] offset:49152
	s_waitcnt lgkmcnt(10)
	v_mfma_f32_16x16x32_bf16 v[24:27], v[166:169], v[162:165], v[24:27]
	s_waitcnt lgkmcnt(1)
	v_mfma_f32_16x16x32_bf16 v[8:11], v[146:149], v[162:165], v[8:11]
	v_mfma_f32_16x16x32_bf16 v[86:89], v[98:101], v[162:165], v[86:89]
	v_mfma_f32_16x16x32_bf16 v[94:97], v[110:113], v[162:165], v[94:97]
	s_waitcnt vmcnt(2)
	ds_write_b128 v2, v[114:117] offset:53248
	v_mfma_f32_16x16x32_bf16 v[28:31], v[166:169], v[62:65], v[28:31]
	v_mfma_f32_16x16x32_bf16 v[40:43], v[98:101], v[62:65], v[42:45]
	v_mfma_f32_16x16x32_bf16 v[12:15], v[146:149], v[62:65], v[12:15]
	v_mfma_f32_16x16x32_bf16 v[90:93], v[110:113], v[62:65], v[90:93]
	s_waitcnt vmcnt(1)
	ds_write_b128 v2, v[82:85] offset:57344
	v_mfma_f32_16x16x32_bf16 v[32:35], v[166:169], v[106:109], v[32:35]
	v_mfma_f32_16x16x32_bf16 v[44:47], v[98:101], v[106:109], v[46:49]
	v_mfma_f32_16x16x32_bf16 v[58:61], v[110:113], v[106:109], v[58:61]
	v_mfma_f32_16x16x32_bf16 v[16:19], v[146:149], v[106:109], v[16:19]
	s_waitcnt vmcnt(0)
	ds_write_b128 v2, v[102:105] offset:61440
	v_mfma_f32_16x16x32_bf16 v[36:39], v[166:169], v[132:135], v[36:39]
	v_mfma_f32_16x16x32_bf16 v[48:51], v[98:101], v[132:135], v[50:53]
	v_mfma_f32_16x16x32_bf16 v[52:55], v[110:113], v[132:135], v[54:57]
	v_mfma_f32_16x16x32_bf16 v[20:23], v[146:149], v[132:135], v[20:23]
	s_setprio 0
	s_waitcnt lgkmcnt(0)
	s_barrier
	ds_read_b128 v[62:65], v6 offset:32768
	ds_read_b128 v[82:85], v6 offset:34816
	ds_read_b128 v[98:101], v7 offset:49152
	ds_read_b128 v[102:105], v7 offset:51200
	ds_read_b128 v[106:109], v6 offset:36864
	ds_read_b128 v[110:113], v6 offset:38912
	ds_read_b128 v[114:117], v7 offset:53248
	ds_read_b128 v[118:121], v7 offset:55296
	s_setprio 2
	ds_read_b128 v[122:125], v4 offset:32768
	ds_read_b128 v[126:129], v5 offset:49152
	s_waitcnt lgkmcnt(7)
	v_mfma_f32_16x16x32_bf16 v[24:27], v[98:101], v[62:65], v[24:27]
	s_waitcnt lgkmcnt(2)
	v_mfma_f32_16x16x32_bf16 v[6:9], v[118:121], v[62:65], v[8:11]
	v_mfma_f32_16x16x32_bf16 v[86:89], v[102:105], v[62:65], v[86:89]
	v_mfma_f32_16x16x32_bf16 v[94:97], v[114:117], v[62:65], v[94:97]
	ds_read_b128 v[132:135], v4 offset:34816
	ds_read_b128 v[146:149], v5 offset:51200
	v_mfma_f32_16x16x32_bf16 v[28:31], v[98:101], v[82:85], v[28:31]
	v_mfma_f32_16x16x32_bf16 v[40:43], v[102:105], v[82:85], v[40:43]
	v_mfma_f32_16x16x32_bf16 v[10:13], v[118:121], v[82:85], v[12:15]
	v_mfma_f32_16x16x32_bf16 v[90:93], v[114:117], v[82:85], v[90:93]
	ds_read_b128 v[82:85], v4 offset:36864
	ds_read_b128 v[150:153], v5 offset:53248
	v_mfma_f32_16x16x32_bf16 v[14:17], v[118:121], v[106:109], v[16:19]
	v_mfma_f32_16x16x32_bf16 v[154:157], v[98:101], v[106:109], v[32:35]
	v_mfma_f32_16x16x32_bf16 v[158:161], v[102:105], v[106:109], v[44:47]
	v_mfma_f32_16x16x32_bf16 v[162:165], v[114:117], v[106:109], v[58:61]
	ds_read_b128 v[106:109], v4 offset:38912
	ds_read_b128 v[2:5], v5 offset:55296
	v_mfma_f32_16x16x32_bf16 v[98:101], v[98:101], v[110:113], v[36:39]
	v_mfma_f32_16x16x32_bf16 v[102:105], v[102:105], v[110:113], v[48:51]
	v_mfma_f32_16x16x32_bf16 v[114:117], v[114:117], v[110:113], v[52:55]
	v_mfma_f32_16x16x32_bf16 v[110:113], v[118:121], v[110:113], v[20:23]
	s_waitcnt lgkmcnt(6)
	v_mfma_f32_16x16x32_bf16 v[62:65], v[126:129], v[122:125], v[24:27]
	s_waitcnt lgkmcnt(4)
	v_mfma_f32_16x16x32_bf16 v[58:61], v[146:149], v[122:125], v[86:89]
	s_waitcnt lgkmcnt(2)
	v_mfma_f32_16x16x32_bf16 v[54:57], v[150:153], v[122:125], v[94:97]
	s_waitcnt lgkmcnt(0)
	v_mfma_f32_16x16x32_bf16 v[50:53], v[2:5], v[122:125], v[6:9]
	v_mfma_f32_16x16x32_bf16 v[46:49], v[126:129], v[132:135], v[28:31]
	v_mfma_f32_16x16x32_bf16 v[42:45], v[146:149], v[132:135], v[40:43]
	v_mfma_f32_16x16x32_bf16 v[38:41], v[150:153], v[132:135], v[90:93]
	v_mfma_f32_16x16x32_bf16 v[34:37], v[2:5], v[132:135], v[10:13]
	v_mfma_f32_16x16x32_bf16 v[30:33], v[126:129], v[82:85], v[154:157]
	v_mfma_f32_16x16x32_bf16 v[26:29], v[146:149], v[82:85], v[158:161]
	v_mfma_f32_16x16x32_bf16 v[22:25], v[150:153], v[82:85], v[162:165]
	v_mfma_f32_16x16x32_bf16 v[18:21], v[2:5], v[82:85], v[14:17]
	v_mfma_f32_16x16x32_bf16 v[14:17], v[126:129], v[106:109], v[98:101]
	v_mfma_f32_16x16x32_bf16 v[10:13], v[146:149], v[106:109], v[102:105]
	v_mfma_f32_16x16x32_bf16 v[6:9], v[150:153], v[106:109], v[114:117]
	v_mfma_f32_16x16x32_bf16 v[2:5], v[2:5], v[106:109], v[110:113]
	s_setprio 0
	s_and_b32 s0, s7, -8
	s_cmp_lg_u32 s0, 16
	s_barrier
; template <int MODE>
; __device__ __forceinline__ void gemm_tile(const Params& P, int tm, int tn, unsigned char* smem) {
;     ...
;         if (n0 >= ZC_FQ && n0 < ZC_FV) {
;             const bool isk = n0 >= ZC_FK;
;             const float* gain = isk ? P.f_k_norm : P.f_q_norm;
;             const float scl = isk ? 1.0f : 0.125f * LOG2E;
;             float gn[4][4];
; #pragma unroll
;             for (int j = 0; j < 4; ++j)
; #pragma unroll
;                 for (int r = 0; r < 4; ++r) gn[j][r] = gain[16 * j + 4 * g + r];
; #pragma unroll
;             for (int i = 0; i < 4; ++i) {
;                 float ss = 0.f;
; #pragma unroll
;                 for (int j = 0; j < 4; ++j)
; #pragma unroll
;                     for (int r = 0; r < 4; ++r) ss += acc[i][j][r] * acc[i][j][r];
;                 ss = x4_sum(ss);
;                 const float rstd = rsqrtf(ss * (1.0f / 64.0f) + EPS) * scl;
	s_cbranch_scc1 .LBB0_223
	v_mul_f32_e32 v68, v63, v63
	v_fmac_f32_e32 v68, v62, v62
	v_fmac_f32_e32 v68, v64, v64
	v_fmac_f32_e32 v68, v65, v65
	v_fmac_f32_e32 v68, v58, v58
	v_fmac_f32_e32 v68, v59, v59
	v_fmac_f32_e32 v68, v60, v60
	v_fmac_f32_e32 v68, v61, v61
	v_fmac_f32_e32 v68, v54, v54
	v_fmac_f32_e32 v68, v55, v55
	v_fmac_f32_e32 v68, v56, v56
	s_cmp_gt_u32 s7, 19
	v_fmac_f32_e32 v68, v57, v57
	v_pk_mul_f32 v[82:83], v[50:51], v[50:51]
	v_mov_b32_e32 v66, 0x3e38aa3b
	s_cselect_b64 s[0:1], -1, 0
	v_add_f32_e32 v68, v82, v68
	v_cndmask_b32_e64 v106, v66, 1.0, s[0:1]
	v_pk_mul_f32 v[66:67], v[52:53], v[52:53]
	v_add_f32_e32 v68, v83, v68
	v_add_f32_e32 v66, v66, v68
	v_add_f32_e32 v66, v67, v66
	v_mov_b32_e32 v67, v66
	s_nop 1
	v_permlane32_swap_b32_e32 v66, v67
	v_add_f32_e32 v67, v66, v67
	v_mul_f32_e32 v66, v47, v47
	v_fmac_f32_e32 v66, v46, v46
	v_fmac_f32_e32 v66, v48, v48
	v_fmac_f32_e32 v66, v49, v49
	v_fmac_f32_e32 v66, v42, v42
	v_fmac_f32_e32 v66, v43, v43
	v_fmac_f32_e32 v66, v44, v44
	v_fmac_f32_e32 v66, v45, v45
	v_fmac_f32_e32 v66, v38, v38
	v_fmac_f32_e32 v66, v39, v39
	v_fmac_f32_e32 v66, v40, v40
	v_fmac_f32_e32 v66, v41, v41
	v_pk_mul_f32 v[86:87], v[34:35], v[34:35]
	v_pk_mul_f32 v[84:85], v[36:37], v[36:37]
	v_add_f32_e32 v66, v86, v66
	v_add_f32_e32 v66, v87, v66
	v_add_f32_e32 v66, v84, v66
	v_add_f32_e32 v66, v85, v66
	v_mov_b32_e32 v68, v66
	s_nop 1
	v_permlane32_swap_b32_e32 v66, v68
	v_add_f32_e32 v66, v66, v68
	s_and_b64 s[0:1], s[0:1], exec
	v_mov_b32_e32 v83, v67
	v_mov_b32_e32 v82, v66
	s_nop 0
	v_permlane16_swap_b32_e32 v67, v83
	v_permlane16_swap_b32_e32 v66, v82
	s_mov_b32 s0, 0x358637bd
	v_pk_add_f32 v[82:83], v[66:67], v[82:83]
	s_mov_b32 s10, 0x3c800000
	v_mov_b64_e32 v[66:67], s[0:1]
	v_mul_f32_e32 v95, v31, v31
	v_pk_fma_f32 v[86:87], v[82:83], s[10:11], v[66:67] op_sel_hi:[1,0,0]
	s_mov_b32 s7, 0x800000
	v_fmac_f32_e32 v95, v30, v30
	v_mul_f32_e32 v68, 0x4b800000, v87
	v_cmp_gt_f32_e32 vcc, s7, v87
	v_fmac_f32_e32 v95, v32, v32
	v_fmac_f32_e32 v95, v33, v33
	v_cndmask_b32_e32 v68, v87, v68, vcc
	v_rsq_f32_e32 v68, v68
	v_mul_f32_e32 v70, 0x4b800000, v86
	v_cmp_gt_f32_e64 s[0:1], s7, v86
	v_fmac_f32_e32 v95, v26, v26
	v_fmac_f32_e32 v95, v27, v27
	v_cndmask_b32_e64 v70, v86, v70, s[0:1]
	v_rsq_f32_e32 v86, v70
	v_fmac_f32_e32 v95, v28, v28
	s_cselect_b32 s9, s41, s39
	s_cselect_b32 s8, s40, s38
	v_lshlrev_b32_e32 v94, 4, v81
	v_fmac_f32_e32 v95, v29, v29
	global_load_dwordx4 v[82:85], v94, s[8:9]
	v_mul_f32_e32 v70, 0x45800000, v68
	v_fmac_f32_e32 v95, v22, v22
	v_cndmask_b32_e32 v68, v68, v70, vcc
	v_fmac_f32_e32 v95, v23, v23
	v_mul_f32_e32 v70, v106, v68
	v_mul_f32_e32 v68, 0x45800000, v86
	v_fmac_f32_e32 v95, v24, v24
	v_cndmask_b32_e64 v68, v86, v68, s[0:1]
	global_load_dwordx4 v[86:89], v94, s[8:9] offset:64
	v_fmac_f32_e32 v95, v25, v25
	v_pk_mul_f32 v[92:93], v[18:19], v[18:19]
	v_pk_mul_f32 v[90:91], v[20:21], v[20:21]
	v_add_f32_e32 v92, v92, v95
	v_add_f32_e32 v92, v93, v92
	v_add_f32_e32 v90, v90, v92
	v_add_f32_e32 v95, v91, v90
	global_load_dwordx4 v[90:93], v94, s[8:9] offset:128
	v_mov_b32_e32 v96, v95
	s_nop 1
	v_permlane32_swap_b32_e32 v95, v96
	v_add_f32_e32 v99, v95, v96
	global_load_dwordx4 v[94:97], v94, s[8:9] offset:192
	v_mul_f32_e32 v98, v15, v15
	v_fmac_f32_e32 v98, v14, v14
	v_fmac_f32_e32 v98, v16, v16
	v_fmac_f32_e32 v98, v17, v17
	v_fmac_f32_e32 v98, v10, v10
	v_fmac_f32_e32 v98, v11, v11
	v_fmac_f32_e32 v98, v12, v12
	v_fmac_f32_e32 v98, v13, v13
	v_fmac_f32_e32 v98, v6, v6
	v_fmac_f32_e32 v98, v7, v7
	v_fmac_f32_e32 v98, v8, v8
	v_fmac_f32_e32 v98, v9, v9
	v_pk_mul_f32 v[104:105], v[2:3], v[2:3]
	v_pk_mul_f32 v[102:103], v[4:5], v[4:5]
	v_add_f32_e32 v98, v104, v98
	v_add_f32_e32 v98, v105, v98
	v_add_f32_e32 v98, v102, v98
	v_add_f32_e32 v98, v103, v98
	v_mov_b32_e32 v100, v98
	s_nop 1
	v_permlane32_swap_b32_e32 v98, v100
	v_add_f32_e32 v98, v98, v100
	v_mov_b32_e32 v101, v99
	v_mov_b32_e32 v100, v98
	s_nop 0
	v_permlane16_swap_b32_e32 v99, v101
	v_permlane16_swap_b32_e32 v98, v100
	v_pk_add_f32 v[98:99], v[98:99], v[100:101]
	v_mul_f32_e32 v68, v106, v68
	v_pk_fma_f32 v[66:67], v[98:99], s[10:11], v[66:67] op_sel_hi:[1,0,0]
	s_waitcnt vmcnt(3)
; template <int MODE>
; __device__ __forceinline__ void gemm_tile(const Params& P, int tm, int tn, unsigned char* smem) {
;     ...
; #pragma unroll
;                 for (int j = 0; j < 4; ++j)
; #pragma unroll
;                     for (int r = 0; r < 4; ++r) acc[i][j][r] *= rstd * gn[j][r];
	v_pk_mul_f32 v[100:101], v[82:83], v[70:71] op_sel_hi:[1,0]
	v_mul_f32_e32 v98, 0x4b800000, v67
	v_cmp_gt_f32_e32 vcc, s7, v67
	v_cmp_gt_f32_e64 s[0:1], s7, v66
	v_pk_mul_f32 v[62:63], v[62:63], v[100:101]
	v_cndmask_b32_e32 v67, v67, v98, vcc
	v_mul_f32_e32 v98, 0x4b800000, v66
	v_rsq_f32_e32 v67, v67
	v_cndmask_b32_e64 v66, v66, v98, s[0:1]
	v_rsq_f32_e32 v98, v66
	v_pk_mul_f32 v[100:101], v[82:83], v[68:69] op_sel_hi:[1,0]
	v_mul_f32_e32 v66, 0x45800000, v67
	v_cndmask_b32_e32 v66, v67, v66, vcc
	v_mul_f32_e32 v67, 0x45800000, v98
	v_cndmask_b32_e64 v67, v98, v67, s[0:1]
	v_mul_f32_e32 v66, v106, v66
	v_mul_f32_e32 v98, v106, v67
	v_pk_mul_f32 v[102:103], v[84:85], v[70:71] op_sel_hi:[1,0]
	v_pk_mul_f32 v[46:47], v[46:47], v[100:101]
	v_pk_mul_f32 v[100:101], v[82:83], v[66:67] op_sel_hi:[1,0]
	v_pk_mul_f32 v[82:83], v[82:83], v[98:99] op_sel_hi:[1,0]
	v_pk_mul_f32 v[64:65], v[64:65], v[102:103]
	v_pk_mul_f32 v[102:103], v[84:85], v[68:69] op_sel_hi:[1,0]
	v_pk_mul_f32 v[14:15], v[14:15], v[82:83]
	s_waitcnt vmcnt(2)
	v_pk_mul_f32 v[82:83], v[86:87], v[70:71] op_sel_hi:[1,0]
	v_pk_mul_f32 v[48:49], v[48:49], v[102:103]
	v_pk_mul_f32 v[102:103], v[84:85], v[66:67] op_sel_hi:[1,0]
	v_pk_mul_f32 v[84:85], v[84:85], v[98:99] op_sel_hi:[1,0]
	v_pk_mul_f32 v[58:59], v[58:59], v[82:83]
	v_pk_mul_f32 v[82:83], v[86:87], v[68:69] op_sel_hi:[1,0]
	v_pk_mul_f32 v[16:17], v[16:17], v[84:85]
	v_pk_mul_f32 v[84:85], v[88:89], v[70:71] op_sel_hi:[1,0]
	v_pk_mul_f32 v[42:43], v[42:43], v[82:83]
	v_pk_mul_f32 v[82:83], v[86:87], v[66:67] op_sel_hi:[1,0]
	v_pk_mul_f32 v[60:61], v[60:61], v[84:85]
	v_pk_mul_f32 v[84:85], v[88:89], v[68:69] op_sel_hi:[1,0]
	v_pk_mul_f32 v[26:27], v[26:27], v[82:83]
	v_pk_mul_f32 v[82:83], v[86:87], v[98:99] op_sel_hi:[1,0]
	v_pk_mul_f32 v[44:45], v[44:45], v[84:85]
	v_pk_mul_f32 v[84:85], v[88:89], v[66:67] op_sel_hi:[1,0]
	v_pk_mul_f32 v[10:11], v[10:11], v[82:83]
	s_waitcnt vmcnt(1)
	v_pk_mul_f32 v[82:83], v[90:91], v[70:71] op_sel_hi:[1,0]
	v_pk_mul_f32 v[28:29], v[28:29], v[84:85]
	v_pk_mul_f32 v[84:85], v[88:89], v[98:99] op_sel_hi:[1,0]
	v_pk_mul_f32 v[54:55], v[54:55], v[82:83]
	v_pk_mul_f32 v[82:83], v[90:91], v[68:69] op_sel_hi:[1,0]
	v_pk_mul_f32 v[12:13], v[12:13], v[84:85]
	v_pk_mul_f32 v[84:85], v[92:93], v[70:71] op_sel_hi:[1,0]
	v_pk_mul_f32 v[38:39], v[38:39], v[82:83]
	v_pk_mul_f32 v[82:83], v[90:91], v[66:67] op_sel_hi:[1,0]
	v_pk_mul_f32 v[56:57], v[56:57], v[84:85]
	v_pk_mul_f32 v[84:85], v[92:93], v[68:69] op_sel_hi:[1,0]
	v_pk_mul_f32 v[22:23], v[22:23], v[82:83]
	v_pk_mul_f32 v[82:83], v[90:91], v[98:99] op_sel_hi:[1,0]
	v_pk_mul_f32 v[40:41], v[40:41], v[84:85]
	v_pk_mul_f32 v[84:85], v[92:93], v[66:67] op_sel_hi:[1,0]
	v_pk_mul_f32 v[6:7], v[6:7], v[82:83]
	s_waitcnt vmcnt(0)
	v_pk_mul_f32 v[82:83], v[94:95], v[70:71] op_sel_hi:[1,0]
	v_pk_mul_f32 v[24:25], v[24:25], v[84:85]
	v_pk_mul_f32 v[84:85], v[92:93], v[98:99] op_sel_hi:[1,0]
	v_pk_mul_f32 v[50:51], v[50:51], v[82:83]
	v_pk_mul_f32 v[82:83], v[94:95], v[68:69] op_sel_hi:[1,0]
	v_pk_mul_f32 v[8:9], v[8:9], v[84:85]
	v_pk_mul_f32 v[84:85], v[96:97], v[70:71] op_sel_hi:[1,0]
	v_pk_mul_f32 v[34:35], v[34:35], v[82:83]
	v_pk_mul_f32 v[82:83], v[94:95], v[66:67] op_sel_hi:[1,0]
	v_pk_mul_f32 v[66:67], v[96:97], v[66:67] op_sel_hi:[1,0]
	v_pk_mul_f32 v[52:53], v[52:53], v[84:85]
	v_pk_mul_f32 v[84:85], v[96:97], v[68:69] op_sel_hi:[1,0]
	v_pk_mul_f32 v[20:21], v[20:21], v[66:67]
	v_pk_mul_f32 v[18:19], v[18:19], v[82:83]
	v_pk_mul_f32 v[66:67], v[94:95], v[98:99] op_sel_hi:[1,0]
	v_pk_mul_f32 v[82:83], v[96:97], v[98:99] op_sel_hi:[1,0]
	v_pk_mul_f32 v[32:33], v[32:33], v[102:103]
	v_pk_mul_f32 v[30:31], v[30:31], v[100:101]
	v_pk_mul_f32 v[36:37], v[36:37], v[84:85]
	v_pk_mul_f32 v[4:5], v[4:5], v[82:83]
	v_pk_mul_f32 v[2:3], v[2:3], v[66:67]

; template <int MODE>
; __device__ __forceinline__ void gemm_tile(const Params& P, int tm, int tn, unsigned char* smem) {
;     ...
;     const int tid = opaque_tid(), lane = tid & 63, wave = tid >> 6, wr = wave >> 1, wc = wave & 1, g = lane >> 4, lr = lane & 15;
;     const int m0 = tm * 128, n0 = tn * 128;
;     const int srow = tid >> 3, sc = tid & 7;
;     constexpr unsigned LDA = (MODE == 2 ? NZ : 1024) * 2u;
;     unsigned aoff, boff; int soff0;
;     {
;         int ar = m0 + srow;
;         if (MODE == 2) { const int b = ar >> 11, t = ar & 2047; ar = b * L + NMETA + t; }
;         aoff = (unsigned)ar * LDA + (unsigned)sc * 16u;
;         boff = (unsigned)(n0 + srow) * 2048u + (unsigned)sc * 16u;
;         soff0 = srow * 128 + ((sc ^ (srow & 7)) << 4);
;     }
;     const unsigned char* Ab = (const unsigned char*)A; const unsigned char* Bb = (const unsigned char*)Bt;
;     float4 ssp0, ssp1, ssp2, ssp3;
;     if (MODE == 3) {
;         const float* ssq = (const float*)(P.ws + WS_SSQ) + (size_t)(m0 + wr * 64 + lr) * 16 + 4 * g;
;         ssp0 = *(const float4*)(ssq); ssp1 = *(const float4*)(ssq + 16 * 16); ssp2 = *(const float4*)(ssq + 32 * 16); ssp3 = *(const float4*)(ssq + 48 * 16);
;     }
;     f32x4 acc[4][4];
; #pragma unroll
;     for (int i = 0; i < 4; ++i)
; #pragma unroll
;         for (int j = 0; j < 4; ++j) acc[i][j] = (f32x4){0.f, 0.f, 0.f, 0.f};
;     uint4 ra0, ra1, ra2, ra3, rb0, rb1, rb2, rb3;
;     ...
;     unsigned char* sA0 = smem; unsigned char* sB0 = smem + 16384; unsigned char* sA1 = smem + 32768; unsigned char* sB1 = smem + 49152;
;     G_LOAD(0)
;     G_WRITE(sA0, sB0)
;     __syncthreads();
;     const int arow_off = (wr * 64 + lr) * 128, brow_off = (wc * 64 + lr) * 128, sw = lr & 7;
;     G_LOAD(1)
;     for (int kt = 0; kt < 16; ++kt) {
;         unsigned char* sA = (kt & 1) ? sA1 : sA0; unsigned char* sB = (kt & 1) ? sB1 : sB0;
;         unsigned char* nA = (kt & 1) ? sA0 : sA1; unsigned char* nB = (kt & 1) ? sB0 : sB1;
;         bf16x8 fa[4], fb[4], ga[4], gb[4];
;         const int ch0 = ((g ^ sw) << 4), ch1 = (((4 + g) ^ sw) << 4);
;         const unsigned ko = (unsigned)(kt + 2) * 128u;
;         const unsigned koa = ko + ((MODE == 2 && kt + 2 >= 8) ? (unsigned)(ZC_FQ - 512) * 2u : 0u);
;         const bool wr_ok = kt < 15, ld_ok = kt < 14;
; #pragma unroll
.LBB0_241:
	s_andn2_b64 vcc, exec, s[4:5]
	s_cbranch_vccnz .LBB0_245
	s_add_i32 s14, s14, s10
	s_mul_hi_i32 s0, s14, 0x92492493
	s_add_i32 s0, s0, s14
	s_lshr_b32 s1, s0, 31
	s_ashr_i32 s0, s0, 7
	s_add_i32 s0, s0, s1
	s_mul_i32 s1, s0, 0xffffff20
	s_lshl_b32 s0, s0, 3
	s_add_i32 s1, s1, s14
	s_sub_i32 s3, 0x81, s0
	s_cmpk_gt_i32 s14, 0xdff
	s_cselect_b32 s3, s3, 8
	s_abs_i32 s4, s3
	v_cvt_f32_u32_e32 v2, s4
	s_sub_i32 s7, 0, s4
	s_abs_i32 s5, s1
	s_xor_b32 s6, s1, s3
	v_rcp_iflag_f32_e32 v2, v2
	s_ashr_i32 s6, s6, 31
	v_mov_b32_e32 v69, v0
	v_mul_f32_e32 v2, 0x4f7ffffe, v2
	v_cvt_u32_f32_e32 v2, v2
	v_lshlrev_b32_e32 v3, 4, v69
	v_and_b32_e32 v5, 0x70, v3
	v_and_b32_e32 v78, 15, v69
	v_readfirstlane_b32 s8, v2
	s_mul_i32 s7, s7, s8
	s_mul_hi_u32 s7, s8, s7
	s_add_i32 s8, s8, s7
	s_mul_hi_u32 s7, s5, s8
	s_mul_i32 s8, s7, s4
	s_sub_i32 s5, s5, s8
	s_add_i32 s9, s7, 1
	s_sub_i32 s8, s5, s4
	s_cmp_ge_u32 s5, s4
	s_cselect_b32 s7, s9, s7
	s_cselect_b32 s5, s8, s5
	s_add_i32 s8, s7, 1
	s_cmp_ge_u32 s5, s4
	s_cselect_b32 s4, s8, s7
	s_xor_b32 s4, s4, s6
	s_sub_i32 s5, s4, s6
	s_mul_i32 s3, s5, s3
	s_add_i32 s1, s1, s0
	s_sub_i32 s0, s1, s3
	s_lshl_b32 s3, s0, 7
	v_ashrrev_i32_e32 v2, 3, v69
	s_lshl_b32 s4, s5, 7
	v_add_u32_e32 v4, s3, v2
	v_add_u32_e32 v3, s4, v2
	v_lshl_or_b32 v8, v4, 11, v5
	v_lshl_or_b32 v3, v3, 11, v5
	s_add_u32 s0, s28, 0xc075800
	v_add_u32_e32 v9, 0x10000, v8
	s_addc_u32 s1, s29, 0
	v_add_u32_e32 v22, 0x20000, v8
	global_load_dwordx4 v[4:7], v9, s[36:37]
	global_load_dwordx4 v[10:13], v22, s[36:37]
	global_load_dwordx4 v[14:17], v8, s[36:37]
	global_load_dwordx4 v[18:21], v3, s[0:1]
	v_add_u32_e32 v9, 0x20000, v3
	v_add_u32_e32 v30, 0x30000, v3
	global_load_dwordx4 v[22:25], v9, s[0:1]
	global_load_dwordx4 v[26:29], v30, s[0:1]
	v_add_u32_e32 v9, 0x30000, v8
	v_add_u32_e32 v38, 0x10000, v3
	global_load_dwordx4 v[30:33], v9, s[36:37]
	global_load_dwordx4 v[34:37], v38, s[0:1]
	v_xor_b32_e32 v9, v2, v69
	s_movk_i32 s6, 0x70
	v_lshlrev_b32_e32 v2, 7, v2
	v_lshlrev_b32_e32 v9, 4, v9
	v_and_or_b32 v2, v9, s6, v2
	v_add_u32_e32 v2, 0, v2
	v_or_b32_e32 v45, 0x80, v8
	v_or_b32_e32 v9, 0x80, v3
	v_add_u32_e32 v42, 0x10080, v3
	v_add_u32_e32 v43, 0x20080, v3
	v_add_u32_e32 v44, 0x30080, v3
	v_add_u32_e32 v46, 0x10080, v8
	v_add_u32_e32 v47, 0x20080, v8
	v_add_u32_e32 v48, 0x30080, v8
	v_ashrrev_i32_e32 v79, 7, v69
	v_bfe_u32 v80, v69, 6, 1
	v_bfe_u32 v81, v69, 4, 2
	s_waitcnt vmcnt(5)
	ds_write_b128 v2, v[14:17]
	s_waitcnt vmcnt(4)
	ds_write_b128 v2, v[18:21] offset:16384
	s_waitcnt vmcnt(3)
	ds_write_b128 v2, v[22:25] offset:24576
	s_waitcnt vmcnt(2)
	ds_write_b128 v2, v[26:29] offset:28672
	ds_write_b128 v2, v[4:7] offset:4096
	ds_write_b128 v2, v[10:13] offset:8192
	s_waitcnt vmcnt(1)
	ds_write_b128 v2, v[30:33] offset:12288
	s_waitcnt vmcnt(0)
	ds_write_b128 v2, v[34:37] offset:20480
	s_waitcnt lgkmcnt(0)
	s_barrier
	global_load_dwordx4 v[10:13], v45, s[36:37]
	global_load_dwordx4 v[14:17], v46, s[36:37]
	global_load_dwordx4 v[18:21], v47, s[36:37]
	global_load_dwordx4 v[22:25], v48, s[36:37]
	global_load_dwordx4 v[26:29], v9, s[0:1]
	global_load_dwordx4 v[30:33], v42, s[0:1]
	global_load_dwordx4 v[34:37], v43, s[0:1]
	global_load_dwordx4 v[38:41], v44, s[0:1]
	v_lshrrev_b32_e32 v4, 4, v69
	v_lshlrev_b32_e32 v5, 7, v78
	v_and_b32_e32 v9, 7, v69
	v_lshl_or_b32 v6, v79, 13, v5
	v_bitop3_b32 v4, v4, v9, 3 bitop3:0x6c
	v_lshl_or_b32 v5, v80, 13, v5
	v_lshlrev_b32_e32 v4, 4, v4
	v_add_u32_e32 v66, 0, v6
	v_add_u32_e32 v6, v66, v4
	v_add_u32_e32 v5, 0, v5
	v_add_u32_e32 v7, v5, v4
	ds_read_b128 v[42:45], v6
	ds_read_b128 v[46:49], v6 offset:2048
	ds_read_b128 v[50:53], v7 offset:16384
	ds_read_b128 v[54:57], v7 offset:18432
	ds_read_b128 v[58:61], v6 offset:4096
	ds_read_b128 v[62:65], v6 offset:6144
	ds_read_b128 v[82:85], v7 offset:20480
	ds_read_b128 v[86:89], v7 offset:22528
	v_bitop3_b32 v4, v81, v9, 4 bitop3:0x36
	v_lshlrev_b32_e32 v9, 4, v4
	s_setprio 2
	global_load_dwordx4 v[90:93], v8, s[36:37] offset:256
	s_waitcnt vmcnt(7)
	ds_write_b128 v2, v[10:13] offset:32768
	v_add_u32_e32 v4, v66, v9
	v_add_u32_e32 v5, v5, v9
	ds_read_b128 v[10:13], v4
	ds_read_b128 v[94:97], v5 offset:16384
	s_waitcnt lgkmcnt(8)
	v_mfma_f32_16x16x32_bf16 v[98:101], v[50:53], v[42:45], 0
	s_waitcnt lgkmcnt(7)
	v_mfma_f32_16x16x32_bf16 v[102:105], v[54:57], v[42:45], 0
	s_waitcnt lgkmcnt(4)
	v_mfma_f32_16x16x32_bf16 v[106:109], v[82:85], v[42:45], 0
	s_waitcnt lgkmcnt(3)
	v_mfma_f32_16x16x32_bf16 v[42:45], v[86:89], v[42:45], 0
	v_add_u32_e32 v228, 0x10000, v8
	global_load_dwordx4 v[110:113], v228, s[36:37] offset:256
	ds_write_b128 v2, v[14:17] offset:36864
	ds_read_b128 v[14:17], v4 offset:2048
	ds_read_b128 v[114:117], v5 offset:18432
	v_mfma_f32_16x16x32_bf16 v[118:121], v[50:53], v[46:49], 0
	v_mfma_f32_16x16x32_bf16 v[122:125], v[54:57], v[46:49], 0
	v_mfma_f32_16x16x32_bf16 v[126:129], v[82:85], v[46:49], 0
	v_mfma_f32_16x16x32_bf16 v[46:49], v[86:89], v[46:49], 0
	v_add_u32_e32 v229, 0x20000, v8
	global_load_dwordx4 v[132:135], v229, s[36:37] offset:256
	s_waitcnt vmcnt(7)
	ds_write_b128 v2, v[18:21] offset:40960
	ds_read_b128 v[18:21], v4 offset:4096
	ds_read_b128 v[146:149], v5 offset:20480
	v_mfma_f32_16x16x32_bf16 v[150:153], v[50:53], v[58:61], 0
	v_mfma_f32_16x16x32_bf16 v[154:157], v[54:57], v[58:61], 0
	v_mfma_f32_16x16x32_bf16 v[158:161], v[82:85], v[58:61], 0
	v_mfma_f32_16x16x32_bf16 v[58:61], v[86:89], v[58:61], 0
	v_add_u32_e32 v230, 0x30000, v8
	global_load_dwordx4 v[162:165], v230, s[36:37] offset:256
	ds_write_b128 v2, v[22:25] offset:45056
	ds_read_b128 v[22:25], v4 offset:6144
	ds_read_b128 v[166:169], v5 offset:22528
	v_mfma_f32_16x16x32_bf16 v[50:53], v[50:53], v[62:65], 0
	v_mfma_f32_16x16x32_bf16 v[54:57], v[54:57], v[62:65], 0
	v_mfma_f32_16x16x32_bf16 v[82:85], v[82:85], v[62:65], 0
	v_mfma_f32_16x16x32_bf16 v[62:65], v[86:89], v[62:65], 0
	global_load_dwordx4 v[86:89], v3, s[0:1] offset:256
	s_waitcnt vmcnt(7)
; template <int MODE>
; __device__ __forceinline__ void gemm_tile(const Params& P, int tm, int tn, unsigned char* smem) {
;     ...
; #pragma unroll
;         for (int i = 0; i < 4; ++i) { fa[i] = *(const bf16x8*)(sA + arow_off + i * 2048 + ch0); fb[i] = *(const bf16x8*)(sB + brow_off + i * 2048 + ch0); }
;         __builtin_amdgcn_sched_barrier(0);
;         __builtin_amdgcn_s_setprio(2);
;         if (wr_ok) *(uint4*)(nA + soff0) = ra0;
;         if (ld_ok) ra0 = *(const uint4*)(Ab + (aoff + 0u * LDA + koa));
;         ga[0] = *(const bf16x8*)(sA + arow_off + 0 * 2048 + ch1); gb[0] = *(const bf16x8*)(sB + brow_off + 0 * 2048 + ch1);
;         __builtin_amdgcn_sched_barrier(0);
; #pragma unroll
;         for (int j = 0; j < 4; ++j) acc[0][j] = __builtin_amdgcn_mfma_f32_16x16x32_bf16(fb[j], fa[0], acc[0][j], 0, 0, 0);
;         __builtin_amdgcn_sched_barrier(0);
;         if (wr_ok) *(uint4*)(nA + soff0 + 4096) = ra1;
;         if (ld_ok) ra1 = *(const uint4*)(Ab + (aoff + 32u * LDA + koa));
;         ga[1] = *(const bf16x8*)(sA + arow_off + 1 * 2048 + ch1); gb[1] = *(const bf16x8*)(sB + brow_off + 1 * 2048 + ch1);
;         __builtin_amdgcn_sched_barrier(0);
; #pragma unroll
;         for (int j = 0; j < 4; ++j) acc[1][j] = __builtin_amdgcn_mfma_f32_16x16x32_bf16(fb[j], fa[1], acc[1][j], 0, 0, 0);
;         __builtin_amdgcn_sched_barrier(0);
;         if (wr_ok) *(uint4*)(nA + soff0 + 8192) = ra2;
;         if (ld_ok) ra2 = *(const uint4*)(Ab + (aoff + 64u * LDA + koa));
;         ga[2] = *(const bf16x8*)(sA + arow_off + 2 * 2048 + ch1); gb[2] = *(const bf16x8*)(sB + brow_off + 2 * 2048 + ch1);
;         __builtin_amdgcn_sched_barrier(0);
; #pragma unroll
;         for (int j = 0; j < 4; ++j) acc[2][j] = __builtin_amdgcn_mfma_f32_16x16x32_bf16(fb[j], fa[2], acc[2][j], 0, 0, 0);
;         __builtin_amdgcn_sched_barrier(0);
;         if (wr_ok) *(uint4*)(nA + soff0 + 12288) = ra3;
;         if (ld_ok) ra3 = *(const uint4*)(Ab + (aoff + 96u * LDA + koa));
;         ga[3] = *(const bf16x8*)(sA + arow_off + 3 * 2048 + ch1); gb[3] = *(const bf16x8*)(sB + brow_off + 3 * 2048 + ch1);
;         __builtin_amdgcn_sched_barrier(0);
; #pragma unroll
;         for (int j = 0; j < 4; ++j) acc[3][j] = __builtin_amdgcn_mfma_f32_16x16x32_bf16(fb[j], fa[3], acc[3][j], 0, 0, 0);
;         __builtin_amdgcn_sched_barrier(0);
;         if (wr_ok) *(uint4*)(nB + soff0) = rb0;
	ds_write_b128 v2, v[26:29] offset:49152
	s_waitcnt lgkmcnt(10)
	v_mfma_f32_16x16x32_bf16 v[26:29], v[94:97], v[10:13], v[98:101]
	s_waitcnt lgkmcnt(7)
	v_mfma_f32_16x16x32_bf16 v[98:101], v[114:117], v[10:13], v[102:105]
	s_waitcnt lgkmcnt(4)
	v_mfma_f32_16x16x32_bf16 v[102:105], v[146:149], v[10:13], v[106:109]
	s_waitcnt lgkmcnt(1)
	v_mfma_f32_16x16x32_bf16 v[10:13], v[166:169], v[10:13], v[42:45]
	v_add_u32_e32 v231, 0x10000, v3
	global_load_dwordx4 v[42:45], v231, s[0:1] offset:256
	ds_write_b128 v2, v[30:33] offset:53248
	v_mfma_f32_16x16x32_bf16 v[30:33], v[94:97], v[14:17], v[118:121]
	v_mfma_f32_16x16x32_bf16 v[106:109], v[114:117], v[14:17], v[122:125]
	v_mfma_f32_16x16x32_bf16 v[118:121], v[146:149], v[14:17], v[126:129]
	v_mfma_f32_16x16x32_bf16 v[14:17], v[166:169], v[14:17], v[46:49]
	v_add_u32_e32 v232, 0x20000, v3
	global_load_dwordx4 v[46:49], v232, s[0:1] offset:256
	s_waitcnt vmcnt(7)
	ds_write_b128 v2, v[34:37] offset:57344
	v_mfma_f32_16x16x32_bf16 v[34:37], v[94:97], v[18:21], v[150:153]
	v_mfma_f32_16x16x32_bf16 v[122:125], v[114:117], v[18:21], v[154:157]
	v_mfma_f32_16x16x32_bf16 v[126:129], v[146:149], v[18:21], v[158:161]
	v_mfma_f32_16x16x32_bf16 v[18:21], v[166:169], v[18:21], v[58:61]
	v_add_u32_e32 v233, 0x30000, v3
	global_load_dwordx4 v[58:61], v233, s[0:1] offset:256
	ds_write_b128 v2, v[38:41] offset:61440
	v_mfma_f32_16x16x32_bf16 v[38:41], v[94:97], v[22:25], v[50:53]
	v_mfma_f32_16x16x32_bf16 v[50:53], v[114:117], v[22:25], v[54:57]
	v_mfma_f32_16x16x32_bf16 v[54:57], v[146:149], v[22:25], v[82:85]
	v_mfma_f32_16x16x32_bf16 v[22:25], v[166:169], v[22:25], v[62:65]
	s_setprio 0
	s_waitcnt lgkmcnt(0)
	s_barrier
	ds_read_b128 v[62:65], v6 offset:32768
	ds_read_b128 v[82:85], v6 offset:34816
	ds_read_b128 v[94:97], v7 offset:49152
	ds_read_b128 v[114:117], v7 offset:51200
	ds_read_b128 v[146:149], v6 offset:36864
	ds_read_b128 v[150:153], v6 offset:38912
	ds_read_b128 v[154:157], v7 offset:53248
	ds_read_b128 v[158:161], v7 offset:55296
	s_setprio 2
	global_load_dwordx4 v[166:169], v8, s[36:37] offset:384
	s_waitcnt vmcnt(7)
	ds_write_b128 v2, v[90:93]
	ds_read_b128 v[90:93], v4 offset:32768
	ds_read_b128 v[170:173], v5 offset:49152
	s_waitcnt lgkmcnt(8)
	v_mfma_f32_16x16x32_bf16 v[26:29], v[94:97], v[62:65], v[26:29]
	s_waitcnt lgkmcnt(3)
	v_mfma_f32_16x16x32_bf16 v[10:13], v[158:161], v[62:65], v[10:13]
	v_mfma_f32_16x16x32_bf16 v[98:101], v[114:117], v[62:65], v[98:101]
	v_mfma_f32_16x16x32_bf16 v[102:105], v[154:157], v[62:65], v[102:105]
	global_load_dwordx4 v[62:65], v228, s[36:37] offset:384
	ds_write_b128 v2, v[110:113] offset:4096
	ds_read_b128 v[110:113], v4 offset:34816
	ds_read_b128 v[174:177], v5 offset:51200
	v_mfma_f32_16x16x32_bf16 v[30:33], v[94:97], v[82:85], v[30:33]
	v_mfma_f32_16x16x32_bf16 v[14:17], v[158:161], v[82:85], v[14:17]
	v_mfma_f32_16x16x32_bf16 v[106:109], v[114:117], v[82:85], v[106:109]
	v_mfma_f32_16x16x32_bf16 v[118:121], v[154:157], v[82:85], v[118:121]
	global_load_dwordx4 v[82:85], v229, s[36:37] offset:384
	s_waitcnt vmcnt(7)
	ds_write_b128 v2, v[132:135] offset:8192
	ds_read_b128 v[132:135], v4 offset:36864
	ds_read_b128 v[178:181], v5 offset:53248
	v_mfma_f32_16x16x32_bf16 v[34:37], v[94:97], v[146:149], v[34:37]
	v_mfma_f32_16x16x32_bf16 v[18:21], v[158:161], v[146:149], v[18:21]
	v_mfma_f32_16x16x32_bf16 v[122:125], v[114:117], v[146:149], v[122:125]
	v_mfma_f32_16x16x32_bf16 v[126:129], v[154:157], v[146:149], v[126:129]
	global_load_dwordx4 v[146:149], v230, s[36:37] offset:384
	ds_write_b128 v2, v[162:165] offset:12288
	ds_read_b128 v[162:165], v4 offset:38912
	ds_read_b128 v[182:185], v5 offset:55296
	v_mfma_f32_16x16x32_bf16 v[38:41], v[94:97], v[150:153], v[38:41]
	v_mfma_f32_16x16x32_bf16 v[50:53], v[114:117], v[150:153], v[50:53]
	v_mfma_f32_16x16x32_bf16 v[54:57], v[154:157], v[150:153], v[54:57]
	v_mfma_f32_16x16x32_bf16 v[22:25], v[158:161], v[150:153], v[22:25]
	global_load_dwordx4 v[94:97], v3, s[0:1] offset:384
	s_waitcnt vmcnt(7)
	ds_write_b128 v2, v[86:89] offset:16384
	s_waitcnt lgkmcnt(10)
	v_mfma_f32_16x16x32_bf16 v[26:29], v[170:173], v[90:93], v[26:29]
	s_waitcnt lgkmcnt(1)
	v_mfma_f32_16x16x32_bf16 v[10:13], v[182:185], v[90:93], v[10:13]
	v_mfma_f32_16x16x32_bf16 v[86:89], v[174:177], v[90:93], v[98:101]
	v_mfma_f32_16x16x32_bf16 v[98:101], v[178:181], v[90:93], v[102:105]
	global_load_dwordx4 v[90:93], v231, s[0:1] offset:384
	ds_write_b128 v2, v[42:45] offset:20480
	v_mfma_f32_16x16x32_bf16 v[30:33], v[170:173], v[110:113], v[30:33]
	v_mfma_f32_16x16x32_bf16 v[42:45], v[174:177], v[110:113], v[106:109]
	v_mfma_f32_16x16x32_bf16 v[14:17], v[182:185], v[110:113], v[14:17]
	v_mfma_f32_16x16x32_bf16 v[102:105], v[178:181], v[110:113], v[118:121]
	global_load_dwordx4 v[106:109], v232, s[0:1] offset:384
	s_waitcnt vmcnt(7)
	ds_write_b128 v2, v[46:49] offset:24576
	v_mfma_f32_16x16x32_bf16 v[34:37], v[170:173], v[132:135], v[34:37]
	v_mfma_f32_16x16x32_bf16 v[46:49], v[174:177], v[132:135], v[122:125]
	v_mfma_f32_16x16x32_bf16 v[18:21], v[182:185], v[132:135], v[18:21]
	v_mfma_f32_16x16x32_bf16 v[110:113], v[178:181], v[132:135], v[126:129]
	global_load_dwordx4 v[114:117], v233, s[0:1] offset:384
	ds_write_b128 v2, v[58:61] offset:28672
	v_mfma_f32_16x16x32_bf16 v[38:41], v[170:173], v[162:165], v[38:41]
	v_mfma_f32_16x16x32_bf16 v[50:53], v[174:177], v[162:165], v[50:53]
	v_mfma_f32_16x16x32_bf16 v[54:57], v[178:181], v[162:165], v[54:57]
	v_mfma_f32_16x16x32_bf16 v[22:25], v[182:185], v[162:165], v[22:25]
	s_setprio 0
	s_waitcnt lgkmcnt(0)
	s_barrier
; template <int MODE>
; __device__ __forceinline__ void gemm_tile(const Params& P, int tm, int tn, unsigned char* smem) {
;     ...
; #pragma unroll
;         for (int i = 0; i < 4; ++i) { fa[i] = *(const bf16x8*)(sA + arow_off + i * 2048 + ch0); fb[i] = *(const bf16x8*)(sB + brow_off + i * 2048 + ch0); }
;         __builtin_amdgcn_sched_barrier(0);
;         __builtin_amdgcn_s_setprio(2);
;         if (wr_ok) *(uint4*)(nA + soff0) = ra0;
;         if (ld_ok) ra0 = *(const uint4*)(Ab + (aoff + 0u * LDA + koa));
;         ga[0] = *(const bf16x8*)(sA + arow_off + 0 * 2048 + ch1); gb[0] = *(const bf16x8*)(sB + brow_off + 0 * 2048 + ch1);
;         __builtin_amdgcn_sched_barrier(0);
; #pragma unroll
;         for (int j = 0; j < 4; ++j) acc[0][j] = __builtin_amdgcn_mfma_f32_16x16x32_bf16(fb[j], fa[0], acc[0][j], 0, 0, 0);
;         __builtin_amdgcn_sched_barrier(0);
;         if (wr_ok) *(uint4*)(nA + soff0 + 4096) = ra1;
;         if (ld_ok) ra1 = *(const uint4*)(Ab + (aoff + 32u * LDA + koa));
;         ga[1] = *(const bf16x8*)(sA + arow_off + 1 * 2048 + ch1); gb[1] = *(const bf16x8*)(sB + brow_off + 1 * 2048 + ch1);
;         __builtin_amdgcn_sched_barrier(0);
; #pragma unroll
;         for (int j = 0; j < 4; ++j) acc[1][j] = __builtin_amdgcn_mfma_f32_16x16x32_bf16(fb[j], fa[1], acc[1][j], 0, 0, 0);
;         __builtin_amdgcn_sched_barrier(0);
;         if (wr_ok) *(uint4*)(nA + soff0 + 8192) = ra2;
;         if (ld_ok) ra2 = *(const uint4*)(Ab + (aoff + 64u * LDA + koa));
;         ga[2] = *(const bf16x8*)(sA + arow_off + 2 * 2048 + ch1); gb[2] = *(const bf16x8*)(sB + brow_off + 2 * 2048 + ch1);
;         __builtin_amdgcn_sched_barrier(0);
; #pragma unroll
;         for (int j = 0; j < 4; ++j) acc[2][j] = __builtin_amdgcn_mfma_f32_16x16x32_bf16(fb[j], fa[2], acc[2][j], 0, 0, 0);
;         __builtin_amdgcn_sched_barrier(0);
;         if (wr_ok) *(uint4*)(nA + soff0 + 12288) = ra3;
;         if (ld_ok) ra3 = *(const uint4*)(Ab + (aoff + 96u * LDA + koa));
;         ga[3] = *(const bf16x8*)(sA + arow_off + 3 * 2048 + ch1); gb[3] = *(const bf16x8*)(sB + brow_off + 3 * 2048 + ch1);
;         __builtin_amdgcn_sched_barrier(0);
; #pragma unroll
;         for (int j = 0; j < 4; ++j) acc[3][j] = __builtin_amdgcn_mfma_f32_16x16x32_bf16(fb[j], fa[3], acc[3][j], 0, 0, 0);
;         __builtin_amdgcn_sched_barrier(0);
;         if (wr_ok) *(uint4*)(nB + soff0) = rb0;
	ds_read_b128 v[58:61], v6
	ds_read_b128 v[118:121], v6 offset:2048
	ds_read_b128 v[122:125], v7 offset:16384
	ds_read_b128 v[126:129], v7 offset:18432
	ds_read_b128 v[132:135], v6 offset:4096
	ds_read_b128 v[150:153], v6 offset:6144
	ds_read_b128 v[154:157], v7 offset:20480
	ds_read_b128 v[158:161], v7 offset:22528
	s_setprio 2
	global_load_dwordx4 v[162:165], v8, s[36:37] offset:512
	s_waitcnt vmcnt(7)
	ds_write_b128 v2, v[166:169] offset:32768
	ds_read_b128 v[166:169], v4
	ds_read_b128 v[170:173], v5 offset:16384
	s_waitcnt lgkmcnt(8)
	v_mfma_f32_16x16x32_bf16 v[26:29], v[122:125], v[58:61], v[26:29]
	s_waitcnt lgkmcnt(3)
	v_mfma_f32_16x16x32_bf16 v[10:13], v[158:161], v[58:61], v[10:13]
	v_mfma_f32_16x16x32_bf16 v[86:89], v[126:129], v[58:61], v[86:89]
	v_mfma_f32_16x16x32_bf16 v[98:101], v[154:157], v[58:61], v[98:101]
	global_load_dwordx4 v[58:61], v228, s[36:37] offset:512
	ds_write_b128 v2, v[62:65] offset:36864
	ds_read_b128 v[62:65], v4 offset:2048
	ds_read_b128 v[174:177], v5 offset:18432
	v_mfma_f32_16x16x32_bf16 v[30:33], v[122:125], v[118:121], v[30:33]
	v_mfma_f32_16x16x32_bf16 v[42:45], v[126:129], v[118:121], v[42:45]
	v_mfma_f32_16x16x32_bf16 v[14:17], v[158:161], v[118:121], v[14:17]
	v_mfma_f32_16x16x32_bf16 v[102:105], v[154:157], v[118:121], v[102:105]
	global_load_dwordx4 v[118:121], v229, s[36:37] offset:512
	s_waitcnt vmcnt(7)
	ds_write_b128 v2, v[82:85] offset:40960
	ds_read_b128 v[82:85], v4 offset:4096
	ds_read_b128 v[178:181], v5 offset:20480
	v_mfma_f32_16x16x32_bf16 v[34:37], v[122:125], v[132:135], v[34:37]
	v_mfma_f32_16x16x32_bf16 v[46:49], v[126:129], v[132:135], v[46:49]
	v_mfma_f32_16x16x32_bf16 v[18:21], v[158:161], v[132:135], v[18:21]
	v_mfma_f32_16x16x32_bf16 v[110:113], v[154:157], v[132:135], v[110:113]
	global_load_dwordx4 v[132:135], v230, s[36:37] offset:512
	ds_write_b128 v2, v[146:149] offset:45056
	ds_read_b128 v[146:149], v4 offset:6144
	ds_read_b128 v[182:185], v5 offset:22528
	v_mfma_f32_16x16x32_bf16 v[38:41], v[122:125], v[150:153], v[38:41]
	v_mfma_f32_16x16x32_bf16 v[50:53], v[126:129], v[150:153], v[50:53]
	v_mfma_f32_16x16x32_bf16 v[54:57], v[154:157], v[150:153], v[54:57]
	v_mfma_f32_16x16x32_bf16 v[22:25], v[158:161], v[150:153], v[22:25]
	global_load_dwordx4 v[122:125], v3, s[0:1] offset:512
	s_waitcnt vmcnt(7)
	ds_write_b128 v2, v[94:97] offset:49152
	s_waitcnt lgkmcnt(10)
	v_mfma_f32_16x16x32_bf16 v[26:29], v[170:173], v[166:169], v[26:29]
	s_waitcnt lgkmcnt(1)
	v_mfma_f32_16x16x32_bf16 v[10:13], v[182:185], v[166:169], v[10:13]
	v_mfma_f32_16x16x32_bf16 v[86:89], v[174:177], v[166:169], v[86:89]
	v_mfma_f32_16x16x32_bf16 v[94:97], v[178:181], v[166:169], v[98:101]
	global_load_dwordx4 v[98:101], v231, s[0:1] offset:512
	ds_write_b128 v2, v[90:93] offset:53248
	v_mfma_f32_16x16x32_bf16 v[30:33], v[170:173], v[62:65], v[30:33]
	v_mfma_f32_16x16x32_bf16 v[42:45], v[174:177], v[62:65], v[42:45]
	v_mfma_f32_16x16x32_bf16 v[14:17], v[182:185], v[62:65], v[14:17]
	v_mfma_f32_16x16x32_bf16 v[90:93], v[178:181], v[62:65], v[102:105]
	global_load_dwordx4 v[62:65], v232, s[0:1] offset:512
	s_waitcnt vmcnt(7)
	ds_write_b128 v2, v[106:109] offset:57344
	v_mfma_f32_16x16x32_bf16 v[34:37], v[170:173], v[82:85], v[34:37]
	v_mfma_f32_16x16x32_bf16 v[46:49], v[174:177], v[82:85], v[46:49]
	v_mfma_f32_16x16x32_bf16 v[18:21], v[182:185], v[82:85], v[18:21]
	v_mfma_f32_16x16x32_bf16 v[102:105], v[178:181], v[82:85], v[110:113]
	global_load_dwordx4 v[82:85], v233, s[0:1] offset:512
	ds_write_b128 v2, v[114:117] offset:61440
	v_mfma_f32_16x16x32_bf16 v[38:41], v[170:173], v[146:149], v[38:41]
	v_mfma_f32_16x16x32_bf16 v[50:53], v[174:177], v[146:149], v[50:53]
	v_mfma_f32_16x16x32_bf16 v[54:57], v[178:181], v[146:149], v[54:57]
	v_mfma_f32_16x16x32_bf16 v[22:25], v[182:185], v[146:149], v[22:25]
	s_setprio 0
	s_waitcnt lgkmcnt(0)
	s_barrier
	ds_read_b128 v[106:109], v6 offset:32768
	ds_read_b128 v[110:113], v6 offset:34816
	ds_read_b128 v[114:117], v7 offset:49152
	ds_read_b128 v[126:129], v7 offset:51200
	ds_read_b128 v[146:149], v6 offset:36864
	ds_read_b128 v[150:153], v6 offset:38912
	ds_read_b128 v[154:157], v7 offset:53248
	ds_read_b128 v[158:161], v7 offset:55296
	s_setprio 2
	global_load_dwordx4 v[166:169], v8, s[36:37] offset:640
	s_waitcnt vmcnt(7)
	ds_write_b128 v2, v[162:165]
	ds_read_b128 v[162:165], v4 offset:32768
	ds_read_b128 v[170:173], v5 offset:49152
	s_waitcnt lgkmcnt(8)
	v_mfma_f32_16x16x32_bf16 v[26:29], v[114:117], v[106:109], v[26:29]
	s_waitcnt lgkmcnt(3)
	v_mfma_f32_16x16x32_bf16 v[10:13], v[158:161], v[106:109], v[10:13]
	v_mfma_f32_16x16x32_bf16 v[86:89], v[126:129], v[106:109], v[86:89]
	v_mfma_f32_16x16x32_bf16 v[94:97], v[154:157], v[106:109], v[94:97]
	global_load_dwordx4 v[106:109], v228, s[36:37] offset:640
	ds_write_b128 v2, v[58:61] offset:4096
	ds_read_b128 v[58:61], v4 offset:34816
	ds_read_b128 v[174:177], v5 offset:51200
	v_mfma_f32_16x16x32_bf16 v[30:33], v[114:117], v[110:113], v[30:33]
	v_mfma_f32_16x16x32_bf16 v[42:45], v[126:129], v[110:113], v[42:45]
	v_mfma_f32_16x16x32_bf16 v[14:17], v[158:161], v[110:113], v[14:17]
	v_mfma_f32_16x16x32_bf16 v[90:93], v[154:157], v[110:113], v[90:93]
	global_load_dwordx4 v[110:113], v229, s[36:37] offset:640
	s_waitcnt vmcnt(7)
; template <int MODE>
; __device__ __forceinline__ void gemm_tile(const Params& P, int tm, int tn, unsigned char* smem) {
;     ...
; #pragma unroll
;         for (int i = 0; i < 4; ++i) { fa[i] = *(const bf16x8*)(sA + arow_off + i * 2048 + ch0); fb[i] = *(const bf16x8*)(sB + brow_off + i * 2048 + ch0); }
;         __builtin_amdgcn_sched_barrier(0);
;         __builtin_amdgcn_s_setprio(2);
;         if (wr_ok) *(uint4*)(nA + soff0) = ra0;
;         if (ld_ok) ra0 = *(const uint4*)(Ab + (aoff + 0u * LDA + koa));
;         ga[0] = *(const bf16x8*)(sA + arow_off + 0 * 2048 + ch1); gb[0] = *(const bf16x8*)(sB + brow_off + 0 * 2048 + ch1);
;         __builtin_amdgcn_sched_barrier(0);
; #pragma unroll
;         for (int j = 0; j < 4; ++j) acc[0][j] = __builtin_amdgcn_mfma_f32_16x16x32_bf16(fb[j], fa[0], acc[0][j], 0, 0, 0);
;         __builtin_amdgcn_sched_barrier(0);
;         if (wr_ok) *(uint4*)(nA + soff0 + 4096) = ra1;
;         if (ld_ok) ra1 = *(const uint4*)(Ab + (aoff + 32u * LDA + koa));
;         ga[1] = *(const bf16x8*)(sA + arow_off + 1 * 2048 + ch1); gb[1] = *(const bf16x8*)(sB + brow_off + 1 * 2048 + ch1);
;         __builtin_amdgcn_sched_barrier(0);
; #pragma unroll
;         for (int j = 0; j < 4; ++j) acc[1][j] = __builtin_amdgcn_mfma_f32_16x16x32_bf16(fb[j], fa[1], acc[1][j], 0, 0, 0);
;         __builtin_amdgcn_sched_barrier(0);
;         if (wr_ok) *(uint4*)(nA + soff0 + 8192) = ra2;
;         if (ld_ok) ra2 = *(const uint4*)(Ab + (aoff + 64u * LDA + koa));
;         ga[2] = *(const bf16x8*)(sA + arow_off + 2 * 2048 + ch1); gb[2] = *(const bf16x8*)(sB + brow_off + 2 * 2048 + ch1);
;         __builtin_amdgcn_sched_barrier(0);
; #pragma unroll
;         for (int j = 0; j < 4; ++j) acc[2][j] = __builtin_amdgcn_mfma_f32_16x16x32_bf16(fb[j], fa[2], acc[2][j], 0, 0, 0);
;         __builtin_amdgcn_sched_barrier(0);
;         if (wr_ok) *(uint4*)(nA + soff0 + 12288) = ra3;
;         if (ld_ok) ra3 = *(const uint4*)(Ab + (aoff + 96u * LDA + koa));
;         ga[3] = *(const bf16x8*)(sA + arow_off + 3 * 2048 + ch1); gb[3] = *(const bf16x8*)(sB + brow_off + 3 * 2048 + ch1);
;         __builtin_amdgcn_sched_barrier(0);
; #pragma unroll
;         for (int j = 0; j < 4; ++j) acc[3][j] = __builtin_amdgcn_mfma_f32_16x16x32_bf16(fb[j], fa[3], acc[3][j], 0, 0, 0);
;         __builtin_amdgcn_sched_barrier(0);
;         if (wr_ok) *(uint4*)(nB + soff0) = rb0;
	ds_write_b128 v2, v[118:121] offset:8192
	ds_read_b128 v[118:121], v4 offset:36864
	ds_read_b128 v[178:181], v5 offset:53248
	v_mfma_f32_16x16x32_bf16 v[34:37], v[114:117], v[146:149], v[34:37]
	v_mfma_f32_16x16x32_bf16 v[46:49], v[126:129], v[146:149], v[46:49]
	v_mfma_f32_16x16x32_bf16 v[18:21], v[158:161], v[146:149], v[18:21]
	v_mfma_f32_16x16x32_bf16 v[102:105], v[154:157], v[146:149], v[102:105]
	global_load_dwordx4 v[146:149], v230, s[36:37] offset:640
	ds_write_b128 v2, v[132:135] offset:12288
	ds_read_b128 v[132:135], v4 offset:38912
	ds_read_b128 v[182:185], v5 offset:55296
	v_mfma_f32_16x16x32_bf16 v[38:41], v[114:117], v[150:153], v[38:41]
	v_mfma_f32_16x16x32_bf16 v[50:53], v[126:129], v[150:153], v[50:53]
	v_mfma_f32_16x16x32_bf16 v[54:57], v[154:157], v[150:153], v[54:57]
	v_mfma_f32_16x16x32_bf16 v[22:25], v[158:161], v[150:153], v[22:25]
	global_load_dwordx4 v[114:117], v3, s[0:1] offset:640
	s_waitcnt vmcnt(7)
	ds_write_b128 v2, v[122:125] offset:16384
	s_waitcnt lgkmcnt(10)
	v_mfma_f32_16x16x32_bf16 v[26:29], v[170:173], v[162:165], v[26:29]
	s_waitcnt lgkmcnt(1)
	v_mfma_f32_16x16x32_bf16 v[10:13], v[182:185], v[162:165], v[10:13]
	v_mfma_f32_16x16x32_bf16 v[86:89], v[174:177], v[162:165], v[86:89]
	v_mfma_f32_16x16x32_bf16 v[94:97], v[178:181], v[162:165], v[94:97]
	global_load_dwordx4 v[122:125], v231, s[0:1] offset:640
	ds_write_b128 v2, v[98:101] offset:20480
	v_mfma_f32_16x16x32_bf16 v[30:33], v[170:173], v[58:61], v[30:33]
	v_mfma_f32_16x16x32_bf16 v[42:45], v[174:177], v[58:61], v[42:45]
	v_mfma_f32_16x16x32_bf16 v[14:17], v[182:185], v[58:61], v[14:17]
	v_mfma_f32_16x16x32_bf16 v[90:93], v[178:181], v[58:61], v[90:93]
	global_load_dwordx4 v[58:61], v232, s[0:1] offset:640
	s_waitcnt vmcnt(7)
	ds_write_b128 v2, v[62:65] offset:24576
	v_mfma_f32_16x16x32_bf16 v[34:37], v[170:173], v[118:121], v[34:37]
	v_mfma_f32_16x16x32_bf16 v[46:49], v[174:177], v[118:121], v[46:49]
	v_mfma_f32_16x16x32_bf16 v[62:65], v[178:181], v[118:121], v[102:105]
	v_mfma_f32_16x16x32_bf16 v[18:21], v[182:185], v[118:121], v[18:21]
	global_load_dwordx4 v[98:101], v233, s[0:1] offset:640
	ds_write_b128 v2, v[82:85] offset:28672
	v_mfma_f32_16x16x32_bf16 v[38:41], v[170:173], v[132:135], v[38:41]
	v_mfma_f32_16x16x32_bf16 v[50:53], v[174:177], v[132:135], v[50:53]
	v_mfma_f32_16x16x32_bf16 v[54:57], v[178:181], v[132:135], v[54:57]
	v_mfma_f32_16x16x32_bf16 v[22:25], v[182:185], v[132:135], v[22:25]
	s_setprio 0
	s_waitcnt lgkmcnt(0)
	s_barrier
	ds_read_b128 v[82:85], v6
	ds_read_b128 v[102:105], v6 offset:2048
	ds_read_b128 v[118:121], v7 offset:16384
	ds_read_b128 v[126:129], v7 offset:18432
	ds_read_b128 v[132:135], v6 offset:4096
	ds_read_b128 v[150:153], v6 offset:6144
	ds_read_b128 v[154:157], v7 offset:20480
	ds_read_b128 v[158:161], v7 offset:22528
	s_setprio 2
	global_load_dwordx4 v[162:165], v8, s[36:37] offset:768
	s_waitcnt vmcnt(7)
	ds_write_b128 v2, v[166:169] offset:32768
	ds_read_b128 v[166:169], v4
	ds_read_b128 v[170:173], v5 offset:16384
	s_waitcnt lgkmcnt(8)
	v_mfma_f32_16x16x32_bf16 v[26:29], v[118:121], v[82:85], v[26:29]
	s_waitcnt lgkmcnt(3)
	v_mfma_f32_16x16x32_bf16 v[10:13], v[158:161], v[82:85], v[10:13]
	v_mfma_f32_16x16x32_bf16 v[86:89], v[126:129], v[82:85], v[86:89]
	v_mfma_f32_16x16x32_bf16 v[94:97], v[154:157], v[82:85], v[94:97]
	global_load_dwordx4 v[82:85], v228, s[36:37] offset:768
	ds_write_b128 v2, v[106:109] offset:36864
	ds_read_b128 v[106:109], v4 offset:2048
	ds_read_b128 v[174:177], v5 offset:18432
	v_mfma_f32_16x16x32_bf16 v[30:33], v[118:121], v[102:105], v[30:33]
	v_mfma_f32_16x16x32_bf16 v[42:45], v[126:129], v[102:105], v[42:45]
	v_mfma_f32_16x16x32_bf16 v[14:17], v[158:161], v[102:105], v[14:17]
	v_mfma_f32_16x16x32_bf16 v[90:93], v[154:157], v[102:105], v[90:93]
	global_load_dwordx4 v[102:105], v229, s[36:37] offset:768
	s_waitcnt vmcnt(7)
	ds_write_b128 v2, v[110:113] offset:40960
	ds_read_b128 v[110:113], v4 offset:4096
	ds_read_b128 v[178:181], v5 offset:20480
	v_mfma_f32_16x16x32_bf16 v[34:37], v[118:121], v[132:135], v[34:37]
	v_mfma_f32_16x16x32_bf16 v[46:49], v[126:129], v[132:135], v[46:49]
	v_mfma_f32_16x16x32_bf16 v[62:65], v[154:157], v[132:135], v[62:65]
	v_mfma_f32_16x16x32_bf16 v[18:21], v[158:161], v[132:135], v[18:21]
	global_load_dwordx4 v[132:135], v230, s[36:37] offset:768
	ds_write_b128 v2, v[146:149] offset:45056
	ds_read_b128 v[146:149], v4 offset:6144
	ds_read_b128 v[182:185], v5 offset:22528
	v_mfma_f32_16x16x32_bf16 v[38:41], v[118:121], v[150:153], v[38:41]
	v_mfma_f32_16x16x32_bf16 v[50:53], v[126:129], v[150:153], v[50:53]
	v_mfma_f32_16x16x32_bf16 v[54:57], v[154:157], v[150:153], v[54:57]
	v_mfma_f32_16x16x32_bf16 v[22:25], v[158:161], v[150:153], v[22:25]
	global_load_dwordx4 v[118:121], v3, s[0:1] offset:768
	s_waitcnt vmcnt(7)
	ds_write_b128 v2, v[114:117] offset:49152
	s_waitcnt lgkmcnt(10)
	v_mfma_f32_16x16x32_bf16 v[26:29], v[170:173], v[166:169], v[26:29]
	s_waitcnt lgkmcnt(1)
	v_mfma_f32_16x16x32_bf16 v[10:13], v[182:185], v[166:169], v[10:13]
	v_mfma_f32_16x16x32_bf16 v[86:89], v[174:177], v[166:169], v[86:89]
	v_mfma_f32_16x16x32_bf16 v[94:97], v[178:181], v[166:169], v[94:97]
	global_load_dwordx4 v[114:117], v231, s[0:1] offset:768
	ds_write_b128 v2, v[122:125] offset:53248
	v_mfma_f32_16x16x32_bf16 v[30:33], v[170:173], v[106:109], v[30:33]
	v_mfma_f32_16x16x32_bf16 v[42:45], v[174:177], v[106:109], v[42:45]
	v_mfma_f32_16x16x32_bf16 v[14:17], v[182:185], v[106:109], v[14:17]
	v_mfma_f32_16x16x32_bf16 v[90:93], v[178:181], v[106:109], v[90:93]
	global_load_dwordx4 v[106:109], v232, s[0:1] offset:768
	s_waitcnt vmcnt(7)
	ds_write_b128 v2, v[58:61] offset:57344
	v_mfma_f32_16x16x32_bf16 v[34:37], v[170:173], v[110:113], v[34:37]
	v_mfma_f32_16x16x32_bf16 v[46:49], v[174:177], v[110:113], v[46:49]
	v_mfma_f32_16x16x32_bf16 v[58:61], v[178:181], v[110:113], v[62:65]
	v_mfma_f32_16x16x32_bf16 v[18:21], v[182:185], v[110:113], v[18:21]
	global_load_dwordx4 v[62:65], v233, s[0:1] offset:768
	ds_write_b128 v2, v[98:101] offset:61440
	v_mfma_f32_16x16x32_bf16 v[38:41], v[170:173], v[146:149], v[38:41]
	v_mfma_f32_16x16x32_bf16 v[50:53], v[174:177], v[146:149], v[50:53]
	v_mfma_f32_16x16x32_bf16 v[54:57], v[178:181], v[146:149], v[54:57]
	v_mfma_f32_16x16x32_bf16 v[22:25], v[182:185], v[146:149], v[22:25]
	s_setprio 0
	s_waitcnt lgkmcnt(0)
	s_barrier
; template <int MODE>
; __device__ __forceinline__ void gemm_tile(const Params& P, int tm, int tn, unsigned char* smem) {
;     ...
; #pragma unroll
;         for (int i = 0; i < 4; ++i) { fa[i] = *(const bf16x8*)(sA + arow_off + i * 2048 + ch0); fb[i] = *(const bf16x8*)(sB + brow_off + i * 2048 + ch0); }
;         __builtin_amdgcn_sched_barrier(0);
;         __builtin_amdgcn_s_setprio(2);
;         if (wr_ok) *(uint4*)(nA + soff0) = ra0;
;         if (ld_ok) ra0 = *(const uint4*)(Ab + (aoff + 0u * LDA + koa));
;         ga[0] = *(const bf16x8*)(sA + arow_off + 0 * 2048 + ch1); gb[0] = *(const bf16x8*)(sB + brow_off + 0 * 2048 + ch1);
;         __builtin_amdgcn_sched_barrier(0);
; #pragma unroll
;         for (int j = 0; j < 4; ++j) acc[0][j] = __builtin_amdgcn_mfma_f32_16x16x32_bf16(fb[j], fa[0], acc[0][j], 0, 0, 0);
;         __builtin_amdgcn_sched_barrier(0);
;         if (wr_ok) *(uint4*)(nA + soff0 + 4096) = ra1;
;         if (ld_ok) ra1 = *(const uint4*)(Ab + (aoff + 32u * LDA + koa));
;         ga[1] = *(const bf16x8*)(sA + arow_off + 1 * 2048 + ch1); gb[1] = *(const bf16x8*)(sB + brow_off + 1 * 2048 + ch1);
;         __builtin_amdgcn_sched_barrier(0);
; #pragma unroll
;         for (int j = 0; j < 4; ++j) acc[1][j] = __builtin_amdgcn_mfma_f32_16x16x32_bf16(fb[j], fa[1], acc[1][j], 0, 0, 0);
;         __builtin_amdgcn_sched_barrier(0);
;         if (wr_ok) *(uint4*)(nA + soff0 + 8192) = ra2;
;         if (ld_ok) ra2 = *(const uint4*)(Ab + (aoff + 64u * LDA + koa));
;         ga[2] = *(const bf16x8*)(sA + arow_off + 2 * 2048 + ch1); gb[2] = *(const bf16x8*)(sB + brow_off + 2 * 2048 + ch1);
;         __builtin_amdgcn_sched_barrier(0);
; #pragma unroll
;         for (int j = 0; j < 4; ++j) acc[2][j] = __builtin_amdgcn_mfma_f32_16x16x32_bf16(fb[j], fa[2], acc[2][j], 0, 0, 0);
;         __builtin_amdgcn_sched_barrier(0);
;         if (wr_ok) *(uint4*)(nA + soff0 + 12288) = ra3;
;         if (ld_ok) ra3 = *(const uint4*)(Ab + (aoff + 96u * LDA + koa));
;         ga[3] = *(const bf16x8*)(sA + arow_off + 3 * 2048 + ch1); gb[3] = *(const bf16x8*)(sB + brow_off + 3 * 2048 + ch1);
;         __builtin_amdgcn_sched_barrier(0);
; #pragma unroll
;         for (int j = 0; j < 4; ++j) acc[3][j] = __builtin_amdgcn_mfma_f32_16x16x32_bf16(fb[j], fa[3], acc[3][j], 0, 0, 0);
;         __builtin_amdgcn_sched_barrier(0);
;         if (wr_ok) *(uint4*)(nB + soff0) = rb0;
	ds_read_b128 v[98:101], v6 offset:32768
	ds_read_b128 v[110:113], v6 offset:34816
	ds_read_b128 v[122:125], v7 offset:49152
	ds_read_b128 v[126:129], v7 offset:51200
	ds_read_b128 v[146:149], v6 offset:36864
	ds_read_b128 v[150:153], v6 offset:38912
	ds_read_b128 v[154:157], v7 offset:53248
	ds_read_b128 v[158:161], v7 offset:55296
	s_setprio 2
	global_load_dwordx4 v[166:169], v8, s[36:37] offset:896
	s_waitcnt vmcnt(7)
	ds_write_b128 v2, v[162:165]
	ds_read_b128 v[162:165], v4 offset:32768
	ds_read_b128 v[170:173], v5 offset:49152
	s_waitcnt lgkmcnt(8)
	v_mfma_f32_16x16x32_bf16 v[26:29], v[122:125], v[98:101], v[26:29]
	s_waitcnt lgkmcnt(3)
	v_mfma_f32_16x16x32_bf16 v[10:13], v[158:161], v[98:101], v[10:13]
	v_mfma_f32_16x16x32_bf16 v[86:89], v[126:129], v[98:101], v[86:89]
	v_mfma_f32_16x16x32_bf16 v[94:97], v[154:157], v[98:101], v[94:97]
	global_load_dwordx4 v[98:101], v228, s[36:37] offset:896
	ds_write_b128 v2, v[82:85] offset:4096
	ds_read_b128 v[82:85], v4 offset:34816
	ds_read_b128 v[174:177], v5 offset:51200
	v_mfma_f32_16x16x32_bf16 v[30:33], v[122:125], v[110:113], v[30:33]
	v_mfma_f32_16x16x32_bf16 v[42:45], v[126:129], v[110:113], v[42:45]
	v_mfma_f32_16x16x32_bf16 v[14:17], v[158:161], v[110:113], v[14:17]
	v_mfma_f32_16x16x32_bf16 v[90:93], v[154:157], v[110:113], v[90:93]
	global_load_dwordx4 v[110:113], v229, s[36:37] offset:896
	s_waitcnt vmcnt(7)
	ds_write_b128 v2, v[102:105] offset:8192
	ds_read_b128 v[102:105], v4 offset:36864
	ds_read_b128 v[178:181], v5 offset:53248
	v_mfma_f32_16x16x32_bf16 v[34:37], v[122:125], v[146:149], v[34:37]
	v_mfma_f32_16x16x32_bf16 v[46:49], v[126:129], v[146:149], v[46:49]
	v_mfma_f32_16x16x32_bf16 v[58:61], v[154:157], v[146:149], v[58:61]
	v_mfma_f32_16x16x32_bf16 v[18:21], v[158:161], v[146:149], v[18:21]
	global_load_dwordx4 v[146:149], v230, s[36:37] offset:896
	ds_write_b128 v2, v[132:135] offset:12288
	ds_read_b128 v[132:135], v4 offset:38912
	ds_read_b128 v[182:185], v5 offset:55296
	v_mfma_f32_16x16x32_bf16 v[38:41], v[122:125], v[150:153], v[38:41]
	v_mfma_f32_16x16x32_bf16 v[50:53], v[126:129], v[150:153], v[50:53]
	v_mfma_f32_16x16x32_bf16 v[54:57], v[154:157], v[150:153], v[54:57]
	v_mfma_f32_16x16x32_bf16 v[22:25], v[158:161], v[150:153], v[22:25]
	global_load_dwordx4 v[122:125], v3, s[0:1] offset:896
	s_waitcnt vmcnt(7)
	ds_write_b128 v2, v[118:121] offset:16384
	s_waitcnt lgkmcnt(10)
	v_mfma_f32_16x16x32_bf16 v[26:29], v[170:173], v[162:165], v[26:29]
	s_waitcnt lgkmcnt(1)
	v_mfma_f32_16x16x32_bf16 v[10:13], v[182:185], v[162:165], v[10:13]
	v_mfma_f32_16x16x32_bf16 v[86:89], v[174:177], v[162:165], v[86:89]
	v_mfma_f32_16x16x32_bf16 v[94:97], v[178:181], v[162:165], v[94:97]
	global_load_dwordx4 v[118:121], v231, s[0:1] offset:896
	ds_write_b128 v2, v[114:117] offset:20480
	v_mfma_f32_16x16x32_bf16 v[30:33], v[170:173], v[82:85], v[30:33]
	v_mfma_f32_16x16x32_bf16 v[42:45], v[174:177], v[82:85], v[42:45]
	v_mfma_f32_16x16x32_bf16 v[14:17], v[182:185], v[82:85], v[14:17]
	v_mfma_f32_16x16x32_bf16 v[90:93], v[178:181], v[82:85], v[90:93]
	global_load_dwordx4 v[82:85], v232, s[0:1] offset:896
	s_waitcnt vmcnt(7)
	ds_write_b128 v2, v[106:109] offset:24576
	v_mfma_f32_16x16x32_bf16 v[34:37], v[170:173], v[102:105], v[34:37]
	v_mfma_f32_16x16x32_bf16 v[46:49], v[174:177], v[102:105], v[46:49]
	v_mfma_f32_16x16x32_bf16 v[58:61], v[178:181], v[102:105], v[58:61]
	v_mfma_f32_16x16x32_bf16 v[18:21], v[182:185], v[102:105], v[18:21]
	global_load_dwordx4 v[102:105], v233, s[0:1] offset:896
	ds_write_b128 v2, v[62:65] offset:28672
	v_mfma_f32_16x16x32_bf16 v[38:41], v[170:173], v[132:135], v[38:41]
	v_mfma_f32_16x16x32_bf16 v[50:53], v[174:177], v[132:135], v[50:53]
	v_mfma_f32_16x16x32_bf16 v[54:57], v[178:181], v[132:135], v[54:57]
	v_mfma_f32_16x16x32_bf16 v[22:25], v[182:185], v[132:135], v[22:25]
	s_setprio 0
	s_waitcnt lgkmcnt(0)
	s_barrier
	ds_read_b128 v[62:65], v6
	ds_read_b128 v[106:109], v6 offset:2048
	ds_read_b128 v[114:117], v7 offset:16384
	ds_read_b128 v[126:129], v7 offset:18432
	ds_read_b128 v[132:135], v6 offset:4096
	ds_read_b128 v[150:153], v6 offset:6144
	ds_read_b128 v[154:157], v7 offset:20480
	ds_read_b128 v[158:161], v7 offset:22528
	s_setprio 2
	global_load_dwordx4 v[162:165], v8, s[36:37] offset:1024
	s_waitcnt vmcnt(7)
	ds_write_b128 v2, v[166:169] offset:32768
	ds_read_b128 v[166:169], v4
	ds_read_b128 v[170:173], v5 offset:16384
	s_waitcnt lgkmcnt(8)
	v_mfma_f32_16x16x32_bf16 v[26:29], v[114:117], v[62:65], v[26:29]
	s_waitcnt lgkmcnt(3)
	v_mfma_f32_16x16x32_bf16 v[10:13], v[158:161], v[62:65], v[10:13]
	v_mfma_f32_16x16x32_bf16 v[86:89], v[126:129], v[62:65], v[86:89]
	v_mfma_f32_16x16x32_bf16 v[94:97], v[154:157], v[62:65], v[94:97]
	global_load_dwordx4 v[62:65], v228, s[36:37] offset:1024
	ds_write_b128 v2, v[98:101] offset:36864
	ds_read_b128 v[98:101], v4 offset:2048
	ds_read_b128 v[174:177], v5 offset:18432
	v_mfma_f32_16x16x32_bf16 v[30:33], v[114:117], v[106:109], v[30:33]
	v_mfma_f32_16x16x32_bf16 v[42:45], v[126:129], v[106:109], v[42:45]
	v_mfma_f32_16x16x32_bf16 v[14:17], v[158:161], v[106:109], v[14:17]
	v_mfma_f32_16x16x32_bf16 v[90:93], v[154:157], v[106:109], v[90:93]
	global_load_dwordx4 v[106:109], v229, s[36:37] offset:1024
	s_waitcnt vmcnt(7)
; template <int MODE>
; __device__ __forceinline__ void gemm_tile(const Params& P, int tm, int tn, unsigned char* smem) {
;     ...
; #pragma unroll
;         for (int i = 0; i < 4; ++i) { fa[i] = *(const bf16x8*)(sA + arow_off + i * 2048 + ch0); fb[i] = *(const bf16x8*)(sB + brow_off + i * 2048 + ch0); }
;         __builtin_amdgcn_sched_barrier(0);
;         __builtin_amdgcn_s_setprio(2);
;         if (wr_ok) *(uint4*)(nA + soff0) = ra0;
;         if (ld_ok) ra0 = *(const uint4*)(Ab + (aoff + 0u * LDA + koa));
;         ga[0] = *(const bf16x8*)(sA + arow_off + 0 * 2048 + ch1); gb[0] = *(const bf16x8*)(sB + brow_off + 0 * 2048 + ch1);
;         __builtin_amdgcn_sched_barrier(0);
; #pragma unroll
;         for (int j = 0; j < 4; ++j) acc[0][j] = __builtin_amdgcn_mfma_f32_16x16x32_bf16(fb[j], fa[0], acc[0][j], 0, 0, 0);
;         __builtin_amdgcn_sched_barrier(0);
;         if (wr_ok) *(uint4*)(nA + soff0 + 4096) = ra1;
;         if (ld_ok) ra1 = *(const uint4*)(Ab + (aoff + 32u * LDA + koa));
;         ga[1] = *(const bf16x8*)(sA + arow_off + 1 * 2048 + ch1); gb[1] = *(const bf16x8*)(sB + brow_off + 1 * 2048 + ch1);
;         __builtin_amdgcn_sched_barrier(0);
; #pragma unroll
;         for (int j = 0; j < 4; ++j) acc[1][j] = __builtin_amdgcn_mfma_f32_16x16x32_bf16(fb[j], fa[1], acc[1][j], 0, 0, 0);
;         __builtin_amdgcn_sched_barrier(0);
;         if (wr_ok) *(uint4*)(nA + soff0 + 8192) = ra2;
;         if (ld_ok) ra2 = *(const uint4*)(Ab + (aoff + 64u * LDA + koa));
;         ga[2] = *(const bf16x8*)(sA + arow_off + 2 * 2048 + ch1); gb[2] = *(const bf16x8*)(sB + brow_off + 2 * 2048 + ch1);
;         __builtin_amdgcn_sched_barrier(0);
; #pragma unroll
;         for (int j = 0; j < 4; ++j) acc[2][j] = __builtin_amdgcn_mfma_f32_16x16x32_bf16(fb[j], fa[2], acc[2][j], 0, 0, 0);
;         __builtin_amdgcn_sched_barrier(0);
;         if (wr_ok) *(uint4*)(nA + soff0 + 12288) = ra3;
;         if (ld_ok) ra3 = *(const uint4*)(Ab + (aoff + 96u * LDA + koa));
;         ga[3] = *(const bf16x8*)(sA + arow_off + 3 * 2048 + ch1); gb[3] = *(const bf16x8*)(sB + brow_off + 3 * 2048 + ch1);
;         __builtin_amdgcn_sched_barrier(0);
; #pragma unroll
;         for (int j = 0; j < 4; ++j) acc[3][j] = __builtin_amdgcn_mfma_f32_16x16x32_bf16(fb[j], fa[3], acc[3][j], 0, 0, 0);
;         __builtin_amdgcn_sched_barrier(0);
;         if (wr_ok) *(uint4*)(nB + soff0) = rb0;
	ds_write_b128 v2, v[110:113] offset:40960
	ds_read_b128 v[110:113], v4 offset:4096
	ds_read_b128 v[178:181], v5 offset:20480
	v_mfma_f32_16x16x32_bf16 v[34:37], v[114:117], v[132:135], v[34:37]
	v_mfma_f32_16x16x32_bf16 v[46:49], v[126:129], v[132:135], v[46:49]
	v_mfma_f32_16x16x32_bf16 v[58:61], v[154:157], v[132:135], v[58:61]
	v_mfma_f32_16x16x32_bf16 v[18:21], v[158:161], v[132:135], v[18:21]
	global_load_dwordx4 v[132:135], v230, s[36:37] offset:1024
	ds_write_b128 v2, v[146:149] offset:45056
	ds_read_b128 v[146:149], v4 offset:6144
	ds_read_b128 v[182:185], v5 offset:22528
	v_mfma_f32_16x16x32_bf16 v[38:41], v[114:117], v[150:153], v[38:41]
	v_mfma_f32_16x16x32_bf16 v[50:53], v[126:129], v[150:153], v[50:53]
	v_mfma_f32_16x16x32_bf16 v[54:57], v[154:157], v[150:153], v[54:57]
	v_mfma_f32_16x16x32_bf16 v[22:25], v[158:161], v[150:153], v[22:25]
	global_load_dwordx4 v[114:117], v3, s[0:1] offset:1024
	s_waitcnt vmcnt(7)
	ds_write_b128 v2, v[122:125] offset:49152
	s_waitcnt lgkmcnt(10)
	v_mfma_f32_16x16x32_bf16 v[26:29], v[170:173], v[166:169], v[26:29]
	s_waitcnt lgkmcnt(1)
	v_mfma_f32_16x16x32_bf16 v[10:13], v[182:185], v[166:169], v[10:13]
	v_mfma_f32_16x16x32_bf16 v[86:89], v[174:177], v[166:169], v[86:89]
	v_mfma_f32_16x16x32_bf16 v[94:97], v[178:181], v[166:169], v[94:97]
	global_load_dwordx4 v[122:125], v231, s[0:1] offset:1024
	ds_write_b128 v2, v[118:121] offset:53248
	v_mfma_f32_16x16x32_bf16 v[30:33], v[170:173], v[98:101], v[30:33]
	v_mfma_f32_16x16x32_bf16 v[42:45], v[174:177], v[98:101], v[42:45]
	v_mfma_f32_16x16x32_bf16 v[14:17], v[182:185], v[98:101], v[14:17]
	v_mfma_f32_16x16x32_bf16 v[90:93], v[178:181], v[98:101], v[90:93]
	global_load_dwordx4 v[98:101], v232, s[0:1] offset:1024
	s_waitcnt vmcnt(7)
	ds_write_b128 v2, v[82:85] offset:57344
	v_mfma_f32_16x16x32_bf16 v[34:37], v[170:173], v[110:113], v[34:37]
	v_mfma_f32_16x16x32_bf16 v[46:49], v[174:177], v[110:113], v[46:49]
	v_mfma_f32_16x16x32_bf16 v[58:61], v[178:181], v[110:113], v[58:61]
	v_mfma_f32_16x16x32_bf16 v[18:21], v[182:185], v[110:113], v[18:21]
	global_load_dwordx4 v[82:85], v233, s[0:1] offset:1024
	ds_write_b128 v2, v[102:105] offset:61440
	v_mfma_f32_16x16x32_bf16 v[38:41], v[170:173], v[146:149], v[38:41]
	v_mfma_f32_16x16x32_bf16 v[50:53], v[174:177], v[146:149], v[50:53]
	v_mfma_f32_16x16x32_bf16 v[54:57], v[178:181], v[146:149], v[54:57]
	v_mfma_f32_16x16x32_bf16 v[22:25], v[182:185], v[146:149], v[22:25]
	s_setprio 0
	s_waitcnt lgkmcnt(0)
	s_barrier
	ds_read_b128 v[102:105], v6 offset:32768
	ds_read_b128 v[110:113], v6 offset:34816
	ds_read_b128 v[118:121], v7 offset:49152
	ds_read_b128 v[126:129], v7 offset:51200
	ds_read_b128 v[146:149], v6 offset:36864
	ds_read_b128 v[150:153], v6 offset:38912
	ds_read_b128 v[154:157], v7 offset:53248
	ds_read_b128 v[158:161], v7 offset:55296
	s_setprio 2
	global_load_dwordx4 v[166:169], v8, s[36:37] offset:1152
	s_waitcnt vmcnt(7)
	ds_write_b128 v2, v[162:165]
	ds_read_b128 v[162:165], v4 offset:32768
	ds_read_b128 v[170:173], v5 offset:49152
	s_waitcnt lgkmcnt(8)
	v_mfma_f32_16x16x32_bf16 v[26:29], v[118:121], v[102:105], v[26:29]
	s_waitcnt lgkmcnt(3)
	v_mfma_f32_16x16x32_bf16 v[10:13], v[158:161], v[102:105], v[10:13]
	v_mfma_f32_16x16x32_bf16 v[86:89], v[126:129], v[102:105], v[86:89]
	v_mfma_f32_16x16x32_bf16 v[94:97], v[154:157], v[102:105], v[94:97]
	global_load_dwordx4 v[102:105], v228, s[36:37] offset:1152
	ds_write_b128 v2, v[62:65] offset:4096
	ds_read_b128 v[62:65], v4 offset:34816
	ds_read_b128 v[174:177], v5 offset:51200
	v_mfma_f32_16x16x32_bf16 v[30:33], v[118:121], v[110:113], v[30:33]
	v_mfma_f32_16x16x32_bf16 v[42:45], v[126:129], v[110:113], v[42:45]
	v_mfma_f32_16x16x32_bf16 v[14:17], v[158:161], v[110:113], v[14:17]
	v_mfma_f32_16x16x32_bf16 v[90:93], v[154:157], v[110:113], v[90:93]
	global_load_dwordx4 v[110:113], v229, s[36:37] offset:1152
	s_waitcnt vmcnt(7)
	ds_write_b128 v2, v[106:109] offset:8192
	ds_read_b128 v[106:109], v4 offset:36864
	ds_read_b128 v[178:181], v5 offset:53248
	v_mfma_f32_16x16x32_bf16 v[34:37], v[118:121], v[146:149], v[34:37]
	v_mfma_f32_16x16x32_bf16 v[46:49], v[126:129], v[146:149], v[46:49]
	v_mfma_f32_16x16x32_bf16 v[58:61], v[154:157], v[146:149], v[58:61]
	v_mfma_f32_16x16x32_bf16 v[18:21], v[158:161], v[146:149], v[18:21]
	global_load_dwordx4 v[146:149], v230, s[36:37] offset:1152
	ds_write_b128 v2, v[132:135] offset:12288
	ds_read_b128 v[132:135], v4 offset:38912
	ds_read_b128 v[182:185], v5 offset:55296
	v_mfma_f32_16x16x32_bf16 v[38:41], v[118:121], v[150:153], v[38:41]
	v_mfma_f32_16x16x32_bf16 v[50:53], v[126:129], v[150:153], v[50:53]
	v_mfma_f32_16x16x32_bf16 v[54:57], v[154:157], v[150:153], v[54:57]
	v_mfma_f32_16x16x32_bf16 v[22:25], v[158:161], v[150:153], v[22:25]
	global_load_dwordx4 v[118:121], v3, s[0:1] offset:1152
	s_waitcnt vmcnt(7)
	ds_write_b128 v2, v[114:117] offset:16384
	s_waitcnt lgkmcnt(10)
	v_mfma_f32_16x16x32_bf16 v[26:29], v[170:173], v[162:165], v[26:29]
	s_waitcnt lgkmcnt(1)
	v_mfma_f32_16x16x32_bf16 v[10:13], v[182:185], v[162:165], v[10:13]
	v_mfma_f32_16x16x32_bf16 v[86:89], v[174:177], v[162:165], v[86:89]
	v_mfma_f32_16x16x32_bf16 v[94:97], v[178:181], v[162:165], v[94:97]
	global_load_dwordx4 v[114:117], v231, s[0:1] offset:1152
	ds_write_b128 v2, v[122:125] offset:20480
	v_mfma_f32_16x16x32_bf16 v[30:33], v[170:173], v[62:65], v[30:33]
	v_mfma_f32_16x16x32_bf16 v[42:45], v[174:177], v[62:65], v[42:45]
	v_mfma_f32_16x16x32_bf16 v[14:17], v[182:185], v[62:65], v[14:17]
	v_mfma_f32_16x16x32_bf16 v[90:93], v[178:181], v[62:65], v[90:93]
	global_load_dwordx4 v[62:65], v232, s[0:1] offset:1152
	s_waitcnt vmcnt(7)
	ds_write_b128 v2, v[98:101] offset:24576
	v_mfma_f32_16x16x32_bf16 v[34:37], v[170:173], v[106:109], v[34:37]
	v_mfma_f32_16x16x32_bf16 v[46:49], v[174:177], v[106:109], v[46:49]
	v_mfma_f32_16x16x32_bf16 v[58:61], v[178:181], v[106:109], v[58:61]
	v_mfma_f32_16x16x32_bf16 v[18:21], v[182:185], v[106:109], v[18:21]
	global_load_dwordx4 v[98:101], v233, s[0:1] offset:1152
	ds_write_b128 v2, v[82:85] offset:28672
	v_mfma_f32_16x16x32_bf16 v[38:41], v[170:173], v[132:135], v[38:41]
	v_mfma_f32_16x16x32_bf16 v[50:53], v[174:177], v[132:135], v[50:53]
	v_mfma_f32_16x16x32_bf16 v[54:57], v[178:181], v[132:135], v[54:57]
	v_mfma_f32_16x16x32_bf16 v[22:25], v[182:185], v[132:135], v[22:25]
	s_setprio 0
	s_waitcnt lgkmcnt(0)
	s_barrier
; template <int MODE>
; __device__ __forceinline__ void gemm_tile(const Params& P, int tm, int tn, unsigned char* smem) {
;     ...
; #pragma unroll
;         for (int i = 0; i < 4; ++i) { fa[i] = *(const bf16x8*)(sA + arow_off + i * 2048 + ch0); fb[i] = *(const bf16x8*)(sB + brow_off + i * 2048 + ch0); }
;         __builtin_amdgcn_sched_barrier(0);
;         __builtin_amdgcn_s_setprio(2);
;         if (wr_ok) *(uint4*)(nA + soff0) = ra0;
;         if (ld_ok) ra0 = *(const uint4*)(Ab + (aoff + 0u * LDA + koa));
;         ga[0] = *(const bf16x8*)(sA + arow_off + 0 * 2048 + ch1); gb[0] = *(const bf16x8*)(sB + brow_off + 0 * 2048 + ch1);
;         __builtin_amdgcn_sched_barrier(0);
; #pragma unroll
;         for (int j = 0; j < 4; ++j) acc[0][j] = __builtin_amdgcn_mfma_f32_16x16x32_bf16(fb[j], fa[0], acc[0][j], 0, 0, 0);
;         __builtin_amdgcn_sched_barrier(0);
;         if (wr_ok) *(uint4*)(nA + soff0 + 4096) = ra1;
;         if (ld_ok) ra1 = *(const uint4*)(Ab + (aoff + 32u * LDA + koa));
;         ga[1] = *(const bf16x8*)(sA + arow_off + 1 * 2048 + ch1); gb[1] = *(const bf16x8*)(sB + brow_off + 1 * 2048 + ch1);
;         __builtin_amdgcn_sched_barrier(0);
; #pragma unroll
;         for (int j = 0; j < 4; ++j) acc[1][j] = __builtin_amdgcn_mfma_f32_16x16x32_bf16(fb[j], fa[1], acc[1][j], 0, 0, 0);
;         __builtin_amdgcn_sched_barrier(0);
;         if (wr_ok) *(uint4*)(nA + soff0 + 8192) = ra2;
;         if (ld_ok) ra2 = *(const uint4*)(Ab + (aoff + 64u * LDA + koa));
;         ga[2] = *(const bf16x8*)(sA + arow_off + 2 * 2048 + ch1); gb[2] = *(const bf16x8*)(sB + brow_off + 2 * 2048 + ch1);
;         __builtin_amdgcn_sched_barrier(0);
; #pragma unroll
;         for (int j = 0; j < 4; ++j) acc[2][j] = __builtin_amdgcn_mfma_f32_16x16x32_bf16(fb[j], fa[2], acc[2][j], 0, 0, 0);
;         __builtin_amdgcn_sched_barrier(0);
;         if (wr_ok) *(uint4*)(nA + soff0 + 12288) = ra3;
;         if (ld_ok) ra3 = *(const uint4*)(Ab + (aoff + 96u * LDA + koa));
;         ga[3] = *(const bf16x8*)(sA + arow_off + 3 * 2048 + ch1); gb[3] = *(const bf16x8*)(sB + brow_off + 3 * 2048 + ch1);
;         __builtin_amdgcn_sched_barrier(0);
; #pragma unroll
;         for (int j = 0; j < 4; ++j) acc[3][j] = __builtin_amdgcn_mfma_f32_16x16x32_bf16(fb[j], fa[3], acc[3][j], 0, 0, 0);
;         __builtin_amdgcn_sched_barrier(0);
;         if (wr_ok) *(uint4*)(nB + soff0) = rb0;
	ds_read_b128 v[82:85], v6
	ds_read_b128 v[106:109], v6 offset:2048
	ds_read_b128 v[122:125], v7 offset:16384
	ds_read_b128 v[126:129], v7 offset:18432
	ds_read_b128 v[132:135], v6 offset:4096
	ds_read_b128 v[150:153], v6 offset:6144
	ds_read_b128 v[154:157], v7 offset:20480
	ds_read_b128 v[158:161], v7 offset:22528
	s_setprio 2
	global_load_dwordx4 v[162:165], v8, s[36:37] offset:1280
	s_waitcnt vmcnt(7)
	ds_write_b128 v2, v[166:169] offset:32768
	ds_read_b128 v[166:169], v4
	ds_read_b128 v[170:173], v5 offset:16384
	s_waitcnt lgkmcnt(8)
	v_mfma_f32_16x16x32_bf16 v[26:29], v[122:125], v[82:85], v[26:29]
	s_waitcnt lgkmcnt(3)
	v_mfma_f32_16x16x32_bf16 v[10:13], v[158:161], v[82:85], v[10:13]
	v_mfma_f32_16x16x32_bf16 v[86:89], v[126:129], v[82:85], v[86:89]
	v_mfma_f32_16x16x32_bf16 v[94:97], v[154:157], v[82:85], v[94:97]
	global_load_dwordx4 v[82:85], v228, s[36:37] offset:1280
	ds_write_b128 v2, v[102:105] offset:36864
	ds_read_b128 v[102:105], v4 offset:2048
	ds_read_b128 v[174:177], v5 offset:18432
	v_mfma_f32_16x16x32_bf16 v[30:33], v[122:125], v[106:109], v[30:33]
	v_mfma_f32_16x16x32_bf16 v[42:45], v[126:129], v[106:109], v[42:45]
	v_mfma_f32_16x16x32_bf16 v[14:17], v[158:161], v[106:109], v[14:17]
	v_mfma_f32_16x16x32_bf16 v[90:93], v[154:157], v[106:109], v[90:93]
	global_load_dwordx4 v[106:109], v229, s[36:37] offset:1280
	s_waitcnt vmcnt(7)
	ds_write_b128 v2, v[110:113] offset:40960
	ds_read_b128 v[110:113], v4 offset:4096
	ds_read_b128 v[178:181], v5 offset:20480
	v_mfma_f32_16x16x32_bf16 v[34:37], v[122:125], v[132:135], v[34:37]
	v_mfma_f32_16x16x32_bf16 v[46:49], v[126:129], v[132:135], v[46:49]
	v_mfma_f32_16x16x32_bf16 v[58:61], v[154:157], v[132:135], v[58:61]
	v_mfma_f32_16x16x32_bf16 v[18:21], v[158:161], v[132:135], v[18:21]
	global_load_dwordx4 v[132:135], v230, s[36:37] offset:1280
	ds_write_b128 v2, v[146:149] offset:45056
	ds_read_b128 v[146:149], v4 offset:6144
	ds_read_b128 v[182:185], v5 offset:22528
	v_mfma_f32_16x16x32_bf16 v[38:41], v[122:125], v[150:153], v[38:41]
	v_mfma_f32_16x16x32_bf16 v[50:53], v[126:129], v[150:153], v[50:53]
	v_mfma_f32_16x16x32_bf16 v[54:57], v[154:157], v[150:153], v[54:57]
	v_mfma_f32_16x16x32_bf16 v[22:25], v[158:161], v[150:153], v[22:25]
	global_load_dwordx4 v[122:125], v3, s[0:1] offset:1280
	s_waitcnt vmcnt(7)
	ds_write_b128 v2, v[118:121] offset:49152
	s_waitcnt lgkmcnt(10)
	v_mfma_f32_16x16x32_bf16 v[26:29], v[170:173], v[166:169], v[26:29]
	s_waitcnt lgkmcnt(1)
	v_mfma_f32_16x16x32_bf16 v[10:13], v[182:185], v[166:169], v[10:13]
	v_mfma_f32_16x16x32_bf16 v[86:89], v[174:177], v[166:169], v[86:89]
	v_mfma_f32_16x16x32_bf16 v[94:97], v[178:181], v[166:169], v[94:97]
	global_load_dwordx4 v[118:121], v231, s[0:1] offset:1280
	ds_write_b128 v2, v[114:117] offset:53248
	v_mfma_f32_16x16x32_bf16 v[30:33], v[170:173], v[102:105], v[30:33]
	v_mfma_f32_16x16x32_bf16 v[42:45], v[174:177], v[102:105], v[42:45]
	v_mfma_f32_16x16x32_bf16 v[14:17], v[182:185], v[102:105], v[14:17]
	v_mfma_f32_16x16x32_bf16 v[90:93], v[178:181], v[102:105], v[90:93]
	global_load_dwordx4 v[102:105], v232, s[0:1] offset:1280
	s_waitcnt vmcnt(7)
	ds_write_b128 v2, v[62:65] offset:57344
	v_mfma_f32_16x16x32_bf16 v[34:37], v[170:173], v[110:113], v[34:37]
	v_mfma_f32_16x16x32_bf16 v[46:49], v[174:177], v[110:113], v[46:49]
	v_mfma_f32_16x16x32_bf16 v[58:61], v[178:181], v[110:113], v[58:61]
	v_mfma_f32_16x16x32_bf16 v[18:21], v[182:185], v[110:113], v[18:21]
	global_load_dwordx4 v[62:65], v233, s[0:1] offset:1280
	ds_write_b128 v2, v[98:101] offset:61440
	v_mfma_f32_16x16x32_bf16 v[38:41], v[170:173], v[146:149], v[38:41]
	v_mfma_f32_16x16x32_bf16 v[50:53], v[174:177], v[146:149], v[50:53]
	v_mfma_f32_16x16x32_bf16 v[54:57], v[178:181], v[146:149], v[54:57]
	v_mfma_f32_16x16x32_bf16 v[22:25], v[182:185], v[146:149], v[22:25]
	s_setprio 0
	s_waitcnt lgkmcnt(0)
	s_barrier
	ds_read_b128 v[98:101], v6 offset:32768
	ds_read_b128 v[110:113], v6 offset:34816
	ds_read_b128 v[114:117], v7 offset:49152
	ds_read_b128 v[126:129], v7 offset:51200
	ds_read_b128 v[146:149], v6 offset:36864
	ds_read_b128 v[150:153], v6 offset:38912
	ds_read_b128 v[154:157], v7 offset:53248
	ds_read_b128 v[158:161], v7 offset:55296
	s_setprio 2
	global_load_dwordx4 v[166:169], v8, s[36:37] offset:1408
	s_waitcnt vmcnt(7)
	ds_write_b128 v2, v[162:165]
	ds_read_b128 v[162:165], v4 offset:32768
	ds_read_b128 v[170:173], v5 offset:49152
	s_waitcnt lgkmcnt(8)
	v_mfma_f32_16x16x32_bf16 v[26:29], v[114:117], v[98:101], v[26:29]
	s_waitcnt lgkmcnt(3)
	v_mfma_f32_16x16x32_bf16 v[10:13], v[158:161], v[98:101], v[10:13]
	v_mfma_f32_16x16x32_bf16 v[86:89], v[126:129], v[98:101], v[86:89]
	v_mfma_f32_16x16x32_bf16 v[94:97], v[154:157], v[98:101], v[94:97]
	global_load_dwordx4 v[98:101], v228, s[36:37] offset:1408
	ds_write_b128 v2, v[82:85] offset:4096
	ds_read_b128 v[82:85], v4 offset:34816
	ds_read_b128 v[174:177], v5 offset:51200
	v_mfma_f32_16x16x32_bf16 v[30:33], v[114:117], v[110:113], v[30:33]
	v_mfma_f32_16x16x32_bf16 v[42:45], v[126:129], v[110:113], v[42:45]
	v_mfma_f32_16x16x32_bf16 v[14:17], v[158:161], v[110:113], v[14:17]
	v_mfma_f32_16x16x32_bf16 v[90:93], v[154:157], v[110:113], v[90:93]
	global_load_dwordx4 v[110:113], v229, s[36:37] offset:1408
	s_waitcnt vmcnt(7)
; template <int MODE>
; __device__ __forceinline__ void gemm_tile(const Params& P, int tm, int tn, unsigned char* smem) {
;     ...
; #pragma unroll
;         for (int i = 0; i < 4; ++i) { fa[i] = *(const bf16x8*)(sA + arow_off + i * 2048 + ch0); fb[i] = *(const bf16x8*)(sB + brow_off + i * 2048 + ch0); }
;         __builtin_amdgcn_sched_barrier(0);
;         __builtin_amdgcn_s_setprio(2);
;         if (wr_ok) *(uint4*)(nA + soff0) = ra0;
;         if (ld_ok) ra0 = *(const uint4*)(Ab + (aoff + 0u * LDA + koa));
;         ga[0] = *(const bf16x8*)(sA + arow_off + 0 * 2048 + ch1); gb[0] = *(const bf16x8*)(sB + brow_off + 0 * 2048 + ch1);
;         __builtin_amdgcn_sched_barrier(0);
; #pragma unroll
;         for (int j = 0; j < 4; ++j) acc[0][j] = __builtin_amdgcn_mfma_f32_16x16x32_bf16(fb[j], fa[0], acc[0][j], 0, 0, 0);
;         __builtin_amdgcn_sched_barrier(0);
;         if (wr_ok) *(uint4*)(nA + soff0 + 4096) = ra1;
;         if (ld_ok) ra1 = *(const uint4*)(Ab + (aoff + 32u * LDA + koa));
;         ga[1] = *(const bf16x8*)(sA + arow_off + 1 * 2048 + ch1); gb[1] = *(const bf16x8*)(sB + brow_off + 1 * 2048 + ch1);
;         __builtin_amdgcn_sched_barrier(0);
; #pragma unroll
;         for (int j = 0; j < 4; ++j) acc[1][j] = __builtin_amdgcn_mfma_f32_16x16x32_bf16(fb[j], fa[1], acc[1][j], 0, 0, 0);
;         __builtin_amdgcn_sched_barrier(0);
;         if (wr_ok) *(uint4*)(nA + soff0 + 8192) = ra2;
;         if (ld_ok) ra2 = *(const uint4*)(Ab + (aoff + 64u * LDA + koa));
;         ga[2] = *(const bf16x8*)(sA + arow_off + 2 * 2048 + ch1); gb[2] = *(const bf16x8*)(sB + brow_off + 2 * 2048 + ch1);
;         __builtin_amdgcn_sched_barrier(0);
; #pragma unroll
;         for (int j = 0; j < 4; ++j) acc[2][j] = __builtin_amdgcn_mfma_f32_16x16x32_bf16(fb[j], fa[2], acc[2][j], 0, 0, 0);
;         __builtin_amdgcn_sched_barrier(0);
;         if (wr_ok) *(uint4*)(nA + soff0 + 12288) = ra3;
;         if (ld_ok) ra3 = *(const uint4*)(Ab + (aoff + 96u * LDA + koa));
;         ga[3] = *(const bf16x8*)(sA + arow_off + 3 * 2048 + ch1); gb[3] = *(const bf16x8*)(sB + brow_off + 3 * 2048 + ch1);
;         __builtin_amdgcn_sched_barrier(0);
; #pragma unroll
;         for (int j = 0; j < 4; ++j) acc[3][j] = __builtin_amdgcn_mfma_f32_16x16x32_bf16(fb[j], fa[3], acc[3][j], 0, 0, 0);
;         __builtin_amdgcn_sched_barrier(0);
;         if (wr_ok) *(uint4*)(nB + soff0) = rb0;
	ds_write_b128 v2, v[106:109] offset:8192
	ds_read_b128 v[106:109], v4 offset:36864
	ds_read_b128 v[178:181], v5 offset:53248
	v_mfma_f32_16x16x32_bf16 v[34:37], v[114:117], v[146:149], v[34:37]
	v_mfma_f32_16x16x32_bf16 v[46:49], v[126:129], v[146:149], v[46:49]
	v_mfma_f32_16x16x32_bf16 v[58:61], v[154:157], v[146:149], v[58:61]
	v_mfma_f32_16x16x32_bf16 v[18:21], v[158:161], v[146:149], v[18:21]
	global_load_dwordx4 v[146:149], v230, s[36:37] offset:1408
	ds_write_b128 v2, v[132:135] offset:12288
	ds_read_b128 v[132:135], v4 offset:38912
	ds_read_b128 v[182:185], v5 offset:55296
	v_mfma_f32_16x16x32_bf16 v[38:41], v[114:117], v[150:153], v[38:41]
	v_mfma_f32_16x16x32_bf16 v[50:53], v[126:129], v[150:153], v[50:53]
	v_mfma_f32_16x16x32_bf16 v[54:57], v[154:157], v[150:153], v[54:57]
	v_mfma_f32_16x16x32_bf16 v[22:25], v[158:161], v[150:153], v[22:25]
	global_load_dwordx4 v[114:117], v3, s[0:1] offset:1408
	s_waitcnt vmcnt(7)
	ds_write_b128 v2, v[122:125] offset:16384
	s_waitcnt lgkmcnt(10)
	v_mfma_f32_16x16x32_bf16 v[26:29], v[170:173], v[162:165], v[26:29]
	s_waitcnt lgkmcnt(1)
	v_mfma_f32_16x16x32_bf16 v[10:13], v[182:185], v[162:165], v[10:13]
	v_mfma_f32_16x16x32_bf16 v[86:89], v[174:177], v[162:165], v[86:89]
	v_mfma_f32_16x16x32_bf16 v[94:97], v[178:181], v[162:165], v[94:97]
	global_load_dwordx4 v[122:125], v231, s[0:1] offset:1408
	ds_write_b128 v2, v[118:121] offset:20480
	v_mfma_f32_16x16x32_bf16 v[30:33], v[170:173], v[82:85], v[30:33]
	v_mfma_f32_16x16x32_bf16 v[42:45], v[174:177], v[82:85], v[42:45]
	v_mfma_f32_16x16x32_bf16 v[14:17], v[182:185], v[82:85], v[14:17]
	v_mfma_f32_16x16x32_bf16 v[90:93], v[178:181], v[82:85], v[90:93]
	global_load_dwordx4 v[82:85], v232, s[0:1] offset:1408
	s_waitcnt vmcnt(7)
	ds_write_b128 v2, v[102:105] offset:24576
	v_mfma_f32_16x16x32_bf16 v[34:37], v[170:173], v[106:109], v[34:37]
	v_mfma_f32_16x16x32_bf16 v[46:49], v[174:177], v[106:109], v[46:49]
	v_mfma_f32_16x16x32_bf16 v[58:61], v[178:181], v[106:109], v[58:61]
	v_mfma_f32_16x16x32_bf16 v[18:21], v[182:185], v[106:109], v[18:21]
	global_load_dwordx4 v[102:105], v233, s[0:1] offset:1408
	ds_write_b128 v2, v[62:65] offset:28672
	v_mfma_f32_16x16x32_bf16 v[38:41], v[170:173], v[132:135], v[38:41]
	v_mfma_f32_16x16x32_bf16 v[50:53], v[174:177], v[132:135], v[50:53]
	v_mfma_f32_16x16x32_bf16 v[54:57], v[178:181], v[132:135], v[54:57]
	v_mfma_f32_16x16x32_bf16 v[22:25], v[182:185], v[132:135], v[22:25]
	s_setprio 0
	s_waitcnt lgkmcnt(0)
	s_barrier
	ds_read_b128 v[62:65], v6
	ds_read_b128 v[106:109], v6 offset:2048
	ds_read_b128 v[118:121], v7 offset:16384
	ds_read_b128 v[126:129], v7 offset:18432
	ds_read_b128 v[132:135], v6 offset:4096
	ds_read_b128 v[150:153], v6 offset:6144
	ds_read_b128 v[154:157], v7 offset:20480
	ds_read_b128 v[158:161], v7 offset:22528
	s_setprio 2
	global_load_dwordx4 v[162:165], v8, s[36:37] offset:1536
	s_waitcnt vmcnt(7)
	ds_write_b128 v2, v[166:169] offset:32768
	ds_read_b128 v[166:169], v4
	ds_read_b128 v[170:173], v5 offset:16384
	s_waitcnt lgkmcnt(8)
	v_mfma_f32_16x16x32_bf16 v[26:29], v[118:121], v[62:65], v[26:29]
	s_waitcnt lgkmcnt(3)
	v_mfma_f32_16x16x32_bf16 v[10:13], v[158:161], v[62:65], v[10:13]
	v_mfma_f32_16x16x32_bf16 v[86:89], v[126:129], v[62:65], v[86:89]
	v_mfma_f32_16x16x32_bf16 v[94:97], v[154:157], v[62:65], v[94:97]
	global_load_dwordx4 v[62:65], v228, s[36:37] offset:1536
	ds_write_b128 v2, v[98:101] offset:36864
	ds_read_b128 v[98:101], v4 offset:2048
	ds_read_b128 v[174:177], v5 offset:18432
	v_mfma_f32_16x16x32_bf16 v[30:33], v[118:121], v[106:109], v[30:33]
	v_mfma_f32_16x16x32_bf16 v[42:45], v[126:129], v[106:109], v[42:45]
	v_mfma_f32_16x16x32_bf16 v[14:17], v[158:161], v[106:109], v[14:17]
	v_mfma_f32_16x16x32_bf16 v[90:93], v[154:157], v[106:109], v[90:93]
	global_load_dwordx4 v[106:109], v229, s[36:37] offset:1536
	s_waitcnt vmcnt(7)
	ds_write_b128 v2, v[110:113] offset:40960
	ds_read_b128 v[110:113], v4 offset:4096
	ds_read_b128 v[178:181], v5 offset:20480
	v_mfma_f32_16x16x32_bf16 v[34:37], v[118:121], v[132:135], v[34:37]
	v_mfma_f32_16x16x32_bf16 v[46:49], v[126:129], v[132:135], v[46:49]
	v_mfma_f32_16x16x32_bf16 v[58:61], v[154:157], v[132:135], v[58:61]
	v_mfma_f32_16x16x32_bf16 v[18:21], v[158:161], v[132:135], v[18:21]
	global_load_dwordx4 v[132:135], v230, s[36:37] offset:1536
	ds_write_b128 v2, v[146:149] offset:45056
	ds_read_b128 v[146:149], v4 offset:6144
	ds_read_b128 v[182:185], v5 offset:22528
	v_mfma_f32_16x16x32_bf16 v[38:41], v[118:121], v[150:153], v[38:41]
	v_mfma_f32_16x16x32_bf16 v[50:53], v[126:129], v[150:153], v[50:53]
	v_mfma_f32_16x16x32_bf16 v[54:57], v[154:157], v[150:153], v[54:57]
	v_mfma_f32_16x16x32_bf16 v[22:25], v[158:161], v[150:153], v[22:25]
	global_load_dwordx4 v[118:121], v3, s[0:1] offset:1536
	s_waitcnt vmcnt(7)
	ds_write_b128 v2, v[114:117] offset:49152
	s_waitcnt lgkmcnt(10)
	v_mfma_f32_16x16x32_bf16 v[26:29], v[170:173], v[166:169], v[26:29]
	s_waitcnt lgkmcnt(1)
	v_mfma_f32_16x16x32_bf16 v[10:13], v[182:185], v[166:169], v[10:13]
	v_mfma_f32_16x16x32_bf16 v[86:89], v[174:177], v[166:169], v[86:89]
	v_mfma_f32_16x16x32_bf16 v[94:97], v[178:181], v[166:169], v[94:97]
	global_load_dwordx4 v[114:117], v231, s[0:1] offset:1536
	ds_write_b128 v2, v[122:125] offset:53248
	v_mfma_f32_16x16x32_bf16 v[30:33], v[170:173], v[98:101], v[30:33]
	v_mfma_f32_16x16x32_bf16 v[42:45], v[174:177], v[98:101], v[42:45]
	v_mfma_f32_16x16x32_bf16 v[14:17], v[182:185], v[98:101], v[14:17]
	v_mfma_f32_16x16x32_bf16 v[90:93], v[178:181], v[98:101], v[90:93]
	global_load_dwordx4 v[98:101], v232, s[0:1] offset:1536
	s_waitcnt vmcnt(7)
	ds_write_b128 v2, v[82:85] offset:57344
	v_mfma_f32_16x16x32_bf16 v[34:37], v[170:173], v[110:113], v[34:37]
	v_mfma_f32_16x16x32_bf16 v[46:49], v[174:177], v[110:113], v[46:49]
	v_mfma_f32_16x16x32_bf16 v[58:61], v[178:181], v[110:113], v[58:61]
	v_mfma_f32_16x16x32_bf16 v[18:21], v[182:185], v[110:113], v[18:21]
	global_load_dwordx4 v[82:85], v233, s[0:1] offset:1536
	ds_write_b128 v2, v[102:105] offset:61440
	v_mfma_f32_16x16x32_bf16 v[38:41], v[170:173], v[146:149], v[38:41]
	v_mfma_f32_16x16x32_bf16 v[50:53], v[174:177], v[146:149], v[50:53]
	v_mfma_f32_16x16x32_bf16 v[54:57], v[178:181], v[146:149], v[54:57]
	v_mfma_f32_16x16x32_bf16 v[22:25], v[182:185], v[146:149], v[22:25]
	s_setprio 0
	s_waitcnt lgkmcnt(0)
	s_barrier
; template <int MODE>
; __device__ __forceinline__ void gemm_tile(const Params& P, int tm, int tn, unsigned char* smem) {
;     ...
; #pragma unroll
;         for (int i = 0; i < 4; ++i) { fa[i] = *(const bf16x8*)(sA + arow_off + i * 2048 + ch0); fb[i] = *(const bf16x8*)(sB + brow_off + i * 2048 + ch0); }
;         __builtin_amdgcn_sched_barrier(0);
;         __builtin_amdgcn_s_setprio(2);
;         if (wr_ok) *(uint4*)(nA + soff0) = ra0;
;         if (ld_ok) ra0 = *(const uint4*)(Ab + (aoff + 0u * LDA + koa));
;         ga[0] = *(const bf16x8*)(sA + arow_off + 0 * 2048 + ch1); gb[0] = *(const bf16x8*)(sB + brow_off + 0 * 2048 + ch1);
;         __builtin_amdgcn_sched_barrier(0);
; #pragma unroll
;         for (int j = 0; j < 4; ++j) acc[0][j] = __builtin_amdgcn_mfma_f32_16x16x32_bf16(fb[j], fa[0], acc[0][j], 0, 0, 0);
;         __builtin_amdgcn_sched_barrier(0);
;         if (wr_ok) *(uint4*)(nA + soff0 + 4096) = ra1;
;         if (ld_ok) ra1 = *(const uint4*)(Ab + (aoff + 32u * LDA + koa));
;         ga[1] = *(const bf16x8*)(sA + arow_off + 1 * 2048 + ch1); gb[1] = *(const bf16x8*)(sB + brow_off + 1 * 2048 + ch1);
;         __builtin_amdgcn_sched_barrier(0);
; #pragma unroll
;         for (int j = 0; j < 4; ++j) acc[1][j] = __builtin_amdgcn_mfma_f32_16x16x32_bf16(fb[j], fa[1], acc[1][j], 0, 0, 0);
;         __builtin_amdgcn_sched_barrier(0);
;         if (wr_ok) *(uint4*)(nA + soff0 + 8192) = ra2;
;         if (ld_ok) ra2 = *(const uint4*)(Ab + (aoff + 64u * LDA + koa));
;         ga[2] = *(const bf16x8*)(sA + arow_off + 2 * 2048 + ch1); gb[2] = *(const bf16x8*)(sB + brow_off + 2 * 2048 + ch1);
;         __builtin_amdgcn_sched_barrier(0);
; #pragma unroll
;         for (int j = 0; j < 4; ++j) acc[2][j] = __builtin_amdgcn_mfma_f32_16x16x32_bf16(fb[j], fa[2], acc[2][j], 0, 0, 0);
;         __builtin_amdgcn_sched_barrier(0);
;         if (wr_ok) *(uint4*)(nA + soff0 + 12288) = ra3;
;         if (ld_ok) ra3 = *(const uint4*)(Ab + (aoff + 96u * LDA + koa));
;         ga[3] = *(const bf16x8*)(sA + arow_off + 3 * 2048 + ch1); gb[3] = *(const bf16x8*)(sB + brow_off + 3 * 2048 + ch1);
;         __builtin_amdgcn_sched_barrier(0);
; #pragma unroll
;         for (int j = 0; j < 4; ++j) acc[3][j] = __builtin_amdgcn_mfma_f32_16x16x32_bf16(fb[j], fa[3], acc[3][j], 0, 0, 0);
;         __builtin_amdgcn_sched_barrier(0);
;         if (wr_ok) *(uint4*)(nB + soff0) = rb0;
	ds_read_b128 v[102:105], v6 offset:32768
	ds_read_b128 v[110:113], v6 offset:34816
	ds_read_b128 v[122:125], v7 offset:49152
	ds_read_b128 v[126:129], v7 offset:51200
	ds_read_b128 v[146:149], v6 offset:36864
	ds_read_b128 v[150:153], v6 offset:38912
	ds_read_b128 v[154:157], v7 offset:53248
	ds_read_b128 v[158:161], v7 offset:55296
	s_setprio 2
	global_load_dwordx4 v[166:169], v8, s[36:37] offset:1664
	s_waitcnt vmcnt(7)
	ds_write_b128 v2, v[162:165]
	ds_read_b128 v[162:165], v4 offset:32768
	ds_read_b128 v[170:173], v5 offset:49152
	s_waitcnt lgkmcnt(8)
	v_mfma_f32_16x16x32_bf16 v[26:29], v[122:125], v[102:105], v[26:29]
	s_waitcnt lgkmcnt(3)
	v_mfma_f32_16x16x32_bf16 v[10:13], v[158:161], v[102:105], v[10:13]
	v_mfma_f32_16x16x32_bf16 v[86:89], v[126:129], v[102:105], v[86:89]
	v_mfma_f32_16x16x32_bf16 v[94:97], v[154:157], v[102:105], v[94:97]
	global_load_dwordx4 v[102:105], v228, s[36:37] offset:1664
	ds_write_b128 v2, v[62:65] offset:4096
	ds_read_b128 v[62:65], v4 offset:34816
	ds_read_b128 v[174:177], v5 offset:51200
	v_mfma_f32_16x16x32_bf16 v[30:33], v[122:125], v[110:113], v[30:33]
	v_mfma_f32_16x16x32_bf16 v[42:45], v[126:129], v[110:113], v[42:45]
	v_mfma_f32_16x16x32_bf16 v[14:17], v[158:161], v[110:113], v[14:17]
	v_mfma_f32_16x16x32_bf16 v[90:93], v[154:157], v[110:113], v[90:93]
	global_load_dwordx4 v[110:113], v229, s[36:37] offset:1664
	s_waitcnt vmcnt(7)
	ds_write_b128 v2, v[106:109] offset:8192
	ds_read_b128 v[106:109], v4 offset:36864
	ds_read_b128 v[178:181], v5 offset:53248
	v_mfma_f32_16x16x32_bf16 v[34:37], v[122:125], v[146:149], v[34:37]
	v_mfma_f32_16x16x32_bf16 v[46:49], v[126:129], v[146:149], v[46:49]
	v_mfma_f32_16x16x32_bf16 v[58:61], v[154:157], v[146:149], v[58:61]
	v_mfma_f32_16x16x32_bf16 v[18:21], v[158:161], v[146:149], v[18:21]
	global_load_dwordx4 v[146:149], v230, s[36:37] offset:1664
	ds_write_b128 v2, v[132:135] offset:12288
	ds_read_b128 v[132:135], v4 offset:38912
	ds_read_b128 v[182:185], v5 offset:55296
	v_mfma_f32_16x16x32_bf16 v[38:41], v[122:125], v[150:153], v[38:41]
	v_mfma_f32_16x16x32_bf16 v[50:53], v[126:129], v[150:153], v[50:53]
	v_mfma_f32_16x16x32_bf16 v[54:57], v[154:157], v[150:153], v[54:57]
	v_mfma_f32_16x16x32_bf16 v[22:25], v[158:161], v[150:153], v[22:25]
	global_load_dwordx4 v[122:125], v3, s[0:1] offset:1664
	s_waitcnt vmcnt(7)
	ds_write_b128 v2, v[118:121] offset:16384
	s_waitcnt lgkmcnt(10)
	v_mfma_f32_16x16x32_bf16 v[26:29], v[170:173], v[162:165], v[26:29]
	s_waitcnt lgkmcnt(1)
	v_mfma_f32_16x16x32_bf16 v[10:13], v[182:185], v[162:165], v[10:13]
	v_mfma_f32_16x16x32_bf16 v[86:89], v[174:177], v[162:165], v[86:89]
	v_mfma_f32_16x16x32_bf16 v[94:97], v[178:181], v[162:165], v[94:97]
	global_load_dwordx4 v[118:121], v231, s[0:1] offset:1664
	ds_write_b128 v2, v[114:117] offset:20480
	v_mfma_f32_16x16x32_bf16 v[30:33], v[170:173], v[62:65], v[30:33]
	v_mfma_f32_16x16x32_bf16 v[42:45], v[174:177], v[62:65], v[42:45]
	v_mfma_f32_16x16x32_bf16 v[14:17], v[182:185], v[62:65], v[14:17]
	v_mfma_f32_16x16x32_bf16 v[90:93], v[178:181], v[62:65], v[90:93]
	global_load_dwordx4 v[62:65], v232, s[0:1] offset:1664
	s_waitcnt vmcnt(7)
	ds_write_b128 v2, v[98:101] offset:24576
	v_mfma_f32_16x16x32_bf16 v[34:37], v[170:173], v[106:109], v[34:37]
	v_mfma_f32_16x16x32_bf16 v[46:49], v[174:177], v[106:109], v[46:49]
	v_mfma_f32_16x16x32_bf16 v[58:61], v[178:181], v[106:109], v[58:61]
	v_mfma_f32_16x16x32_bf16 v[18:21], v[182:185], v[106:109], v[18:21]
	global_load_dwordx4 v[98:101], v233, s[0:1] offset:1664
	ds_write_b128 v2, v[82:85] offset:28672
	v_mfma_f32_16x16x32_bf16 v[38:41], v[170:173], v[132:135], v[38:41]
	v_mfma_f32_16x16x32_bf16 v[50:53], v[174:177], v[132:135], v[50:53]
	v_mfma_f32_16x16x32_bf16 v[54:57], v[178:181], v[132:135], v[54:57]
	v_mfma_f32_16x16x32_bf16 v[22:25], v[182:185], v[132:135], v[22:25]
	s_setprio 0
	s_waitcnt lgkmcnt(0)
	s_barrier
	ds_read_b128 v[82:85], v6
	ds_read_b128 v[106:109], v6 offset:2048
	ds_read_b128 v[114:117], v7 offset:16384
	ds_read_b128 v[126:129], v7 offset:18432
	ds_read_b128 v[132:135], v6 offset:4096
	ds_read_b128 v[150:153], v6 offset:6144
	ds_read_b128 v[154:157], v7 offset:20480
	ds_read_b128 v[158:161], v7 offset:22528
	s_setprio 2
	global_load_dwordx4 v[162:165], v8, s[36:37] offset:1792
	s_waitcnt vmcnt(7)
	ds_write_b128 v2, v[166:169] offset:32768
	ds_read_b128 v[166:169], v4
	ds_read_b128 v[170:173], v5 offset:16384
	s_waitcnt lgkmcnt(8)
	v_mfma_f32_16x16x32_bf16 v[26:29], v[114:117], v[82:85], v[26:29]
	s_waitcnt lgkmcnt(3)
	v_mfma_f32_16x16x32_bf16 v[10:13], v[158:161], v[82:85], v[10:13]
	v_mfma_f32_16x16x32_bf16 v[86:89], v[126:129], v[82:85], v[86:89]
	v_mfma_f32_16x16x32_bf16 v[94:97], v[154:157], v[82:85], v[94:97]
	global_load_dwordx4 v[82:85], v228, s[36:37] offset:1792
	ds_write_b128 v2, v[102:105] offset:36864
	ds_read_b128 v[102:105], v4 offset:2048
	ds_read_b128 v[174:177], v5 offset:18432
	v_mfma_f32_16x16x32_bf16 v[30:33], v[114:117], v[106:109], v[30:33]
	v_mfma_f32_16x16x32_bf16 v[42:45], v[126:129], v[106:109], v[42:45]
	v_mfma_f32_16x16x32_bf16 v[14:17], v[158:161], v[106:109], v[14:17]
	v_mfma_f32_16x16x32_bf16 v[90:93], v[154:157], v[106:109], v[90:93]
	global_load_dwordx4 v[106:109], v229, s[36:37] offset:1792
	s_waitcnt vmcnt(7)
; template <int MODE>
; __device__ __forceinline__ void gemm_tile(const Params& P, int tm, int tn, unsigned char* smem) {
;     ...
; #pragma unroll
;         for (int i = 0; i < 4; ++i) { fa[i] = *(const bf16x8*)(sA + arow_off + i * 2048 + ch0); fb[i] = *(const bf16x8*)(sB + brow_off + i * 2048 + ch0); }
;         __builtin_amdgcn_sched_barrier(0);
;         __builtin_amdgcn_s_setprio(2);
;         if (wr_ok) *(uint4*)(nA + soff0) = ra0;
;         if (ld_ok) ra0 = *(const uint4*)(Ab + (aoff + 0u * LDA + koa));
;         ga[0] = *(const bf16x8*)(sA + arow_off + 0 * 2048 + ch1); gb[0] = *(const bf16x8*)(sB + brow_off + 0 * 2048 + ch1);
;         __builtin_amdgcn_sched_barrier(0);
; #pragma unroll
;         for (int j = 0; j < 4; ++j) acc[0][j] = __builtin_amdgcn_mfma_f32_16x16x32_bf16(fb[j], fa[0], acc[0][j], 0, 0, 0);
;         __builtin_amdgcn_sched_barrier(0);
;         if (wr_ok) *(uint4*)(nA + soff0 + 4096) = ra1;
;         if (ld_ok) ra1 = *(const uint4*)(Ab + (aoff + 32u * LDA + koa));
;         ga[1] = *(const bf16x8*)(sA + arow_off + 1 * 2048 + ch1); gb[1] = *(const bf16x8*)(sB + brow_off + 1 * 2048 + ch1);
;         __builtin_amdgcn_sched_barrier(0);
; #pragma unroll
;         for (int j = 0; j < 4; ++j) acc[1][j] = __builtin_amdgcn_mfma_f32_16x16x32_bf16(fb[j], fa[1], acc[1][j], 0, 0, 0);
;         __builtin_amdgcn_sched_barrier(0);
;         if (wr_ok) *(uint4*)(nA + soff0 + 8192) = ra2;
;         if (ld_ok) ra2 = *(const uint4*)(Ab + (aoff + 64u * LDA + koa));
;         ga[2] = *(const bf16x8*)(sA + arow_off + 2 * 2048 + ch1); gb[2] = *(const bf16x8*)(sB + brow_off + 2 * 2048 + ch1);
;         __builtin_amdgcn_sched_barrier(0);
; #pragma unroll
;         for (int j = 0; j < 4; ++j) acc[2][j] = __builtin_amdgcn_mfma_f32_16x16x32_bf16(fb[j], fa[2], acc[2][j], 0, 0, 0);
;         __builtin_amdgcn_sched_barrier(0);
;         if (wr_ok) *(uint4*)(nA + soff0 + 12288) = ra3;
;         if (ld_ok) ra3 = *(const uint4*)(Ab + (aoff + 96u * LDA + koa));
;         ga[3] = *(const bf16x8*)(sA + arow_off + 3 * 2048 + ch1); gb[3] = *(const bf16x8*)(sB + brow_off + 3 * 2048 + ch1);
;         __builtin_amdgcn_sched_barrier(0);
; #pragma unroll
;         for (int j = 0; j < 4; ++j) acc[3][j] = __builtin_amdgcn_mfma_f32_16x16x32_bf16(fb[j], fa[3], acc[3][j], 0, 0, 0);
;         __builtin_amdgcn_sched_barrier(0);
;         if (wr_ok) *(uint4*)(nB + soff0) = rb0;
	ds_write_b128 v2, v[110:113] offset:40960
	ds_read_b128 v[110:113], v4 offset:4096
	ds_read_b128 v[178:181], v5 offset:20480
	v_mfma_f32_16x16x32_bf16 v[34:37], v[114:117], v[132:135], v[34:37]
	v_mfma_f32_16x16x32_bf16 v[46:49], v[126:129], v[132:135], v[46:49]
	v_mfma_f32_16x16x32_bf16 v[58:61], v[154:157], v[132:135], v[58:61]
	v_mfma_f32_16x16x32_bf16 v[18:21], v[158:161], v[132:135], v[18:21]
	global_load_dwordx4 v[132:135], v230, s[36:37] offset:1792
	ds_write_b128 v2, v[146:149] offset:45056
	ds_read_b128 v[146:149], v4 offset:6144
	ds_read_b128 v[182:185], v5 offset:22528
	v_mfma_f32_16x16x32_bf16 v[38:41], v[114:117], v[150:153], v[38:41]
	v_mfma_f32_16x16x32_bf16 v[50:53], v[126:129], v[150:153], v[50:53]
	v_mfma_f32_16x16x32_bf16 v[54:57], v[154:157], v[150:153], v[54:57]
	v_mfma_f32_16x16x32_bf16 v[22:25], v[158:161], v[150:153], v[22:25]
	global_load_dwordx4 v[114:117], v3, s[0:1] offset:1792
	s_waitcnt vmcnt(7)
	ds_write_b128 v2, v[122:125] offset:49152
	s_waitcnt lgkmcnt(10)
	v_mfma_f32_16x16x32_bf16 v[26:29], v[170:173], v[166:169], v[26:29]
	s_waitcnt lgkmcnt(1)
	v_mfma_f32_16x16x32_bf16 v[10:13], v[182:185], v[166:169], v[10:13]
	v_mfma_f32_16x16x32_bf16 v[86:89], v[174:177], v[166:169], v[86:89]
	v_mfma_f32_16x16x32_bf16 v[94:97], v[178:181], v[166:169], v[94:97]
	global_load_dwordx4 v[122:125], v231, s[0:1] offset:1792
	ds_write_b128 v2, v[118:121] offset:53248
	v_mfma_f32_16x16x32_bf16 v[30:33], v[170:173], v[102:105], v[30:33]
	v_mfma_f32_16x16x32_bf16 v[42:45], v[174:177], v[102:105], v[42:45]
	v_mfma_f32_16x16x32_bf16 v[14:17], v[182:185], v[102:105], v[14:17]
	v_mfma_f32_16x16x32_bf16 v[90:93], v[178:181], v[102:105], v[90:93]
	global_load_dwordx4 v[102:105], v232, s[0:1] offset:1792
	s_waitcnt vmcnt(7)
	ds_write_b128 v2, v[62:65] offset:57344
	v_mfma_f32_16x16x32_bf16 v[34:37], v[170:173], v[110:113], v[34:37]
	v_mfma_f32_16x16x32_bf16 v[46:49], v[174:177], v[110:113], v[46:49]
	v_mfma_f32_16x16x32_bf16 v[58:61], v[178:181], v[110:113], v[58:61]
	v_mfma_f32_16x16x32_bf16 v[18:21], v[182:185], v[110:113], v[18:21]
	global_load_dwordx4 v[62:65], v233, s[0:1] offset:1792
	ds_write_b128 v2, v[98:101] offset:61440
	v_mfma_f32_16x16x32_bf16 v[38:41], v[170:173], v[146:149], v[38:41]
	v_mfma_f32_16x16x32_bf16 v[50:53], v[174:177], v[146:149], v[50:53]
	v_mfma_f32_16x16x32_bf16 v[54:57], v[178:181], v[146:149], v[54:57]
	v_mfma_f32_16x16x32_bf16 v[22:25], v[182:185], v[146:149], v[22:25]
	s_setprio 0
	s_waitcnt lgkmcnt(0)
	s_barrier
	ds_read_b128 v[98:101], v6 offset:32768
	ds_read_b128 v[110:113], v6 offset:34816
	ds_read_b128 v[118:121], v7 offset:49152
	ds_read_b128 v[126:129], v7 offset:51200
	ds_read_b128 v[146:149], v6 offset:36864
	ds_read_b128 v[150:153], v6 offset:38912
	ds_read_b128 v[154:157], v7 offset:53248
	ds_read_b128 v[158:161], v7 offset:55296
	s_setprio 2
	global_load_dwordx4 v[166:169], v8, s[36:37] offset:1920
	s_waitcnt vmcnt(7)
	ds_write_b128 v2, v[162:165]
	ds_read_b128 v[162:165], v4 offset:32768
	ds_read_b128 v[170:173], v5 offset:49152
	s_waitcnt lgkmcnt(8)
	v_mfma_f32_16x16x32_bf16 v[26:29], v[118:121], v[98:101], v[26:29]
	s_waitcnt lgkmcnt(3)
	v_mfma_f32_16x16x32_bf16 v[10:13], v[158:161], v[98:101], v[10:13]
	v_mfma_f32_16x16x32_bf16 v[86:89], v[126:129], v[98:101], v[86:89]
	v_mfma_f32_16x16x32_bf16 v[94:97], v[154:157], v[98:101], v[94:97]
	global_load_dwordx4 v[98:101], v228, s[36:37] offset:1920
	ds_write_b128 v2, v[82:85] offset:4096
	ds_read_b128 v[82:85], v4 offset:34816
	ds_read_b128 v[174:177], v5 offset:51200
	v_mfma_f32_16x16x32_bf16 v[30:33], v[118:121], v[110:113], v[30:33]
	v_mfma_f32_16x16x32_bf16 v[42:45], v[126:129], v[110:113], v[42:45]
	v_mfma_f32_16x16x32_bf16 v[14:17], v[158:161], v[110:113], v[14:17]
	v_mfma_f32_16x16x32_bf16 v[90:93], v[154:157], v[110:113], v[90:93]
	global_load_dwordx4 v[110:113], v229, s[36:37] offset:1920
	s_waitcnt vmcnt(7)
	ds_write_b128 v2, v[106:109] offset:8192
	ds_read_b128 v[106:109], v4 offset:36864
	ds_read_b128 v[178:181], v5 offset:53248
	v_mfma_f32_16x16x32_bf16 v[34:37], v[118:121], v[146:149], v[34:37]
	v_mfma_f32_16x16x32_bf16 v[46:49], v[126:129], v[146:149], v[46:49]
	v_mfma_f32_16x16x32_bf16 v[58:61], v[154:157], v[146:149], v[58:61]
	v_mfma_f32_16x16x32_bf16 v[18:21], v[158:161], v[146:149], v[18:21]
	v_add_u32_e32 v8, 0x30780, v8
	global_load_dwordx4 v[146:149], v8, s[36:37]
	ds_write_b128 v2, v[132:135] offset:12288
	ds_read_b128 v[132:135], v4 offset:38912
	ds_read_b128 v[182:185], v5 offset:55296
	v_mfma_f32_16x16x32_bf16 v[38:41], v[118:121], v[150:153], v[38:41]
	v_mfma_f32_16x16x32_bf16 v[50:53], v[126:129], v[150:153], v[50:53]
	v_mfma_f32_16x16x32_bf16 v[54:57], v[154:157], v[150:153], v[54:57]
	v_mfma_f32_16x16x32_bf16 v[22:25], v[158:161], v[150:153], v[22:25]
	global_load_dwordx4 v[118:121], v3, s[0:1] offset:1920
	s_waitcnt vmcnt(7)
	ds_write_b128 v2, v[114:117] offset:16384
	s_waitcnt lgkmcnt(10)
	v_mfma_f32_16x16x32_bf16 v[26:29], v[170:173], v[162:165], v[26:29]
	s_waitcnt lgkmcnt(1)
	v_mfma_f32_16x16x32_bf16 v[8:11], v[182:185], v[162:165], v[10:13]
	v_mfma_f32_16x16x32_bf16 v[86:89], v[174:177], v[162:165], v[86:89]
	v_mfma_f32_16x16x32_bf16 v[94:97], v[178:181], v[162:165], v[94:97]
	s_nop 0
	global_load_dwordx4 v[114:117], v231, s[0:1] offset:1920
	ds_write_b128 v2, v[122:125] offset:20480
	v_mfma_f32_16x16x32_bf16 v[30:33], v[170:173], v[82:85], v[30:33]
	v_mfma_f32_16x16x32_bf16 v[42:45], v[174:177], v[82:85], v[42:45]
	v_mfma_f32_16x16x32_bf16 v[12:15], v[182:185], v[82:85], v[14:17]
	v_mfma_f32_16x16x32_bf16 v[90:93], v[178:181], v[82:85], v[90:93]
	s_nop 1
	global_load_dwordx4 v[82:85], v232, s[0:1] offset:1920
	s_waitcnt vmcnt(7)
	ds_write_b128 v2, v[102:105] offset:24576
	v_mfma_f32_16x16x32_bf16 v[34:37], v[170:173], v[106:109], v[34:37]
	v_mfma_f32_16x16x32_bf16 v[46:49], v[174:177], v[106:109], v[46:49]
	v_mfma_f32_16x16x32_bf16 v[58:61], v[178:181], v[106:109], v[58:61]
	v_mfma_f32_16x16x32_bf16 v[16:19], v[182:185], v[106:109], v[18:21]
	v_add_u32_e32 v3, 0x30780, v3
	global_load_dwordx4 v[102:105], v3, s[0:1]
	ds_write_b128 v2, v[62:65] offset:28672
	v_mfma_f32_16x16x32_bf16 v[38:41], v[170:173], v[132:135], v[38:41]
	v_mfma_f32_16x16x32_bf16 v[50:53], v[174:177], v[132:135], v[50:53]
	v_mfma_f32_16x16x32_bf16 v[54:57], v[178:181], v[132:135], v[54:57]
	v_mfma_f32_16x16x32_bf16 v[20:23], v[182:185], v[132:135], v[22:25]
	s_setprio 0
	s_waitcnt lgkmcnt(0)
	s_barrier
; template <int MODE>
; __device__ __forceinline__ void gemm_tile(const Params& P, int tm, int tn, unsigned char* smem) {
;     ...
; #pragma unroll
;         for (int i = 0; i < 4; ++i) { fa[i] = *(const bf16x8*)(sA + arow_off + i * 2048 + ch0); fb[i] = *(const bf16x8*)(sB + brow_off + i * 2048 + ch0); }
;         __builtin_amdgcn_sched_barrier(0);
;         __builtin_amdgcn_s_setprio(2);
;         if (wr_ok) *(uint4*)(nA + soff0) = ra0;
;         if (ld_ok) ra0 = *(const uint4*)(Ab + (aoff + 0u * LDA + koa));
;         ga[0] = *(const bf16x8*)(sA + arow_off + 0 * 2048 + ch1); gb[0] = *(const bf16x8*)(sB + brow_off + 0 * 2048 + ch1);
;         __builtin_amdgcn_sched_barrier(0);
; #pragma unroll
;         for (int j = 0; j < 4; ++j) acc[0][j] = __builtin_amdgcn_mfma_f32_16x16x32_bf16(fb[j], fa[0], acc[0][j], 0, 0, 0);
;         __builtin_amdgcn_sched_barrier(0);
;         if (wr_ok) *(uint4*)(nA + soff0 + 4096) = ra1;
;         if (ld_ok) ra1 = *(const uint4*)(Ab + (aoff + 32u * LDA + koa));
;         ga[1] = *(const bf16x8*)(sA + arow_off + 1 * 2048 + ch1); gb[1] = *(const bf16x8*)(sB + brow_off + 1 * 2048 + ch1);
;         __builtin_amdgcn_sched_barrier(0);
; #pragma unroll
;         for (int j = 0; j < 4; ++j) acc[1][j] = __builtin_amdgcn_mfma_f32_16x16x32_bf16(fb[j], fa[1], acc[1][j], 0, 0, 0);
;         __builtin_amdgcn_sched_barrier(0);
;         if (wr_ok) *(uint4*)(nA + soff0 + 8192) = ra2;
;         if (ld_ok) ra2 = *(const uint4*)(Ab + (aoff + 64u * LDA + koa));
;         ga[2] = *(const bf16x8*)(sA + arow_off + 2 * 2048 + ch1); gb[2] = *(const bf16x8*)(sB + brow_off + 2 * 2048 + ch1);
;         __builtin_amdgcn_sched_barrier(0);
; #pragma unroll
;         for (int j = 0; j < 4; ++j) acc[2][j] = __builtin_amdgcn_mfma_f32_16x16x32_bf16(fb[j], fa[2], acc[2][j], 0, 0, 0);
;         __builtin_amdgcn_sched_barrier(0);
;         if (wr_ok) *(uint4*)(nA + soff0 + 12288) = ra3;
;         if (ld_ok) ra3 = *(const uint4*)(Ab + (aoff + 96u * LDA + koa));
;         ga[3] = *(const bf16x8*)(sA + arow_off + 3 * 2048 + ch1); gb[3] = *(const bf16x8*)(sB + brow_off + 3 * 2048 + ch1);
;         __builtin_amdgcn_sched_barrier(0);
; #pragma unroll
;         for (int j = 0; j < 4; ++j) acc[3][j] = __builtin_amdgcn_mfma_f32_16x16x32_bf16(fb[j], fa[3], acc[3][j], 0, 0, 0);
;         __builtin_amdgcn_sched_barrier(0);
;         if (wr_ok) *(uint4*)(nB + soff0) = rb0;
	ds_read_b128 v[62:65], v6
	ds_read_b128 v[106:109], v6 offset:2048
	ds_read_b128 v[122:125], v7 offset:16384
	ds_read_b128 v[126:129], v7 offset:18432
	ds_read_b128 v[132:135], v6 offset:4096
	ds_read_b128 v[150:153], v6 offset:6144
	ds_read_b128 v[154:157], v7 offset:20480
	ds_read_b128 v[158:161], v7 offset:22528
	s_setprio 2
	s_waitcnt vmcnt(7)
	ds_write_b128 v2, v[166:169] offset:32768
	ds_read_b128 v[162:165], v4
	ds_read_b128 v[166:169], v5 offset:16384
	s_waitcnt lgkmcnt(8)
	v_mfma_f32_16x16x32_bf16 v[24:27], v[122:125], v[62:65], v[26:29]
	s_waitcnt lgkmcnt(3)
	v_mfma_f32_16x16x32_bf16 v[8:11], v[158:161], v[62:65], v[8:11]
	v_mfma_f32_16x16x32_bf16 v[86:89], v[126:129], v[62:65], v[86:89]
	v_mfma_f32_16x16x32_bf16 v[94:97], v[154:157], v[62:65], v[94:97]
	s_waitcnt vmcnt(6)
	ds_write_b128 v2, v[98:101] offset:36864
	ds_read_b128 v[62:65], v4 offset:2048
	ds_read_b128 v[98:101], v5 offset:18432
	v_mfma_f32_16x16x32_bf16 v[28:31], v[122:125], v[106:109], v[30:33]
	v_mfma_f32_16x16x32_bf16 v[42:45], v[126:129], v[106:109], v[42:45]
	v_mfma_f32_16x16x32_bf16 v[12:15], v[158:161], v[106:109], v[12:15]
	v_mfma_f32_16x16x32_bf16 v[90:93], v[154:157], v[106:109], v[90:93]
	s_waitcnt vmcnt(5)
	ds_write_b128 v2, v[110:113] offset:40960
	ds_read_b128 v[106:109], v4 offset:4096
	ds_read_b128 v[110:113], v5 offset:20480
	v_mfma_f32_16x16x32_bf16 v[32:35], v[122:125], v[132:135], v[34:37]
	v_mfma_f32_16x16x32_bf16 v[46:49], v[126:129], v[132:135], v[46:49]
	v_mfma_f32_16x16x32_bf16 v[58:61], v[154:157], v[132:135], v[58:61]
	v_mfma_f32_16x16x32_bf16 v[16:19], v[158:161], v[132:135], v[16:19]
	s_waitcnt vmcnt(4)
	ds_write_b128 v2, v[146:149] offset:45056
	ds_read_b128 v[132:135], v4 offset:6144
	ds_read_b128 v[146:149], v5 offset:22528
	v_mfma_f32_16x16x32_bf16 v[36:39], v[122:125], v[150:153], v[38:41]
	v_mfma_f32_16x16x32_bf16 v[50:53], v[126:129], v[150:153], v[50:53]
	v_mfma_f32_16x16x32_bf16 v[54:57], v[154:157], v[150:153], v[54:57]
	v_mfma_f32_16x16x32_bf16 v[20:23], v[158:161], v[150:153], v[20:23]
	s_waitcnt vmcnt(3)
	ds_write_b128 v2, v[118:121] offset:49152
	s_waitcnt lgkmcnt(10)
	v_mfma_f32_16x16x32_bf16 v[24:27], v[166:169], v[162:165], v[24:27]
	s_waitcnt lgkmcnt(1)
	v_mfma_f32_16x16x32_bf16 v[8:11], v[146:149], v[162:165], v[8:11]
	v_mfma_f32_16x16x32_bf16 v[86:89], v[98:101], v[162:165], v[86:89]
	v_mfma_f32_16x16x32_bf16 v[94:97], v[110:113], v[162:165], v[94:97]
	s_waitcnt vmcnt(2)
	ds_write_b128 v2, v[114:117] offset:53248
	v_mfma_f32_16x16x32_bf16 v[28:31], v[166:169], v[62:65], v[28:31]
	v_mfma_f32_16x16x32_bf16 v[40:43], v[98:101], v[62:65], v[42:45]
	v_mfma_f32_16x16x32_bf16 v[12:15], v[146:149], v[62:65], v[12:15]
	v_mfma_f32_16x16x32_bf16 v[90:93], v[110:113], v[62:65], v[90:93]
	s_waitcnt vmcnt(1)
	ds_write_b128 v2, v[82:85] offset:57344
	v_mfma_f32_16x16x32_bf16 v[32:35], v[166:169], v[106:109], v[32:35]
	v_mfma_f32_16x16x32_bf16 v[44:47], v[98:101], v[106:109], v[46:49]
	v_mfma_f32_16x16x32_bf16 v[58:61], v[110:113], v[106:109], v[58:61]
	v_mfma_f32_16x16x32_bf16 v[16:19], v[146:149], v[106:109], v[16:19]
	s_waitcnt vmcnt(0)
	ds_write_b128 v2, v[102:105] offset:61440
	v_mfma_f32_16x16x32_bf16 v[36:39], v[166:169], v[132:135], v[36:39]
	v_mfma_f32_16x16x32_bf16 v[48:51], v[98:101], v[132:135], v[50:53]
	v_mfma_f32_16x16x32_bf16 v[52:55], v[110:113], v[132:135], v[54:57]
	v_mfma_f32_16x16x32_bf16 v[20:23], v[146:149], v[132:135], v[20:23]
	s_setprio 0
	s_waitcnt lgkmcnt(0)
	s_barrier
	ds_read_b128 v[62:65], v6 offset:32768
	ds_read_b128 v[82:85], v6 offset:34816
	ds_read_b128 v[98:101], v7 offset:49152
	ds_read_b128 v[102:105], v7 offset:51200
	ds_read_b128 v[106:109], v6 offset:36864
	ds_read_b128 v[110:113], v6 offset:38912
	ds_read_b128 v[114:117], v7 offset:53248
	ds_read_b128 v[118:121], v7 offset:55296
	s_setprio 2
	ds_read_b128 v[122:125], v4 offset:32768
	ds_read_b128 v[126:129], v5 offset:49152
	s_waitcnt lgkmcnt(7)
	v_mfma_f32_16x16x32_bf16 v[24:27], v[98:101], v[62:65], v[24:27]
	s_waitcnt lgkmcnt(2)
	v_mfma_f32_16x16x32_bf16 v[6:9], v[118:121], v[62:65], v[8:11]
	v_mfma_f32_16x16x32_bf16 v[86:89], v[102:105], v[62:65], v[86:89]
	v_mfma_f32_16x16x32_bf16 v[94:97], v[114:117], v[62:65], v[94:97]
	ds_read_b128 v[132:135], v4 offset:34816
	ds_read_b128 v[146:149], v5 offset:51200
	v_mfma_f32_16x16x32_bf16 v[28:31], v[98:101], v[82:85], v[28:31]
	v_mfma_f32_16x16x32_bf16 v[40:43], v[102:105], v[82:85], v[40:43]
	v_mfma_f32_16x16x32_bf16 v[10:13], v[118:121], v[82:85], v[12:15]
	v_mfma_f32_16x16x32_bf16 v[90:93], v[114:117], v[82:85], v[90:93]
	ds_read_b128 v[82:85], v4 offset:36864
	ds_read_b128 v[150:153], v5 offset:53248
	v_mfma_f32_16x16x32_bf16 v[14:17], v[118:121], v[106:109], v[16:19]
	v_mfma_f32_16x16x32_bf16 v[154:157], v[98:101], v[106:109], v[32:35]
	v_mfma_f32_16x16x32_bf16 v[158:161], v[102:105], v[106:109], v[44:47]
	v_mfma_f32_16x16x32_bf16 v[162:165], v[114:117], v[106:109], v[58:61]
	ds_read_b128 v[106:109], v4 offset:38912
	ds_read_b128 v[2:5], v5 offset:55296
	v_mfma_f32_16x16x32_bf16 v[98:101], v[98:101], v[110:113], v[36:39]
	v_mfma_f32_16x16x32_bf16 v[102:105], v[102:105], v[110:113], v[48:51]
	v_mfma_f32_16x16x32_bf16 v[114:117], v[114:117], v[110:113], v[52:55]
	v_mfma_f32_16x16x32_bf16 v[110:113], v[118:121], v[110:113], v[20:23]
	s_waitcnt lgkmcnt(6)
	v_mfma_f32_16x16x32_bf16 v[62:65], v[126:129], v[122:125], v[24:27]
	s_waitcnt lgkmcnt(4)
	v_mfma_f32_16x16x32_bf16 v[58:61], v[146:149], v[122:125], v[86:89]
	s_waitcnt lgkmcnt(2)
	v_mfma_f32_16x16x32_bf16 v[54:57], v[150:153], v[122:125], v[94:97]
	s_waitcnt lgkmcnt(0)
	v_mfma_f32_16x16x32_bf16 v[50:53], v[2:5], v[122:125], v[6:9]
	v_mfma_f32_16x16x32_bf16 v[46:49], v[126:129], v[132:135], v[28:31]
	v_mfma_f32_16x16x32_bf16 v[42:45], v[146:149], v[132:135], v[40:43]
	v_mfma_f32_16x16x32_bf16 v[38:41], v[150:153], v[132:135], v[90:93]
	v_mfma_f32_16x16x32_bf16 v[34:37], v[2:5], v[132:135], v[10:13]
	v_mfma_f32_16x16x32_bf16 v[30:33], v[126:129], v[82:85], v[154:157]
	v_mfma_f32_16x16x32_bf16 v[26:29], v[146:149], v[82:85], v[158:161]
	v_mfma_f32_16x16x32_bf16 v[22:25], v[150:153], v[82:85], v[162:165]
	v_mfma_f32_16x16x32_bf16 v[18:21], v[2:5], v[82:85], v[14:17]
	v_mfma_f32_16x16x32_bf16 v[14:17], v[126:129], v[106:109], v[98:101]
	v_mfma_f32_16x16x32_bf16 v[10:13], v[146:149], v[106:109], v[102:105]
	v_mfma_f32_16x16x32_bf16 v[6:9], v[150:153], v[106:109], v[114:117]
	v_mfma_f32_16x16x32_bf16 v[2:5], v[2:5], v[106:109], v[110:113]
	s_setprio 0
	s_and_b32 s0, s5, -8
	s_cmp_lg_u32 s0, 16
	s_barrier
; template <int MODE>
; __device__ __forceinline__ void gemm_tile(const Params& P, int tm, int tn, unsigned char* smem) {
;     ...
;         if (n0 >= ZC_FQ && n0 < ZC_FV) {
;             const bool isk = n0 >= ZC_FK;
;             const float* gain = isk ? P.f_k_norm : P.f_q_norm;
;             const float scl = isk ? 1.0f : 0.125f * LOG2E;
;             float gn[4][4];
; #pragma unroll
;             for (int j = 0; j < 4; ++j)
; #pragma unroll
;                 for (int r = 0; r < 4; ++r) gn[j][r] = gain[16 * j + 4 * g + r];
; #pragma unroll
;             for (int i = 0; i < 4; ++i) {
;                 float ss = 0.f;
; #pragma unroll
;                 for (int j = 0; j < 4; ++j)
; #pragma unroll
;                     for (int r = 0; r < 4; ++r) ss += acc[i][j][r] * acc[i][j][r];
;                 ss = x4_sum(ss);
;                 const float rstd = rsqrtf(ss * (1.0f / 64.0f) + EPS) * scl;
	s_cbranch_scc1 .LBB0_244
	v_mul_f32_e32 v68, v63, v63
	v_fmac_f32_e32 v68, v62, v62
	v_fmac_f32_e32 v68, v64, v64
	v_fmac_f32_e32 v68, v65, v65
	v_fmac_f32_e32 v68, v58, v58
	v_fmac_f32_e32 v68, v59, v59
	v_fmac_f32_e32 v68, v60, v60
	v_fmac_f32_e32 v68, v61, v61
	v_fmac_f32_e32 v68, v54, v54
	v_fmac_f32_e32 v68, v55, v55
	v_fmac_f32_e32 v68, v56, v56
	s_cmp_gt_u32 s5, 19
	v_fmac_f32_e32 v68, v57, v57
	v_pk_mul_f32 v[82:83], v[50:51], v[50:51]
	v_mov_b32_e32 v66, 0x3e38aa3b
	s_cselect_b64 s[0:1], -1, 0
	v_add_f32_e32 v68, v82, v68
	v_cndmask_b32_e64 v106, v66, 1.0, s[0:1]
	v_pk_mul_f32 v[66:67], v[52:53], v[52:53]
	v_add_f32_e32 v68, v83, v68
	v_add_f32_e32 v66, v66, v68
	v_add_f32_e32 v66, v67, v66
	v_mov_b32_e32 v67, v66
	s_nop 1
	v_permlane32_swap_b32_e32 v66, v67
	v_add_f32_e32 v67, v66, v67
	v_mul_f32_e32 v66, v47, v47
	v_fmac_f32_e32 v66, v46, v46
	v_fmac_f32_e32 v66, v48, v48
	v_fmac_f32_e32 v66, v49, v49
	v_fmac_f32_e32 v66, v42, v42
	v_fmac_f32_e32 v66, v43, v43
	v_fmac_f32_e32 v66, v44, v44
	v_fmac_f32_e32 v66, v45, v45
	v_fmac_f32_e32 v66, v38, v38
	v_fmac_f32_e32 v66, v39, v39
	v_fmac_f32_e32 v66, v40, v40
	v_fmac_f32_e32 v66, v41, v41
	v_pk_mul_f32 v[86:87], v[34:35], v[34:35]
	v_pk_mul_f32 v[84:85], v[36:37], v[36:37]
	v_add_f32_e32 v66, v86, v66
	v_add_f32_e32 v66, v87, v66
	v_add_f32_e32 v66, v84, v66
	v_add_f32_e32 v66, v85, v66
	v_mov_b32_e32 v68, v66
	s_nop 1
	v_permlane32_swap_b32_e32 v66, v68
	v_add_f32_e32 v66, v66, v68
	s_and_b64 s[0:1], s[0:1], exec
	v_mov_b32_e32 v83, v67
	v_mov_b32_e32 v82, v66
	s_nop 0
	v_permlane16_swap_b32_e32 v67, v83
	v_permlane16_swap_b32_e32 v66, v82
	s_mov_b32 s0, 0x358637bd
	v_pk_add_f32 v[82:83], v[66:67], v[82:83]
	s_mov_b32 s8, 0x3c800000
	v_mov_b64_e32 v[66:67], s[0:1]
	v_mul_f32_e32 v95, v31, v31
	v_pk_fma_f32 v[86:87], v[82:83], s[8:9], v[66:67] op_sel_hi:[1,0,0]
	s_mov_b32 s5, 0x800000
	v_fmac_f32_e32 v95, v30, v30
	v_mul_f32_e32 v68, 0x4b800000, v87
	v_cmp_gt_f32_e32 vcc, s5, v87
	v_fmac_f32_e32 v95, v32, v32
	v_fmac_f32_e32 v95, v33, v33
	v_cndmask_b32_e32 v68, v87, v68, vcc
	v_rsq_f32_e32 v68, v68
	v_mul_f32_e32 v70, 0x4b800000, v86
	v_cmp_gt_f32_e64 s[0:1], s5, v86
	v_fmac_f32_e32 v95, v26, v26
	v_fmac_f32_e32 v95, v27, v27
	v_cndmask_b32_e64 v70, v86, v70, s[0:1]
	v_rsq_f32_e32 v86, v70
	v_fmac_f32_e32 v95, v28, v28
	s_cselect_b32 s7, s41, s39
	s_cselect_b32 s6, s40, s38
	v_lshlrev_b32_e32 v94, 4, v81
	v_fmac_f32_e32 v95, v29, v29
	global_load_dwordx4 v[82:85], v94, s[6:7]
	v_mul_f32_e32 v70, 0x45800000, v68
	v_fmac_f32_e32 v95, v22, v22
	v_cndmask_b32_e32 v68, v68, v70, vcc
	v_fmac_f32_e32 v95, v23, v23
	v_mul_f32_e32 v70, v106, v68
	v_mul_f32_e32 v68, 0x45800000, v86
	v_fmac_f32_e32 v95, v24, v24
	v_cndmask_b32_e64 v68, v86, v68, s[0:1]
	global_load_dwordx4 v[86:89], v94, s[6:7] offset:64
	v_fmac_f32_e32 v95, v25, v25
	v_pk_mul_f32 v[92:93], v[18:19], v[18:19]
	v_pk_mul_f32 v[90:91], v[20:21], v[20:21]
	v_add_f32_e32 v92, v92, v95
	v_add_f32_e32 v92, v93, v92
	v_add_f32_e32 v90, v90, v92
	v_add_f32_e32 v95, v91, v90
	global_load_dwordx4 v[90:93], v94, s[6:7] offset:128
	v_mov_b32_e32 v96, v95
	s_nop 1
	v_permlane32_swap_b32_e32 v95, v96
	v_add_f32_e32 v99, v95, v96
	global_load_dwordx4 v[94:97], v94, s[6:7] offset:192
	v_mul_f32_e32 v98, v15, v15
	v_fmac_f32_e32 v98, v14, v14
	v_fmac_f32_e32 v98, v16, v16
	v_fmac_f32_e32 v98, v17, v17
	v_fmac_f32_e32 v98, v10, v10
	v_fmac_f32_e32 v98, v11, v11
	v_fmac_f32_e32 v98, v12, v12
	v_fmac_f32_e32 v98, v13, v13
	v_fmac_f32_e32 v98, v6, v6
	v_fmac_f32_e32 v98, v7, v7
	v_fmac_f32_e32 v98, v8, v8
	v_fmac_f32_e32 v98, v9, v9
	v_pk_mul_f32 v[104:105], v[2:3], v[2:3]
	v_pk_mul_f32 v[102:103], v[4:5], v[4:5]
	v_add_f32_e32 v98, v104, v98
	v_add_f32_e32 v98, v105, v98
	v_add_f32_e32 v98, v102, v98
	v_add_f32_e32 v98, v103, v98
	v_mov_b32_e32 v100, v98
	s_nop 1
	v_permlane32_swap_b32_e32 v98, v100
	v_add_f32_e32 v98, v98, v100
	v_mov_b32_e32 v101, v99
	v_mov_b32_e32 v100, v98
	s_nop 0
	v_permlane16_swap_b32_e32 v99, v101
	v_permlane16_swap_b32_e32 v98, v100
	v_pk_add_f32 v[98:99], v[98:99], v[100:101]
	v_mul_f32_e32 v68, v106, v68
	v_pk_fma_f32 v[66:67], v[98:99], s[8:9], v[66:67] op_sel_hi:[1,0,0]
	s_waitcnt vmcnt(3)
; template <int MODE>
; __device__ __forceinline__ void gemm_tile(const Params& P, int tm, int tn, unsigned char* smem) {
;     ...
; #pragma unroll
;                 for (int j = 0; j < 4; ++j)
; #pragma unroll
;                     for (int r = 0; r < 4; ++r) acc[i][j][r] *= rstd * gn[j][r];
	v_pk_mul_f32 v[100:101], v[82:83], v[70:71] op_sel_hi:[1,0]
	v_mul_f32_e32 v98, 0x4b800000, v67
	v_cmp_gt_f32_e32 vcc, s5, v67
	v_cmp_gt_f32_e64 s[0:1], s5, v66
	v_pk_mul_f32 v[62:63], v[62:63], v[100:101]
	v_cndmask_b32_e32 v67, v67, v98, vcc
	v_mul_f32_e32 v98, 0x4b800000, v66
	v_rsq_f32_e32 v67, v67
	v_cndmask_b32_e64 v66, v66, v98, s[0:1]
	v_rsq_f32_e32 v98, v66
	v_pk_mul_f32 v[100:101], v[82:83], v[68:69] op_sel_hi:[1,0]
	v_mul_f32_e32 v66, 0x45800000, v67
	v_cndmask_b32_e32 v66, v67, v66, vcc
	v_mul_f32_e32 v67, 0x45800000, v98
	v_cndmask_b32_e64 v67, v98, v67, s[0:1]
	v_mul_f32_e32 v66, v106, v66
	v_mul_f32_e32 v98, v106, v67
	v_pk_mul_f32 v[102:103], v[84:85], v[70:71] op_sel_hi:[1,0]
	v_pk_mul_f32 v[46:47], v[46:47], v[100:101]
	v_pk_mul_f32 v[100:101], v[82:83], v[66:67] op_sel_hi:[1,0]
	v_pk_mul_f32 v[82:83], v[82:83], v[98:99] op_sel_hi:[1,0]
	v_pk_mul_f32 v[64:65], v[64:65], v[102:103]
	v_pk_mul_f32 v[102:103], v[84:85], v[68:69] op_sel_hi:[1,0]
	v_pk_mul_f32 v[14:15], v[14:15], v[82:83]
	s_waitcnt vmcnt(2)
	v_pk_mul_f32 v[82:83], v[86:87], v[70:71] op_sel_hi:[1,0]
	v_pk_mul_f32 v[48:49], v[48:49], v[102:103]
	v_pk_mul_f32 v[102:103], v[84:85], v[66:67] op_sel_hi:[1,0]
	v_pk_mul_f32 v[84:85], v[84:85], v[98:99] op_sel_hi:[1,0]
	v_pk_mul_f32 v[58:59], v[58:59], v[82:83]
	v_pk_mul_f32 v[82:83], v[86:87], v[68:69] op_sel_hi:[1,0]
	v_pk_mul_f32 v[16:17], v[16:17], v[84:85]
	v_pk_mul_f32 v[84:85], v[88:89], v[70:71] op_sel_hi:[1,0]
	v_pk_mul_f32 v[42:43], v[42:43], v[82:83]
	v_pk_mul_f32 v[82:83], v[86:87], v[66:67] op_sel_hi:[1,0]
	v_pk_mul_f32 v[60:61], v[60:61], v[84:85]
	v_pk_mul_f32 v[84:85], v[88:89], v[68:69] op_sel_hi:[1,0]
	v_pk_mul_f32 v[26:27], v[26:27], v[82:83]
	v_pk_mul_f32 v[82:83], v[86:87], v[98:99] op_sel_hi:[1,0]
	v_pk_mul_f32 v[44:45], v[44:45], v[84:85]
	v_pk_mul_f32 v[84:85], v[88:89], v[66:67] op_sel_hi:[1,0]
	v_pk_mul_f32 v[10:11], v[10:11], v[82:83]
	s_waitcnt vmcnt(1)
	v_pk_mul_f32 v[82:83], v[90:91], v[70:71] op_sel_hi:[1,0]
	v_pk_mul_f32 v[28:29], v[28:29], v[84:85]
	v_pk_mul_f32 v[84:85], v[88:89], v[98:99] op_sel_hi:[1,0]
	v_pk_mul_f32 v[54:55], v[54:55], v[82:83]
	v_pk_mul_f32 v[82:83], v[90:91], v[68:69] op_sel_hi:[1,0]
	v_pk_mul_f32 v[12:13], v[12:13], v[84:85]
	v_pk_mul_f32 v[84:85], v[92:93], v[70:71] op_sel_hi:[1,0]
	v_pk_mul_f32 v[38:39], v[38:39], v[82:83]
	v_pk_mul_f32 v[82:83], v[90:91], v[66:67] op_sel_hi:[1,0]
	v_pk_mul_f32 v[56:57], v[56:57], v[84:85]
	v_pk_mul_f32 v[84:85], v[92:93], v[68:69] op_sel_hi:[1,0]
	v_pk_mul_f32 v[22:23], v[22:23], v[82:83]
	v_pk_mul_f32 v[82:83], v[90:91], v[98:99] op_sel_hi:[1,0]
	v_pk_mul_f32 v[40:41], v[40:41], v[84:85]
	v_pk_mul_f32 v[84:85], v[92:93], v[66:67] op_sel_hi:[1,0]
	v_pk_mul_f32 v[6:7], v[6:7], v[82:83]
	s_waitcnt vmcnt(0)
	v_pk_mul_f32 v[82:83], v[94:95], v[70:71] op_sel_hi:[1,0]
	v_pk_mul_f32 v[24:25], v[24:25], v[84:85]
	v_pk_mul_f32 v[84:85], v[92:93], v[98:99] op_sel_hi:[1,0]
	v_pk_mul_f32 v[50:51], v[50:51], v[82:83]
	v_pk_mul_f32 v[82:83], v[94:95], v[68:69] op_sel_hi:[1,0]
	v_pk_mul_f32 v[8:9], v[8:9], v[84:85]
	v_pk_mul_f32 v[84:85], v[96:97], v[70:71] op_sel_hi:[1,0]
	v_pk_mul_f32 v[34:35], v[34:35], v[82:83]
	v_pk_mul_f32 v[82:83], v[94:95], v[66:67] op_sel_hi:[1,0]
	v_pk_mul_f32 v[66:67], v[96:97], v[66:67] op_sel_hi:[1,0]
	v_pk_mul_f32 v[52:53], v[52:53], v[84:85]
	v_pk_mul_f32 v[84:85], v[96:97], v[68:69] op_sel_hi:[1,0]
	v_pk_mul_f32 v[20:21], v[20:21], v[66:67]
	v_pk_mul_f32 v[18:19], v[18:19], v[82:83]
	v_pk_mul_f32 v[66:67], v[94:95], v[98:99] op_sel_hi:[1,0]
	v_pk_mul_f32 v[82:83], v[96:97], v[98:99] op_sel_hi:[1,0]
	v_pk_mul_f32 v[32:33], v[32:33], v[102:103]
	v_pk_mul_f32 v[30:31], v[30:31], v[100:101]
	v_pk_mul_f32 v[36:37], v[36:37], v[84:85]
	v_pk_mul_f32 v[4:5], v[4:5], v[82:83]
	v_pk_mul_f32 v[2:3], v[2:3], v[66:67]

; template <int MODE>
; __device__ __forceinline__ void gemm_tile(const Params& P, int tm, int tn, unsigned char* smem) {
;     ...
;     const int srow = tid >> 3, sc = tid & 7;
;     constexpr unsigned LDA = (MODE == 2 ? NZ : 1024) * 2u;
;     unsigned aoff, boff; int soff0;
;     {
;         int ar = m0 + srow;
;         if (MODE == 2) { const int b = ar >> 11, t = ar & 2047; ar = b * L + NMETA + t; }
;         aoff = (unsigned)ar * LDA + (unsigned)sc * 16u;
;         boff = (unsigned)(n0 + srow) * 2048u + (unsigned)sc * 16u;
;         soff0 = srow * 128 + ((sc ^ (srow & 7)) << 4);
;     }
;     ...
;     unsigned char* sA0 = smem; unsigned char* sB0 = smem + 16384; unsigned char* sA1 = smem + 32768; unsigned char* sB1 = smem + 49152;
;     G_LOAD(0)
;     G_WRITE(sA0, sB0)
;     __syncthreads();
;     const int arow_off = (wr * 64 + lr) * 128, brow_off = (wc * 64 + lr) * 128, sw = lr & 7;
;     G_LOAD(1)
;     for (int kt = 0; kt < 16; ++kt) {
;         unsigned char* sA = (kt & 1) ? sA1 : sA0; unsigned char* sB = (kt & 1) ? sB1 : sB0;
;         unsigned char* nA = (kt & 1) ? sA0 : sA1; unsigned char* nB = (kt & 1) ? sB0 : sB1;
;         bf16x8 fa[4], fb[4], ga[4], gb[4];
;         const int ch0 = ((g ^ sw) << 4), ch1 = (((4 + g) ^ sw) << 4);
;         const unsigned ko = (unsigned)(kt + 2) * 128u;
;         const unsigned koa = ko + ((MODE == 2 && kt + 2 >= 8) ? (unsigned)(ZC_FQ - 512) * 2u : 0u);
;         const bool wr_ok = kt < 15, ld_ok = kt < 14;
; #pragma unroll
;         for (int i = 0; i < 4; ++i) { fa[i] = *(const bf16x8*)(sA + arow_off + i * 2048 + ch0); fb[i] = *(const bf16x8*)(sB + brow_off + i * 2048 + ch0); }
;         __builtin_amdgcn_sched_barrier(0);
;         __builtin_amdgcn_s_setprio(2);
;         if (wr_ok) *(uint4*)(nA + soff0) = ra0;
;         if (ld_ok) ra0 = *(const uint4*)(Ab + (aoff + 0u * LDA + koa));
;         ga[0] = *(const bf16x8*)(sA + arow_off + 0 * 2048 + ch1); gb[0] = *(const bf16x8*)(sB + brow_off + 0 * 2048 + ch1);
;         __builtin_amdgcn_sched_barrier(0);
; #pragma unroll
;         for (int j = 0; j < 4; ++j) acc[0][j] = __builtin_amdgcn_mfma_f32_16x16x32_bf16(fb[j], fa[0], acc[0][j], 0, 0, 0);
;         __builtin_amdgcn_sched_barrier(0);
;         if (wr_ok) *(uint4*)(nA + soff0 + 4096) = ra1;
;         if (ld_ok) ra1 = *(const uint4*)(Ab + (aoff + 32u * LDA + koa));
.LBB0_1154:
	v_mov_b32_e32 v142, v0
	s_and_b32 s15, s9, 0xffffff80
	v_ashrrev_i32_e32 v2, 3, v142
	v_add_u32_e32 v3, s15, v2
	v_ashrrev_i32_e32 v4, 11, v3
	v_and_b32_e32 v3, 0x7ff, v3
	s_and_b32 s4, s6, 7
	v_mad_i32_i24 v3, v4, s11, v3
	v_lshlrev_b32_e32 v4, 4, v142
	s_lshl_b32 s18, s4, 7
	v_mul_lo_u32 v3, v3, s12
	v_and_b32_e32 v5, 0x70, v4
	v_add_u32_e32 v4, s18, v2
	v_or_b32_e32 v9, v3, v5
	v_lshl_or_b32 v4, v4, 11, v5
	v_add_u32_e32 v234, 0x1c000, v9
	global_load_dwordx4 v[10:13], v234, s[0:1]
	v_add_u32_e32 v3, 0x54000, v9
	v_add_u32_e32 v6, 0x20000, v4
	v_add_u32_e32 v5, 0x8c000, v9
	v_add_u32_e32 v7, 0x30000, v4
	global_load_dwordx4 v[14:17], v6, s[2:3]
	global_load_dwordx4 v[18:21], v7, s[2:3]
	global_load_dwordx4 v[22:25], v3, s[0:1]
	global_load_dwordx4 v[26:29], v5, s[0:1]
	v_add_u32_e32 v235, 0xc4000, v9
	global_load_dwordx4 v[30:33], v235, s[0:1]
	global_load_dwordx4 v[34:37], v4, s[2:3]
	v_add_u32_e32 v236, 0x10000, v4
	global_load_dwordx4 v[38:41], v236, s[2:3]
	v_xor_b32_e32 v3, v2, v142
	v_lshlrev_b32_e32 v2, 7, v2
	v_lshlrev_b32_e32 v3, 4, v3
	v_and_or_b32 v2, v3, s13, v2
	v_add_u32_e32 v3, 0, v2
	v_add_u32_e32 v2, 0x1c080, v9
	v_or_b32_e32 v5, 0x80, v4
	v_add_u32_e32 v6, 0x10080, v4
	v_add_u32_e32 v7, 0x20080, v4
	v_add_u32_e32 v8, 0x30080, v4
	v_add_u32_e32 v44, 0x54080, v9
	v_add_u32_e32 v45, 0x8c080, v9
	v_add_u32_e32 v46, 0xc4080, v9
	v_bfe_u32 v144, v142, 6, 1
	v_and_b32_e32 v143, 15, v142
	v_bfe_u32 v146, v142, 4, 2
	s_waitcnt vmcnt(6)
	ds_write_b128 v3, v[14:17] offset:24576
	s_waitcnt vmcnt(5)
	ds_write_b128 v3, v[18:21] offset:28672
	ds_write_b128 v3, v[10:13]
	s_waitcnt vmcnt(4)
	ds_write_b128 v3, v[22:25] offset:4096
	s_waitcnt vmcnt(3)
	ds_write_b128 v3, v[26:29] offset:8192
	s_waitcnt vmcnt(2)
	ds_write_b128 v3, v[30:33] offset:12288
	s_waitcnt vmcnt(1)
	ds_write_b128 v3, v[34:37] offset:16384
	s_waitcnt vmcnt(0)
	ds_write_b128 v3, v[38:41] offset:20480
	s_waitcnt lgkmcnt(0)
	s_barrier
	global_load_dwordx4 v[12:15], v2, s[0:1]
	global_load_dwordx4 v[16:19], v44, s[0:1]
	global_load_dwordx4 v[20:23], v45, s[0:1]
	global_load_dwordx4 v[24:27], v46, s[0:1]
	global_load_dwordx4 v[28:31], v5, s[2:3]
	global_load_dwordx4 v[32:35], v6, s[2:3]
	global_load_dwordx4 v[36:39], v7, s[2:3]
	global_load_dwordx4 v[40:43], v8, s[2:3]
	v_ashrrev_i32_e32 v2, 1, v142
	v_lshrrev_b32_e32 v5, 4, v142
	v_and_b32_e32 v10, 0xffffffc0, v2
	v_and_b32_e32 v11, 7, v142
	v_or_b32_e32 v145, v10, v143
	v_lshlrev_b32_e32 v2, 6, v144
	v_bitop3_b32 v5, v5, v11, 3 bitop3:0x6c
	v_or_b32_e32 v6, v2, v143
	v_lshlrev_b32_e32 v5, 4, v5
	v_lshl_add_u32 v80, v145, 7, 0
	v_add_u32_e32 v7, v80, v5
	v_lshl_add_u32 v6, v6, 7, 0
	v_add_u32_e32 v8, v6, v5
	ds_read_b128 v[44:47], v7
	ds_read_b128 v[48:51], v7 offset:2048
	ds_read_b128 v[52:55], v8 offset:16384
	ds_read_b128 v[56:59], v8 offset:18432
	ds_read_b128 v[60:63], v7 offset:4096
	ds_read_b128 v[64:67], v7 offset:6144
	ds_read_b128 v[68:71], v8 offset:20480
	ds_read_b128 v[72:75], v8 offset:22528
	v_bitop3_b32 v5, v146, v11, 4 bitop3:0x36
	v_lshlrev_b32_e32 v11, 4, v5
	s_setprio 2
	global_load_dwordx4 v[76:79], v234, s[0:1] offset:256
	s_waitcnt vmcnt(7)
	ds_write_b128 v3, v[12:15] offset:32768
	v_add_u32_e32 v5, v80, v11
	v_add_u32_e32 v6, v6, v11
	ds_read_b128 v[12:15], v5
	ds_read_b128 v[80:83], v6 offset:16384
	s_waitcnt lgkmcnt(8)
	v_mfma_f32_16x16x32_bf16 v[84:87], v[52:55], v[44:47], 0
	s_waitcnt lgkmcnt(7)
	v_mfma_f32_16x16x32_bf16 v[88:91], v[56:59], v[44:47], 0
	s_waitcnt lgkmcnt(4)
	v_mfma_f32_16x16x32_bf16 v[92:95], v[68:71], v[44:47], 0
	s_waitcnt lgkmcnt(3)
	v_mfma_f32_16x16x32_bf16 v[44:47], v[72:75], v[44:47], 0
	v_add_u32_e32 v237, 0x54000, v9
	global_load_dwordx4 v[100:103], v237, s[0:1] offset:256
	ds_write_b128 v3, v[16:19] offset:36864
	ds_read_b128 v[16:19], v5 offset:2048
	ds_read_b128 v[104:107], v6 offset:18432
	v_mfma_f32_16x16x32_bf16 v[108:111], v[52:55], v[48:51], 0
	v_mfma_f32_16x16x32_bf16 v[112:115], v[56:59], v[48:51], 0
	v_mfma_f32_16x16x32_bf16 v[116:119], v[68:71], v[48:51], 0
	v_mfma_f32_16x16x32_bf16 v[48:51], v[72:75], v[48:51], 0
	v_add_u32_e32 v238, 0x8c000, v9
	global_load_dwordx4 v[120:123], v238, s[0:1] offset:256
	s_waitcnt vmcnt(7)
	ds_write_b128 v3, v[20:23] offset:40960
	ds_read_b128 v[20:23], v5 offset:4096
	ds_read_b128 v[124:127], v6 offset:20480
	v_mfma_f32_16x16x32_bf16 v[132:135], v[52:55], v[60:63], 0
	v_mfma_f32_16x16x32_bf16 v[136:139], v[56:59], v[60:63], 0
	v_mfma_f32_16x16x32_bf16 v[148:151], v[68:71], v[60:63], 0
	v_mfma_f32_16x16x32_bf16 v[60:63], v[72:75], v[60:63], 0
	global_load_dwordx4 v[152:155], v235, s[0:1] offset:256
	ds_write_b128 v3, v[24:27] offset:45056
	ds_read_b128 v[24:27], v5 offset:6144
	ds_read_b128 v[156:159], v6 offset:22528
	v_mfma_f32_16x16x32_bf16 v[52:55], v[52:55], v[64:67], 0
	v_mfma_f32_16x16x32_bf16 v[56:59], v[56:59], v[64:67], 0
	v_mfma_f32_16x16x32_bf16 v[68:71], v[68:71], v[64:67], 0
	v_mfma_f32_16x16x32_bf16 v[64:67], v[72:75], v[64:67], 0
	global_load_dwordx4 v[72:75], v4, s[2:3] offset:256
	s_waitcnt vmcnt(7)
	ds_write_b128 v3, v[28:31] offset:49152
	s_waitcnt lgkmcnt(10)
	v_mfma_f32_16x16x32_bf16 v[28:31], v[80:83], v[12:15], v[84:87]
	s_waitcnt lgkmcnt(7)
	v_mfma_f32_16x16x32_bf16 v[84:87], v[104:107], v[12:15], v[88:91]
	s_waitcnt lgkmcnt(4)
	v_mfma_f32_16x16x32_bf16 v[88:91], v[124:127], v[12:15], v[92:95]
	s_waitcnt lgkmcnt(1)
	v_mfma_f32_16x16x32_bf16 v[12:15], v[156:159], v[12:15], v[44:47]
	global_load_dwordx4 v[44:47], v236, s[2:3] offset:256
	ds_write_b128 v3, v[32:35] offset:53248
	v_mfma_f32_16x16x32_bf16 v[32:35], v[80:83], v[16:19], v[108:111]
	v_mfma_f32_16x16x32_bf16 v[92:95], v[104:107], v[16:19], v[112:115]
	v_mfma_f32_16x16x32_bf16 v[108:111], v[124:127], v[16:19], v[116:119]
	v_mfma_f32_16x16x32_bf16 v[16:19], v[156:159], v[16:19], v[48:51]
	v_add_u32_e32 v239, 0x20000, v4
	global_load_dwordx4 v[48:51], v239, s[2:3] offset:256
	s_waitcnt vmcnt(7)
	ds_write_b128 v3, v[36:39] offset:57344
	v_mfma_f32_16x16x32_bf16 v[36:39], v[80:83], v[20:23], v[132:135]
	v_mfma_f32_16x16x32_bf16 v[112:115], v[104:107], v[20:23], v[136:139]
	v_mfma_f32_16x16x32_bf16 v[116:119], v[124:127], v[20:23], v[148:151]
	v_mfma_f32_16x16x32_bf16 v[20:23], v[156:159], v[20:23], v[60:63]
	v_add_u32_e32 v240, 0x30000, v4
	global_load_dwordx4 v[60:63], v240, s[2:3] offset:256
	ds_write_b128 v3, v[40:43] offset:61440
	v_mfma_f32_16x16x32_bf16 v[40:43], v[80:83], v[24:27], v[52:55]
	v_mfma_f32_16x16x32_bf16 v[52:55], v[104:107], v[24:27], v[56:59]
	v_mfma_f32_16x16x32_bf16 v[56:59], v[124:127], v[24:27], v[68:71]
	v_mfma_f32_16x16x32_bf16 v[24:27], v[156:159], v[24:27], v[64:67]
	s_setprio 0
	s_waitcnt lgkmcnt(0)
	s_barrier
; template <int MODE>
; __device__ __forceinline__ void gemm_tile(const Params& P, int tm, int tn, unsigned char* smem) {
;     ...
;     for (int kt = 0; kt < 16; ++kt) {
;         unsigned char* sA = (kt & 1) ? sA1 : sA0; unsigned char* sB = (kt & 1) ? sB1 : sB0;
;         unsigned char* nA = (kt & 1) ? sA0 : sA1; unsigned char* nB = (kt & 1) ? sB0 : sB1;
;         bf16x8 fa[4], fb[4], ga[4], gb[4];
;         const int ch0 = ((g ^ sw) << 4), ch1 = (((4 + g) ^ sw) << 4);
;         const unsigned ko = (unsigned)(kt + 2) * 128u;
;         const unsigned koa = ko + ((MODE == 2 && kt + 2 >= 8) ? (unsigned)(ZC_FQ - 512) * 2u : 0u);
;         const bool wr_ok = kt < 15, ld_ok = kt < 14;
; #pragma unroll
;         for (int i = 0; i < 4; ++i) { fa[i] = *(const bf16x8*)(sA + arow_off + i * 2048 + ch0); fb[i] = *(const bf16x8*)(sB + brow_off + i * 2048 + ch0); }
;         __builtin_amdgcn_sched_barrier(0);
;         __builtin_amdgcn_s_setprio(2);
;         if (wr_ok) *(uint4*)(nA + soff0) = ra0;
;         if (ld_ok) ra0 = *(const uint4*)(Ab + (aoff + 0u * LDA + koa));
;         ga[0] = *(const bf16x8*)(sA + arow_off + 0 * 2048 + ch1); gb[0] = *(const bf16x8*)(sB + brow_off + 0 * 2048 + ch1);
;         __builtin_amdgcn_sched_barrier(0);
; #pragma unroll
;         for (int j = 0; j < 4; ++j) acc[0][j] = __builtin_amdgcn_mfma_f32_16x16x32_bf16(fb[j], fa[0], acc[0][j], 0, 0, 0);
;         __builtin_amdgcn_sched_barrier(0);
;         if (wr_ok) *(uint4*)(nA + soff0 + 4096) = ra1;
;         if (ld_ok) ra1 = *(const uint4*)(Ab + (aoff + 32u * LDA + koa));
;         ga[1] = *(const bf16x8*)(sA + arow_off + 1 * 2048 + ch1); gb[1] = *(const bf16x8*)(sB + brow_off + 1 * 2048 + ch1);
;         __builtin_amdgcn_sched_barrier(0);
; #pragma unroll
;         for (int j = 0; j < 4; ++j) acc[1][j] = __builtin_amdgcn_mfma_f32_16x16x32_bf16(fb[j], fa[1], acc[1][j], 0, 0, 0);
;         __builtin_amdgcn_sched_barrier(0);
;         if (wr_ok) *(uint4*)(nA + soff0 + 8192) = ra2;
;         if (ld_ok) ra2 = *(const uint4*)(Ab + (aoff + 64u * LDA + koa));
;         ga[2] = *(const bf16x8*)(sA + arow_off + 2 * 2048 + ch1); gb[2] = *(const bf16x8*)(sB + brow_off + 2 * 2048 + ch1);
;         __builtin_amdgcn_sched_barrier(0);
; #pragma unroll
;         for (int j = 0; j < 4; ++j) acc[2][j] = __builtin_amdgcn_mfma_f32_16x16x32_bf16(fb[j], fa[2], acc[2][j], 0, 0, 0);
	ds_read_b128 v[64:67], v7 offset:32768
	ds_read_b128 v[68:71], v7 offset:34816
	ds_read_b128 v[80:83], v8 offset:49152
	ds_read_b128 v[104:107], v8 offset:51200
	ds_read_b128 v[124:127], v7 offset:36864
	ds_read_b128 v[132:135], v7 offset:38912
	ds_read_b128 v[136:139], v8 offset:53248
	ds_read_b128 v[148:151], v8 offset:55296
	s_setprio 2
	global_load_dwordx4 v[156:159], v234, s[0:1] offset:384
	s_waitcnt vmcnt(7)
	ds_write_b128 v3, v[76:79]
	ds_read_b128 v[76:79], v5 offset:32768
	ds_read_b128 v[160:163], v6 offset:49152
	s_waitcnt lgkmcnt(8)
	v_mfma_f32_16x16x32_bf16 v[28:31], v[80:83], v[64:67], v[28:31]
	s_waitcnt lgkmcnt(7)
	v_mfma_f32_16x16x32_bf16 v[84:87], v[104:107], v[64:67], v[84:87]
	s_waitcnt lgkmcnt(4)
	v_mfma_f32_16x16x32_bf16 v[88:91], v[136:139], v[64:67], v[88:91]
	s_waitcnt lgkmcnt(3)
	v_mfma_f32_16x16x32_bf16 v[12:15], v[148:151], v[64:67], v[12:15]
	global_load_dwordx4 v[64:67], v237, s[0:1] offset:384
	ds_write_b128 v3, v[100:103] offset:4096
	ds_read_b128 v[100:103], v5 offset:34816
	ds_read_b128 v[164:167], v6 offset:51200
	v_mfma_f32_16x16x32_bf16 v[32:35], v[80:83], v[68:71], v[32:35]
	v_mfma_f32_16x16x32_bf16 v[92:95], v[104:107], v[68:71], v[92:95]
	v_mfma_f32_16x16x32_bf16 v[108:111], v[136:139], v[68:71], v[108:111]
	v_mfma_f32_16x16x32_bf16 v[16:19], v[148:151], v[68:71], v[16:19]
	global_load_dwordx4 v[68:71], v238, s[0:1] offset:384
	s_waitcnt vmcnt(7)
	ds_write_b128 v3, v[120:123] offset:8192
	ds_read_b128 v[120:123], v5 offset:36864
	ds_read_b128 v[168:171], v6 offset:53248
	v_mfma_f32_16x16x32_bf16 v[36:39], v[80:83], v[124:127], v[36:39]
	v_mfma_f32_16x16x32_bf16 v[112:115], v[104:107], v[124:127], v[112:115]
	v_mfma_f32_16x16x32_bf16 v[116:119], v[136:139], v[124:127], v[116:119]
	v_mfma_f32_16x16x32_bf16 v[20:23], v[148:151], v[124:127], v[20:23]
	global_load_dwordx4 v[124:127], v235, s[0:1] offset:384
	ds_write_b128 v3, v[152:155] offset:12288
	ds_read_b128 v[152:155], v5 offset:38912
	ds_read_b128 v[172:175], v6 offset:55296
	v_mfma_f32_16x16x32_bf16 v[40:43], v[80:83], v[132:135], v[40:43]
	v_mfma_f32_16x16x32_bf16 v[52:55], v[104:107], v[132:135], v[52:55]
	v_mfma_f32_16x16x32_bf16 v[56:59], v[136:139], v[132:135], v[56:59]
	v_mfma_f32_16x16x32_bf16 v[24:27], v[148:151], v[132:135], v[24:27]
	global_load_dwordx4 v[80:83], v4, s[2:3] offset:384
	s_waitcnt vmcnt(7)
	ds_write_b128 v3, v[72:75] offset:16384
	s_waitcnt lgkmcnt(10)
	v_mfma_f32_16x16x32_bf16 v[28:31], v[160:163], v[76:79], v[28:31]
	s_waitcnt lgkmcnt(7)
	v_mfma_f32_16x16x32_bf16 v[72:75], v[164:167], v[76:79], v[84:87]
	s_waitcnt lgkmcnt(4)
	v_mfma_f32_16x16x32_bf16 v[84:87], v[168:171], v[76:79], v[88:91]
	s_waitcnt lgkmcnt(1)
	v_mfma_f32_16x16x32_bf16 v[12:15], v[172:175], v[76:79], v[12:15]
	global_load_dwordx4 v[76:79], v236, s[2:3] offset:384
	ds_write_b128 v3, v[44:47] offset:20480
	v_mfma_f32_16x16x32_bf16 v[32:35], v[160:163], v[100:103], v[32:35]
	v_mfma_f32_16x16x32_bf16 v[44:47], v[164:167], v[100:103], v[92:95]
	v_mfma_f32_16x16x32_bf16 v[88:91], v[168:171], v[100:103], v[108:111]
	v_mfma_f32_16x16x32_bf16 v[16:19], v[172:175], v[100:103], v[16:19]
	global_load_dwordx4 v[92:95], v239, s[2:3] offset:384
	s_waitcnt vmcnt(7)
	ds_write_b128 v3, v[48:51] offset:24576
	v_mfma_f32_16x16x32_bf16 v[36:39], v[160:163], v[120:123], v[36:39]
	v_mfma_f32_16x16x32_bf16 v[48:51], v[164:167], v[120:123], v[112:115]
	v_mfma_f32_16x16x32_bf16 v[100:103], v[168:171], v[120:123], v[116:119]
	v_mfma_f32_16x16x32_bf16 v[20:23], v[172:175], v[120:123], v[20:23]
	global_load_dwordx4 v[104:107], v240, s[2:3] offset:384
	ds_write_b128 v3, v[60:63] offset:28672
	v_mfma_f32_16x16x32_bf16 v[40:43], v[160:163], v[152:155], v[40:43]
	v_mfma_f32_16x16x32_bf16 v[52:55], v[164:167], v[152:155], v[52:55]
	v_mfma_f32_16x16x32_bf16 v[56:59], v[168:171], v[152:155], v[56:59]
	v_mfma_f32_16x16x32_bf16 v[24:27], v[172:175], v[152:155], v[24:27]
	s_setprio 0
	s_waitcnt lgkmcnt(0)
	s_barrier
	ds_read_b128 v[60:63], v7
	ds_read_b128 v[108:111], v7 offset:2048
	ds_read_b128 v[112:115], v8 offset:16384
	ds_read_b128 v[116:119], v8 offset:18432
	ds_read_b128 v[120:123], v7 offset:4096
	ds_read_b128 v[132:135], v7 offset:6144
	ds_read_b128 v[136:139], v8 offset:20480
	ds_read_b128 v[148:151], v8 offset:22528
	s_setprio 2
	global_load_dwordx4 v[152:155], v234, s[0:1] offset:512
	s_waitcnt vmcnt(7)
	ds_write_b128 v3, v[156:159] offset:32768
	ds_read_b128 v[156:159], v5
	ds_read_b128 v[160:163], v6 offset:16384
	s_waitcnt lgkmcnt(8)
	v_mfma_f32_16x16x32_bf16 v[28:31], v[112:115], v[60:63], v[28:31]
	s_waitcnt lgkmcnt(4)
	v_mfma_f32_16x16x32_bf16 v[84:87], v[136:139], v[60:63], v[84:87]
	s_waitcnt lgkmcnt(3)
	v_mfma_f32_16x16x32_bf16 v[12:15], v[148:151], v[60:63], v[12:15]
	v_mfma_f32_16x16x32_bf16 v[72:75], v[116:119], v[60:63], v[72:75]
	global_load_dwordx4 v[60:63], v237, s[0:1] offset:512
	ds_write_b128 v3, v[64:67] offset:36864
	ds_read_b128 v[64:67], v5 offset:2048
	ds_read_b128 v[164:167], v6 offset:18432
	v_mfma_f32_16x16x32_bf16 v[32:35], v[112:115], v[108:111], v[32:35]
	v_mfma_f32_16x16x32_bf16 v[44:47], v[116:119], v[108:111], v[44:47]
	v_mfma_f32_16x16x32_bf16 v[88:91], v[136:139], v[108:111], v[88:91]
	v_mfma_f32_16x16x32_bf16 v[16:19], v[148:151], v[108:111], v[16:19]
	global_load_dwordx4 v[108:111], v238, s[0:1] offset:512
	s_waitcnt vmcnt(7)
; template <int MODE>
; __device__ __forceinline__ void gemm_tile(const Params& P, int tm, int tn, unsigned char* smem) {
;     ...
;     for (int kt = 0; kt < 16; ++kt) {
;         unsigned char* sA = (kt & 1) ? sA1 : sA0; unsigned char* sB = (kt & 1) ? sB1 : sB0;
;         unsigned char* nA = (kt & 1) ? sA0 : sA1; unsigned char* nB = (kt & 1) ? sB0 : sB1;
;         bf16x8 fa[4], fb[4], ga[4], gb[4];
;         const int ch0 = ((g ^ sw) << 4), ch1 = (((4 + g) ^ sw) << 4);
;         const unsigned ko = (unsigned)(kt + 2) * 128u;
;         const unsigned koa = ko + ((MODE == 2 && kt + 2 >= 8) ? (unsigned)(ZC_FQ - 512) * 2u : 0u);
;         const bool wr_ok = kt < 15, ld_ok = kt < 14;
; #pragma unroll
;         for (int i = 0; i < 4; ++i) { fa[i] = *(const bf16x8*)(sA + arow_off + i * 2048 + ch0); fb[i] = *(const bf16x8*)(sB + brow_off + i * 2048 + ch0); }
;         __builtin_amdgcn_sched_barrier(0);
;         __builtin_amdgcn_s_setprio(2);
;         if (wr_ok) *(uint4*)(nA + soff0) = ra0;
;         if (ld_ok) ra0 = *(const uint4*)(Ab + (aoff + 0u * LDA + koa));
;         ga[0] = *(const bf16x8*)(sA + arow_off + 0 * 2048 + ch1); gb[0] = *(const bf16x8*)(sB + brow_off + 0 * 2048 + ch1);
;         __builtin_amdgcn_sched_barrier(0);
; #pragma unroll
;         for (int j = 0; j < 4; ++j) acc[0][j] = __builtin_amdgcn_mfma_f32_16x16x32_bf16(fb[j], fa[0], acc[0][j], 0, 0, 0);
;         __builtin_amdgcn_sched_barrier(0);
;         if (wr_ok) *(uint4*)(nA + soff0 + 4096) = ra1;
;         if (ld_ok) ra1 = *(const uint4*)(Ab + (aoff + 32u * LDA + koa));
;         ga[1] = *(const bf16x8*)(sA + arow_off + 1 * 2048 + ch1); gb[1] = *(const bf16x8*)(sB + brow_off + 1 * 2048 + ch1);
;         __builtin_amdgcn_sched_barrier(0);
; #pragma unroll
;         for (int j = 0; j < 4; ++j) acc[1][j] = __builtin_amdgcn_mfma_f32_16x16x32_bf16(fb[j], fa[1], acc[1][j], 0, 0, 0);
;         __builtin_amdgcn_sched_barrier(0);
;         if (wr_ok) *(uint4*)(nA + soff0 + 8192) = ra2;
;         if (ld_ok) ra2 = *(const uint4*)(Ab + (aoff + 64u * LDA + koa));
;         ga[2] = *(const bf16x8*)(sA + arow_off + 2 * 2048 + ch1); gb[2] = *(const bf16x8*)(sB + brow_off + 2 * 2048 + ch1);
;         __builtin_amdgcn_sched_barrier(0);
; #pragma unroll
;         for (int j = 0; j < 4; ++j) acc[2][j] = __builtin_amdgcn_mfma_f32_16x16x32_bf16(fb[j], fa[2], acc[2][j], 0, 0, 0);
	ds_write_b128 v3, v[68:71] offset:40960
	ds_read_b128 v[68:71], v5 offset:4096
	ds_read_b128 v[168:171], v6 offset:20480
	v_mfma_f32_16x16x32_bf16 v[36:39], v[112:115], v[120:123], v[36:39]
	v_mfma_f32_16x16x32_bf16 v[48:51], v[116:119], v[120:123], v[48:51]
	v_mfma_f32_16x16x32_bf16 v[100:103], v[136:139], v[120:123], v[100:103]
	v_mfma_f32_16x16x32_bf16 v[20:23], v[148:151], v[120:123], v[20:23]
	global_load_dwordx4 v[120:123], v235, s[0:1] offset:512
	ds_write_b128 v3, v[124:127] offset:45056
	ds_read_b128 v[124:127], v5 offset:6144
	ds_read_b128 v[172:175], v6 offset:22528
	v_mfma_f32_16x16x32_bf16 v[40:43], v[112:115], v[132:135], v[40:43]
	v_mfma_f32_16x16x32_bf16 v[52:55], v[116:119], v[132:135], v[52:55]
	v_mfma_f32_16x16x32_bf16 v[56:59], v[136:139], v[132:135], v[56:59]
	v_mfma_f32_16x16x32_bf16 v[24:27], v[148:151], v[132:135], v[24:27]
	global_load_dwordx4 v[112:115], v4, s[2:3] offset:512
	s_waitcnt vmcnt(7)
	ds_write_b128 v3, v[80:83] offset:49152
	s_waitcnt lgkmcnt(10)
	v_mfma_f32_16x16x32_bf16 v[28:31], v[160:163], v[156:159], v[28:31]
	s_waitcnt lgkmcnt(4)
	v_mfma_f32_16x16x32_bf16 v[80:83], v[168:171], v[156:159], v[84:87]
	s_waitcnt lgkmcnt(1)
	v_mfma_f32_16x16x32_bf16 v[12:15], v[172:175], v[156:159], v[12:15]
	v_mfma_f32_16x16x32_bf16 v[72:75], v[164:167], v[156:159], v[72:75]
	global_load_dwordx4 v[84:87], v236, s[2:3] offset:512
	ds_write_b128 v3, v[76:79] offset:53248
	v_mfma_f32_16x16x32_bf16 v[32:35], v[160:163], v[64:67], v[32:35]
	v_mfma_f32_16x16x32_bf16 v[44:47], v[164:167], v[64:67], v[44:47]
	v_mfma_f32_16x16x32_bf16 v[16:19], v[172:175], v[64:67], v[16:19]
	v_mfma_f32_16x16x32_bf16 v[76:79], v[168:171], v[64:67], v[88:91]
	global_load_dwordx4 v[64:67], v239, s[2:3] offset:512
	s_waitcnt vmcnt(7)
	ds_write_b128 v3, v[92:95] offset:57344
	v_mfma_f32_16x16x32_bf16 v[36:39], v[160:163], v[68:71], v[36:39]
	v_mfma_f32_16x16x32_bf16 v[48:51], v[164:167], v[68:71], v[48:51]
	v_mfma_f32_16x16x32_bf16 v[88:91], v[168:171], v[68:71], v[100:103]
	v_mfma_f32_16x16x32_bf16 v[20:23], v[172:175], v[68:71], v[20:23]
	global_load_dwordx4 v[68:71], v240, s[2:3] offset:512
	ds_write_b128 v3, v[104:107] offset:61440
	v_mfma_f32_16x16x32_bf16 v[40:43], v[160:163], v[124:127], v[40:43]
	v_mfma_f32_16x16x32_bf16 v[52:55], v[164:167], v[124:127], v[52:55]
	v_mfma_f32_16x16x32_bf16 v[56:59], v[168:171], v[124:127], v[56:59]
	v_mfma_f32_16x16x32_bf16 v[24:27], v[172:175], v[124:127], v[24:27]
	s_setprio 0
	s_waitcnt lgkmcnt(0)
	s_barrier
	ds_read_b128 v[92:95], v7 offset:32768
	ds_read_b128 v[100:103], v7 offset:34816
	ds_read_b128 v[104:107], v8 offset:49152
	ds_read_b128 v[116:119], v8 offset:51200
	ds_read_b128 v[124:127], v7 offset:36864
	ds_read_b128 v[132:135], v7 offset:38912
	ds_read_b128 v[136:139], v8 offset:53248
	ds_read_b128 v[148:151], v8 offset:55296
	s_setprio 2
	global_load_dwordx4 v[156:159], v234, s[0:1] offset:640
	s_waitcnt vmcnt(7)
	ds_write_b128 v3, v[152:155]
	ds_read_b128 v[152:155], v5 offset:32768
	ds_read_b128 v[160:163], v6 offset:49152
	s_waitcnt lgkmcnt(8)
	v_mfma_f32_16x16x32_bf16 v[28:31], v[104:107], v[92:95], v[28:31]
	s_waitcnt lgkmcnt(4)
	v_mfma_f32_16x16x32_bf16 v[80:83], v[136:139], v[92:95], v[80:83]
	s_waitcnt lgkmcnt(3)
	v_mfma_f32_16x16x32_bf16 v[12:15], v[148:151], v[92:95], v[12:15]
	v_mfma_f32_16x16x32_bf16 v[72:75], v[116:119], v[92:95], v[72:75]
	global_load_dwordx4 v[92:95], v237, s[0:1] offset:640
	ds_write_b128 v3, v[60:63] offset:4096
	ds_read_b128 v[60:63], v5 offset:34816
	ds_read_b128 v[164:167], v6 offset:51200
	v_mfma_f32_16x16x32_bf16 v[32:35], v[104:107], v[100:103], v[32:35]
	v_mfma_f32_16x16x32_bf16 v[44:47], v[116:119], v[100:103], v[44:47]
	v_mfma_f32_16x16x32_bf16 v[16:19], v[148:151], v[100:103], v[16:19]
	v_mfma_f32_16x16x32_bf16 v[76:79], v[136:139], v[100:103], v[76:79]
	global_load_dwordx4 v[100:103], v238, s[0:1] offset:640
	s_waitcnt vmcnt(7)
	ds_write_b128 v3, v[108:111] offset:8192
	ds_read_b128 v[108:111], v5 offset:36864
	ds_read_b128 v[168:171], v6 offset:53248
	v_mfma_f32_16x16x32_bf16 v[36:39], v[104:107], v[124:127], v[36:39]
	v_mfma_f32_16x16x32_bf16 v[48:51], v[116:119], v[124:127], v[48:51]
	v_mfma_f32_16x16x32_bf16 v[88:91], v[136:139], v[124:127], v[88:91]
	v_mfma_f32_16x16x32_bf16 v[20:23], v[148:151], v[124:127], v[20:23]
	global_load_dwordx4 v[124:127], v235, s[0:1] offset:640
	ds_write_b128 v3, v[120:123] offset:12288
	ds_read_b128 v[120:123], v5 offset:38912
	ds_read_b128 v[172:175], v6 offset:55296
	v_mfma_f32_16x16x32_bf16 v[40:43], v[104:107], v[132:135], v[40:43]
	v_mfma_f32_16x16x32_bf16 v[52:55], v[116:119], v[132:135], v[52:55]
	v_mfma_f32_16x16x32_bf16 v[56:59], v[136:139], v[132:135], v[56:59]
	v_mfma_f32_16x16x32_bf16 v[24:27], v[148:151], v[132:135], v[24:27]
	global_load_dwordx4 v[104:107], v4, s[2:3] offset:640
	s_waitcnt vmcnt(7)
	ds_write_b128 v3, v[112:115] offset:16384
	s_waitcnt lgkmcnt(10)
	v_mfma_f32_16x16x32_bf16 v[28:31], v[160:163], v[152:155], v[28:31]
	s_waitcnt lgkmcnt(4)
	v_mfma_f32_16x16x32_bf16 v[80:83], v[168:171], v[152:155], v[80:83]
	s_waitcnt lgkmcnt(1)
	v_mfma_f32_16x16x32_bf16 v[12:15], v[172:175], v[152:155], v[12:15]
	v_mfma_f32_16x16x32_bf16 v[72:75], v[164:167], v[152:155], v[72:75]
	global_load_dwordx4 v[112:115], v236, s[2:3] offset:640
	ds_write_b128 v3, v[84:87] offset:20480
	v_mfma_f32_16x16x32_bf16 v[32:35], v[160:163], v[60:63], v[32:35]
	v_mfma_f32_16x16x32_bf16 v[44:47], v[164:167], v[60:63], v[44:47]
	v_mfma_f32_16x16x32_bf16 v[16:19], v[172:175], v[60:63], v[16:19]
	v_mfma_f32_16x16x32_bf16 v[76:79], v[168:171], v[60:63], v[76:79]
	global_load_dwordx4 v[60:63], v239, s[2:3] offset:640
	s_waitcnt vmcnt(7)
	ds_write_b128 v3, v[64:67] offset:24576
	v_mfma_f32_16x16x32_bf16 v[36:39], v[160:163], v[108:111], v[36:39]
	v_mfma_f32_16x16x32_bf16 v[48:51], v[164:167], v[108:111], v[48:51]
	v_mfma_f32_16x16x32_bf16 v[64:67], v[168:171], v[108:111], v[88:91]
	v_mfma_f32_16x16x32_bf16 v[20:23], v[172:175], v[108:111], v[20:23]
	global_load_dwordx4 v[84:87], v240, s[2:3] offset:640
	ds_write_b128 v3, v[68:71] offset:28672
	v_mfma_f32_16x16x32_bf16 v[40:43], v[160:163], v[120:123], v[40:43]
	v_mfma_f32_16x16x32_bf16 v[52:55], v[164:167], v[120:123], v[52:55]
	v_mfma_f32_16x16x32_bf16 v[56:59], v[168:171], v[120:123], v[56:59]
	v_mfma_f32_16x16x32_bf16 v[24:27], v[172:175], v[120:123], v[24:27]
	s_setprio 0
	s_waitcnt lgkmcnt(0)
	s_barrier
; template <int MODE>
; __device__ __forceinline__ void gemm_tile(const Params& P, int tm, int tn, unsigned char* smem) {
;     ...
;     for (int kt = 0; kt < 16; ++kt) {
;         unsigned char* sA = (kt & 1) ? sA1 : sA0; unsigned char* sB = (kt & 1) ? sB1 : sB0;
;         unsigned char* nA = (kt & 1) ? sA0 : sA1; unsigned char* nB = (kt & 1) ? sB0 : sB1;
;         bf16x8 fa[4], fb[4], ga[4], gb[4];
;         const int ch0 = ((g ^ sw) << 4), ch1 = (((4 + g) ^ sw) << 4);
;         const unsigned ko = (unsigned)(kt + 2) * 128u;
;         const unsigned koa = ko + ((MODE == 2 && kt + 2 >= 8) ? (unsigned)(ZC_FQ - 512) * 2u : 0u);
;         const bool wr_ok = kt < 15, ld_ok = kt < 14;
; #pragma unroll
;         for (int i = 0; i < 4; ++i) { fa[i] = *(const bf16x8*)(sA + arow_off + i * 2048 + ch0); fb[i] = *(const bf16x8*)(sB + brow_off + i * 2048 + ch0); }
;         __builtin_amdgcn_sched_barrier(0);
;         __builtin_amdgcn_s_setprio(2);
;         if (wr_ok) *(uint4*)(nA + soff0) = ra0;
;         if (ld_ok) ra0 = *(const uint4*)(Ab + (aoff + 0u * LDA + koa));
;         ga[0] = *(const bf16x8*)(sA + arow_off + 0 * 2048 + ch1); gb[0] = *(const bf16x8*)(sB + brow_off + 0 * 2048 + ch1);
;         __builtin_amdgcn_sched_barrier(0);
; #pragma unroll
;         for (int j = 0; j < 4; ++j) acc[0][j] = __builtin_amdgcn_mfma_f32_16x16x32_bf16(fb[j], fa[0], acc[0][j], 0, 0, 0);
;         __builtin_amdgcn_sched_barrier(0);
;         if (wr_ok) *(uint4*)(nA + soff0 + 4096) = ra1;
;         if (ld_ok) ra1 = *(const uint4*)(Ab + (aoff + 32u * LDA + koa));
;         ga[1] = *(const bf16x8*)(sA + arow_off + 1 * 2048 + ch1); gb[1] = *(const bf16x8*)(sB + brow_off + 1 * 2048 + ch1);
;         __builtin_amdgcn_sched_barrier(0);
; #pragma unroll
;         for (int j = 0; j < 4; ++j) acc[1][j] = __builtin_amdgcn_mfma_f32_16x16x32_bf16(fb[j], fa[1], acc[1][j], 0, 0, 0);
;         __builtin_amdgcn_sched_barrier(0);
;         if (wr_ok) *(uint4*)(nA + soff0 + 8192) = ra2;
;         if (ld_ok) ra2 = *(const uint4*)(Ab + (aoff + 64u * LDA + koa));
;         ga[2] = *(const bf16x8*)(sA + arow_off + 2 * 2048 + ch1); gb[2] = *(const bf16x8*)(sB + brow_off + 2 * 2048 + ch1);
;         __builtin_amdgcn_sched_barrier(0);
; #pragma unroll
;         for (int j = 0; j < 4; ++j) acc[2][j] = __builtin_amdgcn_mfma_f32_16x16x32_bf16(fb[j], fa[2], acc[2][j], 0, 0, 0);
	ds_read_b128 v[68:71], v7
	ds_read_b128 v[88:91], v7 offset:2048
	ds_read_b128 v[108:111], v8 offset:16384
	ds_read_b128 v[116:119], v8 offset:18432
	ds_read_b128 v[120:123], v7 offset:4096
	ds_read_b128 v[132:135], v7 offset:6144
	ds_read_b128 v[136:139], v8 offset:20480
	ds_read_b128 v[148:151], v8 offset:22528
	s_setprio 2
	global_load_dwordx4 v[152:155], v234, s[0:1] offset:768
	s_waitcnt vmcnt(7)
	ds_write_b128 v3, v[156:159] offset:32768
	ds_read_b128 v[156:159], v5
	ds_read_b128 v[160:163], v6 offset:16384
	s_waitcnt lgkmcnt(8)
	v_mfma_f32_16x16x32_bf16 v[28:31], v[108:111], v[68:71], v[28:31]
	s_waitcnt lgkmcnt(4)
	v_mfma_f32_16x16x32_bf16 v[80:83], v[136:139], v[68:71], v[80:83]
	s_waitcnt lgkmcnt(3)
	v_mfma_f32_16x16x32_bf16 v[12:15], v[148:151], v[68:71], v[12:15]
	v_mfma_f32_16x16x32_bf16 v[72:75], v[116:119], v[68:71], v[72:75]
	global_load_dwordx4 v[68:71], v237, s[0:1] offset:768
	ds_write_b128 v3, v[92:95] offset:36864
	ds_read_b128 v[92:95], v5 offset:2048
	ds_read_b128 v[164:167], v6 offset:18432
	v_mfma_f32_16x16x32_bf16 v[32:35], v[108:111], v[88:91], v[32:35]
	v_mfma_f32_16x16x32_bf16 v[44:47], v[116:119], v[88:91], v[44:47]
	v_mfma_f32_16x16x32_bf16 v[16:19], v[148:151], v[88:91], v[16:19]
	v_mfma_f32_16x16x32_bf16 v[76:79], v[136:139], v[88:91], v[76:79]
	global_load_dwordx4 v[88:91], v238, s[0:1] offset:768
	s_waitcnt vmcnt(7)
	ds_write_b128 v3, v[100:103] offset:40960
	ds_read_b128 v[100:103], v5 offset:4096
	ds_read_b128 v[168:171], v6 offset:20480
	v_mfma_f32_16x16x32_bf16 v[36:39], v[108:111], v[120:123], v[36:39]
	v_mfma_f32_16x16x32_bf16 v[48:51], v[116:119], v[120:123], v[48:51]
	v_mfma_f32_16x16x32_bf16 v[64:67], v[136:139], v[120:123], v[64:67]
	v_mfma_f32_16x16x32_bf16 v[20:23], v[148:151], v[120:123], v[20:23]
	global_load_dwordx4 v[120:123], v235, s[0:1] offset:768
	ds_write_b128 v3, v[124:127] offset:45056
	ds_read_b128 v[124:127], v5 offset:6144
	ds_read_b128 v[172:175], v6 offset:22528
	v_mfma_f32_16x16x32_bf16 v[40:43], v[108:111], v[132:135], v[40:43]
	v_mfma_f32_16x16x32_bf16 v[52:55], v[116:119], v[132:135], v[52:55]
	v_mfma_f32_16x16x32_bf16 v[56:59], v[136:139], v[132:135], v[56:59]
	v_mfma_f32_16x16x32_bf16 v[24:27], v[148:151], v[132:135], v[24:27]
	global_load_dwordx4 v[108:111], v4, s[2:3] offset:768
	s_waitcnt vmcnt(7)
	ds_write_b128 v3, v[104:107] offset:49152
	s_waitcnt lgkmcnt(10)
	v_mfma_f32_16x16x32_bf16 v[28:31], v[160:163], v[156:159], v[28:31]
	s_waitcnt lgkmcnt(4)
	v_mfma_f32_16x16x32_bf16 v[80:83], v[168:171], v[156:159], v[80:83]
	s_waitcnt lgkmcnt(1)
	v_mfma_f32_16x16x32_bf16 v[12:15], v[172:175], v[156:159], v[12:15]
	v_mfma_f32_16x16x32_bf16 v[72:75], v[164:167], v[156:159], v[72:75]
	global_load_dwordx4 v[104:107], v236, s[2:3] offset:768
	ds_write_b128 v3, v[112:115] offset:53248
	v_mfma_f32_16x16x32_bf16 v[32:35], v[160:163], v[92:95], v[32:35]
	v_mfma_f32_16x16x32_bf16 v[44:47], v[164:167], v[92:95], v[44:47]
	v_mfma_f32_16x16x32_bf16 v[16:19], v[172:175], v[92:95], v[16:19]
	v_mfma_f32_16x16x32_bf16 v[76:79], v[168:171], v[92:95], v[76:79]
	global_load_dwordx4 v[92:95], v239, s[2:3] offset:768
	s_waitcnt vmcnt(7)
	ds_write_b128 v3, v[60:63] offset:57344
	v_mfma_f32_16x16x32_bf16 v[36:39], v[160:163], v[100:103], v[36:39]
	v_mfma_f32_16x16x32_bf16 v[48:51], v[164:167], v[100:103], v[48:51]
	v_mfma_f32_16x16x32_bf16 v[60:63], v[168:171], v[100:103], v[64:67]
	v_mfma_f32_16x16x32_bf16 v[20:23], v[172:175], v[100:103], v[20:23]
	global_load_dwordx4 v[64:67], v240, s[2:3] offset:768
	ds_write_b128 v3, v[84:87] offset:61440
	v_mfma_f32_16x16x32_bf16 v[40:43], v[160:163], v[124:127], v[40:43]
	v_mfma_f32_16x16x32_bf16 v[52:55], v[164:167], v[124:127], v[52:55]
	v_mfma_f32_16x16x32_bf16 v[56:59], v[168:171], v[124:127], v[56:59]
	v_mfma_f32_16x16x32_bf16 v[24:27], v[172:175], v[124:127], v[24:27]
	s_setprio 0
	s_waitcnt lgkmcnt(0)
	s_barrier
	ds_read_b128 v[84:87], v7 offset:32768
	ds_read_b128 v[100:103], v7 offset:34816
	ds_read_b128 v[112:115], v8 offset:49152
	ds_read_b128 v[116:119], v8 offset:51200
	ds_read_b128 v[124:127], v7 offset:36864
	ds_read_b128 v[132:135], v7 offset:38912
	ds_read_b128 v[136:139], v8 offset:53248
	ds_read_b128 v[148:151], v8 offset:55296
	s_setprio 2
	global_load_dwordx4 v[156:159], v234, s[0:1] offset:896
	s_waitcnt vmcnt(7)
	ds_write_b128 v3, v[152:155]
	ds_read_b128 v[152:155], v5 offset:32768
	ds_read_b128 v[160:163], v6 offset:49152
	s_waitcnt lgkmcnt(8)
	v_mfma_f32_16x16x32_bf16 v[28:31], v[112:115], v[84:87], v[28:31]
	s_waitcnt lgkmcnt(4)
	v_mfma_f32_16x16x32_bf16 v[80:83], v[136:139], v[84:87], v[80:83]
	s_waitcnt lgkmcnt(3)
	v_mfma_f32_16x16x32_bf16 v[12:15], v[148:151], v[84:87], v[12:15]
	v_mfma_f32_16x16x32_bf16 v[72:75], v[116:119], v[84:87], v[72:75]
	global_load_dwordx4 v[84:87], v237, s[0:1] offset:896
	ds_write_b128 v3, v[68:71] offset:4096
	ds_read_b128 v[68:71], v5 offset:34816
	ds_read_b128 v[164:167], v6 offset:51200
	v_mfma_f32_16x16x32_bf16 v[32:35], v[112:115], v[100:103], v[32:35]
	v_mfma_f32_16x16x32_bf16 v[44:47], v[116:119], v[100:103], v[44:47]
	v_mfma_f32_16x16x32_bf16 v[16:19], v[148:151], v[100:103], v[16:19]
	v_mfma_f32_16x16x32_bf16 v[76:79], v[136:139], v[100:103], v[76:79]
	global_load_dwordx4 v[100:103], v238, s[0:1] offset:896
	s_waitcnt vmcnt(7)
; template <int MODE>
; __device__ __forceinline__ void gemm_tile(const Params& P, int tm, int tn, unsigned char* smem) {
;     ...
;     for (int kt = 0; kt < 16; ++kt) {
;         unsigned char* sA = (kt & 1) ? sA1 : sA0; unsigned char* sB = (kt & 1) ? sB1 : sB0;
;         unsigned char* nA = (kt & 1) ? sA0 : sA1; unsigned char* nB = (kt & 1) ? sB0 : sB1;
;         bf16x8 fa[4], fb[4], ga[4], gb[4];
;         const int ch0 = ((g ^ sw) << 4), ch1 = (((4 + g) ^ sw) << 4);
;         const unsigned ko = (unsigned)(kt + 2) * 128u;
;         const unsigned koa = ko + ((MODE == 2 && kt + 2 >= 8) ? (unsigned)(ZC_FQ - 512) * 2u : 0u);
;         const bool wr_ok = kt < 15, ld_ok = kt < 14;
; #pragma unroll
;         for (int i = 0; i < 4; ++i) { fa[i] = *(const bf16x8*)(sA + arow_off + i * 2048 + ch0); fb[i] = *(const bf16x8*)(sB + brow_off + i * 2048 + ch0); }
;         __builtin_amdgcn_sched_barrier(0);
;         __builtin_amdgcn_s_setprio(2);
;         if (wr_ok) *(uint4*)(nA + soff0) = ra0;
;         if (ld_ok) ra0 = *(const uint4*)(Ab + (aoff + 0u * LDA + koa));
;         ga[0] = *(const bf16x8*)(sA + arow_off + 0 * 2048 + ch1); gb[0] = *(const bf16x8*)(sB + brow_off + 0 * 2048 + ch1);
;         __builtin_amdgcn_sched_barrier(0);
; #pragma unroll
;         for (int j = 0; j < 4; ++j) acc[0][j] = __builtin_amdgcn_mfma_f32_16x16x32_bf16(fb[j], fa[0], acc[0][j], 0, 0, 0);
;         __builtin_amdgcn_sched_barrier(0);
;         if (wr_ok) *(uint4*)(nA + soff0 + 4096) = ra1;
;         if (ld_ok) ra1 = *(const uint4*)(Ab + (aoff + 32u * LDA + koa));
;         ga[1] = *(const bf16x8*)(sA + arow_off + 1 * 2048 + ch1); gb[1] = *(const bf16x8*)(sB + brow_off + 1 * 2048 + ch1);
;         __builtin_amdgcn_sched_barrier(0);
; #pragma unroll
;         for (int j = 0; j < 4; ++j) acc[1][j] = __builtin_amdgcn_mfma_f32_16x16x32_bf16(fb[j], fa[1], acc[1][j], 0, 0, 0);
;         __builtin_amdgcn_sched_barrier(0);
;         if (wr_ok) *(uint4*)(nA + soff0 + 8192) = ra2;
;         if (ld_ok) ra2 = *(const uint4*)(Ab + (aoff + 64u * LDA + koa));
;         ga[2] = *(const bf16x8*)(sA + arow_off + 2 * 2048 + ch1); gb[2] = *(const bf16x8*)(sB + brow_off + 2 * 2048 + ch1);
;         __builtin_amdgcn_sched_barrier(0);
; #pragma unroll
;         for (int j = 0; j < 4; ++j) acc[2][j] = __builtin_amdgcn_mfma_f32_16x16x32_bf16(fb[j], fa[2], acc[2][j], 0, 0, 0);
	ds_write_b128 v3, v[88:91] offset:8192
	ds_read_b128 v[88:91], v5 offset:36864
	ds_read_b128 v[168:171], v6 offset:53248
	v_mfma_f32_16x16x32_bf16 v[36:39], v[112:115], v[124:127], v[36:39]
	v_mfma_f32_16x16x32_bf16 v[48:51], v[116:119], v[124:127], v[48:51]
	v_mfma_f32_16x16x32_bf16 v[60:63], v[136:139], v[124:127], v[60:63]
	v_mfma_f32_16x16x32_bf16 v[20:23], v[148:151], v[124:127], v[20:23]
	global_load_dwordx4 v[124:127], v235, s[0:1] offset:896
	ds_write_b128 v3, v[120:123] offset:12288
	ds_read_b128 v[120:123], v5 offset:38912
	ds_read_b128 v[172:175], v6 offset:55296
	v_mfma_f32_16x16x32_bf16 v[40:43], v[112:115], v[132:135], v[40:43]
	v_mfma_f32_16x16x32_bf16 v[52:55], v[116:119], v[132:135], v[52:55]
	v_mfma_f32_16x16x32_bf16 v[56:59], v[136:139], v[132:135], v[56:59]
	v_mfma_f32_16x16x32_bf16 v[24:27], v[148:151], v[132:135], v[24:27]
	global_load_dwordx4 v[112:115], v4, s[2:3] offset:896
	s_waitcnt vmcnt(7)
	ds_write_b128 v3, v[108:111] offset:16384
	s_waitcnt lgkmcnt(10)
	v_mfma_f32_16x16x32_bf16 v[28:31], v[160:163], v[152:155], v[28:31]
	s_waitcnt lgkmcnt(4)
	v_mfma_f32_16x16x32_bf16 v[80:83], v[168:171], v[152:155], v[80:83]
	s_waitcnt lgkmcnt(1)
	v_mfma_f32_16x16x32_bf16 v[12:15], v[172:175], v[152:155], v[12:15]
	v_mfma_f32_16x16x32_bf16 v[72:75], v[164:167], v[152:155], v[72:75]
	global_load_dwordx4 v[108:111], v236, s[2:3] offset:896
	ds_write_b128 v3, v[104:107] offset:20480
	v_mfma_f32_16x16x32_bf16 v[32:35], v[160:163], v[68:71], v[32:35]
	v_mfma_f32_16x16x32_bf16 v[44:47], v[164:167], v[68:71], v[44:47]
	v_mfma_f32_16x16x32_bf16 v[16:19], v[172:175], v[68:71], v[16:19]
	v_mfma_f32_16x16x32_bf16 v[76:79], v[168:171], v[68:71], v[76:79]
	global_load_dwordx4 v[68:71], v239, s[2:3] offset:896
	s_waitcnt vmcnt(7)
	ds_write_b128 v3, v[92:95] offset:24576
	v_mfma_f32_16x16x32_bf16 v[36:39], v[160:163], v[88:91], v[36:39]
	v_mfma_f32_16x16x32_bf16 v[48:51], v[164:167], v[88:91], v[48:51]
	v_mfma_f32_16x16x32_bf16 v[60:63], v[168:171], v[88:91], v[60:63]
	v_mfma_f32_16x16x32_bf16 v[20:23], v[172:175], v[88:91], v[20:23]
	global_load_dwordx4 v[88:91], v240, s[2:3] offset:896
	ds_write_b128 v3, v[64:67] offset:28672
	v_mfma_f32_16x16x32_bf16 v[40:43], v[160:163], v[120:123], v[40:43]
	v_mfma_f32_16x16x32_bf16 v[52:55], v[164:167], v[120:123], v[52:55]
	v_mfma_f32_16x16x32_bf16 v[56:59], v[168:171], v[120:123], v[56:59]
	v_mfma_f32_16x16x32_bf16 v[24:27], v[172:175], v[120:123], v[24:27]
	s_setprio 0
	s_waitcnt lgkmcnt(0)
	s_barrier
	ds_read_b128 v[64:67], v7
	ds_read_b128 v[92:95], v7 offset:2048
	ds_read_b128 v[104:107], v8 offset:16384
	ds_read_b128 v[116:119], v8 offset:18432
	ds_read_b128 v[120:123], v7 offset:4096
	ds_read_b128 v[132:135], v7 offset:6144
	ds_read_b128 v[136:139], v8 offset:20480
	ds_read_b128 v[148:151], v8 offset:22528
	s_setprio 2
	v_add_u32_e32 v241, 0x1d000, v9
	global_load_dwordx4 v[152:155], v241, s[0:1]
	s_waitcnt vmcnt(7)
	ds_write_b128 v3, v[156:159] offset:32768
	ds_read_b128 v[156:159], v5
	ds_read_b128 v[160:163], v6 offset:16384
	s_waitcnt lgkmcnt(8)
	v_mfma_f32_16x16x32_bf16 v[28:31], v[104:107], v[64:67], v[28:31]
	s_waitcnt lgkmcnt(4)
	v_mfma_f32_16x16x32_bf16 v[80:83], v[136:139], v[64:67], v[80:83]
	s_waitcnt lgkmcnt(3)
	v_mfma_f32_16x16x32_bf16 v[12:15], v[148:151], v[64:67], v[12:15]
	v_mfma_f32_16x16x32_bf16 v[72:75], v[116:119], v[64:67], v[72:75]
	v_add_u32_e32 v242, 0x55000, v9
	global_load_dwordx4 v[64:67], v242, s[0:1]
	ds_write_b128 v3, v[84:87] offset:36864
	ds_read_b128 v[84:87], v5 offset:2048
	ds_read_b128 v[164:167], v6 offset:18432
	v_mfma_f32_16x16x32_bf16 v[32:35], v[104:107], v[92:95], v[32:35]
	v_mfma_f32_16x16x32_bf16 v[44:47], v[116:119], v[92:95], v[44:47]
	v_mfma_f32_16x16x32_bf16 v[16:19], v[148:151], v[92:95], v[16:19]
	v_mfma_f32_16x16x32_bf16 v[76:79], v[136:139], v[92:95], v[76:79]
	v_add_u32_e32 v243, 0x8d000, v9
	global_load_dwordx4 v[92:95], v243, s[0:1]
	s_waitcnt vmcnt(7)
	ds_write_b128 v3, v[100:103] offset:40960
	ds_read_b128 v[100:103], v5 offset:4096
	ds_read_b128 v[168:171], v6 offset:20480
	v_mfma_f32_16x16x32_bf16 v[36:39], v[104:107], v[120:123], v[36:39]
	v_mfma_f32_16x16x32_bf16 v[48:51], v[116:119], v[120:123], v[48:51]
	v_mfma_f32_16x16x32_bf16 v[60:63], v[136:139], v[120:123], v[60:63]
	v_mfma_f32_16x16x32_bf16 v[20:23], v[148:151], v[120:123], v[20:23]
	v_add_u32_e32 v244, 0xc5000, v9
	global_load_dwordx4 v[120:123], v244, s[0:1]
	ds_write_b128 v3, v[124:127] offset:45056
	ds_read_b128 v[124:127], v5 offset:6144
	ds_read_b128 v[172:175], v6 offset:22528
	v_mfma_f32_16x16x32_bf16 v[40:43], v[104:107], v[132:135], v[40:43]
	v_mfma_f32_16x16x32_bf16 v[52:55], v[116:119], v[132:135], v[52:55]
	v_mfma_f32_16x16x32_bf16 v[56:59], v[136:139], v[132:135], v[56:59]
	v_mfma_f32_16x16x32_bf16 v[24:27], v[148:151], v[132:135], v[24:27]
	global_load_dwordx4 v[104:107], v4, s[2:3] offset:1024
	s_waitcnt vmcnt(7)
	ds_write_b128 v3, v[112:115] offset:49152
	s_waitcnt lgkmcnt(10)
	v_mfma_f32_16x16x32_bf16 v[28:31], v[160:163], v[156:159], v[28:31]
	s_waitcnt lgkmcnt(4)
	v_mfma_f32_16x16x32_bf16 v[80:83], v[168:171], v[156:159], v[80:83]
	s_waitcnt lgkmcnt(1)
	v_mfma_f32_16x16x32_bf16 v[12:15], v[172:175], v[156:159], v[12:15]
	v_mfma_f32_16x16x32_bf16 v[72:75], v[164:167], v[156:159], v[72:75]
	global_load_dwordx4 v[112:115], v236, s[2:3] offset:1024
	ds_write_b128 v3, v[108:111] offset:53248
	v_mfma_f32_16x16x32_bf16 v[32:35], v[160:163], v[84:87], v[32:35]
	v_mfma_f32_16x16x32_bf16 v[44:47], v[164:167], v[84:87], v[44:47]
	v_mfma_f32_16x16x32_bf16 v[16:19], v[172:175], v[84:87], v[16:19]
	v_mfma_f32_16x16x32_bf16 v[76:79], v[168:171], v[84:87], v[76:79]
	global_load_dwordx4 v[84:87], v239, s[2:3] offset:1024
	s_waitcnt vmcnt(7)
	ds_write_b128 v3, v[68:71] offset:57344
	v_mfma_f32_16x16x32_bf16 v[36:39], v[160:163], v[100:103], v[36:39]
	v_mfma_f32_16x16x32_bf16 v[48:51], v[164:167], v[100:103], v[48:51]
	v_mfma_f32_16x16x32_bf16 v[60:63], v[168:171], v[100:103], v[60:63]
	v_mfma_f32_16x16x32_bf16 v[20:23], v[172:175], v[100:103], v[20:23]
	global_load_dwordx4 v[68:71], v240, s[2:3] offset:1024
	ds_write_b128 v3, v[88:91] offset:61440
	v_mfma_f32_16x16x32_bf16 v[40:43], v[160:163], v[124:127], v[40:43]
	v_mfma_f32_16x16x32_bf16 v[52:55], v[164:167], v[124:127], v[52:55]
	v_mfma_f32_16x16x32_bf16 v[56:59], v[168:171], v[124:127], v[56:59]
	v_mfma_f32_16x16x32_bf16 v[24:27], v[172:175], v[124:127], v[24:27]
	s_setprio 0
	s_waitcnt lgkmcnt(0)
	s_barrier
; template <int MODE>
; __device__ __forceinline__ void gemm_tile(const Params& P, int tm, int tn, unsigned char* smem) {
;     ...
;     for (int kt = 0; kt < 16; ++kt) {
;         unsigned char* sA = (kt & 1) ? sA1 : sA0; unsigned char* sB = (kt & 1) ? sB1 : sB0;
;         unsigned char* nA = (kt & 1) ? sA0 : sA1; unsigned char* nB = (kt & 1) ? sB0 : sB1;
;         bf16x8 fa[4], fb[4], ga[4], gb[4];
;         const int ch0 = ((g ^ sw) << 4), ch1 = (((4 + g) ^ sw) << 4);
;         const unsigned ko = (unsigned)(kt + 2) * 128u;
;         const unsigned koa = ko + ((MODE == 2 && kt + 2 >= 8) ? (unsigned)(ZC_FQ - 512) * 2u : 0u);
;         const bool wr_ok = kt < 15, ld_ok = kt < 14;
; #pragma unroll
;         for (int i = 0; i < 4; ++i) { fa[i] = *(const bf16x8*)(sA + arow_off + i * 2048 + ch0); fb[i] = *(const bf16x8*)(sB + brow_off + i * 2048 + ch0); }
;         __builtin_amdgcn_sched_barrier(0);
;         __builtin_amdgcn_s_setprio(2);
;         if (wr_ok) *(uint4*)(nA + soff0) = ra0;
;         if (ld_ok) ra0 = *(const uint4*)(Ab + (aoff + 0u * LDA + koa));
;         ga[0] = *(const bf16x8*)(sA + arow_off + 0 * 2048 + ch1); gb[0] = *(const bf16x8*)(sB + brow_off + 0 * 2048 + ch1);
;         __builtin_amdgcn_sched_barrier(0);
; #pragma unroll
;         for (int j = 0; j < 4; ++j) acc[0][j] = __builtin_amdgcn_mfma_f32_16x16x32_bf16(fb[j], fa[0], acc[0][j], 0, 0, 0);
;         __builtin_amdgcn_sched_barrier(0);
;         if (wr_ok) *(uint4*)(nA + soff0 + 4096) = ra1;
;         if (ld_ok) ra1 = *(const uint4*)(Ab + (aoff + 32u * LDA + koa));
;         ga[1] = *(const bf16x8*)(sA + arow_off + 1 * 2048 + ch1); gb[1] = *(const bf16x8*)(sB + brow_off + 1 * 2048 + ch1);
;         __builtin_amdgcn_sched_barrier(0);
; #pragma unroll
;         for (int j = 0; j < 4; ++j) acc[1][j] = __builtin_amdgcn_mfma_f32_16x16x32_bf16(fb[j], fa[1], acc[1][j], 0, 0, 0);
;         __builtin_amdgcn_sched_barrier(0);
;         if (wr_ok) *(uint4*)(nA + soff0 + 8192) = ra2;
;         if (ld_ok) ra2 = *(const uint4*)(Ab + (aoff + 64u * LDA + koa));
;         ga[2] = *(const bf16x8*)(sA + arow_off + 2 * 2048 + ch1); gb[2] = *(const bf16x8*)(sB + brow_off + 2 * 2048 + ch1);
;         __builtin_amdgcn_sched_barrier(0);
; #pragma unroll
;         for (int j = 0; j < 4; ++j) acc[2][j] = __builtin_amdgcn_mfma_f32_16x16x32_bf16(fb[j], fa[2], acc[2][j], 0, 0, 0);
	ds_read_b128 v[88:91], v7 offset:32768
	ds_read_b128 v[100:103], v7 offset:34816
	ds_read_b128 v[108:111], v8 offset:49152
	ds_read_b128 v[116:119], v8 offset:51200
	ds_read_b128 v[124:127], v7 offset:36864
	ds_read_b128 v[132:135], v7 offset:38912
	ds_read_b128 v[136:139], v8 offset:53248
	ds_read_b128 v[148:151], v8 offset:55296
	s_setprio 2
	global_load_dwordx4 v[156:159], v241, s[0:1] offset:128
	s_waitcnt vmcnt(7)
	ds_write_b128 v3, v[152:155]
	ds_read_b128 v[152:155], v5 offset:32768
	ds_read_b128 v[160:163], v6 offset:49152
	s_waitcnt lgkmcnt(8)
	v_mfma_f32_16x16x32_bf16 v[28:31], v[108:111], v[88:91], v[28:31]
	s_waitcnt lgkmcnt(4)
	v_mfma_f32_16x16x32_bf16 v[80:83], v[136:139], v[88:91], v[80:83]
	s_waitcnt lgkmcnt(3)
	v_mfma_f32_16x16x32_bf16 v[12:15], v[148:151], v[88:91], v[12:15]
	v_mfma_f32_16x16x32_bf16 v[72:75], v[116:119], v[88:91], v[72:75]
	global_load_dwordx4 v[88:91], v242, s[0:1] offset:128
	ds_write_b128 v3, v[64:67] offset:4096
	ds_read_b128 v[64:67], v5 offset:34816
	ds_read_b128 v[164:167], v6 offset:51200
	v_mfma_f32_16x16x32_bf16 v[32:35], v[108:111], v[100:103], v[32:35]
	v_mfma_f32_16x16x32_bf16 v[44:47], v[116:119], v[100:103], v[44:47]
	v_mfma_f32_16x16x32_bf16 v[16:19], v[148:151], v[100:103], v[16:19]
	v_mfma_f32_16x16x32_bf16 v[76:79], v[136:139], v[100:103], v[76:79]
	global_load_dwordx4 v[100:103], v243, s[0:1] offset:128
	s_waitcnt vmcnt(7)
	ds_write_b128 v3, v[92:95] offset:8192
	ds_read_b128 v[92:95], v5 offset:36864
	ds_read_b128 v[168:171], v6 offset:53248
	v_mfma_f32_16x16x32_bf16 v[36:39], v[108:111], v[124:127], v[36:39]
	v_mfma_f32_16x16x32_bf16 v[48:51], v[116:119], v[124:127], v[48:51]
	v_mfma_f32_16x16x32_bf16 v[60:63], v[136:139], v[124:127], v[60:63]
	v_mfma_f32_16x16x32_bf16 v[20:23], v[148:151], v[124:127], v[20:23]
	global_load_dwordx4 v[124:127], v244, s[0:1] offset:128
	ds_write_b128 v3, v[120:123] offset:12288
	ds_read_b128 v[120:123], v5 offset:38912
	ds_read_b128 v[172:175], v6 offset:55296
	v_mfma_f32_16x16x32_bf16 v[40:43], v[108:111], v[132:135], v[40:43]
	v_mfma_f32_16x16x32_bf16 v[52:55], v[116:119], v[132:135], v[52:55]
	v_mfma_f32_16x16x32_bf16 v[56:59], v[136:139], v[132:135], v[56:59]
	v_mfma_f32_16x16x32_bf16 v[24:27], v[148:151], v[132:135], v[24:27]
	global_load_dwordx4 v[108:111], v4, s[2:3] offset:1152
	s_waitcnt vmcnt(7)
	ds_write_b128 v3, v[104:107] offset:16384
	s_waitcnt lgkmcnt(10)
	v_mfma_f32_16x16x32_bf16 v[28:31], v[160:163], v[152:155], v[28:31]
	s_waitcnt lgkmcnt(4)
	v_mfma_f32_16x16x32_bf16 v[80:83], v[168:171], v[152:155], v[80:83]
	s_waitcnt lgkmcnt(1)
	v_mfma_f32_16x16x32_bf16 v[12:15], v[172:175], v[152:155], v[12:15]
	v_mfma_f32_16x16x32_bf16 v[72:75], v[164:167], v[152:155], v[72:75]
	global_load_dwordx4 v[104:107], v236, s[2:3] offset:1152
	ds_write_b128 v3, v[112:115] offset:20480
	v_mfma_f32_16x16x32_bf16 v[32:35], v[160:163], v[64:67], v[32:35]
	v_mfma_f32_16x16x32_bf16 v[44:47], v[164:167], v[64:67], v[44:47]
	v_mfma_f32_16x16x32_bf16 v[16:19], v[172:175], v[64:67], v[16:19]
	v_mfma_f32_16x16x32_bf16 v[76:79], v[168:171], v[64:67], v[76:79]
	global_load_dwordx4 v[64:67], v239, s[2:3] offset:1152
	s_waitcnt vmcnt(7)
	ds_write_b128 v3, v[84:87] offset:24576
	v_mfma_f32_16x16x32_bf16 v[36:39], v[160:163], v[92:95], v[36:39]
	v_mfma_f32_16x16x32_bf16 v[48:51], v[164:167], v[92:95], v[48:51]
	v_mfma_f32_16x16x32_bf16 v[60:63], v[168:171], v[92:95], v[60:63]
	v_mfma_f32_16x16x32_bf16 v[20:23], v[172:175], v[92:95], v[20:23]
	global_load_dwordx4 v[84:87], v240, s[2:3] offset:1152
	ds_write_b128 v3, v[68:71] offset:28672
	v_mfma_f32_16x16x32_bf16 v[40:43], v[160:163], v[120:123], v[40:43]
	v_mfma_f32_16x16x32_bf16 v[52:55], v[164:167], v[120:123], v[52:55]
	v_mfma_f32_16x16x32_bf16 v[56:59], v[168:171], v[120:123], v[56:59]
	v_mfma_f32_16x16x32_bf16 v[24:27], v[172:175], v[120:123], v[24:27]
	s_setprio 0
	s_waitcnt lgkmcnt(0)
	s_barrier
	ds_read_b128 v[68:71], v7
	ds_read_b128 v[92:95], v7 offset:2048
	ds_read_b128 v[112:115], v8 offset:16384
	ds_read_b128 v[116:119], v8 offset:18432
	ds_read_b128 v[120:123], v7 offset:4096
	ds_read_b128 v[132:135], v7 offset:6144
	ds_read_b128 v[136:139], v8 offset:20480
	ds_read_b128 v[148:151], v8 offset:22528
	s_setprio 2
	global_load_dwordx4 v[152:155], v241, s[0:1] offset:256
	s_waitcnt vmcnt(7)
	ds_write_b128 v3, v[156:159] offset:32768
	ds_read_b128 v[156:159], v5
	ds_read_b128 v[160:163], v6 offset:16384
	s_waitcnt lgkmcnt(8)
	v_mfma_f32_16x16x32_bf16 v[28:31], v[112:115], v[68:71], v[28:31]
	s_waitcnt lgkmcnt(4)
	v_mfma_f32_16x16x32_bf16 v[80:83], v[136:139], v[68:71], v[80:83]
	s_waitcnt lgkmcnt(3)
	v_mfma_f32_16x16x32_bf16 v[12:15], v[148:151], v[68:71], v[12:15]
	v_mfma_f32_16x16x32_bf16 v[72:75], v[116:119], v[68:71], v[72:75]
	global_load_dwordx4 v[68:71], v242, s[0:1] offset:256
	ds_write_b128 v3, v[88:91] offset:36864
	ds_read_b128 v[88:91], v5 offset:2048
	ds_read_b128 v[164:167], v6 offset:18432
	v_mfma_f32_16x16x32_bf16 v[32:35], v[112:115], v[92:95], v[32:35]
	v_mfma_f32_16x16x32_bf16 v[44:47], v[116:119], v[92:95], v[44:47]
	v_mfma_f32_16x16x32_bf16 v[16:19], v[148:151], v[92:95], v[16:19]
	v_mfma_f32_16x16x32_bf16 v[76:79], v[136:139], v[92:95], v[76:79]
	global_load_dwordx4 v[92:95], v243, s[0:1] offset:256
	s_waitcnt vmcnt(7)
; template <int MODE>
; __device__ __forceinline__ void gemm_tile(const Params& P, int tm, int tn, unsigned char* smem) {
;     ...
;     for (int kt = 0; kt < 16; ++kt) {
;         unsigned char* sA = (kt & 1) ? sA1 : sA0; unsigned char* sB = (kt & 1) ? sB1 : sB0;
;         unsigned char* nA = (kt & 1) ? sA0 : sA1; unsigned char* nB = (kt & 1) ? sB0 : sB1;
;         bf16x8 fa[4], fb[4], ga[4], gb[4];
;         const int ch0 = ((g ^ sw) << 4), ch1 = (((4 + g) ^ sw) << 4);
;         const unsigned ko = (unsigned)(kt + 2) * 128u;
;         const unsigned koa = ko + ((MODE == 2 && kt + 2 >= 8) ? (unsigned)(ZC_FQ - 512) * 2u : 0u);
;         const bool wr_ok = kt < 15, ld_ok = kt < 14;
; #pragma unroll
;         for (int i = 0; i < 4; ++i) { fa[i] = *(const bf16x8*)(sA + arow_off + i * 2048 + ch0); fb[i] = *(const bf16x8*)(sB + brow_off + i * 2048 + ch0); }
;         __builtin_amdgcn_sched_barrier(0);
;         __builtin_amdgcn_s_setprio(2);
;         if (wr_ok) *(uint4*)(nA + soff0) = ra0;
;         if (ld_ok) ra0 = *(const uint4*)(Ab + (aoff + 0u * LDA + koa));
;         ga[0] = *(const bf16x8*)(sA + arow_off + 0 * 2048 + ch1); gb[0] = *(const bf16x8*)(sB + brow_off + 0 * 2048 + ch1);
;         __builtin_amdgcn_sched_barrier(0);
; #pragma unroll
;         for (int j = 0; j < 4; ++j) acc[0][j] = __builtin_amdgcn_mfma_f32_16x16x32_bf16(fb[j], fa[0], acc[0][j], 0, 0, 0);
;         __builtin_amdgcn_sched_barrier(0);
;         if (wr_ok) *(uint4*)(nA + soff0 + 4096) = ra1;
;         if (ld_ok) ra1 = *(const uint4*)(Ab + (aoff + 32u * LDA + koa));
;         ga[1] = *(const bf16x8*)(sA + arow_off + 1 * 2048 + ch1); gb[1] = *(const bf16x8*)(sB + brow_off + 1 * 2048 + ch1);
;         __builtin_amdgcn_sched_barrier(0);
; #pragma unroll
;         for (int j = 0; j < 4; ++j) acc[1][j] = __builtin_amdgcn_mfma_f32_16x16x32_bf16(fb[j], fa[1], acc[1][j], 0, 0, 0);
;         __builtin_amdgcn_sched_barrier(0);
;         if (wr_ok) *(uint4*)(nA + soff0 + 8192) = ra2;
;         if (ld_ok) ra2 = *(const uint4*)(Ab + (aoff + 64u * LDA + koa));
;         ga[2] = *(const bf16x8*)(sA + arow_off + 2 * 2048 + ch1); gb[2] = *(const bf16x8*)(sB + brow_off + 2 * 2048 + ch1);
;         __builtin_amdgcn_sched_barrier(0);
; #pragma unroll
;         for (int j = 0; j < 4; ++j) acc[2][j] = __builtin_amdgcn_mfma_f32_16x16x32_bf16(fb[j], fa[2], acc[2][j], 0, 0, 0);
	ds_write_b128 v3, v[100:103] offset:40960
	ds_read_b128 v[100:103], v5 offset:4096
	ds_read_b128 v[168:171], v6 offset:20480
	v_mfma_f32_16x16x32_bf16 v[36:39], v[112:115], v[120:123], v[36:39]
	v_mfma_f32_16x16x32_bf16 v[48:51], v[116:119], v[120:123], v[48:51]
	v_mfma_f32_16x16x32_bf16 v[60:63], v[136:139], v[120:123], v[60:63]
	v_mfma_f32_16x16x32_bf16 v[20:23], v[148:151], v[120:123], v[20:23]
	global_load_dwordx4 v[120:123], v244, s[0:1] offset:256
	ds_write_b128 v3, v[124:127] offset:45056
	ds_read_b128 v[124:127], v5 offset:6144
	ds_read_b128 v[172:175], v6 offset:22528
	v_mfma_f32_16x16x32_bf16 v[40:43], v[112:115], v[132:135], v[40:43]
	v_mfma_f32_16x16x32_bf16 v[52:55], v[116:119], v[132:135], v[52:55]
	v_mfma_f32_16x16x32_bf16 v[56:59], v[136:139], v[132:135], v[56:59]
	v_mfma_f32_16x16x32_bf16 v[24:27], v[148:151], v[132:135], v[24:27]
	global_load_dwordx4 v[112:115], v4, s[2:3] offset:1280
	s_waitcnt vmcnt(7)
	ds_write_b128 v3, v[108:111] offset:49152
	s_waitcnt lgkmcnt(10)
	v_mfma_f32_16x16x32_bf16 v[28:31], v[160:163], v[156:159], v[28:31]
	s_waitcnt lgkmcnt(4)
	v_mfma_f32_16x16x32_bf16 v[80:83], v[168:171], v[156:159], v[80:83]
	s_waitcnt lgkmcnt(1)
	v_mfma_f32_16x16x32_bf16 v[12:15], v[172:175], v[156:159], v[12:15]
	v_mfma_f32_16x16x32_bf16 v[72:75], v[164:167], v[156:159], v[72:75]
	global_load_dwordx4 v[108:111], v236, s[2:3] offset:1280
	ds_write_b128 v3, v[104:107] offset:53248
	v_mfma_f32_16x16x32_bf16 v[32:35], v[160:163], v[88:91], v[32:35]
	v_mfma_f32_16x16x32_bf16 v[44:47], v[164:167], v[88:91], v[44:47]
	v_mfma_f32_16x16x32_bf16 v[16:19], v[172:175], v[88:91], v[16:19]
	v_mfma_f32_16x16x32_bf16 v[76:79], v[168:171], v[88:91], v[76:79]
	global_load_dwordx4 v[88:91], v239, s[2:3] offset:1280
	s_waitcnt vmcnt(7)
	ds_write_b128 v3, v[64:67] offset:57344
	v_mfma_f32_16x16x32_bf16 v[36:39], v[160:163], v[100:103], v[36:39]
	v_mfma_f32_16x16x32_bf16 v[48:51], v[164:167], v[100:103], v[48:51]
	v_mfma_f32_16x16x32_bf16 v[60:63], v[168:171], v[100:103], v[60:63]
	v_mfma_f32_16x16x32_bf16 v[20:23], v[172:175], v[100:103], v[20:23]
	global_load_dwordx4 v[64:67], v240, s[2:3] offset:1280
	ds_write_b128 v3, v[84:87] offset:61440
	v_mfma_f32_16x16x32_bf16 v[40:43], v[160:163], v[124:127], v[40:43]
	v_mfma_f32_16x16x32_bf16 v[52:55], v[164:167], v[124:127], v[52:55]
	v_mfma_f32_16x16x32_bf16 v[56:59], v[168:171], v[124:127], v[56:59]
	v_mfma_f32_16x16x32_bf16 v[24:27], v[172:175], v[124:127], v[24:27]
	s_setprio 0
	s_waitcnt lgkmcnt(0)
	s_barrier
	ds_read_b128 v[84:87], v7 offset:32768
	ds_read_b128 v[100:103], v7 offset:34816
	ds_read_b128 v[104:107], v8 offset:49152
	ds_read_b128 v[116:119], v8 offset:51200
	ds_read_b128 v[124:127], v7 offset:36864
	ds_read_b128 v[132:135], v7 offset:38912
	ds_read_b128 v[136:139], v8 offset:53248
	ds_read_b128 v[148:151], v8 offset:55296
	s_setprio 2
	global_load_dwordx4 v[156:159], v241, s[0:1] offset:384
	s_waitcnt vmcnt(7)
	ds_write_b128 v3, v[152:155]
	ds_read_b128 v[152:155], v5 offset:32768
	ds_read_b128 v[160:163], v6 offset:49152
	s_waitcnt lgkmcnt(8)
	v_mfma_f32_16x16x32_bf16 v[28:31], v[104:107], v[84:87], v[28:31]
	s_waitcnt lgkmcnt(4)
	v_mfma_f32_16x16x32_bf16 v[80:83], v[136:139], v[84:87], v[80:83]
	s_waitcnt lgkmcnt(3)
	v_mfma_f32_16x16x32_bf16 v[12:15], v[148:151], v[84:87], v[12:15]
	v_mfma_f32_16x16x32_bf16 v[72:75], v[116:119], v[84:87], v[72:75]
	global_load_dwordx4 v[84:87], v242, s[0:1] offset:384
	ds_write_b128 v3, v[68:71] offset:4096
	ds_read_b128 v[68:71], v5 offset:34816
	ds_read_b128 v[164:167], v6 offset:51200
	v_mfma_f32_16x16x32_bf16 v[32:35], v[104:107], v[100:103], v[32:35]
	v_mfma_f32_16x16x32_bf16 v[44:47], v[116:119], v[100:103], v[44:47]
	v_mfma_f32_16x16x32_bf16 v[16:19], v[148:151], v[100:103], v[16:19]
	v_mfma_f32_16x16x32_bf16 v[76:79], v[136:139], v[100:103], v[76:79]
	global_load_dwordx4 v[100:103], v243, s[0:1] offset:384
	s_waitcnt vmcnt(7)
	ds_write_b128 v3, v[92:95] offset:8192
	ds_read_b128 v[92:95], v5 offset:36864
	ds_read_b128 v[168:171], v6 offset:53248
	v_mfma_f32_16x16x32_bf16 v[36:39], v[104:107], v[124:127], v[36:39]
	v_mfma_f32_16x16x32_bf16 v[48:51], v[116:119], v[124:127], v[48:51]
	v_mfma_f32_16x16x32_bf16 v[60:63], v[136:139], v[124:127], v[60:63]
	v_mfma_f32_16x16x32_bf16 v[20:23], v[148:151], v[124:127], v[20:23]
	global_load_dwordx4 v[124:127], v244, s[0:1] offset:384
	ds_write_b128 v3, v[120:123] offset:12288
	ds_read_b128 v[120:123], v5 offset:38912
	ds_read_b128 v[172:175], v6 offset:55296
	v_mfma_f32_16x16x32_bf16 v[40:43], v[104:107], v[132:135], v[40:43]
	v_mfma_f32_16x16x32_bf16 v[52:55], v[116:119], v[132:135], v[52:55]
	v_mfma_f32_16x16x32_bf16 v[56:59], v[136:139], v[132:135], v[56:59]
	v_mfma_f32_16x16x32_bf16 v[24:27], v[148:151], v[132:135], v[24:27]
	global_load_dwordx4 v[104:107], v4, s[2:3] offset:1408
	s_waitcnt vmcnt(7)
	ds_write_b128 v3, v[112:115] offset:16384
	s_waitcnt lgkmcnt(10)
	v_mfma_f32_16x16x32_bf16 v[28:31], v[160:163], v[152:155], v[28:31]
	s_waitcnt lgkmcnt(4)
	v_mfma_f32_16x16x32_bf16 v[80:83], v[168:171], v[152:155], v[80:83]
	s_waitcnt lgkmcnt(1)
	v_mfma_f32_16x16x32_bf16 v[12:15], v[172:175], v[152:155], v[12:15]
	v_mfma_f32_16x16x32_bf16 v[72:75], v[164:167], v[152:155], v[72:75]
	global_load_dwordx4 v[112:115], v236, s[2:3] offset:1408
	ds_write_b128 v3, v[108:111] offset:20480
	v_mfma_f32_16x16x32_bf16 v[32:35], v[160:163], v[68:71], v[32:35]
	v_mfma_f32_16x16x32_bf16 v[44:47], v[164:167], v[68:71], v[44:47]
	v_mfma_f32_16x16x32_bf16 v[16:19], v[172:175], v[68:71], v[16:19]
	v_mfma_f32_16x16x32_bf16 v[76:79], v[168:171], v[68:71], v[76:79]
	global_load_dwordx4 v[68:71], v239, s[2:3] offset:1408
	s_waitcnt vmcnt(7)
	ds_write_b128 v3, v[88:91] offset:24576
	v_mfma_f32_16x16x32_bf16 v[36:39], v[160:163], v[92:95], v[36:39]
	v_mfma_f32_16x16x32_bf16 v[48:51], v[164:167], v[92:95], v[48:51]
	v_mfma_f32_16x16x32_bf16 v[60:63], v[168:171], v[92:95], v[60:63]
	v_mfma_f32_16x16x32_bf16 v[20:23], v[172:175], v[92:95], v[20:23]
	global_load_dwordx4 v[88:91], v240, s[2:3] offset:1408
	ds_write_b128 v3, v[64:67] offset:28672
	v_mfma_f32_16x16x32_bf16 v[40:43], v[160:163], v[120:123], v[40:43]
	v_mfma_f32_16x16x32_bf16 v[52:55], v[164:167], v[120:123], v[52:55]
	v_mfma_f32_16x16x32_bf16 v[56:59], v[168:171], v[120:123], v[56:59]
	v_mfma_f32_16x16x32_bf16 v[24:27], v[172:175], v[120:123], v[24:27]
	s_setprio 0
	s_waitcnt lgkmcnt(0)
	s_barrier
; template <int MODE>
; __device__ __forceinline__ void gemm_tile(const Params& P, int tm, int tn, unsigned char* smem) {
;     ...
;     for (int kt = 0; kt < 16; ++kt) {
;         unsigned char* sA = (kt & 1) ? sA1 : sA0; unsigned char* sB = (kt & 1) ? sB1 : sB0;
;         unsigned char* nA = (kt & 1) ? sA0 : sA1; unsigned char* nB = (kt & 1) ? sB0 : sB1;
;         bf16x8 fa[4], fb[4], ga[4], gb[4];
;         const int ch0 = ((g ^ sw) << 4), ch1 = (((4 + g) ^ sw) << 4);
;         const unsigned ko = (unsigned)(kt + 2) * 128u;
;         const unsigned koa = ko + ((MODE == 2 && kt + 2 >= 8) ? (unsigned)(ZC_FQ - 512) * 2u : 0u);
;         const bool wr_ok = kt < 15, ld_ok = kt < 14;
; #pragma unroll
;         for (int i = 0; i < 4; ++i) { fa[i] = *(const bf16x8*)(sA + arow_off + i * 2048 + ch0); fb[i] = *(const bf16x8*)(sB + brow_off + i * 2048 + ch0); }
;         __builtin_amdgcn_sched_barrier(0);
;         __builtin_amdgcn_s_setprio(2);
;         if (wr_ok) *(uint4*)(nA + soff0) = ra0;
;         if (ld_ok) ra0 = *(const uint4*)(Ab + (aoff + 0u * LDA + koa));
;         ga[0] = *(const bf16x8*)(sA + arow_off + 0 * 2048 + ch1); gb[0] = *(const bf16x8*)(sB + brow_off + 0 * 2048 + ch1);
;         __builtin_amdgcn_sched_barrier(0);
; #pragma unroll
;         for (int j = 0; j < 4; ++j) acc[0][j] = __builtin_amdgcn_mfma_f32_16x16x32_bf16(fb[j], fa[0], acc[0][j], 0, 0, 0);
;         __builtin_amdgcn_sched_barrier(0);
;         if (wr_ok) *(uint4*)(nA + soff0 + 4096) = ra1;
;         if (ld_ok) ra1 = *(const uint4*)(Ab + (aoff + 32u * LDA + koa));
;         ga[1] = *(const bf16x8*)(sA + arow_off + 1 * 2048 + ch1); gb[1] = *(const bf16x8*)(sB + brow_off + 1 * 2048 + ch1);
;         __builtin_amdgcn_sched_barrier(0);
; #pragma unroll
;         for (int j = 0; j < 4; ++j) acc[1][j] = __builtin_amdgcn_mfma_f32_16x16x32_bf16(fb[j], fa[1], acc[1][j], 0, 0, 0);
;         __builtin_amdgcn_sched_barrier(0);
;         if (wr_ok) *(uint4*)(nA + soff0 + 8192) = ra2;
;         if (ld_ok) ra2 = *(const uint4*)(Ab + (aoff + 64u * LDA + koa));
;         ga[2] = *(const bf16x8*)(sA + arow_off + 2 * 2048 + ch1); gb[2] = *(const bf16x8*)(sB + brow_off + 2 * 2048 + ch1);
;         __builtin_amdgcn_sched_barrier(0);
; #pragma unroll
;         for (int j = 0; j < 4; ++j) acc[2][j] = __builtin_amdgcn_mfma_f32_16x16x32_bf16(fb[j], fa[2], acc[2][j], 0, 0, 0);
	ds_read_b128 v[64:67], v7
	ds_read_b128 v[92:95], v7 offset:2048
	ds_read_b128 v[108:111], v8 offset:16384
	ds_read_b128 v[116:119], v8 offset:18432
	ds_read_b128 v[120:123], v7 offset:4096
	ds_read_b128 v[132:135], v7 offset:6144
	ds_read_b128 v[136:139], v8 offset:20480
	ds_read_b128 v[148:151], v8 offset:22528
	s_setprio 2
	global_load_dwordx4 v[152:155], v241, s[0:1] offset:512
	s_waitcnt vmcnt(7)
	ds_write_b128 v3, v[156:159] offset:32768
	ds_read_b128 v[156:159], v5
	ds_read_b128 v[160:163], v6 offset:16384
	s_waitcnt lgkmcnt(8)
	v_mfma_f32_16x16x32_bf16 v[28:31], v[108:111], v[64:67], v[28:31]
	s_waitcnt lgkmcnt(4)
	v_mfma_f32_16x16x32_bf16 v[80:83], v[136:139], v[64:67], v[80:83]
	s_waitcnt lgkmcnt(3)
	v_mfma_f32_16x16x32_bf16 v[12:15], v[148:151], v[64:67], v[12:15]
	v_mfma_f32_16x16x32_bf16 v[72:75], v[116:119], v[64:67], v[72:75]
	global_load_dwordx4 v[64:67], v242, s[0:1] offset:512
	ds_write_b128 v3, v[84:87] offset:36864
	ds_read_b128 v[84:87], v5 offset:2048
	ds_read_b128 v[164:167], v6 offset:18432
	v_mfma_f32_16x16x32_bf16 v[32:35], v[108:111], v[92:95], v[32:35]
	v_mfma_f32_16x16x32_bf16 v[44:47], v[116:119], v[92:95], v[44:47]
	v_mfma_f32_16x16x32_bf16 v[16:19], v[148:151], v[92:95], v[16:19]
	v_mfma_f32_16x16x32_bf16 v[76:79], v[136:139], v[92:95], v[76:79]
	global_load_dwordx4 v[92:95], v243, s[0:1] offset:512
	s_waitcnt vmcnt(7)
	ds_write_b128 v3, v[100:103] offset:40960
	ds_read_b128 v[100:103], v5 offset:4096
	ds_read_b128 v[168:171], v6 offset:20480
	v_mfma_f32_16x16x32_bf16 v[36:39], v[108:111], v[120:123], v[36:39]
	v_mfma_f32_16x16x32_bf16 v[48:51], v[116:119], v[120:123], v[48:51]
	v_mfma_f32_16x16x32_bf16 v[60:63], v[136:139], v[120:123], v[60:63]
	v_mfma_f32_16x16x32_bf16 v[20:23], v[148:151], v[120:123], v[20:23]
	global_load_dwordx4 v[120:123], v244, s[0:1] offset:512
	ds_write_b128 v3, v[124:127] offset:45056
	ds_read_b128 v[124:127], v5 offset:6144
	ds_read_b128 v[172:175], v6 offset:22528
	v_mfma_f32_16x16x32_bf16 v[40:43], v[108:111], v[132:135], v[40:43]
	v_mfma_f32_16x16x32_bf16 v[52:55], v[116:119], v[132:135], v[52:55]
	v_mfma_f32_16x16x32_bf16 v[56:59], v[136:139], v[132:135], v[56:59]
	v_mfma_f32_16x16x32_bf16 v[24:27], v[148:151], v[132:135], v[24:27]
	global_load_dwordx4 v[108:111], v4, s[2:3] offset:1536
	s_waitcnt vmcnt(7)
	ds_write_b128 v3, v[104:107] offset:49152
	s_waitcnt lgkmcnt(10)
	v_mfma_f32_16x16x32_bf16 v[28:31], v[160:163], v[156:159], v[28:31]
	s_waitcnt lgkmcnt(4)
	v_mfma_f32_16x16x32_bf16 v[80:83], v[168:171], v[156:159], v[80:83]
	s_waitcnt lgkmcnt(1)
	v_mfma_f32_16x16x32_bf16 v[12:15], v[172:175], v[156:159], v[12:15]
	v_mfma_f32_16x16x32_bf16 v[72:75], v[164:167], v[156:159], v[72:75]
	global_load_dwordx4 v[104:107], v236, s[2:3] offset:1536
	ds_write_b128 v3, v[112:115] offset:53248
	v_mfma_f32_16x16x32_bf16 v[32:35], v[160:163], v[84:87], v[32:35]
	v_mfma_f32_16x16x32_bf16 v[44:47], v[164:167], v[84:87], v[44:47]
	v_mfma_f32_16x16x32_bf16 v[16:19], v[172:175], v[84:87], v[16:19]
	v_mfma_f32_16x16x32_bf16 v[76:79], v[168:171], v[84:87], v[76:79]
	global_load_dwordx4 v[84:87], v239, s[2:3] offset:1536
	s_waitcnt vmcnt(7)
	ds_write_b128 v3, v[68:71] offset:57344
	v_mfma_f32_16x16x32_bf16 v[36:39], v[160:163], v[100:103], v[36:39]
	v_mfma_f32_16x16x32_bf16 v[48:51], v[164:167], v[100:103], v[48:51]
	v_mfma_f32_16x16x32_bf16 v[60:63], v[168:171], v[100:103], v[60:63]
	v_mfma_f32_16x16x32_bf16 v[20:23], v[172:175], v[100:103], v[20:23]
	global_load_dwordx4 v[68:71], v240, s[2:3] offset:1536
	ds_write_b128 v3, v[88:91] offset:61440
	v_mfma_f32_16x16x32_bf16 v[40:43], v[160:163], v[124:127], v[40:43]
	v_mfma_f32_16x16x32_bf16 v[52:55], v[164:167], v[124:127], v[52:55]
	v_mfma_f32_16x16x32_bf16 v[56:59], v[168:171], v[124:127], v[56:59]
	v_mfma_f32_16x16x32_bf16 v[24:27], v[172:175], v[124:127], v[24:27]
	s_setprio 0
	s_waitcnt lgkmcnt(0)
	s_barrier
	ds_read_b128 v[88:91], v7 offset:32768
	ds_read_b128 v[100:103], v7 offset:34816
	ds_read_b128 v[112:115], v8 offset:49152
	ds_read_b128 v[116:119], v8 offset:51200
	ds_read_b128 v[124:127], v7 offset:36864
	ds_read_b128 v[132:135], v7 offset:38912
	ds_read_b128 v[136:139], v8 offset:53248
	ds_read_b128 v[148:151], v8 offset:55296
	s_setprio 2
	global_load_dwordx4 v[156:159], v241, s[0:1] offset:640
	s_waitcnt vmcnt(7)
	ds_write_b128 v3, v[152:155]
	ds_read_b128 v[152:155], v5 offset:32768
	ds_read_b128 v[160:163], v6 offset:49152
	s_waitcnt lgkmcnt(8)
	v_mfma_f32_16x16x32_bf16 v[28:31], v[112:115], v[88:91], v[28:31]
	s_waitcnt lgkmcnt(4)
	v_mfma_f32_16x16x32_bf16 v[80:83], v[136:139], v[88:91], v[80:83]
	s_waitcnt lgkmcnt(3)
	v_mfma_f32_16x16x32_bf16 v[12:15], v[148:151], v[88:91], v[12:15]
	v_mfma_f32_16x16x32_bf16 v[72:75], v[116:119], v[88:91], v[72:75]
	global_load_dwordx4 v[88:91], v242, s[0:1] offset:640
	ds_write_b128 v3, v[64:67] offset:4096
	ds_read_b128 v[64:67], v5 offset:34816
	ds_read_b128 v[164:167], v6 offset:51200
	v_mfma_f32_16x16x32_bf16 v[32:35], v[112:115], v[100:103], v[32:35]
	v_mfma_f32_16x16x32_bf16 v[44:47], v[116:119], v[100:103], v[44:47]
	v_mfma_f32_16x16x32_bf16 v[16:19], v[148:151], v[100:103], v[16:19]
	v_mfma_f32_16x16x32_bf16 v[76:79], v[136:139], v[100:103], v[76:79]
	global_load_dwordx4 v[100:103], v243, s[0:1] offset:640
	s_waitcnt vmcnt(7)
; template <int MODE>
; __device__ __forceinline__ void gemm_tile(const Params& P, int tm, int tn, unsigned char* smem) {
;     ...
;     for (int kt = 0; kt < 16; ++kt) {
;         unsigned char* sA = (kt & 1) ? sA1 : sA0; unsigned char* sB = (kt & 1) ? sB1 : sB0;
;         unsigned char* nA = (kt & 1) ? sA0 : sA1; unsigned char* nB = (kt & 1) ? sB0 : sB1;
;         bf16x8 fa[4], fb[4], ga[4], gb[4];
;         const int ch0 = ((g ^ sw) << 4), ch1 = (((4 + g) ^ sw) << 4);
;         const unsigned ko = (unsigned)(kt + 2) * 128u;
;         const unsigned koa = ko + ((MODE == 2 && kt + 2 >= 8) ? (unsigned)(ZC_FQ - 512) * 2u : 0u);
;         const bool wr_ok = kt < 15, ld_ok = kt < 14;
; #pragma unroll
;         for (int i = 0; i < 4; ++i) { fa[i] = *(const bf16x8*)(sA + arow_off + i * 2048 + ch0); fb[i] = *(const bf16x8*)(sB + brow_off + i * 2048 + ch0); }
;         __builtin_amdgcn_sched_barrier(0);
;         __builtin_amdgcn_s_setprio(2);
;         if (wr_ok) *(uint4*)(nA + soff0) = ra0;
;         if (ld_ok) ra0 = *(const uint4*)(Ab + (aoff + 0u * LDA + koa));
;         ga[0] = *(const bf16x8*)(sA + arow_off + 0 * 2048 + ch1); gb[0] = *(const bf16x8*)(sB + brow_off + 0 * 2048 + ch1);
;         __builtin_amdgcn_sched_barrier(0);
; #pragma unroll
;         for (int j = 0; j < 4; ++j) acc[0][j] = __builtin_amdgcn_mfma_f32_16x16x32_bf16(fb[j], fa[0], acc[0][j], 0, 0, 0);
;         __builtin_amdgcn_sched_barrier(0);
;         if (wr_ok) *(uint4*)(nA + soff0 + 4096) = ra1;
;         if (ld_ok) ra1 = *(const uint4*)(Ab + (aoff + 32u * LDA + koa));
;         ga[1] = *(const bf16x8*)(sA + arow_off + 1 * 2048 + ch1); gb[1] = *(const bf16x8*)(sB + brow_off + 1 * 2048 + ch1);
;         __builtin_amdgcn_sched_barrier(0);
; #pragma unroll
;         for (int j = 0; j < 4; ++j) acc[1][j] = __builtin_amdgcn_mfma_f32_16x16x32_bf16(fb[j], fa[1], acc[1][j], 0, 0, 0);
;         __builtin_amdgcn_sched_barrier(0);
;         if (wr_ok) *(uint4*)(nA + soff0 + 8192) = ra2;
;         if (ld_ok) ra2 = *(const uint4*)(Ab + (aoff + 64u * LDA + koa));
;         ga[2] = *(const bf16x8*)(sA + arow_off + 2 * 2048 + ch1); gb[2] = *(const bf16x8*)(sB + brow_off + 2 * 2048 + ch1);
;         __builtin_amdgcn_sched_barrier(0);
; #pragma unroll
;         for (int j = 0; j < 4; ++j) acc[2][j] = __builtin_amdgcn_mfma_f32_16x16x32_bf16(fb[j], fa[2], acc[2][j], 0, 0, 0);
	ds_write_b128 v3, v[92:95] offset:8192
	ds_read_b128 v[92:95], v5 offset:36864
	ds_read_b128 v[168:171], v6 offset:53248
	v_mfma_f32_16x16x32_bf16 v[36:39], v[112:115], v[124:127], v[36:39]
	v_mfma_f32_16x16x32_bf16 v[48:51], v[116:119], v[124:127], v[48:51]
	v_mfma_f32_16x16x32_bf16 v[60:63], v[136:139], v[124:127], v[60:63]
	v_mfma_f32_16x16x32_bf16 v[20:23], v[148:151], v[124:127], v[20:23]
	global_load_dwordx4 v[124:127], v244, s[0:1] offset:640
	ds_write_b128 v3, v[120:123] offset:12288
	ds_read_b128 v[120:123], v5 offset:38912
	ds_read_b128 v[172:175], v6 offset:55296
	v_mfma_f32_16x16x32_bf16 v[40:43], v[112:115], v[132:135], v[40:43]
	v_mfma_f32_16x16x32_bf16 v[52:55], v[116:119], v[132:135], v[52:55]
	v_mfma_f32_16x16x32_bf16 v[56:59], v[136:139], v[132:135], v[56:59]
	v_mfma_f32_16x16x32_bf16 v[24:27], v[148:151], v[132:135], v[24:27]
	global_load_dwordx4 v[112:115], v4, s[2:3] offset:1664
	s_waitcnt vmcnt(7)
	ds_write_b128 v3, v[108:111] offset:16384
	s_waitcnt lgkmcnt(10)
	v_mfma_f32_16x16x32_bf16 v[28:31], v[160:163], v[152:155], v[28:31]
	s_waitcnt lgkmcnt(4)
	v_mfma_f32_16x16x32_bf16 v[80:83], v[168:171], v[152:155], v[80:83]
	s_waitcnt lgkmcnt(1)
	v_mfma_f32_16x16x32_bf16 v[12:15], v[172:175], v[152:155], v[12:15]
	v_mfma_f32_16x16x32_bf16 v[72:75], v[164:167], v[152:155], v[72:75]
	global_load_dwordx4 v[108:111], v236, s[2:3] offset:1664
	ds_write_b128 v3, v[104:107] offset:20480
	v_mfma_f32_16x16x32_bf16 v[32:35], v[160:163], v[64:67], v[32:35]
	v_mfma_f32_16x16x32_bf16 v[44:47], v[164:167], v[64:67], v[44:47]
	v_mfma_f32_16x16x32_bf16 v[16:19], v[172:175], v[64:67], v[16:19]
	v_mfma_f32_16x16x32_bf16 v[76:79], v[168:171], v[64:67], v[76:79]
	global_load_dwordx4 v[64:67], v239, s[2:3] offset:1664
	s_waitcnt vmcnt(7)
	ds_write_b128 v3, v[84:87] offset:24576
	v_mfma_f32_16x16x32_bf16 v[36:39], v[160:163], v[92:95], v[36:39]
	v_mfma_f32_16x16x32_bf16 v[48:51], v[164:167], v[92:95], v[48:51]
	v_mfma_f32_16x16x32_bf16 v[60:63], v[168:171], v[92:95], v[60:63]
	v_mfma_f32_16x16x32_bf16 v[20:23], v[172:175], v[92:95], v[20:23]
	global_load_dwordx4 v[84:87], v240, s[2:3] offset:1664
	ds_write_b128 v3, v[68:71] offset:28672
	v_mfma_f32_16x16x32_bf16 v[40:43], v[160:163], v[120:123], v[40:43]
	v_mfma_f32_16x16x32_bf16 v[52:55], v[164:167], v[120:123], v[52:55]
	v_mfma_f32_16x16x32_bf16 v[56:59], v[168:171], v[120:123], v[56:59]
	v_mfma_f32_16x16x32_bf16 v[24:27], v[172:175], v[120:123], v[24:27]
	s_setprio 0
	s_waitcnt lgkmcnt(0)
	s_barrier
	ds_read_b128 v[68:71], v7
	ds_read_b128 v[92:95], v7 offset:2048
	ds_read_b128 v[104:107], v8 offset:16384
	ds_read_b128 v[116:119], v8 offset:18432
	ds_read_b128 v[120:123], v7 offset:4096
	ds_read_b128 v[132:135], v7 offset:6144
	ds_read_b128 v[136:139], v8 offset:20480
	ds_read_b128 v[148:151], v8 offset:22528
	s_setprio 2
	global_load_dwordx4 v[152:155], v241, s[0:1] offset:768
	s_waitcnt vmcnt(7)
	ds_write_b128 v3, v[156:159] offset:32768
	ds_read_b128 v[156:159], v5
	ds_read_b128 v[160:163], v6 offset:16384
	s_waitcnt lgkmcnt(8)
	v_mfma_f32_16x16x32_bf16 v[28:31], v[104:107], v[68:71], v[28:31]
	s_waitcnt lgkmcnt(4)
	v_mfma_f32_16x16x32_bf16 v[80:83], v[136:139], v[68:71], v[80:83]
	s_waitcnt lgkmcnt(3)
	v_mfma_f32_16x16x32_bf16 v[12:15], v[148:151], v[68:71], v[12:15]
	v_mfma_f32_16x16x32_bf16 v[72:75], v[116:119], v[68:71], v[72:75]
	global_load_dwordx4 v[68:71], v242, s[0:1] offset:768
	ds_write_b128 v3, v[88:91] offset:36864
	ds_read_b128 v[88:91], v5 offset:2048
	ds_read_b128 v[164:167], v6 offset:18432
	v_mfma_f32_16x16x32_bf16 v[32:35], v[104:107], v[92:95], v[32:35]
	v_mfma_f32_16x16x32_bf16 v[44:47], v[116:119], v[92:95], v[44:47]
	v_mfma_f32_16x16x32_bf16 v[16:19], v[148:151], v[92:95], v[16:19]
	v_mfma_f32_16x16x32_bf16 v[76:79], v[136:139], v[92:95], v[76:79]
	global_load_dwordx4 v[92:95], v243, s[0:1] offset:768
	s_waitcnt vmcnt(7)
	ds_write_b128 v3, v[100:103] offset:40960
	ds_read_b128 v[100:103], v5 offset:4096
	ds_read_b128 v[168:171], v6 offset:20480
	v_mfma_f32_16x16x32_bf16 v[36:39], v[104:107], v[120:123], v[36:39]
	v_mfma_f32_16x16x32_bf16 v[48:51], v[116:119], v[120:123], v[48:51]
	v_mfma_f32_16x16x32_bf16 v[60:63], v[136:139], v[120:123], v[60:63]
	v_mfma_f32_16x16x32_bf16 v[20:23], v[148:151], v[120:123], v[20:23]
	global_load_dwordx4 v[120:123], v244, s[0:1] offset:768
	ds_write_b128 v3, v[124:127] offset:45056
	ds_read_b128 v[124:127], v5 offset:6144
	ds_read_b128 v[172:175], v6 offset:22528
	v_mfma_f32_16x16x32_bf16 v[40:43], v[104:107], v[132:135], v[40:43]
	v_mfma_f32_16x16x32_bf16 v[52:55], v[116:119], v[132:135], v[52:55]
	v_mfma_f32_16x16x32_bf16 v[56:59], v[136:139], v[132:135], v[56:59]
	v_mfma_f32_16x16x32_bf16 v[24:27], v[148:151], v[132:135], v[24:27]
	global_load_dwordx4 v[104:107], v4, s[2:3] offset:1792
	s_waitcnt vmcnt(7)
	ds_write_b128 v3, v[112:115] offset:49152
	s_waitcnt lgkmcnt(10)
	v_mfma_f32_16x16x32_bf16 v[28:31], v[160:163], v[156:159], v[28:31]
	s_waitcnt lgkmcnt(4)
	v_mfma_f32_16x16x32_bf16 v[80:83], v[168:171], v[156:159], v[80:83]
	s_waitcnt lgkmcnt(1)
	v_mfma_f32_16x16x32_bf16 v[12:15], v[172:175], v[156:159], v[12:15]
	v_mfma_f32_16x16x32_bf16 v[72:75], v[164:167], v[156:159], v[72:75]
	global_load_dwordx4 v[112:115], v236, s[2:3] offset:1792
	ds_write_b128 v3, v[108:111] offset:53248
	v_mfma_f32_16x16x32_bf16 v[32:35], v[160:163], v[88:91], v[32:35]
	v_mfma_f32_16x16x32_bf16 v[44:47], v[164:167], v[88:91], v[44:47]
	v_mfma_f32_16x16x32_bf16 v[16:19], v[172:175], v[88:91], v[16:19]
	v_mfma_f32_16x16x32_bf16 v[76:79], v[168:171], v[88:91], v[76:79]
	global_load_dwordx4 v[88:91], v239, s[2:3] offset:1792
	s_waitcnt vmcnt(7)
	ds_write_b128 v3, v[64:67] offset:57344
	v_mfma_f32_16x16x32_bf16 v[36:39], v[160:163], v[100:103], v[36:39]
	v_mfma_f32_16x16x32_bf16 v[48:51], v[164:167], v[100:103], v[48:51]
	v_mfma_f32_16x16x32_bf16 v[60:63], v[168:171], v[100:103], v[60:63]
	v_mfma_f32_16x16x32_bf16 v[20:23], v[172:175], v[100:103], v[20:23]
	global_load_dwordx4 v[64:67], v240, s[2:3] offset:1792
	ds_write_b128 v3, v[84:87] offset:61440
	v_mfma_f32_16x16x32_bf16 v[40:43], v[160:163], v[124:127], v[40:43]
	v_mfma_f32_16x16x32_bf16 v[52:55], v[164:167], v[124:127], v[52:55]
	v_mfma_f32_16x16x32_bf16 v[56:59], v[168:171], v[124:127], v[56:59]
	v_mfma_f32_16x16x32_bf16 v[24:27], v[172:175], v[124:127], v[24:27]
	s_setprio 0
	s_waitcnt lgkmcnt(0)
	s_barrier
; template <int MODE>
; __device__ __forceinline__ void gemm_tile(const Params& P, int tm, int tn, unsigned char* smem) {
;     ...
;     for (int kt = 0; kt < 16; ++kt) {
;         unsigned char* sA = (kt & 1) ? sA1 : sA0; unsigned char* sB = (kt & 1) ? sB1 : sB0;
;         unsigned char* nA = (kt & 1) ? sA0 : sA1; unsigned char* nB = (kt & 1) ? sB0 : sB1;
;         bf16x8 fa[4], fb[4], ga[4], gb[4];
;         const int ch0 = ((g ^ sw) << 4), ch1 = (((4 + g) ^ sw) << 4);
;         const unsigned ko = (unsigned)(kt + 2) * 128u;
;         const unsigned koa = ko + ((MODE == 2 && kt + 2 >= 8) ? (unsigned)(ZC_FQ - 512) * 2u : 0u);
;         const bool wr_ok = kt < 15, ld_ok = kt < 14;
; #pragma unroll
;         for (int i = 0; i < 4; ++i) { fa[i] = *(const bf16x8*)(sA + arow_off + i * 2048 + ch0); fb[i] = *(const bf16x8*)(sB + brow_off + i * 2048 + ch0); }
;         __builtin_amdgcn_sched_barrier(0);
;         __builtin_amdgcn_s_setprio(2);
;         if (wr_ok) *(uint4*)(nA + soff0) = ra0;
;         if (ld_ok) ra0 = *(const uint4*)(Ab + (aoff + 0u * LDA + koa));
;         ga[0] = *(const bf16x8*)(sA + arow_off + 0 * 2048 + ch1); gb[0] = *(const bf16x8*)(sB + brow_off + 0 * 2048 + ch1);
;         __builtin_amdgcn_sched_barrier(0);
; #pragma unroll
;         for (int j = 0; j < 4; ++j) acc[0][j] = __builtin_amdgcn_mfma_f32_16x16x32_bf16(fb[j], fa[0], acc[0][j], 0, 0, 0);
;         __builtin_amdgcn_sched_barrier(0);
;         if (wr_ok) *(uint4*)(nA + soff0 + 4096) = ra1;
;         if (ld_ok) ra1 = *(const uint4*)(Ab + (aoff + 32u * LDA + koa));
;         ga[1] = *(const bf16x8*)(sA + arow_off + 1 * 2048 + ch1); gb[1] = *(const bf16x8*)(sB + brow_off + 1 * 2048 + ch1);
;         __builtin_amdgcn_sched_barrier(0);
; #pragma unroll
;         for (int j = 0; j < 4; ++j) acc[1][j] = __builtin_amdgcn_mfma_f32_16x16x32_bf16(fb[j], fa[1], acc[1][j], 0, 0, 0);
;         __builtin_amdgcn_sched_barrier(0);
;         if (wr_ok) *(uint4*)(nA + soff0 + 8192) = ra2;
;         if (ld_ok) ra2 = *(const uint4*)(Ab + (aoff + 64u * LDA + koa));
;         ga[2] = *(const bf16x8*)(sA + arow_off + 2 * 2048 + ch1); gb[2] = *(const bf16x8*)(sB + brow_off + 2 * 2048 + ch1);
;         __builtin_amdgcn_sched_barrier(0);
; #pragma unroll
;         for (int j = 0; j < 4; ++j) acc[2][j] = __builtin_amdgcn_mfma_f32_16x16x32_bf16(fb[j], fa[2], acc[2][j], 0, 0, 0);
	ds_read_b128 v[84:87], v7 offset:32768
	ds_read_b128 v[100:103], v7 offset:34816
	ds_read_b128 v[108:111], v8 offset:49152
	ds_read_b128 v[116:119], v8 offset:51200
	ds_read_b128 v[124:127], v7 offset:36864
	ds_read_b128 v[132:135], v7 offset:38912
	ds_read_b128 v[136:139], v8 offset:53248
	ds_read_b128 v[148:151], v8 offset:55296
	s_setprio 2
	global_load_dwordx4 v[156:159], v241, s[0:1] offset:896
	s_waitcnt vmcnt(7)
	ds_write_b128 v3, v[152:155]
	ds_read_b128 v[152:155], v5 offset:32768
	ds_read_b128 v[160:163], v6 offset:49152
	s_waitcnt lgkmcnt(8)
	v_mfma_f32_16x16x32_bf16 v[28:31], v[108:111], v[84:87], v[28:31]
	s_waitcnt lgkmcnt(4)
	v_mfma_f32_16x16x32_bf16 v[80:83], v[136:139], v[84:87], v[80:83]
	s_waitcnt lgkmcnt(3)
	v_mfma_f32_16x16x32_bf16 v[12:15], v[148:151], v[84:87], v[12:15]
	v_mfma_f32_16x16x32_bf16 v[72:75], v[116:119], v[84:87], v[72:75]
	global_load_dwordx4 v[84:87], v242, s[0:1] offset:896
	ds_write_b128 v3, v[68:71] offset:4096
	ds_read_b128 v[68:71], v5 offset:34816
	ds_read_b128 v[164:167], v6 offset:51200
	v_mfma_f32_16x16x32_bf16 v[32:35], v[108:111], v[100:103], v[32:35]
	v_mfma_f32_16x16x32_bf16 v[44:47], v[116:119], v[100:103], v[44:47]
	v_mfma_f32_16x16x32_bf16 v[16:19], v[148:151], v[100:103], v[16:19]
	v_mfma_f32_16x16x32_bf16 v[76:79], v[136:139], v[100:103], v[76:79]
	global_load_dwordx4 v[100:103], v243, s[0:1] offset:896
	s_waitcnt vmcnt(7)
	ds_write_b128 v3, v[92:95] offset:8192
	ds_read_b128 v[92:95], v5 offset:36864
	ds_read_b128 v[168:171], v6 offset:53248
	v_mfma_f32_16x16x32_bf16 v[36:39], v[108:111], v[124:127], v[36:39]
	v_mfma_f32_16x16x32_bf16 v[48:51], v[116:119], v[124:127], v[48:51]
	v_mfma_f32_16x16x32_bf16 v[60:63], v[136:139], v[124:127], v[60:63]
	v_mfma_f32_16x16x32_bf16 v[20:23], v[148:151], v[124:127], v[20:23]
	v_add_u32_e32 v9, 0xc5380, v9
	global_load_dwordx4 v[124:127], v9, s[0:1]
	ds_write_b128 v3, v[120:123] offset:12288
	ds_read_b128 v[120:123], v5 offset:38912
	ds_read_b128 v[172:175], v6 offset:55296
	v_mfma_f32_16x16x32_bf16 v[40:43], v[108:111], v[132:135], v[40:43]
	v_mfma_f32_16x16x32_bf16 v[52:55], v[116:119], v[132:135], v[52:55]
	v_mfma_f32_16x16x32_bf16 v[56:59], v[136:139], v[132:135], v[56:59]
	v_mfma_f32_16x16x32_bf16 v[24:27], v[148:151], v[132:135], v[24:27]
	global_load_dwordx4 v[108:111], v4, s[2:3] offset:1920
	s_waitcnt vmcnt(7)
	ds_write_b128 v3, v[104:107] offset:16384
	s_waitcnt lgkmcnt(10)
	v_mfma_f32_16x16x32_bf16 v[28:31], v[160:163], v[152:155], v[28:31]
	s_waitcnt lgkmcnt(4)
	v_mfma_f32_16x16x32_bf16 v[80:83], v[168:171], v[152:155], v[80:83]
	s_waitcnt lgkmcnt(1)
	v_mfma_f32_16x16x32_bf16 v[12:15], v[172:175], v[152:155], v[12:15]
	v_mfma_f32_16x16x32_bf16 v[72:75], v[164:167], v[152:155], v[72:75]
	global_load_dwordx4 v[104:107], v236, s[2:3] offset:1920
	ds_write_b128 v3, v[112:115] offset:20480
	v_mfma_f32_16x16x32_bf16 v[32:35], v[160:163], v[68:71], v[32:35]
	v_mfma_f32_16x16x32_bf16 v[44:47], v[164:167], v[68:71], v[44:47]
	v_mfma_f32_16x16x32_bf16 v[16:19], v[172:175], v[68:71], v[16:19]
	v_mfma_f32_16x16x32_bf16 v[76:79], v[168:171], v[68:71], v[76:79]
	global_load_dwordx4 v[68:71], v239, s[2:3] offset:1920
	s_waitcnt vmcnt(7)
	ds_write_b128 v3, v[88:91] offset:24576
	v_mfma_f32_16x16x32_bf16 v[36:39], v[160:163], v[92:95], v[36:39]
	v_mfma_f32_16x16x32_bf16 v[48:51], v[164:167], v[92:95], v[48:51]
	v_mfma_f32_16x16x32_bf16 v[60:63], v[168:171], v[92:95], v[60:63]
	v_mfma_f32_16x16x32_bf16 v[20:23], v[172:175], v[92:95], v[20:23]
	v_add_u32_e32 v4, 0x30780, v4
	global_load_dwordx4 v[88:91], v4, s[2:3]
	ds_write_b128 v3, v[64:67] offset:28672
	v_mfma_f32_16x16x32_bf16 v[40:43], v[160:163], v[120:123], v[40:43]
	v_mfma_f32_16x16x32_bf16 v[52:55], v[164:167], v[120:123], v[52:55]
	v_mfma_f32_16x16x32_bf16 v[56:59], v[168:171], v[120:123], v[56:59]
	v_mfma_f32_16x16x32_bf16 v[24:27], v[172:175], v[120:123], v[24:27]
	s_setprio 0
	s_waitcnt lgkmcnt(0)
	s_barrier
	ds_read_b128 v[64:67], v7
	ds_read_b128 v[92:95], v7 offset:2048
	ds_read_b128 v[112:115], v8 offset:16384
	ds_read_b128 v[116:119], v8 offset:18432
	ds_read_b128 v[120:123], v7 offset:4096
	ds_read_b128 v[132:135], v7 offset:6144
	ds_read_b128 v[136:139], v8 offset:20480
	ds_read_b128 v[148:151], v8 offset:22528
	s_setprio 2
	s_waitcnt vmcnt(7)
	ds_write_b128 v3, v[156:159] offset:32768
	ds_read_b128 v[152:155], v5
	ds_read_b128 v[156:159], v6 offset:16384
	s_waitcnt lgkmcnt(8)
	v_mfma_f32_16x16x32_bf16 v[28:31], v[112:115], v[64:67], v[28:31]
	s_waitcnt lgkmcnt(4)
	v_mfma_f32_16x16x32_bf16 v[80:83], v[136:139], v[64:67], v[80:83]
	s_waitcnt lgkmcnt(3)
	v_mfma_f32_16x16x32_bf16 v[12:15], v[148:151], v[64:67], v[12:15]
	v_mfma_f32_16x16x32_bf16 v[72:75], v[116:119], v[64:67], v[72:75]
	s_waitcnt vmcnt(6)
	ds_write_b128 v3, v[84:87] offset:36864
	ds_read_b128 v[64:67], v5 offset:2048
	ds_read_b128 v[84:87], v6 offset:18432
	v_mfma_f32_16x16x32_bf16 v[32:35], v[112:115], v[92:95], v[32:35]
	v_mfma_f32_16x16x32_bf16 v[44:47], v[116:119], v[92:95], v[44:47]
	v_mfma_f32_16x16x32_bf16 v[16:19], v[148:151], v[92:95], v[16:19]
	v_mfma_f32_16x16x32_bf16 v[76:79], v[136:139], v[92:95], v[76:79]
	s_waitcnt vmcnt(5)
	ds_write_b128 v3, v[100:103] offset:40960
	ds_read_b128 v[92:95], v5 offset:4096
	ds_read_b128 v[100:103], v6 offset:20480
	v_mfma_f32_16x16x32_bf16 v[36:39], v[112:115], v[120:123], v[36:39]
	v_mfma_f32_16x16x32_bf16 v[48:51], v[116:119], v[120:123], v[48:51]
	v_mfma_f32_16x16x32_bf16 v[60:63], v[136:139], v[120:123], v[60:63]
	v_mfma_f32_16x16x32_bf16 v[20:23], v[148:151], v[120:123], v[20:23]
	s_waitcnt vmcnt(4)
; template <int MODE>
; __device__ __forceinline__ void gemm_tile(const Params& P, int tm, int tn, unsigned char* smem) {
;     ...
;     for (int kt = 0; kt < 16; ++kt) {
;         unsigned char* sA = (kt & 1) ? sA1 : sA0; unsigned char* sB = (kt & 1) ? sB1 : sB0;
;         unsigned char* nA = (kt & 1) ? sA0 : sA1; unsigned char* nB = (kt & 1) ? sB0 : sB1;
;         bf16x8 fa[4], fb[4], ga[4], gb[4];
;         const int ch0 = ((g ^ sw) << 4), ch1 = (((4 + g) ^ sw) << 4);
;         const unsigned ko = (unsigned)(kt + 2) * 128u;
;         const unsigned koa = ko + ((MODE == 2 && kt + 2 >= 8) ? (unsigned)(ZC_FQ - 512) * 2u : 0u);
;         const bool wr_ok = kt < 15, ld_ok = kt < 14;
; #pragma unroll
;         for (int i = 0; i < 4; ++i) { fa[i] = *(const bf16x8*)(sA + arow_off + i * 2048 + ch0); fb[i] = *(const bf16x8*)(sB + brow_off + i * 2048 + ch0); }
;         __builtin_amdgcn_sched_barrier(0);
;         __builtin_amdgcn_s_setprio(2);
;         if (wr_ok) *(uint4*)(nA + soff0) = ra0;
;         if (ld_ok) ra0 = *(const uint4*)(Ab + (aoff + 0u * LDA + koa));
;         ga[0] = *(const bf16x8*)(sA + arow_off + 0 * 2048 + ch1); gb[0] = *(const bf16x8*)(sB + brow_off + 0 * 2048 + ch1);
;         __builtin_amdgcn_sched_barrier(0);
; #pragma unroll
;         for (int j = 0; j < 4; ++j) acc[0][j] = __builtin_amdgcn_mfma_f32_16x16x32_bf16(fb[j], fa[0], acc[0][j], 0, 0, 0);
;         __builtin_amdgcn_sched_barrier(0);
;         if (wr_ok) *(uint4*)(nA + soff0 + 4096) = ra1;
;         if (ld_ok) ra1 = *(const uint4*)(Ab + (aoff + 32u * LDA + koa));
;         ga[1] = *(const bf16x8*)(sA + arow_off + 1 * 2048 + ch1); gb[1] = *(const bf16x8*)(sB + brow_off + 1 * 2048 + ch1);
;         __builtin_amdgcn_sched_barrier(0);
; #pragma unroll
;         for (int j = 0; j < 4; ++j) acc[1][j] = __builtin_amdgcn_mfma_f32_16x16x32_bf16(fb[j], fa[1], acc[1][j], 0, 0, 0);
;         __builtin_amdgcn_sched_barrier(0);
;         if (wr_ok) *(uint4*)(nA + soff0 + 8192) = ra2;
;         if (ld_ok) ra2 = *(const uint4*)(Ab + (aoff + 64u * LDA + koa));
;         ga[2] = *(const bf16x8*)(sA + arow_off + 2 * 2048 + ch1); gb[2] = *(const bf16x8*)(sB + brow_off + 2 * 2048 + ch1);
;         __builtin_amdgcn_sched_barrier(0);
; #pragma unroll
;         for (int j = 0; j < 4; ++j) acc[2][j] = __builtin_amdgcn_mfma_f32_16x16x32_bf16(fb[j], fa[2], acc[2][j], 0, 0, 0);
	ds_write_b128 v3, v[124:127] offset:45056
	ds_read_b128 v[120:123], v5 offset:6144
	ds_read_b128 v[124:127], v6 offset:22528
	v_mfma_f32_16x16x32_bf16 v[40:43], v[112:115], v[132:135], v[40:43]
	v_mfma_f32_16x16x32_bf16 v[52:55], v[116:119], v[132:135], v[52:55]
	v_mfma_f32_16x16x32_bf16 v[56:59], v[136:139], v[132:135], v[56:59]
	v_mfma_f32_16x16x32_bf16 v[24:27], v[148:151], v[132:135], v[24:27]
	s_waitcnt vmcnt(3)
	ds_write_b128 v3, v[108:111] offset:49152
	s_waitcnt lgkmcnt(10)
	v_mfma_f32_16x16x32_bf16 v[28:31], v[156:159], v[152:155], v[28:31]
	s_waitcnt lgkmcnt(4)
	v_mfma_f32_16x16x32_bf16 v[80:83], v[100:103], v[152:155], v[80:83]
	s_waitcnt lgkmcnt(1)
	v_mfma_f32_16x16x32_bf16 v[12:15], v[124:127], v[152:155], v[12:15]
	v_mfma_f32_16x16x32_bf16 v[72:75], v[84:87], v[152:155], v[72:75]
	s_waitcnt vmcnt(2)
	ds_write_b128 v3, v[104:107] offset:53248
	v_mfma_f32_16x16x32_bf16 v[32:35], v[156:159], v[64:67], v[32:35]
	v_mfma_f32_16x16x32_bf16 v[44:47], v[84:87], v[64:67], v[44:47]
	v_mfma_f32_16x16x32_bf16 v[16:19], v[124:127], v[64:67], v[16:19]
	v_mfma_f32_16x16x32_bf16 v[76:79], v[100:103], v[64:67], v[76:79]
	s_waitcnt vmcnt(1)
	ds_write_b128 v3, v[68:71] offset:57344
	v_mfma_f32_16x16x32_bf16 v[36:39], v[156:159], v[92:95], v[36:39]
	v_mfma_f32_16x16x32_bf16 v[48:51], v[84:87], v[92:95], v[48:51]
	v_mfma_f32_16x16x32_bf16 v[60:63], v[100:103], v[92:95], v[60:63]
	v_mfma_f32_16x16x32_bf16 v[20:23], v[124:127], v[92:95], v[20:23]
	s_waitcnt vmcnt(0)
	ds_write_b128 v3, v[88:91] offset:61440
	v_mfma_f32_16x16x32_bf16 v[40:43], v[156:159], v[120:123], v[40:43]
	v_mfma_f32_16x16x32_bf16 v[52:55], v[84:87], v[120:123], v[52:55]
	v_mfma_f32_16x16x32_bf16 v[56:59], v[100:103], v[120:123], v[56:59]
	v_mfma_f32_16x16x32_bf16 v[24:27], v[124:127], v[120:123], v[24:27]
	s_setprio 0
	s_waitcnt lgkmcnt(0)
	s_barrier
	ds_read_b128 v[64:67], v7 offset:32768
	ds_read_b128 v[68:71], v7 offset:34816
	ds_read_b128 v[84:87], v8 offset:49152
	ds_read_b128 v[88:91], v8 offset:51200
	ds_read_b128 v[92:95], v7 offset:36864
	ds_read_b128 v[100:103], v7 offset:38912
	ds_read_b128 v[104:107], v8 offset:53248
	ds_read_b128 v[108:111], v8 offset:55296
	s_setprio 2
	ds_read_b128 v[112:115], v5 offset:32768
	ds_read_b128 v[116:119], v6 offset:49152
	s_waitcnt lgkmcnt(7)
	v_mfma_f32_16x16x32_bf16 v[28:31], v[84:87], v[64:67], v[28:31]
	s_waitcnt lgkmcnt(3)
	v_mfma_f32_16x16x32_bf16 v[80:83], v[104:107], v[64:67], v[80:83]
	s_waitcnt lgkmcnt(2)
	v_mfma_f32_16x16x32_bf16 v[12:15], v[108:111], v[64:67], v[12:15]
	v_mfma_f32_16x16x32_bf16 v[72:75], v[88:91], v[64:67], v[72:75]
	ds_read_b128 v[64:67], v5 offset:34816
	ds_read_b128 v[120:123], v6 offset:51200
	v_mfma_f32_16x16x32_bf16 v[32:35], v[84:87], v[68:71], v[32:35]
	v_mfma_f32_16x16x32_bf16 v[44:47], v[88:91], v[68:71], v[44:47]
	v_mfma_f32_16x16x32_bf16 v[16:19], v[108:111], v[68:71], v[16:19]
	v_mfma_f32_16x16x32_bf16 v[76:79], v[104:107], v[68:71], v[76:79]
	ds_read_b128 v[124:127], v5 offset:36864
	ds_read_b128 v[132:135], v6 offset:53248
	v_mfma_f32_16x16x32_bf16 v[36:39], v[84:87], v[92:95], v[36:39]
	v_mfma_f32_16x16x32_bf16 v[48:51], v[88:91], v[92:95], v[48:51]
	v_mfma_f32_16x16x32_bf16 v[20:23], v[108:111], v[92:95], v[20:23]
	v_mfma_f32_16x16x32_bf16 v[136:139], v[104:107], v[92:95], v[60:63]
	ds_read_b128 v[148:151], v5 offset:38912
	ds_read_b128 v[4:7], v6 offset:55296
	v_mfma_f32_16x16x32_bf16 v[40:43], v[84:87], v[100:103], v[40:43]
	v_mfma_f32_16x16x32_bf16 v[152:155], v[88:91], v[100:103], v[52:55]
	v_mfma_f32_16x16x32_bf16 v[104:107], v[104:107], v[100:103], v[56:59]
	v_mfma_f32_16x16x32_bf16 v[100:103], v[108:111], v[100:103], v[24:27]
	s_waitcnt lgkmcnt(6)
	v_mfma_f32_16x16x32_bf16 v[108:111], v[116:119], v[112:115], v[28:31]
	s_waitcnt lgkmcnt(4)
	v_mfma_f32_16x16x32_bf16 v[70:73], v[120:123], v[112:115], v[72:75]
	s_waitcnt lgkmcnt(2)
	v_mfma_f32_16x16x32_bf16 v[156:159], v[132:135], v[112:115], v[80:83]
	s_waitcnt lgkmcnt(0)
	v_mfma_f32_16x16x32_bf16 v[160:163], v[4:7], v[112:115], v[12:15]
	v_mfma_f32_16x16x32_bf16 v[94:97], v[116:119], v[64:67], v[32:35]
	v_mfma_f32_16x16x32_bf16 v[90:93], v[120:123], v[64:67], v[44:47]
	v_mfma_f32_16x16x32_bf16 v[86:89], v[132:135], v[64:67], v[76:79]
	v_mfma_f32_16x16x32_bf16 v[82:85], v[4:7], v[64:67], v[16:19]
	v_mfma_f32_16x16x32_bf16 v[66:69], v[116:119], v[124:127], v[36:39]
	v_mfma_f32_16x16x32_bf16 v[62:65], v[120:123], v[124:127], v[48:51]
	v_mfma_f32_16x16x32_bf16 v[58:61], v[132:135], v[124:127], v[136:139]
	v_mfma_f32_16x16x32_bf16 v[54:57], v[4:7], v[124:127], v[20:23]
	v_mfma_f32_16x16x32_bf16 v[26:29], v[116:119], v[148:151], v[40:43]
	v_mfma_f32_16x16x32_bf16 v[22:25], v[120:123], v[148:151], v[152:155]
	v_mfma_f32_16x16x32_bf16 v[18:21], v[132:135], v[148:151], v[104:107]
	v_mfma_f32_16x16x32_bf16 v[14:17], v[4:7], v[148:151], v[100:103]
	s_setprio 0
	v_add_u32_e32 v10, s15, v10
	s_lshl_b32 s4, s4, 3
	v_or_b32_e32 v120, v10, v143
	v_lshlrev_b32_e32 v3, 2, v146
	s_add_u32 s4, s7, s4
	v_ashrrev_i32_e32 v121, 31, v120
	v_or3_b32 v2, v3, v2, s18
	s_addc_u32 s5, s8, 0
	v_lshlrev_b32_e32 v98, 2, v144
	v_lshlrev_b64 v[10:11], 12, v[120:121]
	v_lshl_add_u64 v[100:101], s[4:5], 0, v[98:99]
	v_lshlrev_b32_e32 v98, 2, v2
	v_lshl_add_u64 v[30:31], s[52:53], 0, v[10:11]
	s_barrier
; template <int MODE>
; __device__ __forceinline__ void gemm_tile(const Params& P, int tm, int tn, unsigned char* smem) {
;     ...
;     } else if (MODE == 2) {
;         float* ssq = (float*)(P.ws + WS_SSQ);
; #pragma unroll
;         for (int i = 0; i < 4; ++i) {
;             const int row = m0 + wr * 64 + 16 * i + lr;
;             float ss = 0.f;
; #pragma unroll
;             for (int j = 0; j < 4; ++j) {
;                 const int col = n0 + wc * 64 + 16 * j + 4 * g;
;                 const float4 xv = *(const float4*)(P.x + (size_t)row * DM + col);
;                 const float4 gv = *(const float4*)(P.norm_ffn + col);
;                 float4 hv; hv.x = acc[i][j][0] + xv.x; hv.y = acc[i][j][1] + xv.y; hv.z = acc[i][j][2] + xv.z; hv.w = acc[i][j][3] + xv.w;
;                 ss += hv.x * hv.x + hv.y * hv.y + hv.z * hv.z + hv.w * hv.w;
;                 acc[i][j][0] = hv.x * gv.x; acc[i][j][1] = hv.y * gv.y; acc[i][j][2] = hv.z * gv.z; acc[i][j][3] = hv.w * gv.w;
;             }
;             ss = x4_sum(ss);
;             if (g == 0) ssq[(size_t)row * 16 + tn * 2 + wc] = ss;
;         }
;         store_tile_bf16(acc, smem, (bf16_t*)(P.ws + WS_XN), 1024, m0, n0, tid, wr, wc, g, lr);
	global_load_dwordx4 v[6:9], v98, s[44:45] offset:64
	global_load_dwordx4 v[2:5], v98, s[44:45]
	global_load_dwordx4 v[10:13], v98, s[44:45] offset:128
	v_lshl_add_u64 v[34:35], v[30:31], 0, v[98:99]
	global_load_dwordx4 v[30:33], v98, s[44:45] offset:192
	global_load_dwordx4 v[74:77], v[34:35], off
	global_load_dwordx4 v[78:81], v[34:35], off offset:64
	global_load_dwordx4 v[112:115], v[34:35], off offset:128
	global_load_dwordx4 v[124:127], v[34:35], off offset:192
	v_cmp_eq_u32_e32 vcc, 0, v146
	v_lshl_add_u64 v[122:123], s[44:45], 0, v[98:99]
	s_waitcnt vmcnt(4)
	v_mov_b64_e32 v[48:49], v[32:33]
	s_waitcnt vmcnt(3)
	v_pk_add_f32 v[102:103], v[108:109], v[74:75]
	s_waitcnt vmcnt(2)
	v_pk_add_f32 v[106:107], v[70:71], v[78:79]
	v_pk_add_f32 v[104:105], v[110:111], v[76:77]
	s_waitcnt vmcnt(1)
	v_pk_add_f32 v[110:111], v[156:157], v[112:113]
	v_mul_f32_e32 v46, v103, v103
	v_mul_f32_e32 v52, v107, v107
	v_pk_add_f32 v[108:109], v[72:73], v[80:81]
	v_pk_add_f32 v[112:113], v[158:159], v[114:115]
	s_waitcnt vmcnt(0)
	v_pk_add_f32 v[114:115], v[160:161], v[124:125]
	v_mul_f32_e32 v72, v111, v111
	v_pk_fma_f32 v[46:47], v[102:103], v[102:103], v[46:47] op_sel_hi:[1,1,0]
	v_pk_fma_f32 v[52:53], v[106:107], v[106:107], v[52:53] op_sel_hi:[1,1,0]
	v_mov_b32_e32 v51, v7
	v_mul_f32_e32 v50, v105, v105
	v_mul_f32_e32 v70, v109, v109
	v_mul_f32_e32 v76, v115, v115
	v_pk_fma_f32 v[72:73], v[110:111], v[110:111], v[72:73] op_sel_hi:[1,1,0]
	v_pk_fma_f32 v[46:47], v[104:105], v[104:105], v[46:47]
	v_pk_fma_f32 v[52:53], v[108:109], v[108:109], v[52:53]
	v_pk_add_f32 v[116:117], v[162:163], v[126:127]
	v_mul_f32_e32 v74, v113, v113
	v_pk_fma_f32 v[76:77], v[114:115], v[114:115], v[76:77] op_sel_hi:[1,1,0]
	v_pk_fma_f32 v[72:73], v[112:113], v[112:113], v[72:73]
	v_pk_add_f32 v[46:47], v[50:51], v[46:47] op_sel_hi:[0,1]
	v_pk_add_f32 v[52:53], v[70:71], v[52:53] op_sel_hi:[0,1]
	v_mul_f32_e32 v78, v117, v117
	v_pk_fma_f32 v[76:77], v[116:117], v[116:117], v[76:77]
	v_pk_add_f32 v[70:71], v[74:75], v[72:73] op_sel_hi:[0,1]
	v_pk_add_f32 v[46:47], v[46:47], v[52:53]
	v_pk_add_f32 v[72:73], v[78:79], v[76:77] op_sel_hi:[0,1]
	v_pk_add_f32 v[46:47], v[46:47], v[70:71]
	v_mov_b32_e32 v34, v6
	v_pk_add_f32 v[46:47], v[46:47], v[72:73]
	v_mov_b32_e32 v40, v4
	v_mov_b32_e32 v41, v46
	s_nop 1
	v_permlane32_swap_b32_e32 v46, v41
	v_add_f32_e32 v41, v46, v41
	v_mov_b32_e32 v50, v41
	v_mov_b64_e32 v[118:119], v[4:5]
	v_mov_b64_e32 v[38:39], v[2:3]
	v_mov_b32_e32 v35, v7
	v_mov_b64_e32 v[36:37], v[8:9]
	v_mov_b64_e32 v[44:45], v[12:13]
	v_mov_b64_e32 v[42:43], v[10:11]
	v_permlane16_swap_b32_e32 v41, v50
	v_mov_b64_e32 v[46:47], v[30:31]
	s_and_saveexec_b64 s[4:5], vcc
	s_cbranch_execz .LBB0_1156
	v_lshlrev_b64 v[34:35], 6, v[120:121]
	v_lshl_add_u64 v[34:35], v[100:101], 0, v[34:35]
	v_add_f32_e32 v36, v41, v50
	global_store_dword v[34:35], v36, off
	global_load_dwordx4 v[34:37], v[122:123], off offset:64
	s_nop 0
	global_load_dwordx4 v[38:41], v[122:123], off
	global_load_dwordx4 v[42:45], v[122:123], off offset:128
	global_load_dwordx4 v[46:49], v[122:123], off offset:192
	s_waitcnt vmcnt(3)
	v_mov_b32_e32 v51, v35
	s_waitcnt vmcnt(2)
	v_mov_b64_e32 v[118:119], v[40:41]

; template <int MODE>
; __device__ __forceinline__ void gemm_tile(const Params& P, int tm, int tn, unsigned char* smem) {
;     ...
;     const int tid = opaque_tid(), lane = tid & 63, wave = tid >> 6, wr = wave >> 1, wc = wave & 1, g = lane >> 4, lr = lane & 15;
;     const int m0 = tm * 128, n0 = tn * 128;
;     const int srow = tid >> 3, sc = tid & 7;
;     constexpr unsigned LDA = (MODE == 2 ? NZ : 1024) * 2u;
;     unsigned aoff, boff; int soff0;
;     {
;         int ar = m0 + srow;
;         if (MODE == 2) { const int b = ar >> 11, t = ar & 2047; ar = b * L + NMETA + t; }
;         aoff = (unsigned)ar * LDA + (unsigned)sc * 16u;
;         boff = (unsigned)(n0 + srow) * 2048u + (unsigned)sc * 16u;
;         soff0 = srow * 128 + ((sc ^ (srow & 7)) << 4);
;     }
;     const unsigned char* Ab = (const unsigned char*)A; const unsigned char* Bb = (const unsigned char*)Bt;
;     float4 ssp0, ssp1, ssp2, ssp3;
;     if (MODE == 3) {
;         const float* ssq = (const float*)(P.ws + WS_SSQ) + (size_t)(m0 + wr * 64 + lr) * 16 + 4 * g;
;         ssp0 = *(const float4*)(ssq); ssp1 = *(const float4*)(ssq + 16 * 16); ssp2 = *(const float4*)(ssq + 32 * 16); ssp3 = *(const float4*)(ssq + 48 * 16);
;     }
;     f32x4 acc[4][4];
; #pragma unroll
;     for (int i = 0; i < 4; ++i)
; #pragma unroll
;         for (int j = 0; j < 4; ++j) acc[i][j] = (f32x4){0.f, 0.f, 0.f, 0.f};
;     uint4 ra0, ra1, ra2, ra3, rb0, rb1, rb2, rb3;
;     ...
;     unsigned char* sA0 = smem; unsigned char* sB0 = smem + 16384; unsigned char* sA1 = smem + 32768; unsigned char* sB1 = smem + 49152;
;     G_LOAD(0)
;     G_WRITE(sA0, sB0)
;     __syncthreads();
;     const int arow_off = (wr * 64 + lr) * 128, brow_off = (wc * 64 + lr) * 128, sw = lr & 7;
;     G_LOAD(1)
;     for (int kt = 0; kt < 16; ++kt) {
;         unsigned char* sA = (kt & 1) ? sA1 : sA0; unsigned char* sB = (kt & 1) ? sB1 : sB0;
;         unsigned char* nA = (kt & 1) ? sA0 : sA1; unsigned char* nB = (kt & 1) ? sB0 : sB1;
;         bf16x8 fa[4], fb[4], ga[4], gb[4];
;         const int ch0 = ((g ^ sw) << 4), ch1 = (((4 + g) ^ sw) << 4);
;         const unsigned ko = (unsigned)(kt + 2) * 128u;
;         const unsigned koa = ko + ((MODE == 2 && kt + 2 >= 8) ? (unsigned)(ZC_FQ - 512) * 2u : 0u);
;         const bool wr_ok = kt < 15, ld_ok = kt < 14;
; #pragma unroll
.LBB0_1263:
	s_lshr_b32 s0, s14, 4
	s_and_b32 s0, s0, 0x1fffff8
	s_and_b32 s1, s14, 7
	s_or_b32 s0, s0, s1
	v_mov_b32_e32 v88, v0
	s_bfe_u32 s2, s14, 0x40003
	s_lshl_b32 s23, s0, 7
	v_ashrrev_i32_e32 v6, 3, v88
	v_lshlrev_b32_e32 v3, 4, v88
	v_add_u32_e32 v2, s23, v6
	v_and_b32_e32 v3, 0x70, v3
	s_lshl_b32 s0, s2, 18
	v_lshl_add_u32 v4, v6, 11, s0
	v_lshl_or_b32 v24, v2, 11, v3
	v_or_b32_e32 v18, v4, v3
	v_add_u32_e32 v2, 0x10000, v24
	v_add_u32_e32 v3, 0x20000, v24
	global_load_dwordx4 v[20:23], v2, s[36:37]
	global_load_dwordx4 v[26:29], v3, s[36:37]
	v_add_u32_e32 v2, 0x20000, v18
	v_add_u32_e32 v3, 0x30000, v18
	global_load_dwordx4 v[30:33], v2, s[6:7]
	global_load_dwordx4 v[34:37], v3, s[6:7]
	v_add_u32_e32 v2, 0x30000, v24
	v_add_u32_e32 v3, 0x10000, v18
	global_load_dwordx4 v[38:41], v2, s[36:37]
	global_load_dwordx4 v[42:45], v3, s[6:7]
	global_load_dwordx4 v[46:49], v24, s[36:37]
	global_load_dwordx4 v[50:53], v18, s[6:7]
	v_ashrrev_i32_e32 v2, 1, v88
	v_and_b32_e32 v25, 0xffffffc0, v2
	v_and_b32_e32 v90, 15, v88
	v_add_u32_e32 v2, s23, v25
	v_or_b32_e32 v84, v2, v90
	v_ashrrev_i32_e32 v85, 31, v84
	v_xor_b32_e32 v7, v6, v88
	v_bfe_u32 v89, v88, 4, 2
	v_lshlrev_b64 v[2:3], 6, v[84:85]
	v_lshlrev_b32_e32 v6, 7, v6
	v_lshlrev_b32_e32 v7, 4, v7
	v_lshlrev_b32_e32 v82, 4, v89
	v_lshl_add_u64 v[2:3], s[4:5], 0, v[2:3]
	v_and_or_b32 v6, v7, s15, v6
	v_lshl_add_u64 v[54:55], v[2:3], 0, v[82:83]
	v_add_u32_e32 v19, 0, v6
	v_or_b32_e32 v62, 0x80, v24
	global_load_dwordx4 v[10:13], v[54:55], off
	global_load_dwordx4 v[2:5], v[54:55], off offset:3072
	v_or_b32_e32 v58, 0x80, v18
	v_add_u32_e32 v59, 0x10080, v18
	v_add_u32_e32 v60, 0x20080, v18
	v_add_u32_e32 v61, 0x30080, v18
	v_add_u32_e32 v63, 0x10080, v24
	v_add_u32_e32 v64, 0x20080, v24
	v_add_u32_e32 v65, 0x30080, v24
	global_load_dwordx4 v[14:17], v[54:55], off offset:1024
	global_load_dwordx4 v[6:9], v[54:55], off offset:2048
	v_or_b32_e32 v82, v25, v90
	v_and_b32_e32 v25, 7, v88
	v_bfe_u32 v91, v88, 6, 1
	v_lshl_add_u32 v104, v82, 7, 0
	s_waitcnt vmcnt(9)
	ds_write_b128 v19, v[30:33] offset:24576
	s_waitcnt vmcnt(8)
	ds_write_b128 v19, v[34:37] offset:28672
	ds_write_b128 v19, v[20:23] offset:4096
	ds_write_b128 v19, v[26:29] offset:8192
	s_waitcnt vmcnt(7)
	ds_write_b128 v19, v[38:41] offset:12288
	s_waitcnt vmcnt(6)
	ds_write_b128 v19, v[42:45] offset:20480
	s_waitcnt vmcnt(5)
	ds_write_b128 v19, v[46:49]
	s_waitcnt vmcnt(4)
	ds_write_b128 v19, v[50:53] offset:16384
	s_waitcnt lgkmcnt(0)
	s_barrier
	global_load_dwordx4 v[26:29], v62, s[36:37]
	global_load_dwordx4 v[30:33], v63, s[36:37]
	global_load_dwordx4 v[34:37], v64, s[36:37]
	global_load_dwordx4 v[38:41], v65, s[36:37]
	global_load_dwordx4 v[42:45], v58, s[6:7]
	global_load_dwordx4 v[46:49], v59, s[6:7]
	global_load_dwordx4 v[50:53], v60, s[6:7]
	global_load_dwordx4 v[54:57], v61, s[6:7]
	v_lshrrev_b32_e32 v20, 4, v88
	v_lshlrev_b32_e32 v21, 7, v90
	v_bitop3_b32 v20, v20, v25, 3 bitop3:0x6c
	v_lshl_or_b32 v21, v91, 13, v21
	v_lshlrev_b32_e32 v20, 4, v20
	v_add_u32_e32 v22, v104, v20
	v_add_u32_e32 v21, 0, v21
	v_add_u32_e32 v23, v21, v20
	ds_read_b128 v[58:61], v22
	ds_read_b128 v[62:65], v22 offset:2048
	ds_read_b128 v[66:69], v23 offset:16384
	ds_read_b128 v[70:73], v23 offset:18432
	ds_read_b128 v[74:77], v22 offset:4096
	ds_read_b128 v[78:81], v22 offset:6144
	ds_read_b128 v[92:95], v23 offset:20480
	ds_read_b128 v[96:99], v23 offset:22528
	v_bitop3_b32 v20, v89, v25, 4 bitop3:0x36
	v_lshlrev_b32_e32 v25, 4, v20
	s_setprio 2
	global_load_dwordx4 v[100:103], v24, s[36:37] offset:256
	s_waitcnt vmcnt(7)
	ds_write_b128 v19, v[26:29] offset:32768
	v_add_u32_e32 v20, v104, v25
	v_add_u32_e32 v21, v21, v25
	ds_read_b128 v[26:29], v20
	ds_read_b128 v[104:107], v21 offset:16384
	s_waitcnt lgkmcnt(8)
	v_mfma_f32_16x16x32_bf16 v[108:111], v[66:69], v[58:61], 0
	s_waitcnt lgkmcnt(7)
	v_mfma_f32_16x16x32_bf16 v[112:115], v[70:73], v[58:61], 0
	s_waitcnt lgkmcnt(4)
	v_mfma_f32_16x16x32_bf16 v[116:119], v[92:95], v[58:61], 0
	s_waitcnt lgkmcnt(3)
	v_mfma_f32_16x16x32_bf16 v[58:61], v[96:99], v[58:61], 0
	v_add_u32_e32 v245, 0x10000, v24
	global_load_dwordx4 v[120:123], v245, s[36:37] offset:256
	ds_write_b128 v19, v[30:33] offset:36864
	ds_read_b128 v[30:33], v20 offset:2048
	ds_read_b128 v[124:127], v21 offset:18432
	v_mfma_f32_16x16x32_bf16 v[132:135], v[66:69], v[62:65], 0
	v_mfma_f32_16x16x32_bf16 v[136:139], v[70:73], v[62:65], 0
	v_mfma_f32_16x16x32_bf16 v[140:143], v[92:95], v[62:65], 0
	v_mfma_f32_16x16x32_bf16 v[62:65], v[96:99], v[62:65], 0
	v_add_u32_e32 v246, 0x20000, v24
	global_load_dwordx4 v[144:147], v246, s[36:37] offset:256
	s_waitcnt vmcnt(7)
	ds_write_b128 v19, v[34:37] offset:40960
	ds_read_b128 v[34:37], v20 offset:4096
	ds_read_b128 v[148:151], v21 offset:20480
	v_mfma_f32_16x16x32_bf16 v[152:155], v[66:69], v[74:77], 0
	v_mfma_f32_16x16x32_bf16 v[156:159], v[70:73], v[74:77], 0
	v_mfma_f32_16x16x32_bf16 v[160:163], v[92:95], v[74:77], 0
	v_mfma_f32_16x16x32_bf16 v[74:77], v[96:99], v[74:77], 0
	v_add_u32_e32 v247, 0x30000, v24
	global_load_dwordx4 v[164:167], v247, s[36:37] offset:256
	ds_write_b128 v19, v[38:41] offset:45056
	ds_read_b128 v[38:41], v20 offset:6144
	ds_read_b128 v[168:171], v21 offset:22528
	v_mfma_f32_16x16x32_bf16 v[66:69], v[66:69], v[78:81], 0
	v_mfma_f32_16x16x32_bf16 v[70:73], v[70:73], v[78:81], 0
	v_mfma_f32_16x16x32_bf16 v[92:95], v[92:95], v[78:81], 0
	v_mfma_f32_16x16x32_bf16 v[78:81], v[96:99], v[78:81], 0
	global_load_dwordx4 v[96:99], v18, s[6:7] offset:256
	s_waitcnt vmcnt(7)
	ds_write_b128 v19, v[42:45] offset:49152
	s_waitcnt lgkmcnt(10)
; template <int MODE>
; __device__ __forceinline__ void gemm_tile(const Params& P, int tm, int tn, unsigned char* smem) {
;     ...
;     for (int kt = 0; kt < 16; ++kt) {
;         unsigned char* sA = (kt & 1) ? sA1 : sA0; unsigned char* sB = (kt & 1) ? sB1 : sB0;
;         unsigned char* nA = (kt & 1) ? sA0 : sA1; unsigned char* nB = (kt & 1) ? sB0 : sB1;
;         bf16x8 fa[4], fb[4], ga[4], gb[4];
;         const int ch0 = ((g ^ sw) << 4), ch1 = (((4 + g) ^ sw) << 4);
;         const unsigned ko = (unsigned)(kt + 2) * 128u;
;         const unsigned koa = ko + ((MODE == 2 && kt + 2 >= 8) ? (unsigned)(ZC_FQ - 512) * 2u : 0u);
;         const bool wr_ok = kt < 15, ld_ok = kt < 14;
; #pragma unroll
;         for (int i = 0; i < 4; ++i) { fa[i] = *(const bf16x8*)(sA + arow_off + i * 2048 + ch0); fb[i] = *(const bf16x8*)(sB + brow_off + i * 2048 + ch0); }
;         __builtin_amdgcn_sched_barrier(0);
;         __builtin_amdgcn_s_setprio(2);
;         if (wr_ok) *(uint4*)(nA + soff0) = ra0;
;         if (ld_ok) ra0 = *(const uint4*)(Ab + (aoff + 0u * LDA + koa));
;         ga[0] = *(const bf16x8*)(sA + arow_off + 0 * 2048 + ch1); gb[0] = *(const bf16x8*)(sB + brow_off + 0 * 2048 + ch1);
;         __builtin_amdgcn_sched_barrier(0);
; #pragma unroll
;         for (int j = 0; j < 4; ++j) acc[0][j] = __builtin_amdgcn_mfma_f32_16x16x32_bf16(fb[j], fa[0], acc[0][j], 0, 0, 0);
;         __builtin_amdgcn_sched_barrier(0);
;         if (wr_ok) *(uint4*)(nA + soff0 + 4096) = ra1;
;         if (ld_ok) ra1 = *(const uint4*)(Ab + (aoff + 32u * LDA + koa));
;         ga[1] = *(const bf16x8*)(sA + arow_off + 1 * 2048 + ch1); gb[1] = *(const bf16x8*)(sB + brow_off + 1 * 2048 + ch1);
;         __builtin_amdgcn_sched_barrier(0);
; #pragma unroll
;         for (int j = 0; j < 4; ++j) acc[1][j] = __builtin_amdgcn_mfma_f32_16x16x32_bf16(fb[j], fa[1], acc[1][j], 0, 0, 0);
;         __builtin_amdgcn_sched_barrier(0);
;         if (wr_ok) *(uint4*)(nA + soff0 + 8192) = ra2;
;         if (ld_ok) ra2 = *(const uint4*)(Ab + (aoff + 64u * LDA + koa));
;         ga[2] = *(const bf16x8*)(sA + arow_off + 2 * 2048 + ch1); gb[2] = *(const bf16x8*)(sB + brow_off + 2 * 2048 + ch1);
;         __builtin_amdgcn_sched_barrier(0);
; #pragma unroll
;         for (int j = 0; j < 4; ++j) acc[2][j] = __builtin_amdgcn_mfma_f32_16x16x32_bf16(fb[j], fa[2], acc[2][j], 0, 0, 0);
	v_mfma_f32_16x16x32_bf16 v[42:45], v[104:107], v[26:29], v[108:111]
	s_waitcnt lgkmcnt(7)
	v_mfma_f32_16x16x32_bf16 v[108:111], v[124:127], v[26:29], v[112:115]
	s_waitcnt lgkmcnt(4)
	v_mfma_f32_16x16x32_bf16 v[112:115], v[148:151], v[26:29], v[116:119]
	s_waitcnt lgkmcnt(1)
	v_mfma_f32_16x16x32_bf16 v[26:29], v[168:171], v[26:29], v[58:61]
	v_add_u32_e32 v248, 0x10000, v18
	global_load_dwordx4 v[58:61], v248, s[6:7] offset:256
	ds_write_b128 v19, v[46:49] offset:53248
	v_mfma_f32_16x16x32_bf16 v[46:49], v[104:107], v[30:33], v[132:135]
	v_mfma_f32_16x16x32_bf16 v[116:119], v[124:127], v[30:33], v[136:139]
	v_mfma_f32_16x16x32_bf16 v[132:135], v[148:151], v[30:33], v[140:143]
	v_mfma_f32_16x16x32_bf16 v[30:33], v[168:171], v[30:33], v[62:65]
	v_add_u32_e32 v249, 0x20000, v18
	global_load_dwordx4 v[62:65], v249, s[6:7] offset:256
	s_waitcnt vmcnt(7)
	ds_write_b128 v19, v[50:53] offset:57344
	v_mfma_f32_16x16x32_bf16 v[50:53], v[104:107], v[34:37], v[152:155]
	v_mfma_f32_16x16x32_bf16 v[136:139], v[124:127], v[34:37], v[156:159]
	v_mfma_f32_16x16x32_bf16 v[140:143], v[148:151], v[34:37], v[160:163]
	v_mfma_f32_16x16x32_bf16 v[34:37], v[168:171], v[34:37], v[74:77]
	v_add_u32_e32 v250, 0x30000, v18
	global_load_dwordx4 v[74:77], v250, s[6:7] offset:256
	ds_write_b128 v19, v[54:57] offset:61440
	v_mfma_f32_16x16x32_bf16 v[54:57], v[104:107], v[38:41], v[66:69]
	v_mfma_f32_16x16x32_bf16 v[66:69], v[124:127], v[38:41], v[70:73]
	v_mfma_f32_16x16x32_bf16 v[70:73], v[148:151], v[38:41], v[92:95]
	v_mfma_f32_16x16x32_bf16 v[38:41], v[168:171], v[38:41], v[78:81]
	s_setprio 0
	s_waitcnt lgkmcnt(0)
	s_barrier
	ds_read_b128 v[78:81], v22 offset:32768
	ds_read_b128 v[92:95], v22 offset:34816
	ds_read_b128 v[104:107], v23 offset:49152
	ds_read_b128 v[124:127], v23 offset:51200
	ds_read_b128 v[148:151], v22 offset:36864
	ds_read_b128 v[152:155], v22 offset:38912
	ds_read_b128 v[156:159], v23 offset:53248
	ds_read_b128 v[160:163], v23 offset:55296
	s_setprio 2
	global_load_dwordx4 v[168:171], v24, s[36:37] offset:384
	s_waitcnt vmcnt(7)
	ds_write_b128 v19, v[100:103]
	ds_read_b128 v[100:103], v20 offset:32768
	ds_read_b128 v[172:175], v21 offset:49152
	s_waitcnt lgkmcnt(8)
	v_mfma_f32_16x16x32_bf16 v[42:45], v[104:107], v[78:81], v[42:45]
	s_waitcnt lgkmcnt(3)
	v_mfma_f32_16x16x32_bf16 v[26:29], v[160:163], v[78:81], v[26:29]
	v_mfma_f32_16x16x32_bf16 v[108:111], v[124:127], v[78:81], v[108:111]
	v_mfma_f32_16x16x32_bf16 v[112:115], v[156:159], v[78:81], v[112:115]
	global_load_dwordx4 v[78:81], v245, s[36:37] offset:384
	ds_write_b128 v19, v[120:123] offset:4096
	ds_read_b128 v[120:123], v20 offset:34816
	ds_read_b128 v[176:179], v21 offset:51200
	v_mfma_f32_16x16x32_bf16 v[46:49], v[104:107], v[92:95], v[46:49]
	v_mfma_f32_16x16x32_bf16 v[30:33], v[160:163], v[92:95], v[30:33]
	v_mfma_f32_16x16x32_bf16 v[116:119], v[124:127], v[92:95], v[116:119]
	v_mfma_f32_16x16x32_bf16 v[132:135], v[156:159], v[92:95], v[132:135]
	global_load_dwordx4 v[92:95], v246, s[36:37] offset:384
	s_waitcnt vmcnt(7)
	ds_write_b128 v19, v[144:147] offset:8192
	ds_read_b128 v[144:147], v20 offset:36864
	ds_read_b128 v[180:183], v21 offset:53248
	v_mfma_f32_16x16x32_bf16 v[50:53], v[104:107], v[148:151], v[50:53]
	v_mfma_f32_16x16x32_bf16 v[34:37], v[160:163], v[148:151], v[34:37]
	v_mfma_f32_16x16x32_bf16 v[136:139], v[124:127], v[148:151], v[136:139]
	v_mfma_f32_16x16x32_bf16 v[140:143], v[156:159], v[148:151], v[140:143]
	global_load_dwordx4 v[148:151], v247, s[36:37] offset:384
	ds_write_b128 v19, v[164:167] offset:12288
	ds_read_b128 v[164:167], v20 offset:38912
	ds_read_b128 v[184:187], v21 offset:55296
	v_mfma_f32_16x16x32_bf16 v[54:57], v[104:107], v[152:155], v[54:57]
	v_mfma_f32_16x16x32_bf16 v[66:69], v[124:127], v[152:155], v[66:69]
	v_mfma_f32_16x16x32_bf16 v[70:73], v[156:159], v[152:155], v[70:73]
	v_mfma_f32_16x16x32_bf16 v[38:41], v[160:163], v[152:155], v[38:41]
	global_load_dwordx4 v[104:107], v18, s[6:7] offset:384
	s_waitcnt vmcnt(7)
	ds_write_b128 v19, v[96:99] offset:16384
	s_waitcnt lgkmcnt(10)
	v_mfma_f32_16x16x32_bf16 v[42:45], v[172:175], v[100:103], v[42:45]
	s_waitcnt lgkmcnt(1)
	v_mfma_f32_16x16x32_bf16 v[26:29], v[184:187], v[100:103], v[26:29]
	v_mfma_f32_16x16x32_bf16 v[96:99], v[176:179], v[100:103], v[108:111]
	v_mfma_f32_16x16x32_bf16 v[108:111], v[180:183], v[100:103], v[112:115]
	global_load_dwordx4 v[100:103], v248, s[6:7] offset:384
	ds_write_b128 v19, v[58:61] offset:20480
	v_mfma_f32_16x16x32_bf16 v[46:49], v[172:175], v[120:123], v[46:49]
	v_mfma_f32_16x16x32_bf16 v[58:61], v[176:179], v[120:123], v[116:119]
	v_mfma_f32_16x16x32_bf16 v[30:33], v[184:187], v[120:123], v[30:33]
	v_mfma_f32_16x16x32_bf16 v[112:115], v[180:183], v[120:123], v[132:135]
	global_load_dwordx4 v[116:119], v249, s[6:7] offset:384
	s_waitcnt vmcnt(7)
	ds_write_b128 v19, v[62:65] offset:24576
	v_mfma_f32_16x16x32_bf16 v[50:53], v[172:175], v[144:147], v[50:53]
	v_mfma_f32_16x16x32_bf16 v[62:65], v[176:179], v[144:147], v[136:139]
	v_mfma_f32_16x16x32_bf16 v[34:37], v[184:187], v[144:147], v[34:37]
	v_mfma_f32_16x16x32_bf16 v[120:123], v[180:183], v[144:147], v[140:143]
	global_load_dwordx4 v[124:127], v250, s[6:7] offset:384
	ds_write_b128 v19, v[74:77] offset:28672
	v_mfma_f32_16x16x32_bf16 v[54:57], v[172:175], v[164:167], v[54:57]
	v_mfma_f32_16x16x32_bf16 v[66:69], v[176:179], v[164:167], v[66:69]
	v_mfma_f32_16x16x32_bf16 v[70:73], v[180:183], v[164:167], v[70:73]
	v_mfma_f32_16x16x32_bf16 v[38:41], v[184:187], v[164:167], v[38:41]
	s_setprio 0
	s_waitcnt lgkmcnt(0)
	s_barrier
; template <int MODE>
; __device__ __forceinline__ void gemm_tile(const Params& P, int tm, int tn, unsigned char* smem) {
;     ...
;     for (int kt = 0; kt < 16; ++kt) {
;         unsigned char* sA = (kt & 1) ? sA1 : sA0; unsigned char* sB = (kt & 1) ? sB1 : sB0;
;         unsigned char* nA = (kt & 1) ? sA0 : sA1; unsigned char* nB = (kt & 1) ? sB0 : sB1;
;         bf16x8 fa[4], fb[4], ga[4], gb[4];
;         const int ch0 = ((g ^ sw) << 4), ch1 = (((4 + g) ^ sw) << 4);
;         const unsigned ko = (unsigned)(kt + 2) * 128u;
;         const unsigned koa = ko + ((MODE == 2 && kt + 2 >= 8) ? (unsigned)(ZC_FQ - 512) * 2u : 0u);
;         const bool wr_ok = kt < 15, ld_ok = kt < 14;
; #pragma unroll
;         for (int i = 0; i < 4; ++i) { fa[i] = *(const bf16x8*)(sA + arow_off + i * 2048 + ch0); fb[i] = *(const bf16x8*)(sB + brow_off + i * 2048 + ch0); }
;         __builtin_amdgcn_sched_barrier(0);
;         __builtin_amdgcn_s_setprio(2);
;         if (wr_ok) *(uint4*)(nA + soff0) = ra0;
;         if (ld_ok) ra0 = *(const uint4*)(Ab + (aoff + 0u * LDA + koa));
;         ga[0] = *(const bf16x8*)(sA + arow_off + 0 * 2048 + ch1); gb[0] = *(const bf16x8*)(sB + brow_off + 0 * 2048 + ch1);
;         __builtin_amdgcn_sched_barrier(0);
; #pragma unroll
;         for (int j = 0; j < 4; ++j) acc[0][j] = __builtin_amdgcn_mfma_f32_16x16x32_bf16(fb[j], fa[0], acc[0][j], 0, 0, 0);
;         __builtin_amdgcn_sched_barrier(0);
;         if (wr_ok) *(uint4*)(nA + soff0 + 4096) = ra1;
;         if (ld_ok) ra1 = *(const uint4*)(Ab + (aoff + 32u * LDA + koa));
;         ga[1] = *(const bf16x8*)(sA + arow_off + 1 * 2048 + ch1); gb[1] = *(const bf16x8*)(sB + brow_off + 1 * 2048 + ch1);
;         __builtin_amdgcn_sched_barrier(0);
; #pragma unroll
;         for (int j = 0; j < 4; ++j) acc[1][j] = __builtin_amdgcn_mfma_f32_16x16x32_bf16(fb[j], fa[1], acc[1][j], 0, 0, 0);
;         __builtin_amdgcn_sched_barrier(0);
;         if (wr_ok) *(uint4*)(nA + soff0 + 8192) = ra2;
;         if (ld_ok) ra2 = *(const uint4*)(Ab + (aoff + 64u * LDA + koa));
;         ga[2] = *(const bf16x8*)(sA + arow_off + 2 * 2048 + ch1); gb[2] = *(const bf16x8*)(sB + brow_off + 2 * 2048 + ch1);
;         __builtin_amdgcn_sched_barrier(0);
; #pragma unroll
;         for (int j = 0; j < 4; ++j) acc[2][j] = __builtin_amdgcn_mfma_f32_16x16x32_bf16(fb[j], fa[2], acc[2][j], 0, 0, 0);
	ds_read_b128 v[74:77], v22
	ds_read_b128 v[132:135], v22 offset:2048
	ds_read_b128 v[136:139], v23 offset:16384
	ds_read_b128 v[140:143], v23 offset:18432
	ds_read_b128 v[144:147], v22 offset:4096
	ds_read_b128 v[152:155], v22 offset:6144
	ds_read_b128 v[156:159], v23 offset:20480
	ds_read_b128 v[160:163], v23 offset:22528
	s_setprio 2
	global_load_dwordx4 v[164:167], v24, s[36:37] offset:512
	s_waitcnt vmcnt(7)
	ds_write_b128 v19, v[168:171] offset:32768
	ds_read_b128 v[168:171], v20
	ds_read_b128 v[172:175], v21 offset:16384
	s_waitcnt lgkmcnt(8)
	v_mfma_f32_16x16x32_bf16 v[42:45], v[136:139], v[74:77], v[42:45]
	s_waitcnt lgkmcnt(3)
	v_mfma_f32_16x16x32_bf16 v[26:29], v[160:163], v[74:77], v[26:29]
	v_mfma_f32_16x16x32_bf16 v[96:99], v[140:143], v[74:77], v[96:99]
	v_mfma_f32_16x16x32_bf16 v[108:111], v[156:159], v[74:77], v[108:111]
	global_load_dwordx4 v[74:77], v245, s[36:37] offset:512
	ds_write_b128 v19, v[78:81] offset:36864
	ds_read_b128 v[78:81], v20 offset:2048
	ds_read_b128 v[176:179], v21 offset:18432
	v_mfma_f32_16x16x32_bf16 v[46:49], v[136:139], v[132:135], v[46:49]
	v_mfma_f32_16x16x32_bf16 v[58:61], v[140:143], v[132:135], v[58:61]
	v_mfma_f32_16x16x32_bf16 v[30:33], v[160:163], v[132:135], v[30:33]
	v_mfma_f32_16x16x32_bf16 v[112:115], v[156:159], v[132:135], v[112:115]
	global_load_dwordx4 v[132:135], v246, s[36:37] offset:512
	s_waitcnt vmcnt(7)
	ds_write_b128 v19, v[92:95] offset:40960
	ds_read_b128 v[92:95], v20 offset:4096
	ds_read_b128 v[180:183], v21 offset:20480
	v_mfma_f32_16x16x32_bf16 v[50:53], v[136:139], v[144:147], v[50:53]
	v_mfma_f32_16x16x32_bf16 v[62:65], v[140:143], v[144:147], v[62:65]
	v_mfma_f32_16x16x32_bf16 v[34:37], v[160:163], v[144:147], v[34:37]
	v_mfma_f32_16x16x32_bf16 v[120:123], v[156:159], v[144:147], v[120:123]
	global_load_dwordx4 v[144:147], v247, s[36:37] offset:512
	ds_write_b128 v19, v[148:151] offset:45056
	ds_read_b128 v[148:151], v20 offset:6144
	ds_read_b128 v[184:187], v21 offset:22528
	v_mfma_f32_16x16x32_bf16 v[54:57], v[136:139], v[152:155], v[54:57]
	v_mfma_f32_16x16x32_bf16 v[66:69], v[140:143], v[152:155], v[66:69]
	v_mfma_f32_16x16x32_bf16 v[70:73], v[156:159], v[152:155], v[70:73]
	v_mfma_f32_16x16x32_bf16 v[38:41], v[160:163], v[152:155], v[38:41]
	global_load_dwordx4 v[136:139], v18, s[6:7] offset:512
	s_waitcnt vmcnt(7)
	ds_write_b128 v19, v[104:107] offset:49152
	s_waitcnt lgkmcnt(10)
	v_mfma_f32_16x16x32_bf16 v[42:45], v[172:175], v[168:171], v[42:45]
	s_waitcnt lgkmcnt(1)
	v_mfma_f32_16x16x32_bf16 v[26:29], v[184:187], v[168:171], v[26:29]
	v_mfma_f32_16x16x32_bf16 v[96:99], v[176:179], v[168:171], v[96:99]
	v_mfma_f32_16x16x32_bf16 v[104:107], v[180:183], v[168:171], v[108:111]
	global_load_dwordx4 v[108:111], v248, s[6:7] offset:512
	ds_write_b128 v19, v[100:103] offset:53248
	v_mfma_f32_16x16x32_bf16 v[46:49], v[172:175], v[78:81], v[46:49]
	v_mfma_f32_16x16x32_bf16 v[58:61], v[176:179], v[78:81], v[58:61]
	v_mfma_f32_16x16x32_bf16 v[30:33], v[184:187], v[78:81], v[30:33]
	v_mfma_f32_16x16x32_bf16 v[100:103], v[180:183], v[78:81], v[112:115]
	global_load_dwordx4 v[78:81], v249, s[6:7] offset:512
	s_waitcnt vmcnt(7)
	ds_write_b128 v19, v[116:119] offset:57344
	v_mfma_f32_16x16x32_bf16 v[50:53], v[172:175], v[92:95], v[50:53]
	v_mfma_f32_16x16x32_bf16 v[62:65], v[176:179], v[92:95], v[62:65]
	v_mfma_f32_16x16x32_bf16 v[34:37], v[184:187], v[92:95], v[34:37]
	v_mfma_f32_16x16x32_bf16 v[112:115], v[180:183], v[92:95], v[120:123]
	global_load_dwordx4 v[92:95], v250, s[6:7] offset:512
	ds_write_b128 v19, v[124:127] offset:61440
	v_mfma_f32_16x16x32_bf16 v[54:57], v[172:175], v[148:151], v[54:57]
	v_mfma_f32_16x16x32_bf16 v[66:69], v[176:179], v[148:151], v[66:69]
	v_mfma_f32_16x16x32_bf16 v[70:73], v[180:183], v[148:151], v[70:73]
	v_mfma_f32_16x16x32_bf16 v[38:41], v[184:187], v[148:151], v[38:41]
	s_setprio 0
	s_waitcnt lgkmcnt(0)
	s_barrier
	ds_read_b128 v[116:119], v22 offset:32768
	ds_read_b128 v[120:123], v22 offset:34816
	ds_read_b128 v[124:127], v23 offset:49152
	ds_read_b128 v[140:143], v23 offset:51200
	ds_read_b128 v[148:151], v22 offset:36864
	ds_read_b128 v[152:155], v22 offset:38912
	ds_read_b128 v[156:159], v23 offset:53248
	ds_read_b128 v[160:163], v23 offset:55296
	s_setprio 2
	global_load_dwordx4 v[168:171], v24, s[36:37] offset:640
	s_waitcnt vmcnt(7)
	ds_write_b128 v19, v[164:167]
	ds_read_b128 v[164:167], v20 offset:32768
	ds_read_b128 v[172:175], v21 offset:49152
	s_waitcnt lgkmcnt(8)
	v_mfma_f32_16x16x32_bf16 v[42:45], v[124:127], v[116:119], v[42:45]
	s_waitcnt lgkmcnt(3)
	v_mfma_f32_16x16x32_bf16 v[26:29], v[160:163], v[116:119], v[26:29]
	v_mfma_f32_16x16x32_bf16 v[96:99], v[140:143], v[116:119], v[96:99]
	v_mfma_f32_16x16x32_bf16 v[104:107], v[156:159], v[116:119], v[104:107]
	global_load_dwordx4 v[116:119], v245, s[36:37] offset:640
	ds_write_b128 v19, v[74:77] offset:4096
	ds_read_b128 v[74:77], v20 offset:34816
	ds_read_b128 v[176:179], v21 offset:51200
	v_mfma_f32_16x16x32_bf16 v[46:49], v[124:127], v[120:123], v[46:49]
	v_mfma_f32_16x16x32_bf16 v[58:61], v[140:143], v[120:123], v[58:61]
	v_mfma_f32_16x16x32_bf16 v[30:33], v[160:163], v[120:123], v[30:33]
	v_mfma_f32_16x16x32_bf16 v[100:103], v[156:159], v[120:123], v[100:103]
	global_load_dwordx4 v[120:123], v246, s[36:37] offset:640
	s_waitcnt vmcnt(7)
; template <int MODE>
; __device__ __forceinline__ void gemm_tile(const Params& P, int tm, int tn, unsigned char* smem) {
;     ...
;     for (int kt = 0; kt < 16; ++kt) {
;         unsigned char* sA = (kt & 1) ? sA1 : sA0; unsigned char* sB = (kt & 1) ? sB1 : sB0;
;         unsigned char* nA = (kt & 1) ? sA0 : sA1; unsigned char* nB = (kt & 1) ? sB0 : sB1;
;         bf16x8 fa[4], fb[4], ga[4], gb[4];
;         const int ch0 = ((g ^ sw) << 4), ch1 = (((4 + g) ^ sw) << 4);
;         const unsigned ko = (unsigned)(kt + 2) * 128u;
;         const unsigned koa = ko + ((MODE == 2 && kt + 2 >= 8) ? (unsigned)(ZC_FQ - 512) * 2u : 0u);
;         const bool wr_ok = kt < 15, ld_ok = kt < 14;
; #pragma unroll
;         for (int i = 0; i < 4; ++i) { fa[i] = *(const bf16x8*)(sA + arow_off + i * 2048 + ch0); fb[i] = *(const bf16x8*)(sB + brow_off + i * 2048 + ch0); }
;         __builtin_amdgcn_sched_barrier(0);
;         __builtin_amdgcn_s_setprio(2);
;         if (wr_ok) *(uint4*)(nA + soff0) = ra0;
;         if (ld_ok) ra0 = *(const uint4*)(Ab + (aoff + 0u * LDA + koa));
;         ga[0] = *(const bf16x8*)(sA + arow_off + 0 * 2048 + ch1); gb[0] = *(const bf16x8*)(sB + brow_off + 0 * 2048 + ch1);
;         __builtin_amdgcn_sched_barrier(0);
; #pragma unroll
;         for (int j = 0; j < 4; ++j) acc[0][j] = __builtin_amdgcn_mfma_f32_16x16x32_bf16(fb[j], fa[0], acc[0][j], 0, 0, 0);
;         __builtin_amdgcn_sched_barrier(0);
;         if (wr_ok) *(uint4*)(nA + soff0 + 4096) = ra1;
;         if (ld_ok) ra1 = *(const uint4*)(Ab + (aoff + 32u * LDA + koa));
;         ga[1] = *(const bf16x8*)(sA + arow_off + 1 * 2048 + ch1); gb[1] = *(const bf16x8*)(sB + brow_off + 1 * 2048 + ch1);
;         __builtin_amdgcn_sched_barrier(0);
; #pragma unroll
;         for (int j = 0; j < 4; ++j) acc[1][j] = __builtin_amdgcn_mfma_f32_16x16x32_bf16(fb[j], fa[1], acc[1][j], 0, 0, 0);
;         __builtin_amdgcn_sched_barrier(0);
;         if (wr_ok) *(uint4*)(nA + soff0 + 8192) = ra2;
;         if (ld_ok) ra2 = *(const uint4*)(Ab + (aoff + 64u * LDA + koa));
;         ga[2] = *(const bf16x8*)(sA + arow_off + 2 * 2048 + ch1); gb[2] = *(const bf16x8*)(sB + brow_off + 2 * 2048 + ch1);
;         __builtin_amdgcn_sched_barrier(0);
; #pragma unroll
;         for (int j = 0; j < 4; ++j) acc[2][j] = __builtin_amdgcn_mfma_f32_16x16x32_bf16(fb[j], fa[2], acc[2][j], 0, 0, 0);
	ds_write_b128 v19, v[132:135] offset:8192
	ds_read_b128 v[132:135], v20 offset:36864
	ds_read_b128 v[180:183], v21 offset:53248
	v_mfma_f32_16x16x32_bf16 v[50:53], v[124:127], v[148:151], v[50:53]
	v_mfma_f32_16x16x32_bf16 v[62:65], v[140:143], v[148:151], v[62:65]
	v_mfma_f32_16x16x32_bf16 v[34:37], v[160:163], v[148:151], v[34:37]
	v_mfma_f32_16x16x32_bf16 v[112:115], v[156:159], v[148:151], v[112:115]
	global_load_dwordx4 v[148:151], v247, s[36:37] offset:640
	ds_write_b128 v19, v[144:147] offset:12288
	ds_read_b128 v[144:147], v20 offset:38912
	ds_read_b128 v[184:187], v21 offset:55296
	v_mfma_f32_16x16x32_bf16 v[54:57], v[124:127], v[152:155], v[54:57]
	v_mfma_f32_16x16x32_bf16 v[66:69], v[140:143], v[152:155], v[66:69]
	v_mfma_f32_16x16x32_bf16 v[70:73], v[156:159], v[152:155], v[70:73]
	v_mfma_f32_16x16x32_bf16 v[38:41], v[160:163], v[152:155], v[38:41]
	global_load_dwordx4 v[124:127], v18, s[6:7] offset:640
	s_waitcnt vmcnt(7)
	ds_write_b128 v19, v[136:139] offset:16384
	s_waitcnt lgkmcnt(10)
	v_mfma_f32_16x16x32_bf16 v[42:45], v[172:175], v[164:167], v[42:45]
	s_waitcnt lgkmcnt(1)
	v_mfma_f32_16x16x32_bf16 v[26:29], v[184:187], v[164:167], v[26:29]
	v_mfma_f32_16x16x32_bf16 v[96:99], v[176:179], v[164:167], v[96:99]
	v_mfma_f32_16x16x32_bf16 v[104:107], v[180:183], v[164:167], v[104:107]
	global_load_dwordx4 v[136:139], v248, s[6:7] offset:640
	ds_write_b128 v19, v[108:111] offset:20480
	v_mfma_f32_16x16x32_bf16 v[46:49], v[172:175], v[74:77], v[46:49]
	v_mfma_f32_16x16x32_bf16 v[58:61], v[176:179], v[74:77], v[58:61]
	v_mfma_f32_16x16x32_bf16 v[30:33], v[184:187], v[74:77], v[30:33]
	v_mfma_f32_16x16x32_bf16 v[100:103], v[180:183], v[74:77], v[100:103]
	global_load_dwordx4 v[74:77], v249, s[6:7] offset:640
	s_waitcnt vmcnt(7)
	ds_write_b128 v19, v[78:81] offset:24576
	v_mfma_f32_16x16x32_bf16 v[50:53], v[172:175], v[132:135], v[50:53]
	v_mfma_f32_16x16x32_bf16 v[62:65], v[176:179], v[132:135], v[62:65]
	v_mfma_f32_16x16x32_bf16 v[78:81], v[180:183], v[132:135], v[112:115]
	v_mfma_f32_16x16x32_bf16 v[34:37], v[184:187], v[132:135], v[34:37]
	global_load_dwordx4 v[108:111], v250, s[6:7] offset:640
	ds_write_b128 v19, v[92:95] offset:28672
	v_mfma_f32_16x16x32_bf16 v[54:57], v[172:175], v[144:147], v[54:57]
	v_mfma_f32_16x16x32_bf16 v[66:69], v[176:179], v[144:147], v[66:69]
	v_mfma_f32_16x16x32_bf16 v[70:73], v[180:183], v[144:147], v[70:73]
	v_mfma_f32_16x16x32_bf16 v[38:41], v[184:187], v[144:147], v[38:41]
	s_setprio 0
	s_waitcnt lgkmcnt(0)
	s_barrier
	ds_read_b128 v[92:95], v22
	ds_read_b128 v[112:115], v22 offset:2048
	ds_read_b128 v[132:135], v23 offset:16384
	ds_read_b128 v[140:143], v23 offset:18432
	ds_read_b128 v[144:147], v22 offset:4096
	ds_read_b128 v[152:155], v22 offset:6144
	ds_read_b128 v[156:159], v23 offset:20480
	ds_read_b128 v[160:163], v23 offset:22528
	s_setprio 2
	global_load_dwordx4 v[164:167], v24, s[36:37] offset:768
	s_waitcnt vmcnt(7)
	ds_write_b128 v19, v[168:171] offset:32768
	ds_read_b128 v[168:171], v20
	ds_read_b128 v[172:175], v21 offset:16384
	s_waitcnt lgkmcnt(8)
	v_mfma_f32_16x16x32_bf16 v[42:45], v[132:135], v[92:95], v[42:45]
	s_waitcnt lgkmcnt(3)
	v_mfma_f32_16x16x32_bf16 v[26:29], v[160:163], v[92:95], v[26:29]
	v_mfma_f32_16x16x32_bf16 v[96:99], v[140:143], v[92:95], v[96:99]
	v_mfma_f32_16x16x32_bf16 v[104:107], v[156:159], v[92:95], v[104:107]
	global_load_dwordx4 v[92:95], v245, s[36:37] offset:768
	ds_write_b128 v19, v[116:119] offset:36864
	ds_read_b128 v[116:119], v20 offset:2048
	ds_read_b128 v[176:179], v21 offset:18432
	v_mfma_f32_16x16x32_bf16 v[46:49], v[132:135], v[112:115], v[46:49]
	v_mfma_f32_16x16x32_bf16 v[58:61], v[140:143], v[112:115], v[58:61]
	v_mfma_f32_16x16x32_bf16 v[30:33], v[160:163], v[112:115], v[30:33]
	v_mfma_f32_16x16x32_bf16 v[100:103], v[156:159], v[112:115], v[100:103]
	global_load_dwordx4 v[112:115], v246, s[36:37] offset:768
	s_waitcnt vmcnt(7)
	ds_write_b128 v19, v[120:123] offset:40960
	ds_read_b128 v[120:123], v20 offset:4096
	ds_read_b128 v[180:183], v21 offset:20480
	v_mfma_f32_16x16x32_bf16 v[50:53], v[132:135], v[144:147], v[50:53]
	v_mfma_f32_16x16x32_bf16 v[62:65], v[140:143], v[144:147], v[62:65]
	v_mfma_f32_16x16x32_bf16 v[78:81], v[156:159], v[144:147], v[78:81]
	v_mfma_f32_16x16x32_bf16 v[34:37], v[160:163], v[144:147], v[34:37]
	global_load_dwordx4 v[144:147], v247, s[36:37] offset:768
	ds_write_b128 v19, v[148:151] offset:45056
	ds_read_b128 v[148:151], v20 offset:6144
	ds_read_b128 v[184:187], v21 offset:22528
	v_mfma_f32_16x16x32_bf16 v[54:57], v[132:135], v[152:155], v[54:57]
	v_mfma_f32_16x16x32_bf16 v[66:69], v[140:143], v[152:155], v[66:69]
	v_mfma_f32_16x16x32_bf16 v[70:73], v[156:159], v[152:155], v[70:73]
	v_mfma_f32_16x16x32_bf16 v[38:41], v[160:163], v[152:155], v[38:41]
	global_load_dwordx4 v[132:135], v18, s[6:7] offset:768
	s_waitcnt vmcnt(7)
	ds_write_b128 v19, v[124:127] offset:49152
	s_waitcnt lgkmcnt(10)
	v_mfma_f32_16x16x32_bf16 v[42:45], v[172:175], v[168:171], v[42:45]
	s_waitcnt lgkmcnt(1)
	v_mfma_f32_16x16x32_bf16 v[26:29], v[184:187], v[168:171], v[26:29]
	v_mfma_f32_16x16x32_bf16 v[96:99], v[176:179], v[168:171], v[96:99]
	v_mfma_f32_16x16x32_bf16 v[104:107], v[180:183], v[168:171], v[104:107]
	global_load_dwordx4 v[124:127], v248, s[6:7] offset:768
	ds_write_b128 v19, v[136:139] offset:53248
	v_mfma_f32_16x16x32_bf16 v[46:49], v[172:175], v[116:119], v[46:49]
	v_mfma_f32_16x16x32_bf16 v[58:61], v[176:179], v[116:119], v[58:61]
	v_mfma_f32_16x16x32_bf16 v[30:33], v[184:187], v[116:119], v[30:33]
	v_mfma_f32_16x16x32_bf16 v[100:103], v[180:183], v[116:119], v[100:103]
	global_load_dwordx4 v[116:119], v249, s[6:7] offset:768
	s_waitcnt vmcnt(7)
	ds_write_b128 v19, v[74:77] offset:57344
	v_mfma_f32_16x16x32_bf16 v[50:53], v[172:175], v[120:123], v[50:53]
	v_mfma_f32_16x16x32_bf16 v[62:65], v[176:179], v[120:123], v[62:65]
	v_mfma_f32_16x16x32_bf16 v[74:77], v[180:183], v[120:123], v[78:81]
	v_mfma_f32_16x16x32_bf16 v[34:37], v[184:187], v[120:123], v[34:37]
	global_load_dwordx4 v[78:81], v250, s[6:7] offset:768
	ds_write_b128 v19, v[108:111] offset:61440
	v_mfma_f32_16x16x32_bf16 v[54:57], v[172:175], v[148:151], v[54:57]
	v_mfma_f32_16x16x32_bf16 v[66:69], v[176:179], v[148:151], v[66:69]
	v_mfma_f32_16x16x32_bf16 v[70:73], v[180:183], v[148:151], v[70:73]
	v_mfma_f32_16x16x32_bf16 v[38:41], v[184:187], v[148:151], v[38:41]
	s_setprio 0
	s_waitcnt lgkmcnt(0)
	s_barrier
; template <int MODE>
; __device__ __forceinline__ void gemm_tile(const Params& P, int tm, int tn, unsigned char* smem) {
;     ...
;     for (int kt = 0; kt < 16; ++kt) {
;         unsigned char* sA = (kt & 1) ? sA1 : sA0; unsigned char* sB = (kt & 1) ? sB1 : sB0;
;         unsigned char* nA = (kt & 1) ? sA0 : sA1; unsigned char* nB = (kt & 1) ? sB0 : sB1;
;         bf16x8 fa[4], fb[4], ga[4], gb[4];
;         const int ch0 = ((g ^ sw) << 4), ch1 = (((4 + g) ^ sw) << 4);
;         const unsigned ko = (unsigned)(kt + 2) * 128u;
;         const unsigned koa = ko + ((MODE == 2 && kt + 2 >= 8) ? (unsigned)(ZC_FQ - 512) * 2u : 0u);
;         const bool wr_ok = kt < 15, ld_ok = kt < 14;
; #pragma unroll
;         for (int i = 0; i < 4; ++i) { fa[i] = *(const bf16x8*)(sA + arow_off + i * 2048 + ch0); fb[i] = *(const bf16x8*)(sB + brow_off + i * 2048 + ch0); }
;         __builtin_amdgcn_sched_barrier(0);
;         __builtin_amdgcn_s_setprio(2);
;         if (wr_ok) *(uint4*)(nA + soff0) = ra0;
;         if (ld_ok) ra0 = *(const uint4*)(Ab + (aoff + 0u * LDA + koa));
;         ga[0] = *(const bf16x8*)(sA + arow_off + 0 * 2048 + ch1); gb[0] = *(const bf16x8*)(sB + brow_off + 0 * 2048 + ch1);
;         __builtin_amdgcn_sched_barrier(0);
; #pragma unroll
;         for (int j = 0; j < 4; ++j) acc[0][j] = __builtin_amdgcn_mfma_f32_16x16x32_bf16(fb[j], fa[0], acc[0][j], 0, 0, 0);
;         __builtin_amdgcn_sched_barrier(0);
;         if (wr_ok) *(uint4*)(nA + soff0 + 4096) = ra1;
;         if (ld_ok) ra1 = *(const uint4*)(Ab + (aoff + 32u * LDA + koa));
;         ga[1] = *(const bf16x8*)(sA + arow_off + 1 * 2048 + ch1); gb[1] = *(const bf16x8*)(sB + brow_off + 1 * 2048 + ch1);
;         __builtin_amdgcn_sched_barrier(0);
; #pragma unroll
;         for (int j = 0; j < 4; ++j) acc[1][j] = __builtin_amdgcn_mfma_f32_16x16x32_bf16(fb[j], fa[1], acc[1][j], 0, 0, 0);
;         __builtin_amdgcn_sched_barrier(0);
;         if (wr_ok) *(uint4*)(nA + soff0 + 8192) = ra2;
;         if (ld_ok) ra2 = *(const uint4*)(Ab + (aoff + 64u * LDA + koa));
;         ga[2] = *(const bf16x8*)(sA + arow_off + 2 * 2048 + ch1); gb[2] = *(const bf16x8*)(sB + brow_off + 2 * 2048 + ch1);
;         __builtin_amdgcn_sched_barrier(0);
; #pragma unroll
;         for (int j = 0; j < 4; ++j) acc[2][j] = __builtin_amdgcn_mfma_f32_16x16x32_bf16(fb[j], fa[2], acc[2][j], 0, 0, 0);
	ds_read_b128 v[108:111], v22 offset:32768
	ds_read_b128 v[120:123], v22 offset:34816
	ds_read_b128 v[136:139], v23 offset:49152
	ds_read_b128 v[140:143], v23 offset:51200
	ds_read_b128 v[148:151], v22 offset:36864
	ds_read_b128 v[152:155], v22 offset:38912
	ds_read_b128 v[156:159], v23 offset:53248
	ds_read_b128 v[160:163], v23 offset:55296
	s_setprio 2
	global_load_dwordx4 v[168:171], v24, s[36:37] offset:896
	s_waitcnt vmcnt(7)
	ds_write_b128 v19, v[164:167]
	ds_read_b128 v[164:167], v20 offset:32768
	ds_read_b128 v[172:175], v21 offset:49152
	s_waitcnt lgkmcnt(8)
	v_mfma_f32_16x16x32_bf16 v[42:45], v[136:139], v[108:111], v[42:45]
	s_waitcnt lgkmcnt(3)
	v_mfma_f32_16x16x32_bf16 v[26:29], v[160:163], v[108:111], v[26:29]
	v_mfma_f32_16x16x32_bf16 v[96:99], v[140:143], v[108:111], v[96:99]
	v_mfma_f32_16x16x32_bf16 v[104:107], v[156:159], v[108:111], v[104:107]
	global_load_dwordx4 v[108:111], v245, s[36:37] offset:896
	ds_write_b128 v19, v[92:95] offset:4096
	ds_read_b128 v[92:95], v20 offset:34816
	ds_read_b128 v[176:179], v21 offset:51200
	v_mfma_f32_16x16x32_bf16 v[46:49], v[136:139], v[120:123], v[46:49]
	v_mfma_f32_16x16x32_bf16 v[58:61], v[140:143], v[120:123], v[58:61]
	v_mfma_f32_16x16x32_bf16 v[30:33], v[160:163], v[120:123], v[30:33]
	v_mfma_f32_16x16x32_bf16 v[100:103], v[156:159], v[120:123], v[100:103]
	global_load_dwordx4 v[120:123], v246, s[36:37] offset:896
	s_waitcnt vmcnt(7)
	ds_write_b128 v19, v[112:115] offset:8192
	ds_read_b128 v[112:115], v20 offset:36864
	ds_read_b128 v[180:183], v21 offset:53248
	v_mfma_f32_16x16x32_bf16 v[50:53], v[136:139], v[148:151], v[50:53]
	v_mfma_f32_16x16x32_bf16 v[62:65], v[140:143], v[148:151], v[62:65]
	v_mfma_f32_16x16x32_bf16 v[74:77], v[156:159], v[148:151], v[74:77]
	v_mfma_f32_16x16x32_bf16 v[34:37], v[160:163], v[148:151], v[34:37]
	global_load_dwordx4 v[148:151], v247, s[36:37] offset:896
	ds_write_b128 v19, v[144:147] offset:12288
	ds_read_b128 v[144:147], v20 offset:38912
	ds_read_b128 v[184:187], v21 offset:55296
	v_mfma_f32_16x16x32_bf16 v[54:57], v[136:139], v[152:155], v[54:57]
	v_mfma_f32_16x16x32_bf16 v[66:69], v[140:143], v[152:155], v[66:69]
	v_mfma_f32_16x16x32_bf16 v[70:73], v[156:159], v[152:155], v[70:73]
	v_mfma_f32_16x16x32_bf16 v[38:41], v[160:163], v[152:155], v[38:41]
	global_load_dwordx4 v[136:139], v18, s[6:7] offset:896
	s_waitcnt vmcnt(7)
	ds_write_b128 v19, v[132:135] offset:16384
	s_waitcnt lgkmcnt(10)
	v_mfma_f32_16x16x32_bf16 v[42:45], v[172:175], v[164:167], v[42:45]
	s_waitcnt lgkmcnt(1)
	v_mfma_f32_16x16x32_bf16 v[26:29], v[184:187], v[164:167], v[26:29]
	v_mfma_f32_16x16x32_bf16 v[96:99], v[176:179], v[164:167], v[96:99]
	v_mfma_f32_16x16x32_bf16 v[104:107], v[180:183], v[164:167], v[104:107]
	global_load_dwordx4 v[132:135], v248, s[6:7] offset:896
	ds_write_b128 v19, v[124:127] offset:20480
	v_mfma_f32_16x16x32_bf16 v[46:49], v[172:175], v[92:95], v[46:49]
	v_mfma_f32_16x16x32_bf16 v[58:61], v[176:179], v[92:95], v[58:61]
	v_mfma_f32_16x16x32_bf16 v[30:33], v[184:187], v[92:95], v[30:33]
	v_mfma_f32_16x16x32_bf16 v[100:103], v[180:183], v[92:95], v[100:103]
	global_load_dwordx4 v[92:95], v249, s[6:7] offset:896
	s_waitcnt vmcnt(7)
	ds_write_b128 v19, v[116:119] offset:24576
	v_mfma_f32_16x16x32_bf16 v[50:53], v[172:175], v[112:115], v[50:53]
	v_mfma_f32_16x16x32_bf16 v[62:65], v[176:179], v[112:115], v[62:65]
	v_mfma_f32_16x16x32_bf16 v[74:77], v[180:183], v[112:115], v[74:77]
	v_mfma_f32_16x16x32_bf16 v[34:37], v[184:187], v[112:115], v[34:37]
	global_load_dwordx4 v[112:115], v250, s[6:7] offset:896
	ds_write_b128 v19, v[78:81] offset:28672
	v_mfma_f32_16x16x32_bf16 v[54:57], v[172:175], v[144:147], v[54:57]
	v_mfma_f32_16x16x32_bf16 v[66:69], v[176:179], v[144:147], v[66:69]
	v_mfma_f32_16x16x32_bf16 v[70:73], v[180:183], v[144:147], v[70:73]
	v_mfma_f32_16x16x32_bf16 v[38:41], v[184:187], v[144:147], v[38:41]
	s_setprio 0
	s_waitcnt lgkmcnt(0)
	s_barrier
	ds_read_b128 v[78:81], v22
	ds_read_b128 v[116:119], v22 offset:2048
	ds_read_b128 v[124:127], v23 offset:16384
	ds_read_b128 v[140:143], v23 offset:18432
	ds_read_b128 v[144:147], v22 offset:4096
	ds_read_b128 v[152:155], v22 offset:6144
	ds_read_b128 v[156:159], v23 offset:20480
	ds_read_b128 v[160:163], v23 offset:22528
	s_setprio 2
	global_load_dwordx4 v[164:167], v24, s[36:37] offset:1024
	s_waitcnt vmcnt(7)
	ds_write_b128 v19, v[168:171] offset:32768
	ds_read_b128 v[168:171], v20
	ds_read_b128 v[172:175], v21 offset:16384
	s_waitcnt lgkmcnt(8)
	v_mfma_f32_16x16x32_bf16 v[42:45], v[124:127], v[78:81], v[42:45]
	s_waitcnt lgkmcnt(3)
	v_mfma_f32_16x16x32_bf16 v[26:29], v[160:163], v[78:81], v[26:29]
	v_mfma_f32_16x16x32_bf16 v[96:99], v[140:143], v[78:81], v[96:99]
	v_mfma_f32_16x16x32_bf16 v[104:107], v[156:159], v[78:81], v[104:107]
	global_load_dwordx4 v[78:81], v245, s[36:37] offset:1024
	ds_write_b128 v19, v[108:111] offset:36864
	ds_read_b128 v[108:111], v20 offset:2048
	ds_read_b128 v[176:179], v21 offset:18432
	v_mfma_f32_16x16x32_bf16 v[46:49], v[124:127], v[116:119], v[46:49]
	v_mfma_f32_16x16x32_bf16 v[58:61], v[140:143], v[116:119], v[58:61]
	v_mfma_f32_16x16x32_bf16 v[30:33], v[160:163], v[116:119], v[30:33]
	v_mfma_f32_16x16x32_bf16 v[100:103], v[156:159], v[116:119], v[100:103]
	global_load_dwordx4 v[116:119], v246, s[36:37] offset:1024
	s_waitcnt vmcnt(7)
; template <int MODE>
; __device__ __forceinline__ void gemm_tile(const Params& P, int tm, int tn, unsigned char* smem) {
;     ...
;     for (int kt = 0; kt < 16; ++kt) {
;         unsigned char* sA = (kt & 1) ? sA1 : sA0; unsigned char* sB = (kt & 1) ? sB1 : sB0;
;         unsigned char* nA = (kt & 1) ? sA0 : sA1; unsigned char* nB = (kt & 1) ? sB0 : sB1;
;         bf16x8 fa[4], fb[4], ga[4], gb[4];
;         const int ch0 = ((g ^ sw) << 4), ch1 = (((4 + g) ^ sw) << 4);
;         const unsigned ko = (unsigned)(kt + 2) * 128u;
;         const unsigned koa = ko + ((MODE == 2 && kt + 2 >= 8) ? (unsigned)(ZC_FQ - 512) * 2u : 0u);
;         const bool wr_ok = kt < 15, ld_ok = kt < 14;
; #pragma unroll
;         for (int i = 0; i < 4; ++i) { fa[i] = *(const bf16x8*)(sA + arow_off + i * 2048 + ch0); fb[i] = *(const bf16x8*)(sB + brow_off + i * 2048 + ch0); }
;         __builtin_amdgcn_sched_barrier(0);
;         __builtin_amdgcn_s_setprio(2);
;         if (wr_ok) *(uint4*)(nA + soff0) = ra0;
;         if (ld_ok) ra0 = *(const uint4*)(Ab + (aoff + 0u * LDA + koa));
;         ga[0] = *(const bf16x8*)(sA + arow_off + 0 * 2048 + ch1); gb[0] = *(const bf16x8*)(sB + brow_off + 0 * 2048 + ch1);
;         __builtin_amdgcn_sched_barrier(0);
; #pragma unroll
;         for (int j = 0; j < 4; ++j) acc[0][j] = __builtin_amdgcn_mfma_f32_16x16x32_bf16(fb[j], fa[0], acc[0][j], 0, 0, 0);
;         __builtin_amdgcn_sched_barrier(0);
;         if (wr_ok) *(uint4*)(nA + soff0 + 4096) = ra1;
;         if (ld_ok) ra1 = *(const uint4*)(Ab + (aoff + 32u * LDA + koa));
;         ga[1] = *(const bf16x8*)(sA + arow_off + 1 * 2048 + ch1); gb[1] = *(const bf16x8*)(sB + brow_off + 1 * 2048 + ch1);
;         __builtin_amdgcn_sched_barrier(0);
; #pragma unroll
;         for (int j = 0; j < 4; ++j) acc[1][j] = __builtin_amdgcn_mfma_f32_16x16x32_bf16(fb[j], fa[1], acc[1][j], 0, 0, 0);
;         __builtin_amdgcn_sched_barrier(0);
;         if (wr_ok) *(uint4*)(nA + soff0 + 8192) = ra2;
;         if (ld_ok) ra2 = *(const uint4*)(Ab + (aoff + 64u * LDA + koa));
;         ga[2] = *(const bf16x8*)(sA + arow_off + 2 * 2048 + ch1); gb[2] = *(const bf16x8*)(sB + brow_off + 2 * 2048 + ch1);
;         __builtin_amdgcn_sched_barrier(0);
; #pragma unroll
;         for (int j = 0; j < 4; ++j) acc[2][j] = __builtin_amdgcn_mfma_f32_16x16x32_bf16(fb[j], fa[2], acc[2][j], 0, 0, 0);
	ds_write_b128 v19, v[120:123] offset:40960
	ds_read_b128 v[120:123], v20 offset:4096
	ds_read_b128 v[180:183], v21 offset:20480
	v_mfma_f32_16x16x32_bf16 v[50:53], v[124:127], v[144:147], v[50:53]
	v_mfma_f32_16x16x32_bf16 v[62:65], v[140:143], v[144:147], v[62:65]
	v_mfma_f32_16x16x32_bf16 v[74:77], v[156:159], v[144:147], v[74:77]
	v_mfma_f32_16x16x32_bf16 v[34:37], v[160:163], v[144:147], v[34:37]
	global_load_dwordx4 v[144:147], v247, s[36:37] offset:1024
	ds_write_b128 v19, v[148:151] offset:45056
	ds_read_b128 v[148:151], v20 offset:6144
	ds_read_b128 v[184:187], v21 offset:22528
	v_mfma_f32_16x16x32_bf16 v[54:57], v[124:127], v[152:155], v[54:57]
	v_mfma_f32_16x16x32_bf16 v[66:69], v[140:143], v[152:155], v[66:69]
	v_mfma_f32_16x16x32_bf16 v[70:73], v[156:159], v[152:155], v[70:73]
	v_mfma_f32_16x16x32_bf16 v[38:41], v[160:163], v[152:155], v[38:41]
	global_load_dwordx4 v[124:127], v18, s[6:7] offset:1024
	s_waitcnt vmcnt(7)
	ds_write_b128 v19, v[136:139] offset:49152
	s_waitcnt lgkmcnt(10)
	v_mfma_f32_16x16x32_bf16 v[42:45], v[172:175], v[168:171], v[42:45]
	s_waitcnt lgkmcnt(1)
	v_mfma_f32_16x16x32_bf16 v[26:29], v[184:187], v[168:171], v[26:29]
	v_mfma_f32_16x16x32_bf16 v[96:99], v[176:179], v[168:171], v[96:99]
	v_mfma_f32_16x16x32_bf16 v[104:107], v[180:183], v[168:171], v[104:107]
	global_load_dwordx4 v[136:139], v248, s[6:7] offset:1024
	ds_write_b128 v19, v[132:135] offset:53248
	v_mfma_f32_16x16x32_bf16 v[46:49], v[172:175], v[108:111], v[46:49]
	v_mfma_f32_16x16x32_bf16 v[58:61], v[176:179], v[108:111], v[58:61]
	v_mfma_f32_16x16x32_bf16 v[30:33], v[184:187], v[108:111], v[30:33]
	v_mfma_f32_16x16x32_bf16 v[100:103], v[180:183], v[108:111], v[100:103]
	global_load_dwordx4 v[108:111], v249, s[6:7] offset:1024
	s_waitcnt vmcnt(7)
	ds_write_b128 v19, v[92:95] offset:57344
	v_mfma_f32_16x16x32_bf16 v[50:53], v[172:175], v[120:123], v[50:53]
	v_mfma_f32_16x16x32_bf16 v[62:65], v[176:179], v[120:123], v[62:65]
	v_mfma_f32_16x16x32_bf16 v[74:77], v[180:183], v[120:123], v[74:77]
	v_mfma_f32_16x16x32_bf16 v[34:37], v[184:187], v[120:123], v[34:37]
	global_load_dwordx4 v[92:95], v250, s[6:7] offset:1024
	ds_write_b128 v19, v[112:115] offset:61440
	v_mfma_f32_16x16x32_bf16 v[54:57], v[172:175], v[148:151], v[54:57]
	v_mfma_f32_16x16x32_bf16 v[66:69], v[176:179], v[148:151], v[66:69]
	v_mfma_f32_16x16x32_bf16 v[70:73], v[180:183], v[148:151], v[70:73]
	v_mfma_f32_16x16x32_bf16 v[38:41], v[184:187], v[148:151], v[38:41]
	s_setprio 0
	s_waitcnt lgkmcnt(0)
	s_barrier
	ds_read_b128 v[112:115], v22 offset:32768
	ds_read_b128 v[120:123], v22 offset:34816
	ds_read_b128 v[132:135], v23 offset:49152
	ds_read_b128 v[140:143], v23 offset:51200
	ds_read_b128 v[148:151], v22 offset:36864
	ds_read_b128 v[152:155], v22 offset:38912
	ds_read_b128 v[156:159], v23 offset:53248
	ds_read_b128 v[160:163], v23 offset:55296
	s_setprio 2
	global_load_dwordx4 v[168:171], v24, s[36:37] offset:1152
	s_waitcnt vmcnt(7)
	ds_write_b128 v19, v[164:167]
	ds_read_b128 v[164:167], v20 offset:32768
	ds_read_b128 v[172:175], v21 offset:49152
	s_waitcnt lgkmcnt(8)
	v_mfma_f32_16x16x32_bf16 v[42:45], v[132:135], v[112:115], v[42:45]
	s_waitcnt lgkmcnt(3)
	v_mfma_f32_16x16x32_bf16 v[26:29], v[160:163], v[112:115], v[26:29]
	v_mfma_f32_16x16x32_bf16 v[96:99], v[140:143], v[112:115], v[96:99]
	v_mfma_f32_16x16x32_bf16 v[104:107], v[156:159], v[112:115], v[104:107]
	global_load_dwordx4 v[112:115], v245, s[36:37] offset:1152
	ds_write_b128 v19, v[78:81] offset:4096
	ds_read_b128 v[78:81], v20 offset:34816
	ds_read_b128 v[176:179], v21 offset:51200
	v_mfma_f32_16x16x32_bf16 v[46:49], v[132:135], v[120:123], v[46:49]
	v_mfma_f32_16x16x32_bf16 v[58:61], v[140:143], v[120:123], v[58:61]
	v_mfma_f32_16x16x32_bf16 v[30:33], v[160:163], v[120:123], v[30:33]
	v_mfma_f32_16x16x32_bf16 v[100:103], v[156:159], v[120:123], v[100:103]
	global_load_dwordx4 v[120:123], v246, s[36:37] offset:1152
	s_waitcnt vmcnt(7)
	ds_write_b128 v19, v[116:119] offset:8192
	ds_read_b128 v[116:119], v20 offset:36864
	ds_read_b128 v[180:183], v21 offset:53248
	v_mfma_f32_16x16x32_bf16 v[50:53], v[132:135], v[148:151], v[50:53]
	v_mfma_f32_16x16x32_bf16 v[62:65], v[140:143], v[148:151], v[62:65]
	v_mfma_f32_16x16x32_bf16 v[74:77], v[156:159], v[148:151], v[74:77]
	v_mfma_f32_16x16x32_bf16 v[34:37], v[160:163], v[148:151], v[34:37]
	global_load_dwordx4 v[148:151], v247, s[36:37] offset:1152
	ds_write_b128 v19, v[144:147] offset:12288
	ds_read_b128 v[144:147], v20 offset:38912
	ds_read_b128 v[184:187], v21 offset:55296
	v_mfma_f32_16x16x32_bf16 v[54:57], v[132:135], v[152:155], v[54:57]
	v_mfma_f32_16x16x32_bf16 v[66:69], v[140:143], v[152:155], v[66:69]
	v_mfma_f32_16x16x32_bf16 v[70:73], v[156:159], v[152:155], v[70:73]
	v_mfma_f32_16x16x32_bf16 v[38:41], v[160:163], v[152:155], v[38:41]
	global_load_dwordx4 v[132:135], v18, s[6:7] offset:1152
	s_waitcnt vmcnt(7)
	ds_write_b128 v19, v[124:127] offset:16384
	s_waitcnt lgkmcnt(10)
	v_mfma_f32_16x16x32_bf16 v[42:45], v[172:175], v[164:167], v[42:45]
	s_waitcnt lgkmcnt(1)
	v_mfma_f32_16x16x32_bf16 v[26:29], v[184:187], v[164:167], v[26:29]
	v_mfma_f32_16x16x32_bf16 v[96:99], v[176:179], v[164:167], v[96:99]
	v_mfma_f32_16x16x32_bf16 v[104:107], v[180:183], v[164:167], v[104:107]
	global_load_dwordx4 v[124:127], v248, s[6:7] offset:1152
	ds_write_b128 v19, v[136:139] offset:20480
	v_mfma_f32_16x16x32_bf16 v[46:49], v[172:175], v[78:81], v[46:49]
	v_mfma_f32_16x16x32_bf16 v[58:61], v[176:179], v[78:81], v[58:61]
	v_mfma_f32_16x16x32_bf16 v[30:33], v[184:187], v[78:81], v[30:33]
	v_mfma_f32_16x16x32_bf16 v[100:103], v[180:183], v[78:81], v[100:103]
	global_load_dwordx4 v[78:81], v249, s[6:7] offset:1152
	s_waitcnt vmcnt(7)
	ds_write_b128 v19, v[108:111] offset:24576
	v_mfma_f32_16x16x32_bf16 v[50:53], v[172:175], v[116:119], v[50:53]
	v_mfma_f32_16x16x32_bf16 v[62:65], v[176:179], v[116:119], v[62:65]
	v_mfma_f32_16x16x32_bf16 v[74:77], v[180:183], v[116:119], v[74:77]
	v_mfma_f32_16x16x32_bf16 v[34:37], v[184:187], v[116:119], v[34:37]
	global_load_dwordx4 v[108:111], v250, s[6:7] offset:1152
	ds_write_b128 v19, v[92:95] offset:28672
	v_mfma_f32_16x16x32_bf16 v[54:57], v[172:175], v[144:147], v[54:57]
	v_mfma_f32_16x16x32_bf16 v[66:69], v[176:179], v[144:147], v[66:69]
	v_mfma_f32_16x16x32_bf16 v[70:73], v[180:183], v[144:147], v[70:73]
	v_mfma_f32_16x16x32_bf16 v[38:41], v[184:187], v[144:147], v[38:41]
	s_setprio 0
	s_waitcnt lgkmcnt(0)
	s_barrier
; template <int MODE>
; __device__ __forceinline__ void gemm_tile(const Params& P, int tm, int tn, unsigned char* smem) {
;     ...
;     for (int kt = 0; kt < 16; ++kt) {
;         unsigned char* sA = (kt & 1) ? sA1 : sA0; unsigned char* sB = (kt & 1) ? sB1 : sB0;
;         unsigned char* nA = (kt & 1) ? sA0 : sA1; unsigned char* nB = (kt & 1) ? sB0 : sB1;
;         bf16x8 fa[4], fb[4], ga[4], gb[4];
;         const int ch0 = ((g ^ sw) << 4), ch1 = (((4 + g) ^ sw) << 4);
;         const unsigned ko = (unsigned)(kt + 2) * 128u;
;         const unsigned koa = ko + ((MODE == 2 && kt + 2 >= 8) ? (unsigned)(ZC_FQ - 512) * 2u : 0u);
;         const bool wr_ok = kt < 15, ld_ok = kt < 14;
; #pragma unroll
;         for (int i = 0; i < 4; ++i) { fa[i] = *(const bf16x8*)(sA + arow_off + i * 2048 + ch0); fb[i] = *(const bf16x8*)(sB + brow_off + i * 2048 + ch0); }
;         __builtin_amdgcn_sched_barrier(0);
;         __builtin_amdgcn_s_setprio(2);
;         if (wr_ok) *(uint4*)(nA + soff0) = ra0;
;         if (ld_ok) ra0 = *(const uint4*)(Ab + (aoff + 0u * LDA + koa));
;         ga[0] = *(const bf16x8*)(sA + arow_off + 0 * 2048 + ch1); gb[0] = *(const bf16x8*)(sB + brow_off + 0 * 2048 + ch1);
;         __builtin_amdgcn_sched_barrier(0);
; #pragma unroll
;         for (int j = 0; j < 4; ++j) acc[0][j] = __builtin_amdgcn_mfma_f32_16x16x32_bf16(fb[j], fa[0], acc[0][j], 0, 0, 0);
;         __builtin_amdgcn_sched_barrier(0);
;         if (wr_ok) *(uint4*)(nA + soff0 + 4096) = ra1;
;         if (ld_ok) ra1 = *(const uint4*)(Ab + (aoff + 32u * LDA + koa));
;         ga[1] = *(const bf16x8*)(sA + arow_off + 1 * 2048 + ch1); gb[1] = *(const bf16x8*)(sB + brow_off + 1 * 2048 + ch1);
;         __builtin_amdgcn_sched_barrier(0);
; #pragma unroll
;         for (int j = 0; j < 4; ++j) acc[1][j] = __builtin_amdgcn_mfma_f32_16x16x32_bf16(fb[j], fa[1], acc[1][j], 0, 0, 0);
;         __builtin_amdgcn_sched_barrier(0);
;         if (wr_ok) *(uint4*)(nA + soff0 + 8192) = ra2;
;         if (ld_ok) ra2 = *(const uint4*)(Ab + (aoff + 64u * LDA + koa));
;         ga[2] = *(const bf16x8*)(sA + arow_off + 2 * 2048 + ch1); gb[2] = *(const bf16x8*)(sB + brow_off + 2 * 2048 + ch1);
;         __builtin_amdgcn_sched_barrier(0);
; #pragma unroll
;         for (int j = 0; j < 4; ++j) acc[2][j] = __builtin_amdgcn_mfma_f32_16x16x32_bf16(fb[j], fa[2], acc[2][j], 0, 0, 0);
	ds_read_b128 v[92:95], v22
	ds_read_b128 v[116:119], v22 offset:2048
	ds_read_b128 v[136:139], v23 offset:16384
	ds_read_b128 v[140:143], v23 offset:18432
	ds_read_b128 v[144:147], v22 offset:4096
	ds_read_b128 v[152:155], v22 offset:6144
	ds_read_b128 v[156:159], v23 offset:20480
	ds_read_b128 v[160:163], v23 offset:22528
	s_setprio 2
	global_load_dwordx4 v[164:167], v24, s[36:37] offset:1280
	s_waitcnt vmcnt(7)
	ds_write_b128 v19, v[168:171] offset:32768
	ds_read_b128 v[168:171], v20
	ds_read_b128 v[172:175], v21 offset:16384
	s_waitcnt lgkmcnt(8)
	v_mfma_f32_16x16x32_bf16 v[42:45], v[136:139], v[92:95], v[42:45]
	s_waitcnt lgkmcnt(3)
	v_mfma_f32_16x16x32_bf16 v[26:29], v[160:163], v[92:95], v[26:29]
	v_mfma_f32_16x16x32_bf16 v[96:99], v[140:143], v[92:95], v[96:99]
	v_mfma_f32_16x16x32_bf16 v[104:107], v[156:159], v[92:95], v[104:107]
	global_load_dwordx4 v[92:95], v245, s[36:37] offset:1280
	ds_write_b128 v19, v[112:115] offset:36864
	ds_read_b128 v[112:115], v20 offset:2048
	ds_read_b128 v[176:179], v21 offset:18432
	v_mfma_f32_16x16x32_bf16 v[46:49], v[136:139], v[116:119], v[46:49]
	v_mfma_f32_16x16x32_bf16 v[58:61], v[140:143], v[116:119], v[58:61]
	v_mfma_f32_16x16x32_bf16 v[30:33], v[160:163], v[116:119], v[30:33]
	v_mfma_f32_16x16x32_bf16 v[100:103], v[156:159], v[116:119], v[100:103]
	global_load_dwordx4 v[116:119], v246, s[36:37] offset:1280
	s_waitcnt vmcnt(7)
	ds_write_b128 v19, v[120:123] offset:40960
	ds_read_b128 v[120:123], v20 offset:4096
	ds_read_b128 v[180:183], v21 offset:20480
	v_mfma_f32_16x16x32_bf16 v[50:53], v[136:139], v[144:147], v[50:53]
	v_mfma_f32_16x16x32_bf16 v[62:65], v[140:143], v[144:147], v[62:65]
	v_mfma_f32_16x16x32_bf16 v[74:77], v[156:159], v[144:147], v[74:77]
	v_mfma_f32_16x16x32_bf16 v[34:37], v[160:163], v[144:147], v[34:37]
	global_load_dwordx4 v[144:147], v247, s[36:37] offset:1280
	ds_write_b128 v19, v[148:151] offset:45056
	ds_read_b128 v[148:151], v20 offset:6144
	ds_read_b128 v[184:187], v21 offset:22528
	v_mfma_f32_16x16x32_bf16 v[54:57], v[136:139], v[152:155], v[54:57]
	v_mfma_f32_16x16x32_bf16 v[66:69], v[140:143], v[152:155], v[66:69]
	v_mfma_f32_16x16x32_bf16 v[70:73], v[156:159], v[152:155], v[70:73]
	v_mfma_f32_16x16x32_bf16 v[38:41], v[160:163], v[152:155], v[38:41]
	global_load_dwordx4 v[136:139], v18, s[6:7] offset:1280
	s_waitcnt vmcnt(7)
	ds_write_b128 v19, v[132:135] offset:49152
	s_waitcnt lgkmcnt(10)
	v_mfma_f32_16x16x32_bf16 v[42:45], v[172:175], v[168:171], v[42:45]
	s_waitcnt lgkmcnt(1)
	v_mfma_f32_16x16x32_bf16 v[26:29], v[184:187], v[168:171], v[26:29]
	v_mfma_f32_16x16x32_bf16 v[96:99], v[176:179], v[168:171], v[96:99]
	v_mfma_f32_16x16x32_bf16 v[104:107], v[180:183], v[168:171], v[104:107]
	global_load_dwordx4 v[132:135], v248, s[6:7] offset:1280
	ds_write_b128 v19, v[124:127] offset:53248
	v_mfma_f32_16x16x32_bf16 v[46:49], v[172:175], v[112:115], v[46:49]
	v_mfma_f32_16x16x32_bf16 v[58:61], v[176:179], v[112:115], v[58:61]
	v_mfma_f32_16x16x32_bf16 v[30:33], v[184:187], v[112:115], v[30:33]
	v_mfma_f32_16x16x32_bf16 v[100:103], v[180:183], v[112:115], v[100:103]
	global_load_dwordx4 v[112:115], v249, s[6:7] offset:1280
	s_waitcnt vmcnt(7)
	ds_write_b128 v19, v[78:81] offset:57344
	v_mfma_f32_16x16x32_bf16 v[50:53], v[172:175], v[120:123], v[50:53]
	v_mfma_f32_16x16x32_bf16 v[62:65], v[176:179], v[120:123], v[62:65]
	v_mfma_f32_16x16x32_bf16 v[74:77], v[180:183], v[120:123], v[74:77]
	v_mfma_f32_16x16x32_bf16 v[34:37], v[184:187], v[120:123], v[34:37]
	global_load_dwordx4 v[78:81], v250, s[6:7] offset:1280
	ds_write_b128 v19, v[108:111] offset:61440
	v_mfma_f32_16x16x32_bf16 v[54:57], v[172:175], v[148:151], v[54:57]
	v_mfma_f32_16x16x32_bf16 v[66:69], v[176:179], v[148:151], v[66:69]
	v_mfma_f32_16x16x32_bf16 v[70:73], v[180:183], v[148:151], v[70:73]
	v_mfma_f32_16x16x32_bf16 v[38:41], v[184:187], v[148:151], v[38:41]
	s_setprio 0
	s_waitcnt lgkmcnt(0)
	s_barrier
	ds_read_b128 v[108:111], v22 offset:32768
	ds_read_b128 v[120:123], v22 offset:34816
	ds_read_b128 v[124:127], v23 offset:49152
	ds_read_b128 v[140:143], v23 offset:51200
	ds_read_b128 v[148:151], v22 offset:36864
	ds_read_b128 v[152:155], v22 offset:38912
	ds_read_b128 v[156:159], v23 offset:53248
	ds_read_b128 v[160:163], v23 offset:55296
	s_setprio 2
	global_load_dwordx4 v[168:171], v24, s[36:37] offset:1408
	s_waitcnt vmcnt(7)
	ds_write_b128 v19, v[164:167]
	ds_read_b128 v[164:167], v20 offset:32768
	ds_read_b128 v[172:175], v21 offset:49152
	s_waitcnt lgkmcnt(8)
	v_mfma_f32_16x16x32_bf16 v[42:45], v[124:127], v[108:111], v[42:45]
	s_waitcnt lgkmcnt(3)
	v_mfma_f32_16x16x32_bf16 v[26:29], v[160:163], v[108:111], v[26:29]
	v_mfma_f32_16x16x32_bf16 v[96:99], v[140:143], v[108:111], v[96:99]
	v_mfma_f32_16x16x32_bf16 v[104:107], v[156:159], v[108:111], v[104:107]
	global_load_dwordx4 v[108:111], v245, s[36:37] offset:1408
	ds_write_b128 v19, v[92:95] offset:4096
	ds_read_b128 v[92:95], v20 offset:34816
	ds_read_b128 v[176:179], v21 offset:51200
	v_mfma_f32_16x16x32_bf16 v[46:49], v[124:127], v[120:123], v[46:49]
	v_mfma_f32_16x16x32_bf16 v[58:61], v[140:143], v[120:123], v[58:61]
	v_mfma_f32_16x16x32_bf16 v[30:33], v[160:163], v[120:123], v[30:33]
	v_mfma_f32_16x16x32_bf16 v[100:103], v[156:159], v[120:123], v[100:103]
	global_load_dwordx4 v[120:123], v246, s[36:37] offset:1408
	s_waitcnt vmcnt(7)
; template <int MODE>
; __device__ __forceinline__ void gemm_tile(const Params& P, int tm, int tn, unsigned char* smem) {
;     ...
;     for (int kt = 0; kt < 16; ++kt) {
;         unsigned char* sA = (kt & 1) ? sA1 : sA0; unsigned char* sB = (kt & 1) ? sB1 : sB0;
;         unsigned char* nA = (kt & 1) ? sA0 : sA1; unsigned char* nB = (kt & 1) ? sB0 : sB1;
;         bf16x8 fa[4], fb[4], ga[4], gb[4];
;         const int ch0 = ((g ^ sw) << 4), ch1 = (((4 + g) ^ sw) << 4);
;         const unsigned ko = (unsigned)(kt + 2) * 128u;
;         const unsigned koa = ko + ((MODE == 2 && kt + 2 >= 8) ? (unsigned)(ZC_FQ - 512) * 2u : 0u);
;         const bool wr_ok = kt < 15, ld_ok = kt < 14;
; #pragma unroll
;         for (int i = 0; i < 4; ++i) { fa[i] = *(const bf16x8*)(sA + arow_off + i * 2048 + ch0); fb[i] = *(const bf16x8*)(sB + brow_off + i * 2048 + ch0); }
;         __builtin_amdgcn_sched_barrier(0);
;         __builtin_amdgcn_s_setprio(2);
;         if (wr_ok) *(uint4*)(nA + soff0) = ra0;
;         if (ld_ok) ra0 = *(const uint4*)(Ab + (aoff + 0u * LDA + koa));
;         ga[0] = *(const bf16x8*)(sA + arow_off + 0 * 2048 + ch1); gb[0] = *(const bf16x8*)(sB + brow_off + 0 * 2048 + ch1);
;         __builtin_amdgcn_sched_barrier(0);
; #pragma unroll
;         for (int j = 0; j < 4; ++j) acc[0][j] = __builtin_amdgcn_mfma_f32_16x16x32_bf16(fb[j], fa[0], acc[0][j], 0, 0, 0);
;         __builtin_amdgcn_sched_barrier(0);
;         if (wr_ok) *(uint4*)(nA + soff0 + 4096) = ra1;
;         if (ld_ok) ra1 = *(const uint4*)(Ab + (aoff + 32u * LDA + koa));
;         ga[1] = *(const bf16x8*)(sA + arow_off + 1 * 2048 + ch1); gb[1] = *(const bf16x8*)(sB + brow_off + 1 * 2048 + ch1);
;         __builtin_amdgcn_sched_barrier(0);
; #pragma unroll
;         for (int j = 0; j < 4; ++j) acc[1][j] = __builtin_amdgcn_mfma_f32_16x16x32_bf16(fb[j], fa[1], acc[1][j], 0, 0, 0);
;         __builtin_amdgcn_sched_barrier(0);
;         if (wr_ok) *(uint4*)(nA + soff0 + 8192) = ra2;
;         if (ld_ok) ra2 = *(const uint4*)(Ab + (aoff + 64u * LDA + koa));
;         ga[2] = *(const bf16x8*)(sA + arow_off + 2 * 2048 + ch1); gb[2] = *(const bf16x8*)(sB + brow_off + 2 * 2048 + ch1);
;         __builtin_amdgcn_sched_barrier(0);
; #pragma unroll
;         for (int j = 0; j < 4; ++j) acc[2][j] = __builtin_amdgcn_mfma_f32_16x16x32_bf16(fb[j], fa[2], acc[2][j], 0, 0, 0);
	ds_write_b128 v19, v[116:119] offset:8192
	ds_read_b128 v[116:119], v20 offset:36864
	ds_read_b128 v[180:183], v21 offset:53248
	v_mfma_f32_16x16x32_bf16 v[50:53], v[124:127], v[148:151], v[50:53]
	v_mfma_f32_16x16x32_bf16 v[62:65], v[140:143], v[148:151], v[62:65]
	v_mfma_f32_16x16x32_bf16 v[74:77], v[156:159], v[148:151], v[74:77]
	v_mfma_f32_16x16x32_bf16 v[34:37], v[160:163], v[148:151], v[34:37]
	global_load_dwordx4 v[148:151], v247, s[36:37] offset:1408
	ds_write_b128 v19, v[144:147] offset:12288
	ds_read_b128 v[144:147], v20 offset:38912
	ds_read_b128 v[184:187], v21 offset:55296
	v_mfma_f32_16x16x32_bf16 v[54:57], v[124:127], v[152:155], v[54:57]
	v_mfma_f32_16x16x32_bf16 v[66:69], v[140:143], v[152:155], v[66:69]
	v_mfma_f32_16x16x32_bf16 v[70:73], v[156:159], v[152:155], v[70:73]
	v_mfma_f32_16x16x32_bf16 v[38:41], v[160:163], v[152:155], v[38:41]
	global_load_dwordx4 v[124:127], v18, s[6:7] offset:1408
	s_waitcnt vmcnt(7)
	ds_write_b128 v19, v[136:139] offset:16384
	s_waitcnt lgkmcnt(10)
	v_mfma_f32_16x16x32_bf16 v[42:45], v[172:175], v[164:167], v[42:45]
	s_waitcnt lgkmcnt(1)
	v_mfma_f32_16x16x32_bf16 v[26:29], v[184:187], v[164:167], v[26:29]
	v_mfma_f32_16x16x32_bf16 v[96:99], v[176:179], v[164:167], v[96:99]
	v_mfma_f32_16x16x32_bf16 v[104:107], v[180:183], v[164:167], v[104:107]
	global_load_dwordx4 v[136:139], v248, s[6:7] offset:1408
	ds_write_b128 v19, v[132:135] offset:20480
	v_mfma_f32_16x16x32_bf16 v[46:49], v[172:175], v[92:95], v[46:49]
	v_mfma_f32_16x16x32_bf16 v[58:61], v[176:179], v[92:95], v[58:61]
	v_mfma_f32_16x16x32_bf16 v[30:33], v[184:187], v[92:95], v[30:33]
	v_mfma_f32_16x16x32_bf16 v[100:103], v[180:183], v[92:95], v[100:103]
	global_load_dwordx4 v[92:95], v249, s[6:7] offset:1408
	s_waitcnt vmcnt(7)
	ds_write_b128 v19, v[112:115] offset:24576
	v_mfma_f32_16x16x32_bf16 v[50:53], v[172:175], v[116:119], v[50:53]
	v_mfma_f32_16x16x32_bf16 v[62:65], v[176:179], v[116:119], v[62:65]
	v_mfma_f32_16x16x32_bf16 v[74:77], v[180:183], v[116:119], v[74:77]
	v_mfma_f32_16x16x32_bf16 v[34:37], v[184:187], v[116:119], v[34:37]
	global_load_dwordx4 v[112:115], v250, s[6:7] offset:1408
	ds_write_b128 v19, v[78:81] offset:28672
	v_mfma_f32_16x16x32_bf16 v[54:57], v[172:175], v[144:147], v[54:57]
	v_mfma_f32_16x16x32_bf16 v[66:69], v[176:179], v[144:147], v[66:69]
	v_mfma_f32_16x16x32_bf16 v[70:73], v[180:183], v[144:147], v[70:73]
	v_mfma_f32_16x16x32_bf16 v[38:41], v[184:187], v[144:147], v[38:41]
	s_setprio 0
	s_waitcnt lgkmcnt(0)
	s_barrier
	ds_read_b128 v[78:81], v22
	ds_read_b128 v[116:119], v22 offset:2048
	ds_read_b128 v[132:135], v23 offset:16384
	ds_read_b128 v[140:143], v23 offset:18432
	ds_read_b128 v[144:147], v22 offset:4096
	ds_read_b128 v[152:155], v22 offset:6144
	ds_read_b128 v[156:159], v23 offset:20480
	ds_read_b128 v[160:163], v23 offset:22528
	s_setprio 2
	global_load_dwordx4 v[164:167], v24, s[36:37] offset:1536
	s_waitcnt vmcnt(7)
	ds_write_b128 v19, v[168:171] offset:32768
	ds_read_b128 v[168:171], v20
	ds_read_b128 v[172:175], v21 offset:16384
	s_waitcnt lgkmcnt(8)
	v_mfma_f32_16x16x32_bf16 v[42:45], v[132:135], v[78:81], v[42:45]
	s_waitcnt lgkmcnt(3)
	v_mfma_f32_16x16x32_bf16 v[26:29], v[160:163], v[78:81], v[26:29]
	v_mfma_f32_16x16x32_bf16 v[96:99], v[140:143], v[78:81], v[96:99]
	v_mfma_f32_16x16x32_bf16 v[104:107], v[156:159], v[78:81], v[104:107]
	global_load_dwordx4 v[78:81], v245, s[36:37] offset:1536
	ds_write_b128 v19, v[108:111] offset:36864
	ds_read_b128 v[108:111], v20 offset:2048
	ds_read_b128 v[176:179], v21 offset:18432
	v_mfma_f32_16x16x32_bf16 v[46:49], v[132:135], v[116:119], v[46:49]
	v_mfma_f32_16x16x32_bf16 v[58:61], v[140:143], v[116:119], v[58:61]
	v_mfma_f32_16x16x32_bf16 v[30:33], v[160:163], v[116:119], v[30:33]
	v_mfma_f32_16x16x32_bf16 v[100:103], v[156:159], v[116:119], v[100:103]
	global_load_dwordx4 v[116:119], v246, s[36:37] offset:1536
	s_waitcnt vmcnt(7)
	ds_write_b128 v19, v[120:123] offset:40960
	ds_read_b128 v[120:123], v20 offset:4096
	ds_read_b128 v[180:183], v21 offset:20480
	v_mfma_f32_16x16x32_bf16 v[50:53], v[132:135], v[144:147], v[50:53]
	v_mfma_f32_16x16x32_bf16 v[62:65], v[140:143], v[144:147], v[62:65]
	v_mfma_f32_16x16x32_bf16 v[74:77], v[156:159], v[144:147], v[74:77]
	v_mfma_f32_16x16x32_bf16 v[34:37], v[160:163], v[144:147], v[34:37]
	global_load_dwordx4 v[144:147], v247, s[36:37] offset:1536
	ds_write_b128 v19, v[148:151] offset:45056
	ds_read_b128 v[148:151], v20 offset:6144
	ds_read_b128 v[184:187], v21 offset:22528
	v_mfma_f32_16x16x32_bf16 v[54:57], v[132:135], v[152:155], v[54:57]
	v_mfma_f32_16x16x32_bf16 v[66:69], v[140:143], v[152:155], v[66:69]
	v_mfma_f32_16x16x32_bf16 v[70:73], v[156:159], v[152:155], v[70:73]
	v_mfma_f32_16x16x32_bf16 v[38:41], v[160:163], v[152:155], v[38:41]
	global_load_dwordx4 v[132:135], v18, s[6:7] offset:1536
	s_waitcnt vmcnt(7)
	ds_write_b128 v19, v[124:127] offset:49152
	s_waitcnt lgkmcnt(10)
	v_mfma_f32_16x16x32_bf16 v[42:45], v[172:175], v[168:171], v[42:45]
	s_waitcnt lgkmcnt(1)
	v_mfma_f32_16x16x32_bf16 v[26:29], v[184:187], v[168:171], v[26:29]
	v_mfma_f32_16x16x32_bf16 v[96:99], v[176:179], v[168:171], v[96:99]
	v_mfma_f32_16x16x32_bf16 v[104:107], v[180:183], v[168:171], v[104:107]
	global_load_dwordx4 v[124:127], v248, s[6:7] offset:1536
	ds_write_b128 v19, v[136:139] offset:53248
	v_mfma_f32_16x16x32_bf16 v[46:49], v[172:175], v[108:111], v[46:49]
	v_mfma_f32_16x16x32_bf16 v[58:61], v[176:179], v[108:111], v[58:61]
	v_mfma_f32_16x16x32_bf16 v[30:33], v[184:187], v[108:111], v[30:33]
	v_mfma_f32_16x16x32_bf16 v[100:103], v[180:183], v[108:111], v[100:103]
	global_load_dwordx4 v[108:111], v249, s[6:7] offset:1536
	s_waitcnt vmcnt(7)
	ds_write_b128 v19, v[92:95] offset:57344
	v_mfma_f32_16x16x32_bf16 v[50:53], v[172:175], v[120:123], v[50:53]
	v_mfma_f32_16x16x32_bf16 v[62:65], v[176:179], v[120:123], v[62:65]
	v_mfma_f32_16x16x32_bf16 v[74:77], v[180:183], v[120:123], v[74:77]
	v_mfma_f32_16x16x32_bf16 v[34:37], v[184:187], v[120:123], v[34:37]
	global_load_dwordx4 v[92:95], v250, s[6:7] offset:1536
	ds_write_b128 v19, v[112:115] offset:61440
	v_mfma_f32_16x16x32_bf16 v[54:57], v[172:175], v[148:151], v[54:57]
	v_mfma_f32_16x16x32_bf16 v[66:69], v[176:179], v[148:151], v[66:69]
	v_mfma_f32_16x16x32_bf16 v[70:73], v[180:183], v[148:151], v[70:73]
	v_mfma_f32_16x16x32_bf16 v[38:41], v[184:187], v[148:151], v[38:41]
	s_setprio 0
	s_waitcnt lgkmcnt(0)
	s_barrier
; template <int MODE>
; __device__ __forceinline__ void gemm_tile(const Params& P, int tm, int tn, unsigned char* smem) {
;     ...
;     for (int kt = 0; kt < 16; ++kt) {
;         unsigned char* sA = (kt & 1) ? sA1 : sA0; unsigned char* sB = (kt & 1) ? sB1 : sB0;
;         unsigned char* nA = (kt & 1) ? sA0 : sA1; unsigned char* nB = (kt & 1) ? sB0 : sB1;
;         bf16x8 fa[4], fb[4], ga[4], gb[4];
;         const int ch0 = ((g ^ sw) << 4), ch1 = (((4 + g) ^ sw) << 4);
;         const unsigned ko = (unsigned)(kt + 2) * 128u;
;         const unsigned koa = ko + ((MODE == 2 && kt + 2 >= 8) ? (unsigned)(ZC_FQ - 512) * 2u : 0u);
;         const bool wr_ok = kt < 15, ld_ok = kt < 14;
; #pragma unroll
;         for (int i = 0; i < 4; ++i) { fa[i] = *(const bf16x8*)(sA + arow_off + i * 2048 + ch0); fb[i] = *(const bf16x8*)(sB + brow_off + i * 2048 + ch0); }
;         __builtin_amdgcn_sched_barrier(0);
;         __builtin_amdgcn_s_setprio(2);
;         if (wr_ok) *(uint4*)(nA + soff0) = ra0;
;         if (ld_ok) ra0 = *(const uint4*)(Ab + (aoff + 0u * LDA + koa));
;         ga[0] = *(const bf16x8*)(sA + arow_off + 0 * 2048 + ch1); gb[0] = *(const bf16x8*)(sB + brow_off + 0 * 2048 + ch1);
;         __builtin_amdgcn_sched_barrier(0);
; #pragma unroll
;         for (int j = 0; j < 4; ++j) acc[0][j] = __builtin_amdgcn_mfma_f32_16x16x32_bf16(fb[j], fa[0], acc[0][j], 0, 0, 0);
;         __builtin_amdgcn_sched_barrier(0);
;         if (wr_ok) *(uint4*)(nA + soff0 + 4096) = ra1;
;         if (ld_ok) ra1 = *(const uint4*)(Ab + (aoff + 32u * LDA + koa));
;         ga[1] = *(const bf16x8*)(sA + arow_off + 1 * 2048 + ch1); gb[1] = *(const bf16x8*)(sB + brow_off + 1 * 2048 + ch1);
;         __builtin_amdgcn_sched_barrier(0);
; #pragma unroll
;         for (int j = 0; j < 4; ++j) acc[1][j] = __builtin_amdgcn_mfma_f32_16x16x32_bf16(fb[j], fa[1], acc[1][j], 0, 0, 0);
;         __builtin_amdgcn_sched_barrier(0);
;         if (wr_ok) *(uint4*)(nA + soff0 + 8192) = ra2;
;         if (ld_ok) ra2 = *(const uint4*)(Ab + (aoff + 64u * LDA + koa));
;         ga[2] = *(const bf16x8*)(sA + arow_off + 2 * 2048 + ch1); gb[2] = *(const bf16x8*)(sB + brow_off + 2 * 2048 + ch1);
;         __builtin_amdgcn_sched_barrier(0);
; #pragma unroll
;         for (int j = 0; j < 4; ++j) acc[2][j] = __builtin_amdgcn_mfma_f32_16x16x32_bf16(fb[j], fa[2], acc[2][j], 0, 0, 0);
	ds_read_b128 v[112:115], v22 offset:32768
	ds_read_b128 v[120:123], v22 offset:34816
	ds_read_b128 v[136:139], v23 offset:49152
	ds_read_b128 v[140:143], v23 offset:51200
	ds_read_b128 v[148:151], v22 offset:36864
	ds_read_b128 v[152:155], v22 offset:38912
	ds_read_b128 v[156:159], v23 offset:53248
	ds_read_b128 v[160:163], v23 offset:55296
	s_setprio 2
	global_load_dwordx4 v[168:171], v24, s[36:37] offset:1664
	s_waitcnt vmcnt(7)
	ds_write_b128 v19, v[164:167]
	ds_read_b128 v[164:167], v20 offset:32768
	ds_read_b128 v[172:175], v21 offset:49152
	s_waitcnt lgkmcnt(8)
	v_mfma_f32_16x16x32_bf16 v[42:45], v[136:139], v[112:115], v[42:45]
	s_waitcnt lgkmcnt(3)
	v_mfma_f32_16x16x32_bf16 v[26:29], v[160:163], v[112:115], v[26:29]
	v_mfma_f32_16x16x32_bf16 v[96:99], v[140:143], v[112:115], v[96:99]
	v_mfma_f32_16x16x32_bf16 v[104:107], v[156:159], v[112:115], v[104:107]
	global_load_dwordx4 v[112:115], v245, s[36:37] offset:1664
	ds_write_b128 v19, v[78:81] offset:4096
	ds_read_b128 v[78:81], v20 offset:34816
	ds_read_b128 v[176:179], v21 offset:51200
	v_mfma_f32_16x16x32_bf16 v[46:49], v[136:139], v[120:123], v[46:49]
	v_mfma_f32_16x16x32_bf16 v[58:61], v[140:143], v[120:123], v[58:61]
	v_mfma_f32_16x16x32_bf16 v[30:33], v[160:163], v[120:123], v[30:33]
	v_mfma_f32_16x16x32_bf16 v[100:103], v[156:159], v[120:123], v[100:103]
	global_load_dwordx4 v[120:123], v246, s[36:37] offset:1664
	s_waitcnt vmcnt(7)
	ds_write_b128 v19, v[116:119] offset:8192
	ds_read_b128 v[116:119], v20 offset:36864
	ds_read_b128 v[180:183], v21 offset:53248
	v_mfma_f32_16x16x32_bf16 v[50:53], v[136:139], v[148:151], v[50:53]
	v_mfma_f32_16x16x32_bf16 v[62:65], v[140:143], v[148:151], v[62:65]
	v_mfma_f32_16x16x32_bf16 v[74:77], v[156:159], v[148:151], v[74:77]
	v_mfma_f32_16x16x32_bf16 v[34:37], v[160:163], v[148:151], v[34:37]
	global_load_dwordx4 v[148:151], v247, s[36:37] offset:1664
	ds_write_b128 v19, v[144:147] offset:12288
	ds_read_b128 v[144:147], v20 offset:38912
	ds_read_b128 v[184:187], v21 offset:55296
	v_mfma_f32_16x16x32_bf16 v[54:57], v[136:139], v[152:155], v[54:57]
	v_mfma_f32_16x16x32_bf16 v[66:69], v[140:143], v[152:155], v[66:69]
	v_mfma_f32_16x16x32_bf16 v[70:73], v[156:159], v[152:155], v[70:73]
	v_mfma_f32_16x16x32_bf16 v[38:41], v[160:163], v[152:155], v[38:41]
	global_load_dwordx4 v[136:139], v18, s[6:7] offset:1664
	s_waitcnt vmcnt(7)
	ds_write_b128 v19, v[132:135] offset:16384
	s_waitcnt lgkmcnt(10)
	v_mfma_f32_16x16x32_bf16 v[42:45], v[172:175], v[164:167], v[42:45]
	s_waitcnt lgkmcnt(1)
	v_mfma_f32_16x16x32_bf16 v[26:29], v[184:187], v[164:167], v[26:29]
	v_mfma_f32_16x16x32_bf16 v[96:99], v[176:179], v[164:167], v[96:99]
	v_mfma_f32_16x16x32_bf16 v[104:107], v[180:183], v[164:167], v[104:107]
	global_load_dwordx4 v[132:135], v248, s[6:7] offset:1664
	ds_write_b128 v19, v[124:127] offset:20480
	v_mfma_f32_16x16x32_bf16 v[46:49], v[172:175], v[78:81], v[46:49]
	v_mfma_f32_16x16x32_bf16 v[58:61], v[176:179], v[78:81], v[58:61]
	v_mfma_f32_16x16x32_bf16 v[30:33], v[184:187], v[78:81], v[30:33]
	v_mfma_f32_16x16x32_bf16 v[100:103], v[180:183], v[78:81], v[100:103]
	global_load_dwordx4 v[78:81], v249, s[6:7] offset:1664
	s_waitcnt vmcnt(7)
	ds_write_b128 v19, v[108:111] offset:24576
	v_mfma_f32_16x16x32_bf16 v[50:53], v[172:175], v[116:119], v[50:53]
	v_mfma_f32_16x16x32_bf16 v[62:65], v[176:179], v[116:119], v[62:65]
	v_mfma_f32_16x16x32_bf16 v[74:77], v[180:183], v[116:119], v[74:77]
	v_mfma_f32_16x16x32_bf16 v[34:37], v[184:187], v[116:119], v[34:37]
	global_load_dwordx4 v[108:111], v250, s[6:7] offset:1664
	ds_write_b128 v19, v[92:95] offset:28672
	v_mfma_f32_16x16x32_bf16 v[54:57], v[172:175], v[144:147], v[54:57]
	v_mfma_f32_16x16x32_bf16 v[66:69], v[176:179], v[144:147], v[66:69]
	v_mfma_f32_16x16x32_bf16 v[70:73], v[180:183], v[144:147], v[70:73]
	v_mfma_f32_16x16x32_bf16 v[38:41], v[184:187], v[144:147], v[38:41]
	s_setprio 0
	s_waitcnt lgkmcnt(0)
	s_barrier
	ds_read_b128 v[92:95], v22
	ds_read_b128 v[116:119], v22 offset:2048
	ds_read_b128 v[124:127], v23 offset:16384
	ds_read_b128 v[140:143], v23 offset:18432
	ds_read_b128 v[144:147], v22 offset:4096
	ds_read_b128 v[152:155], v22 offset:6144
	ds_read_b128 v[156:159], v23 offset:20480
	ds_read_b128 v[160:163], v23 offset:22528
	s_setprio 2
	global_load_dwordx4 v[164:167], v24, s[36:37] offset:1792
	s_waitcnt vmcnt(7)
	ds_write_b128 v19, v[168:171] offset:32768
	ds_read_b128 v[168:171], v20
	ds_read_b128 v[172:175], v21 offset:16384
	s_waitcnt lgkmcnt(8)
	v_mfma_f32_16x16x32_bf16 v[42:45], v[124:127], v[92:95], v[42:45]
	s_waitcnt lgkmcnt(3)
	v_mfma_f32_16x16x32_bf16 v[26:29], v[160:163], v[92:95], v[26:29]
	v_mfma_f32_16x16x32_bf16 v[96:99], v[140:143], v[92:95], v[96:99]
	v_mfma_f32_16x16x32_bf16 v[104:107], v[156:159], v[92:95], v[104:107]
	global_load_dwordx4 v[92:95], v245, s[36:37] offset:1792
	ds_write_b128 v19, v[112:115] offset:36864
	ds_read_b128 v[112:115], v20 offset:2048
	ds_read_b128 v[176:179], v21 offset:18432
	v_mfma_f32_16x16x32_bf16 v[46:49], v[124:127], v[116:119], v[46:49]
	v_mfma_f32_16x16x32_bf16 v[58:61], v[140:143], v[116:119], v[58:61]
	v_mfma_f32_16x16x32_bf16 v[30:33], v[160:163], v[116:119], v[30:33]
	v_mfma_f32_16x16x32_bf16 v[100:103], v[156:159], v[116:119], v[100:103]
	global_load_dwordx4 v[116:119], v246, s[36:37] offset:1792
	s_waitcnt vmcnt(7)
; template <int MODE>
; __device__ __forceinline__ void gemm_tile(const Params& P, int tm, int tn, unsigned char* smem) {
;     ...
;     for (int kt = 0; kt < 16; ++kt) {
;         unsigned char* sA = (kt & 1) ? sA1 : sA0; unsigned char* sB = (kt & 1) ? sB1 : sB0;
;         unsigned char* nA = (kt & 1) ? sA0 : sA1; unsigned char* nB = (kt & 1) ? sB0 : sB1;
;         bf16x8 fa[4], fb[4], ga[4], gb[4];
;         const int ch0 = ((g ^ sw) << 4), ch1 = (((4 + g) ^ sw) << 4);
;         const unsigned ko = (unsigned)(kt + 2) * 128u;
;         const unsigned koa = ko + ((MODE == 2 && kt + 2 >= 8) ? (unsigned)(ZC_FQ - 512) * 2u : 0u);
;         const bool wr_ok = kt < 15, ld_ok = kt < 14;
; #pragma unroll
;         for (int i = 0; i < 4; ++i) { fa[i] = *(const bf16x8*)(sA + arow_off + i * 2048 + ch0); fb[i] = *(const bf16x8*)(sB + brow_off + i * 2048 + ch0); }
;         __builtin_amdgcn_sched_barrier(0);
;         __builtin_amdgcn_s_setprio(2);
;         if (wr_ok) *(uint4*)(nA + soff0) = ra0;
;         if (ld_ok) ra0 = *(const uint4*)(Ab + (aoff + 0u * LDA + koa));
;         ga[0] = *(const bf16x8*)(sA + arow_off + 0 * 2048 + ch1); gb[0] = *(const bf16x8*)(sB + brow_off + 0 * 2048 + ch1);
;         __builtin_amdgcn_sched_barrier(0);
; #pragma unroll
;         for (int j = 0; j < 4; ++j) acc[0][j] = __builtin_amdgcn_mfma_f32_16x16x32_bf16(fb[j], fa[0], acc[0][j], 0, 0, 0);
;         __builtin_amdgcn_sched_barrier(0);
;         if (wr_ok) *(uint4*)(nA + soff0 + 4096) = ra1;
;         if (ld_ok) ra1 = *(const uint4*)(Ab + (aoff + 32u * LDA + koa));
;         ga[1] = *(const bf16x8*)(sA + arow_off + 1 * 2048 + ch1); gb[1] = *(const bf16x8*)(sB + brow_off + 1 * 2048 + ch1);
;         __builtin_amdgcn_sched_barrier(0);
; #pragma unroll
;         for (int j = 0; j < 4; ++j) acc[1][j] = __builtin_amdgcn_mfma_f32_16x16x32_bf16(fb[j], fa[1], acc[1][j], 0, 0, 0);
;         __builtin_amdgcn_sched_barrier(0);
;         if (wr_ok) *(uint4*)(nA + soff0 + 8192) = ra2;
;         if (ld_ok) ra2 = *(const uint4*)(Ab + (aoff + 64u * LDA + koa));
;         ga[2] = *(const bf16x8*)(sA + arow_off + 2 * 2048 + ch1); gb[2] = *(const bf16x8*)(sB + brow_off + 2 * 2048 + ch1);
;         __builtin_amdgcn_sched_barrier(0);
; #pragma unroll
;         for (int j = 0; j < 4; ++j) acc[2][j] = __builtin_amdgcn_mfma_f32_16x16x32_bf16(fb[j], fa[2], acc[2][j], 0, 0, 0);
	ds_write_b128 v19, v[120:123] offset:40960
	ds_read_b128 v[120:123], v20 offset:4096
	ds_read_b128 v[180:183], v21 offset:20480
	v_mfma_f32_16x16x32_bf16 v[50:53], v[124:127], v[144:147], v[50:53]
	v_mfma_f32_16x16x32_bf16 v[62:65], v[140:143], v[144:147], v[62:65]
	v_mfma_f32_16x16x32_bf16 v[74:77], v[156:159], v[144:147], v[74:77]
	v_mfma_f32_16x16x32_bf16 v[34:37], v[160:163], v[144:147], v[34:37]
	global_load_dwordx4 v[144:147], v247, s[36:37] offset:1792
	ds_write_b128 v19, v[148:151] offset:45056
	ds_read_b128 v[148:151], v20 offset:6144
	ds_read_b128 v[184:187], v21 offset:22528
	v_mfma_f32_16x16x32_bf16 v[54:57], v[124:127], v[152:155], v[54:57]
	v_mfma_f32_16x16x32_bf16 v[66:69], v[140:143], v[152:155], v[66:69]
	v_mfma_f32_16x16x32_bf16 v[70:73], v[156:159], v[152:155], v[70:73]
	v_mfma_f32_16x16x32_bf16 v[38:41], v[160:163], v[152:155], v[38:41]
	global_load_dwordx4 v[124:127], v18, s[6:7] offset:1792
	s_waitcnt vmcnt(7)
	ds_write_b128 v19, v[136:139] offset:49152
	s_waitcnt lgkmcnt(10)
	v_mfma_f32_16x16x32_bf16 v[42:45], v[172:175], v[168:171], v[42:45]
	s_waitcnt lgkmcnt(1)
	v_mfma_f32_16x16x32_bf16 v[26:29], v[184:187], v[168:171], v[26:29]
	v_mfma_f32_16x16x32_bf16 v[96:99], v[176:179], v[168:171], v[96:99]
	v_mfma_f32_16x16x32_bf16 v[104:107], v[180:183], v[168:171], v[104:107]
	global_load_dwordx4 v[136:139], v248, s[6:7] offset:1792
	ds_write_b128 v19, v[132:135] offset:53248
	v_mfma_f32_16x16x32_bf16 v[46:49], v[172:175], v[112:115], v[46:49]
	v_mfma_f32_16x16x32_bf16 v[58:61], v[176:179], v[112:115], v[58:61]
	v_mfma_f32_16x16x32_bf16 v[30:33], v[184:187], v[112:115], v[30:33]
	v_mfma_f32_16x16x32_bf16 v[100:103], v[180:183], v[112:115], v[100:103]
	global_load_dwordx4 v[112:115], v249, s[6:7] offset:1792
	s_waitcnt vmcnt(7)
	ds_write_b128 v19, v[78:81] offset:57344
	v_mfma_f32_16x16x32_bf16 v[50:53], v[172:175], v[120:123], v[50:53]
	v_mfma_f32_16x16x32_bf16 v[62:65], v[176:179], v[120:123], v[62:65]
	v_mfma_f32_16x16x32_bf16 v[74:77], v[180:183], v[120:123], v[74:77]
	v_mfma_f32_16x16x32_bf16 v[34:37], v[184:187], v[120:123], v[34:37]
	global_load_dwordx4 v[78:81], v250, s[6:7] offset:1792
	ds_write_b128 v19, v[108:111] offset:61440
	v_mfma_f32_16x16x32_bf16 v[54:57], v[172:175], v[148:151], v[54:57]
	v_mfma_f32_16x16x32_bf16 v[66:69], v[176:179], v[148:151], v[66:69]
	v_mfma_f32_16x16x32_bf16 v[70:73], v[180:183], v[148:151], v[70:73]
	v_mfma_f32_16x16x32_bf16 v[38:41], v[184:187], v[148:151], v[38:41]
	s_setprio 0
	s_waitcnt lgkmcnt(0)
	s_barrier
	ds_read_b128 v[108:111], v22 offset:32768
	ds_read_b128 v[120:123], v22 offset:34816
	ds_read_b128 v[132:135], v23 offset:49152
	ds_read_b128 v[140:143], v23 offset:51200
	ds_read_b128 v[148:151], v22 offset:36864
	ds_read_b128 v[152:155], v22 offset:38912
	ds_read_b128 v[156:159], v23 offset:53248
	ds_read_b128 v[160:163], v23 offset:55296
	s_setprio 2
	global_load_dwordx4 v[168:171], v24, s[36:37] offset:1920
	s_waitcnt vmcnt(7)
	ds_write_b128 v19, v[164:167]
	ds_read_b128 v[164:167], v20 offset:32768
	ds_read_b128 v[172:175], v21 offset:49152
	s_waitcnt lgkmcnt(8)
	v_mfma_f32_16x16x32_bf16 v[42:45], v[132:135], v[108:111], v[42:45]
	s_waitcnt lgkmcnt(3)
	v_mfma_f32_16x16x32_bf16 v[26:29], v[160:163], v[108:111], v[26:29]
	v_mfma_f32_16x16x32_bf16 v[96:99], v[140:143], v[108:111], v[96:99]
	v_mfma_f32_16x16x32_bf16 v[104:107], v[156:159], v[108:111], v[104:107]
	global_load_dwordx4 v[108:111], v245, s[36:37] offset:1920
	ds_write_b128 v19, v[92:95] offset:4096
	ds_read_b128 v[92:95], v20 offset:34816
	ds_read_b128 v[176:179], v21 offset:51200
	v_mfma_f32_16x16x32_bf16 v[46:49], v[132:135], v[120:123], v[46:49]
	v_mfma_f32_16x16x32_bf16 v[58:61], v[140:143], v[120:123], v[58:61]
	v_mfma_f32_16x16x32_bf16 v[30:33], v[160:163], v[120:123], v[30:33]
	v_mfma_f32_16x16x32_bf16 v[100:103], v[156:159], v[120:123], v[100:103]
	global_load_dwordx4 v[120:123], v246, s[36:37] offset:1920
	s_waitcnt vmcnt(7)
	ds_write_b128 v19, v[116:119] offset:8192
	ds_read_b128 v[116:119], v20 offset:36864
	ds_read_b128 v[180:183], v21 offset:53248
	v_mfma_f32_16x16x32_bf16 v[50:53], v[132:135], v[148:151], v[50:53]
	v_mfma_f32_16x16x32_bf16 v[62:65], v[140:143], v[148:151], v[62:65]
	v_mfma_f32_16x16x32_bf16 v[74:77], v[156:159], v[148:151], v[74:77]
	v_mfma_f32_16x16x32_bf16 v[34:37], v[160:163], v[148:151], v[34:37]
	v_add_u32_e32 v24, 0x30780, v24
	global_load_dwordx4 v[148:151], v24, s[36:37]
	ds_write_b128 v19, v[144:147] offset:12288
	ds_read_b128 v[144:147], v20 offset:38912
	ds_read_b128 v[184:187], v21 offset:55296
	v_mfma_f32_16x16x32_bf16 v[54:57], v[132:135], v[152:155], v[54:57]
	v_mfma_f32_16x16x32_bf16 v[66:69], v[140:143], v[152:155], v[66:69]
	v_mfma_f32_16x16x32_bf16 v[70:73], v[156:159], v[152:155], v[70:73]
	v_mfma_f32_16x16x32_bf16 v[38:41], v[160:163], v[152:155], v[38:41]
	global_load_dwordx4 v[132:135], v18, s[6:7] offset:1920
	s_waitcnt vmcnt(7)
	ds_write_b128 v19, v[124:127] offset:16384
	s_waitcnt lgkmcnt(10)
	v_mfma_f32_16x16x32_bf16 v[42:45], v[172:175], v[164:167], v[42:45]
	s_waitcnt lgkmcnt(1)
	v_mfma_f32_16x16x32_bf16 v[24:27], v[184:187], v[164:167], v[26:29]
	v_mfma_f32_16x16x32_bf16 v[96:99], v[176:179], v[164:167], v[96:99]
	v_mfma_f32_16x16x32_bf16 v[104:107], v[180:183], v[164:167], v[104:107]
	s_nop 0
	global_load_dwordx4 v[124:127], v248, s[6:7] offset:1920
	ds_write_b128 v19, v[136:139] offset:20480
	v_mfma_f32_16x16x32_bf16 v[46:49], v[172:175], v[92:95], v[46:49]
	v_mfma_f32_16x16x32_bf16 v[58:61], v[176:179], v[92:95], v[58:61]
	v_mfma_f32_16x16x32_bf16 v[28:31], v[184:187], v[92:95], v[30:33]
	v_mfma_f32_16x16x32_bf16 v[100:103], v[180:183], v[92:95], v[100:103]
	s_nop 1
	global_load_dwordx4 v[92:95], v249, s[6:7] offset:1920
	s_waitcnt vmcnt(7)
	ds_write_b128 v19, v[112:115] offset:24576
	v_mfma_f32_16x16x32_bf16 v[50:53], v[172:175], v[116:119], v[50:53]
	v_mfma_f32_16x16x32_bf16 v[62:65], v[176:179], v[116:119], v[62:65]
	v_mfma_f32_16x16x32_bf16 v[74:77], v[180:183], v[116:119], v[74:77]
	v_mfma_f32_16x16x32_bf16 v[32:35], v[184:187], v[116:119], v[34:37]
	v_add_u32_e32 v18, 0x30780, v18
	global_load_dwordx4 v[112:115], v18, s[6:7]
	ds_write_b128 v19, v[78:81] offset:28672
	v_mfma_f32_16x16x32_bf16 v[54:57], v[172:175], v[144:147], v[54:57]
	v_mfma_f32_16x16x32_bf16 v[66:69], v[176:179], v[144:147], v[66:69]
	v_mfma_f32_16x16x32_bf16 v[70:73], v[180:183], v[144:147], v[70:73]
	v_mfma_f32_16x16x32_bf16 v[36:39], v[184:187], v[144:147], v[38:41]
	s_setprio 0
	s_waitcnt lgkmcnt(0)
	s_barrier
; template <int MODE>
; __device__ __forceinline__ void gemm_tile(const Params& P, int tm, int tn, unsigned char* smem) {
;     ...
;     for (int kt = 0; kt < 16; ++kt) {
;         unsigned char* sA = (kt & 1) ? sA1 : sA0; unsigned char* sB = (kt & 1) ? sB1 : sB0;
;         unsigned char* nA = (kt & 1) ? sA0 : sA1; unsigned char* nB = (kt & 1) ? sB0 : sB1;
;         bf16x8 fa[4], fb[4], ga[4], gb[4];
;         const int ch0 = ((g ^ sw) << 4), ch1 = (((4 + g) ^ sw) << 4);
;         const unsigned ko = (unsigned)(kt + 2) * 128u;
;         const unsigned koa = ko + ((MODE == 2 && kt + 2 >= 8) ? (unsigned)(ZC_FQ - 512) * 2u : 0u);
;         const bool wr_ok = kt < 15, ld_ok = kt < 14;
; #pragma unroll
;         for (int i = 0; i < 4; ++i) { fa[i] = *(const bf16x8*)(sA + arow_off + i * 2048 + ch0); fb[i] = *(const bf16x8*)(sB + brow_off + i * 2048 + ch0); }
;         __builtin_amdgcn_sched_barrier(0);
;         __builtin_amdgcn_s_setprio(2);
;         if (wr_ok) *(uint4*)(nA + soff0) = ra0;
;         if (ld_ok) ra0 = *(const uint4*)(Ab + (aoff + 0u * LDA + koa));
;         ga[0] = *(const bf16x8*)(sA + arow_off + 0 * 2048 + ch1); gb[0] = *(const bf16x8*)(sB + brow_off + 0 * 2048 + ch1);
;         __builtin_amdgcn_sched_barrier(0);
; #pragma unroll
;         for (int j = 0; j < 4; ++j) acc[0][j] = __builtin_amdgcn_mfma_f32_16x16x32_bf16(fb[j], fa[0], acc[0][j], 0, 0, 0);
;         __builtin_amdgcn_sched_barrier(0);
;         if (wr_ok) *(uint4*)(nA + soff0 + 4096) = ra1;
;         if (ld_ok) ra1 = *(const uint4*)(Ab + (aoff + 32u * LDA + koa));
;         ga[1] = *(const bf16x8*)(sA + arow_off + 1 * 2048 + ch1); gb[1] = *(const bf16x8*)(sB + brow_off + 1 * 2048 + ch1);
;         __builtin_amdgcn_sched_barrier(0);
; #pragma unroll
;         for (int j = 0; j < 4; ++j) acc[1][j] = __builtin_amdgcn_mfma_f32_16x16x32_bf16(fb[j], fa[1], acc[1][j], 0, 0, 0);
;         __builtin_amdgcn_sched_barrier(0);
;         if (wr_ok) *(uint4*)(nA + soff0 + 8192) = ra2;
;         if (ld_ok) ra2 = *(const uint4*)(Ab + (aoff + 64u * LDA + koa));
;         ga[2] = *(const bf16x8*)(sA + arow_off + 2 * 2048 + ch1); gb[2] = *(const bf16x8*)(sB + brow_off + 2 * 2048 + ch1);
;         __builtin_amdgcn_sched_barrier(0);
; #pragma unroll
;         for (int j = 0; j < 4; ++j) acc[2][j] = __builtin_amdgcn_mfma_f32_16x16x32_bf16(fb[j], fa[2], acc[2][j], 0, 0, 0);
	ds_read_b128 v[78:81], v22
	ds_read_b128 v[116:119], v22 offset:2048
	ds_read_b128 v[136:139], v23 offset:16384
	ds_read_b128 v[140:143], v23 offset:18432
	ds_read_b128 v[144:147], v22 offset:4096
	ds_read_b128 v[152:155], v22 offset:6144
	ds_read_b128 v[156:159], v23 offset:20480
	ds_read_b128 v[160:163], v23 offset:22528
	s_setprio 2
	s_waitcnt vmcnt(7)
	ds_write_b128 v19, v[168:171] offset:32768
	ds_read_b128 v[164:167], v20
	ds_read_b128 v[168:171], v21 offset:16384
	s_waitcnt lgkmcnt(8)
	v_mfma_f32_16x16x32_bf16 v[40:43], v[136:139], v[78:81], v[42:45]
	s_waitcnt lgkmcnt(3)
	v_mfma_f32_16x16x32_bf16 v[24:27], v[160:163], v[78:81], v[24:27]
	v_mfma_f32_16x16x32_bf16 v[96:99], v[140:143], v[78:81], v[96:99]
	v_mfma_f32_16x16x32_bf16 v[104:107], v[156:159], v[78:81], v[104:107]
	s_waitcnt vmcnt(6)
	ds_write_b128 v19, v[108:111] offset:36864
	ds_read_b128 v[78:81], v20 offset:2048
	ds_read_b128 v[108:111], v21 offset:18432
	v_mfma_f32_16x16x32_bf16 v[44:47], v[136:139], v[116:119], v[46:49]
	v_mfma_f32_16x16x32_bf16 v[58:61], v[140:143], v[116:119], v[58:61]
	v_mfma_f32_16x16x32_bf16 v[28:31], v[160:163], v[116:119], v[28:31]
	v_mfma_f32_16x16x32_bf16 v[100:103], v[156:159], v[116:119], v[100:103]
	s_waitcnt vmcnt(5)
	ds_write_b128 v19, v[120:123] offset:40960
	ds_read_b128 v[116:119], v20 offset:4096
	ds_read_b128 v[120:123], v21 offset:20480
	v_mfma_f32_16x16x32_bf16 v[48:51], v[136:139], v[144:147], v[50:53]
	v_mfma_f32_16x16x32_bf16 v[62:65], v[140:143], v[144:147], v[62:65]
	v_mfma_f32_16x16x32_bf16 v[74:77], v[156:159], v[144:147], v[74:77]
	v_mfma_f32_16x16x32_bf16 v[32:35], v[160:163], v[144:147], v[32:35]
	s_waitcnt vmcnt(4)
	ds_write_b128 v19, v[148:151] offset:45056
	ds_read_b128 v[144:147], v20 offset:6144
	ds_read_b128 v[148:151], v21 offset:22528
	v_mfma_f32_16x16x32_bf16 v[52:55], v[136:139], v[152:155], v[54:57]
	v_mfma_f32_16x16x32_bf16 v[66:69], v[140:143], v[152:155], v[66:69]
	v_mfma_f32_16x16x32_bf16 v[70:73], v[156:159], v[152:155], v[70:73]
	v_mfma_f32_16x16x32_bf16 v[36:39], v[160:163], v[152:155], v[36:39]
	s_waitcnt vmcnt(3)
	ds_write_b128 v19, v[132:135] offset:49152
	s_waitcnt lgkmcnt(10)
	v_mfma_f32_16x16x32_bf16 v[40:43], v[168:171], v[164:167], v[40:43]
	s_waitcnt lgkmcnt(1)
	v_mfma_f32_16x16x32_bf16 v[24:27], v[148:151], v[164:167], v[24:27]
	v_mfma_f32_16x16x32_bf16 v[96:99], v[108:111], v[164:167], v[96:99]
	v_mfma_f32_16x16x32_bf16 v[104:107], v[120:123], v[164:167], v[104:107]
	s_waitcnt vmcnt(2)
	ds_write_b128 v19, v[124:127] offset:53248
	v_mfma_f32_16x16x32_bf16 v[44:47], v[168:171], v[78:81], v[44:47]
	v_mfma_f32_16x16x32_bf16 v[56:59], v[108:111], v[78:81], v[58:61]
	v_mfma_f32_16x16x32_bf16 v[28:31], v[148:151], v[78:81], v[28:31]
	v_mfma_f32_16x16x32_bf16 v[100:103], v[120:123], v[78:81], v[100:103]
	s_waitcnt vmcnt(1)
	ds_write_b128 v19, v[92:95] offset:57344
	v_mfma_f32_16x16x32_bf16 v[48:51], v[168:171], v[116:119], v[48:51]
	v_mfma_f32_16x16x32_bf16 v[60:63], v[108:111], v[116:119], v[62:65]
	v_mfma_f32_16x16x32_bf16 v[74:77], v[120:123], v[116:119], v[74:77]
	v_mfma_f32_16x16x32_bf16 v[32:35], v[148:151], v[116:119], v[32:35]
	s_waitcnt vmcnt(0)
	ds_write_b128 v19, v[112:115] offset:61440
	v_mfma_f32_16x16x32_bf16 v[52:55], v[168:171], v[144:147], v[52:55]
	v_mfma_f32_16x16x32_bf16 v[64:67], v[108:111], v[144:147], v[66:69]
	v_mfma_f32_16x16x32_bf16 v[68:71], v[120:123], v[144:147], v[70:73]
	v_mfma_f32_16x16x32_bf16 v[36:39], v[148:151], v[144:147], v[36:39]
	s_setprio 0
	s_waitcnt lgkmcnt(0)
	s_barrier
; template <int MODE>
; __device__ __forceinline__ void gemm_tile(const Params& P, int tm, int tn, unsigned char* smem) {
;     ...
;     for (int kt = 0; kt < 16; ++kt) {
;         unsigned char* sA = (kt & 1) ? sA1 : sA0; unsigned char* sB = (kt & 1) ? sB1 : sB0;
;         unsigned char* nA = (kt & 1) ? sA0 : sA1; unsigned char* nB = (kt & 1) ? sB0 : sB1;
;         bf16x8 fa[4], fb[4], ga[4], gb[4];
;         const int ch0 = ((g ^ sw) << 4), ch1 = (((4 + g) ^ sw) << 4);
;         const unsigned ko = (unsigned)(kt + 2) * 128u;
;         const unsigned koa = ko + ((MODE == 2 && kt + 2 >= 8) ? (unsigned)(ZC_FQ - 512) * 2u : 0u);
;         const bool wr_ok = kt < 15, ld_ok = kt < 14;
; #pragma unroll
;         for (int i = 0; i < 4; ++i) { fa[i] = *(const bf16x8*)(sA + arow_off + i * 2048 + ch0); fb[i] = *(const bf16x8*)(sB + brow_off + i * 2048 + ch0); }
;         __builtin_amdgcn_sched_barrier(0);
;         __builtin_amdgcn_s_setprio(2);
;         if (wr_ok) *(uint4*)(nA + soff0) = ra0;
;         if (ld_ok) ra0 = *(const uint4*)(Ab + (aoff + 0u * LDA + koa));
;         ga[0] = *(const bf16x8*)(sA + arow_off + 0 * 2048 + ch1); gb[0] = *(const bf16x8*)(sB + brow_off + 0 * 2048 + ch1);
;         __builtin_amdgcn_sched_barrier(0);
; #pragma unroll
;         for (int j = 0; j < 4; ++j) acc[0][j] = __builtin_amdgcn_mfma_f32_16x16x32_bf16(fb[j], fa[0], acc[0][j], 0, 0, 0);
;         __builtin_amdgcn_sched_barrier(0);
;         if (wr_ok) *(uint4*)(nA + soff0 + 4096) = ra1;
;         if (ld_ok) ra1 = *(const uint4*)(Ab + (aoff + 32u * LDA + koa));
;         ga[1] = *(const bf16x8*)(sA + arow_off + 1 * 2048 + ch1); gb[1] = *(const bf16x8*)(sB + brow_off + 1 * 2048 + ch1);
;         __builtin_amdgcn_sched_barrier(0);
; #pragma unroll
;         for (int j = 0; j < 4; ++j) acc[1][j] = __builtin_amdgcn_mfma_f32_16x16x32_bf16(fb[j], fa[1], acc[1][j], 0, 0, 0);
;         __builtin_amdgcn_sched_barrier(0);
;         if (wr_ok) *(uint4*)(nA + soff0 + 8192) = ra2;
;         if (ld_ok) ra2 = *(const uint4*)(Ab + (aoff + 64u * LDA + koa));
;         ga[2] = *(const bf16x8*)(sA + arow_off + 2 * 2048 + ch1); gb[2] = *(const bf16x8*)(sB + brow_off + 2 * 2048 + ch1);
;         __builtin_amdgcn_sched_barrier(0);
; #pragma unroll
;         for (int j = 0; j < 4; ++j) acc[2][j] = __builtin_amdgcn_mfma_f32_16x16x32_bf16(fb[j], fa[2], acc[2][j], 0, 0, 0);
	ds_read_b128 v[78:81], v22 offset:32768
	ds_read_b128 v[92:95], v22 offset:34816
	ds_read_b128 v[108:111], v23 offset:49152
	ds_read_b128 v[112:115], v23 offset:51200
	ds_read_b128 v[116:119], v22 offset:36864
	ds_read_b128 v[120:123], v22 offset:38912
	ds_read_b128 v[124:127], v23 offset:53248
	ds_read_b128 v[132:135], v23 offset:55296
	s_setprio 2
	ds_read_b128 v[136:139], v20 offset:32768
	ds_read_b128 v[140:143], v21 offset:49152
	s_waitcnt lgkmcnt(7)
	v_mfma_f32_16x16x32_bf16 v[40:43], v[108:111], v[78:81], v[40:43]
	s_waitcnt lgkmcnt(2)
	v_mfma_f32_16x16x32_bf16 v[22:25], v[132:135], v[78:81], v[24:27]
	v_mfma_f32_16x16x32_bf16 v[96:99], v[112:115], v[78:81], v[96:99]
	v_mfma_f32_16x16x32_bf16 v[104:107], v[124:127], v[78:81], v[104:107]
	ds_read_b128 v[144:147], v20 offset:34816
	ds_read_b128 v[148:151], v21 offset:51200
	v_mfma_f32_16x16x32_bf16 v[44:47], v[108:111], v[92:95], v[44:47]
	v_mfma_f32_16x16x32_bf16 v[56:59], v[112:115], v[92:95], v[56:59]
	v_mfma_f32_16x16x32_bf16 v[26:29], v[132:135], v[92:95], v[28:31]
	v_mfma_f32_16x16x32_bf16 v[100:103], v[124:127], v[92:95], v[100:103]
	ds_read_b128 v[92:95], v20 offset:36864
	ds_read_b128 v[152:155], v21 offset:53248
	v_mfma_f32_16x16x32_bf16 v[30:33], v[132:135], v[116:119], v[32:35]
	v_mfma_f32_16x16x32_bf16 v[156:159], v[108:111], v[116:119], v[48:51]
	v_mfma_f32_16x16x32_bf16 v[160:163], v[112:115], v[116:119], v[60:63]
	v_mfma_f32_16x16x32_bf16 v[164:167], v[124:127], v[116:119], v[74:77]
	ds_read_b128 v[116:119], v20 offset:38912
	ds_read_b128 v[18:21], v21 offset:55296
	v_mfma_f32_16x16x32_bf16 v[108:111], v[108:111], v[120:123], v[52:55]
	v_mfma_f32_16x16x32_bf16 v[112:115], v[112:115], v[120:123], v[64:67]
	v_mfma_f32_16x16x32_bf16 v[124:127], v[124:127], v[120:123], v[68:71]
	v_mfma_f32_16x16x32_bf16 v[120:123], v[132:135], v[120:123], v[36:39]
	s_waitcnt lgkmcnt(6)
	v_mfma_f32_16x16x32_bf16 v[78:81], v[140:143], v[136:139], v[40:43]
	s_waitcnt lgkmcnt(4)
	v_mfma_f32_16x16x32_bf16 v[74:77], v[148:151], v[136:139], v[96:99]
	s_waitcnt lgkmcnt(2)
	v_mfma_f32_16x16x32_bf16 v[70:73], v[152:155], v[136:139], v[104:107]
	s_waitcnt lgkmcnt(0)
	v_mfma_f32_16x16x32_bf16 v[66:69], v[18:21], v[136:139], v[22:25]
	v_mfma_f32_16x16x32_bf16 v[62:65], v[140:143], v[144:147], v[44:47]
	v_mfma_f32_16x16x32_bf16 v[58:61], v[148:151], v[144:147], v[56:59]
	v_mfma_f32_16x16x32_bf16 v[54:57], v[152:155], v[144:147], v[100:103]
	v_mfma_f32_16x16x32_bf16 v[50:53], v[18:21], v[144:147], v[26:29]
	v_mfma_f32_16x16x32_bf16 v[46:49], v[140:143], v[92:95], v[156:159]
	v_mfma_f32_16x16x32_bf16 v[42:45], v[148:151], v[92:95], v[160:163]
	v_mfma_f32_16x16x32_bf16 v[38:41], v[152:155], v[92:95], v[164:167]
	v_mfma_f32_16x16x32_bf16 v[34:37], v[18:21], v[92:95], v[30:33]
	v_mfma_f32_16x16x32_bf16 v[30:33], v[140:143], v[116:119], v[108:111]
	v_mfma_f32_16x16x32_bf16 v[26:29], v[148:151], v[116:119], v[112:115]
	v_mfma_f32_16x16x32_bf16 v[22:25], v[152:155], v[116:119], v[124:127]
	v_mfma_f32_16x16x32_bf16 v[18:21], v[18:21], v[116:119], v[120:123]
	s_setprio 0
	v_add_f32_e32 v10, v10, v11
	v_add_f32_e32 v11, v12, v13
	v_add_f32_e32 v10, v10, v11
	v_mov_b32_e32 v11, v10
	s_nop 1
	v_permlane32_swap_b32_e32 v10, v11
	v_add_f32_e32 v10, v10, v11
	v_mov_b32_e32 v11, v10
	s_nop 1
	v_permlane16_swap_b32_e32 v10, v11
	v_add_f32_e32 v10, v10, v11
	v_fmamk_f32 v10, v10, 0x3a800000, v86
	v_mul_f32_e32 v11, 0x4b800000, v10
	v_cmp_gt_f32_e64 s[0:1], s19, v10
	v_lshl_add_u64 v[84:85], v[84:85], 2, s[8:9]
	s_nop 0
	v_cndmask_b32_e64 v10, v10, v11, s[0:1]
	v_rsq_f32_e32 v10, v10
	v_or3_b32 v11, v91, s2, v89
	v_cmp_eq_u32_e32 vcc, 0, v11
	s_barrier
	v_mul_f32_e32 v11, 0x45800000, v10
	v_cndmask_b32_e64 v12, v10, v11, s[0:1]
	s_and_saveexec_b64 s[0:1], vcc
	s_cbranch_execz .LBB0_1265
	global_store_dword v[84:85], v12, off
